# stagger the two wave groups per tile instead of per phase: both groups run epilogue and tile header together (extra barriers moved from phase prologue/exit to every K-loop entry/exit)
# speedup vs baseline: 1.0118x; 1.0118x over previous
.LBB0_140:
	s_or_b64 exec, exec, s[0:1]
	s_add_u32 s96, s92, 0xfd00000
	s_addc_u32 s97, s93, 0
	s_add_u32 s80, s92, 0xbd00000
	s_addc_u32 s81, s93, 0
	v_lshlrev_b32_e32 v0, 6, v222
	v_lshlrev_b32_e32 v239, 2, v222
	s_ashr_i32 s77, s2, 31
	v_readfirstlane_b32 s3, v222
	v_and_b32_e32 v163, 15, v222
	v_and_b32_e32 v155, 0x3c0, v0
	v_and_b32_e32 v152, 32, v239
	s_cmpk_gt_i32 s2, 0x5ff
	v_bfe_u32 v157, v222, 2, 2
	v_bfe_u32 v218, v222, 2, 4
	v_lshrrev_b32_e32 v238, 5, v222
	v_lshrrev_b32_e32 v158, 1, v222
	v_lshlrev_b32_e32 v156, 4, v222
	v_and_b32_e32 v159, 32, v222
	v_and_b32_e32 v224, 64, v222
	v_lshrrev_b32_e32 v153, 3, v222
	s_cbranch_scc1 .LBB0_152
	v_and_b32_e32 v0, 4, v238
	s_waitcnt vmcnt(4)
	v_and_b32_e32 v10, 24, v158
	v_add_u32_e32 v8, 0x2000, v156
	v_or3_b32 v0, v0, v157, v10
	v_lshrrev_b32_e32 v1, 7, v8
	s_movk_i32 s0, 0xe0
	v_and_or_b32 v2, v1, s0, v0
	s_movk_i32 s0, 0xf0
	v_bitop3_b32 v9, v156, v159, 48 bitop3:0x6c
	v_and_or_b32 v1, v1, s0, v218
	s_movk_i32 s0, 0x60
	s_add_u32 s22, s92, 0x100000
	v_or_b32_e32 v3, v9, v224
	v_and_or_b32 v0, v153, s0, v0
	s_movk_i32 s0, 0x70
	s_addc_u32 s23, s93, 0
	v_lshl_or_b32 v132, v0, 12, v3
	v_and_or_b32 v0, v153, s0, v218
	s_lshr_b32 s0, s77, 29
	s_add_i32 s0, s2, s0
	s_lshr_b32 s6, s3, 6
	s_ashr_i32 s1, s0, 3
	s_and_b32 s0, s0, -8
	s_lshr_b32 s5, s3, 8
	s_lshl_b32 s24, s6, 10
	s_sub_i32 s0, s2, s0
	s_cmp_lt_i32 s0, 0
	s_movk_i32 s25, 0xc1
	s_cselect_b32 s4, s25, 0xc0
	s_mul_i32 s0, s4, s0
	s_add_i32 s0, s0, s1
	s_mul_hi_i32 s1, s0, 0x2aaaaaab
	s_lshr_b32 s4, s1, 31
	s_ashr_i32 s1, s1, 4
	s_add_i32 s1, s1, s4
	s_lshl_b32 s7, s1, 2
	s_mulk_i32 s1, 0x60
	s_sub_i32 s0, s0, s1
	s_bfe_i32 s1, s0, 0x80000
	s_bfe_u32 s1, s1, 0x2000d
	s_add_i32 s1, s0, s1
	s_bfe_i32 s4, s1, 0x80000
	s_and_b32 s1, s1, 0xfc
	s_sub_i32 s0, s0, s1
	s_sext_i32_i16 s4, s4
	s_sext_i32_i8 s0, s0
	s_lshr_b32 s4, s4, 2
	s_add_i32 s0, s7, s0
	s_ashr_i32 s1, s0, 31
	s_bfe_i64 s[10:11], s[4:5], 0x100000
	s_lshl_b64 s[8:9], s[0:1], 20
	s_lshl_b64 s[10:11], s[10:11], 20
	s_add_u32 s18, s22, s10
	s_addc_u32 s19, s23, s11
	s_add_i32 s1, s24, 0
	s_add_i32 m0, s1, 0x10000
	v_lshl_or_b32 v128, v2, 12, v3
	v_and_b32_e32 v144, 63, v222
	v_lshrrev_b32_e32 v145, 3, v144
	v_lshrrev_b32_e32 v146, 6, v222
	v_lshl_add_u32 v147, v146, 3, v145
	v_and_b32_e32 v148, 7, v144
	v_and_b32_e32 v149, 6, v145
	v_xor_b32_e32 v148, v148, v149
	v_lshlrev_b32_e32 v148, 4, v148
	v_mul_u32_u24_e32 v149, 0x1000, v147
	v_add_u32_e32 v149, v149, v148
	v_mov_b32_e32 v134, v149
	v_add_u32_e32 v130, 0x40000, v149
	v_mov_b32_e32 v136, v149
	v_add_u32_e32 v138, 0x40000, v149
	v_add_u32_e32 v130, 0x40000, v149
	v_add_u32_e32 v138, 0x40000, v149
	v_and_b32_e32 v149, 31, v147
	v_and_b32_e32 v150, 12, v149
	v_lshlrev_b32_e32 v150, 1, v150
	v_lshrrev_b32_e32 v151, 4, v149
	v_lshlrev_b32_e32 v151, 2, v151
	v_and_b32_e32 v149, 3, v149
	v_or3_b32 v149, v150, v151, v149
	v_and_b32_e32 v150, 0x60, v147
	v_add_u32_e32 v149, v149, v150
	v_mul_u32_u24_e32 v149, 0x1000, v149
	v_add_u32_e32 v149, v149, v148
	v_mov_b32_e32 v132, v149
	v_add_u32_e32 v128, 0x40000, v149
	v_add_u32_e32 v128, 0x40000, v149
	v_and_b32_e32 v149, 15, v144
	v_lshrrev_b32_e32 v150, 4, v144
	v_and_b32_e32 v151, 6, v149
	v_xor_b32_e32 v150, v150, v151
	v_lshlrev_b32_e32 v150, 4, v150
	v_lshl_or_b32 v150, v149, 7, v150
	v_lshrrev_b32_e32 v151, 2, v146
	v_lshl_add_u32 v151, v151, 13, v150
	v_add_u32_e32 v166, 0x0, v151
	v_and_b32_e32 v149, 3, v146
	v_lshl_add_u32 v149, v149, 12, v150
	v_add_u32_e32 v161, 0x0, v149
	v_add_u32_e32 v165, 0x10000, v149
	v_add_u32_e32 v167, 0x14000, v149
	global_load_lds_dwordx4 v132, s[18:19]
	s_add_i32 m0, s1, 0x12000
	s_add_u32 s16, s80, s8
	global_load_lds_dwordx4 v128, s[18:19]
	s_addc_u32 s17, s81, s9
	s_mov_b32 m0, s1
	s_add_i32 s26, s1, 0x2000
	global_load_lds_dwordx4 v134, s[16:17]
	s_mov_b32 m0, s26
	s_add_u32 s8, s18, 0x80000
	global_load_lds_dwordx4 v130, s[16:17]
	s_addc_u32 s9, s19, 0
	s_add_i32 m0, s1, 0x14000
	v_mov_b32_e32 v133, 0
	global_load_lds_dwordx4 v132, s[8:9]
	s_add_i32 m0, s1, 0x16000
	v_mov_b32_e32 v129, v133
	global_load_lds_dwordx4 v128, s[8:9]
	s_add_u32 s8, s16, 0x80000
	s_addc_u32 s9, s17, 0
	s_add_i32 s27, s1, 0x4000
	s_mov_b32 m0, s27
	s_add_i32 s28, s1, 0x6000
	global_load_lds_dwordx4 v134, s[8:9]
	s_mov_b32 m0, s28
	v_mov_b32_e32 v135, v133
	global_load_lds_dwordx4 v130, s[8:9]
	v_mov_b32_e32 v131, v133
	s_mov_b32 s29, 0
	v_lshl_add_u64 v[6:7], s[18:19], 0, v[132:133]
	v_lshl_add_u64 v[4:5], s[18:19], 0, v[128:129]
	v_lshl_add_u64 v[2:3], s[16:17], 0, v[134:135]
	s_cmp_lg_u32 s5, 1
	v_lshl_add_u64 v[0:1], s[16:17], 0, v[130:131]
	s_cbranch_scc1 .LBB0_143
.LBB0_143:
	s_lshl_b32 s6, s6, 5
	s_and_b32 s11, s6, 0x60
	s_mov_b64 s[6:7], 0x80
	s_add_i32 m0, s1, 0x18000
	v_lshl_add_u64 v[6:7], v[6:7], 0, s[6:7]
	s_lshl_b32 s10, s5, 13
	s_lshl_b32 s12, s11, 7
	s_waitcnt vmcnt(4)
	s_barrier
	global_load_lds_dwordx4 v[6:7], off
	v_lshl_add_u64 v[4:5], v[4:5], 0, s[6:7]
	s_add_i32 m0, s1, 0x1a000
	s_add_i32 s30, s1, 0x8000
	s_add_i32 s31, s1, 0xa000
	global_load_lds_dwordx4 v[4:5], off
	v_lshl_add_u64 v[2:3], v[2:3], 0, s[6:7]
	s_mov_b32 m0, s30
	s_add_u32 s8, s18, 0x80080
	global_load_lds_dwordx4 v[2:3], off
	v_lshl_add_u64 v[0:1], v[0:1], 0, s[6:7]
	s_mov_b32 m0, s31
	s_addc_u32 s9, s19, 0
	global_load_lds_dwordx4 v[0:1], off
	s_add_i32 m0, s1, 0x1c000
	v_lshl_add_u64 v[0:1], s[8:9], 0, v[132:133]
	global_load_lds_dwordx4 v[0:1], off
	v_lshl_add_u64 v[0:1], s[8:9], 0, v[128:129]
	s_add_i32 m0, s1, 0x1e000
	v_lshlrev_b32_e32 v2, 2, v163
	global_load_lds_dwordx4 v[0:1], off
	v_lshlrev_b32_e32 v0, 1, v10
	v_lshl_or_b32 v1, v163, 6, v0
	v_or_b32_e32 v0, v0, v155
	v_and_b32_e32 v2, 32, v2
	v_lshlrev_b32_e32 v0, 9, v222
	v_bitop3_b32 v1, v1, s10, v2 bitop3:0xde
	v_and_b32_e32 v0, 0x70000, v0
	v_lshlrev_b32_e32 v2, 12, v218
	v_or3_b32 v0, v9, v0, v2
	v_lshlrev_b32_e32 v0, 5, v8
	s_waitcnt vmcnt(6)
	v_and_b32_e32 v0, 0xf0000, v0
	v_or3_b32 v0, v9, v0, v2
	s_add_i32 s35, 0, 0x10000
	s_add_i32 s38, 0, 0x14000
	s_sext_i32_i8 s40, s4
	v_lshl_or_b32 v160, s5, 6, v163
	s_ashr_i32 s33, s94, 31
	s_mov_b32 s34, s94
	v_or_b32_e32 v164, s11, v10
	v_mov_b32_e32 v137, v133
	v_mov_b32_e32 v139, v133
	v_mov_b64_e32 v[140:141], 0x600
	v_mov_b64_e32 v[142:143], 0x5ff
	v_mov_b32_e32 v168, 0x3727c5ac
	s_movk_i32 s39, 0x3000
	s_barrier

.LBB0_146:
	s_ashr_i32 s11, s10, 31
	v_cmp_lt_i64_e32 vcc, s[12:13], v[140:141]
	s_lshl_b64 s[12:13], s[10:11], 20
	s_add_u32 s12, s80, s12
	s_addc_u32 s13, s81, s13
	s_and_b64 s[14:15], vcc, exec
	s_cselect_b32 s11, s13, s17
	s_cselect_b32 s41, s12, s16
	s_ashr_i32 s9, s8, 31
	s_lshl_b64 s[14:15], s[8:9], 20
	s_add_u32 s14, s22, s14
	s_addc_u32 s15, s23, s15
	s_and_b64 s[20:21], vcc, exec
	s_cselect_b32 s9, s15, s19
	s_cselect_b32 s44, s14, s18
	s_add_u32 s16, s16, 0x80080
	s_addc_u32 s17, s17, 0
	s_add_u32 s45, s18, 0x100
	v_mov_b32_e32 v0, 0
	s_addc_u32 s46, s19, 0
	s_mov_b32 s47, -2
	v_mov_b32_e32 v1, v0
	v_mov_b32_e32 v2, v0
	v_mov_b32_e32 v3, v0
	v_mov_b32_e32 v4, v0
	v_mov_b32_e32 v5, v0
	v_mov_b32_e32 v6, v0
	v_mov_b32_e32 v7, v0
	v_mov_b32_e32 v16, v0
	v_mov_b32_e32 v17, v0
	s_waitcnt vmcnt(0)
	v_mov_b32_e32 v18, v0
	v_mov_b32_e32 v19, v0
	v_mov_b32_e32 v20, v0
	v_mov_b32_e32 v21, v0
	v_mov_b32_e32 v22, v0
	v_mov_b32_e32 v23, v0
	v_mov_b32_e32 v32, v0
	v_mov_b32_e32 v33, v0
	v_mov_b32_e32 v34, v0
	v_mov_b32_e32 v35, v0
	v_mov_b32_e32 v36, v0
	v_mov_b32_e32 v37, v0
	v_mov_b32_e32 v38, v0
	v_mov_b32_e32 v39, v0
	v_mov_b32_e32 v48, v0
	v_mov_b32_e32 v49, v0
	v_mov_b32_e32 v50, v0
	v_mov_b32_e32 v51, v0
	v_mov_b32_e32 v52, v0
	v_mov_b32_e32 v53, v0
	v_mov_b32_e32 v54, v0
	v_mov_b32_e32 v55, v0
	v_mov_b32_e32 v8, v0
	v_mov_b32_e32 v9, v0
	v_mov_b32_e32 v10, v0
	v_mov_b32_e32 v11, v0
	v_mov_b32_e32 v12, v0
	v_mov_b32_e32 v13, v0
	v_mov_b32_e32 v14, v0
	v_mov_b32_e32 v15, v0
	v_mov_b32_e32 v24, v0
	v_mov_b32_e32 v25, v0
	v_mov_b32_e32 v26, v0
	v_mov_b32_e32 v27, v0
	v_mov_b32_e32 v28, v0
	v_mov_b32_e32 v29, v0
	v_mov_b32_e32 v30, v0
	v_mov_b32_e32 v31, v0
	v_mov_b32_e32 v40, v0
	v_mov_b32_e32 v41, v0
	v_mov_b32_e32 v42, v0
	v_mov_b32_e32 v43, v0
	v_mov_b32_e32 v44, v0
	v_mov_b32_e32 v45, v0
	v_mov_b32_e32 v46, v0
	v_mov_b32_e32 v47, v0
	v_mov_b32_e32 v56, v0
	v_mov_b32_e32 v57, v0
	v_mov_b32_e32 v58, v0
	v_mov_b32_e32 v59, v0
	v_mov_b32_e32 v60, v0
	v_mov_b32_e32 v61, v0
	v_mov_b32_e32 v62, v0
	v_mov_b32_e32 v63, v0
	v_mov_b32_e32 v64, v0
	v_mov_b32_e32 v65, v0
	v_mov_b32_e32 v66, v0
	v_mov_b32_e32 v67, v0
	v_mov_b32_e32 v68, v0
	v_mov_b32_e32 v69, v0
	v_mov_b32_e32 v70, v0
	v_mov_b32_e32 v71, v0
	v_mov_b32_e32 v80, v0
	v_mov_b32_e32 v81, v0
	v_mov_b32_e32 v82, v0
	v_mov_b32_e32 v83, v0
	v_mov_b32_e32 v84, v0
	v_mov_b32_e32 v85, v0
	v_mov_b32_e32 v86, v0
	v_mov_b32_e32 v87, v0
	v_mov_b32_e32 v96, v0
	v_mov_b32_e32 v97, v0
	v_mov_b32_e32 v98, v0
	v_mov_b32_e32 v99, v0
	v_mov_b32_e32 v100, v0
	v_mov_b32_e32 v101, v0
	v_mov_b32_e32 v102, v0
	v_mov_b32_e32 v103, v0
	v_mov_b32_e32 v112, v0
	v_mov_b32_e32 v113, v0
	v_mov_b32_e32 v114, v0
	v_mov_b32_e32 v115, v0
	v_mov_b32_e32 v116, v0
	v_mov_b32_e32 v117, v0
	v_mov_b32_e32 v118, v0
	v_mov_b32_e32 v119, v0
	v_mov_b32_e32 v72, v0
	v_mov_b32_e32 v73, v0
	v_mov_b32_e32 v74, v0
	v_mov_b32_e32 v75, v0
	v_mov_b32_e32 v76, v0
	v_mov_b32_e32 v77, v0
	v_mov_b32_e32 v78, v0
	v_mov_b32_e32 v79, v0
	v_mov_b32_e32 v88, v0
	v_mov_b32_e32 v89, v0
	v_mov_b32_e32 v90, v0
	v_mov_b32_e32 v91, v0
	v_mov_b32_e32 v92, v0
	v_mov_b32_e32 v93, v0
	v_mov_b32_e32 v94, v0
	v_mov_b32_e32 v95, v0
	v_mov_b32_e32 v104, v0
	v_mov_b32_e32 v105, v0
	v_mov_b32_e32 v106, v0
	v_mov_b32_e32 v107, v0
	v_mov_b32_e32 v108, v0
	v_mov_b32_e32 v109, v0
	v_mov_b32_e32 v110, v0
	v_mov_b32_e32 v111, v0
	v_mov_b32_e32 v120, v0
	v_mov_b32_e32 v121, v0
	v_mov_b32_e32 v122, v0
	v_mov_b32_e32 v123, v0
	v_mov_b32_e32 v124, v0
	v_mov_b32_e32 v125, v0
	v_mov_b32_e32 v126, v0
	v_mov_b32_e32 v127, v0
	v_xor_b32_e32 v220, 64, v165
	v_xor_b32_e32 v221, 64, v166
	v_xor_b32_e32 v234, 64, v167
	v_add_u32_e32 v235, 0x18000, v161
	v_xor_b32_e32 v236, 64, v235
	s_cmpk_lt_u32 s3, 0x100
	s_cbranch_scc1 .Lst_in_s1
	s_barrier
.Lst_in_s1:
.LBB0_147:
	ds_read_b128 v[144:147], v165
	ds_read_b128 v[148:151], v220
	ds_read_b128 v[170:173], v165 offset:2048
	ds_read_b128 v[174:177], v220 offset:2048
	s_add_u32 s18, s16, 0xfff80080
	s_addc_u32 s19, s17, -1
	s_cmp_eq_u32 s47, 28
	s_cselect_b32 s21, s11, s19
	s_cselect_b32 s20, s41, s18
	s_cselect_b32 s19, s9, s46
	s_cselect_b32 s18, s44, s45
	s_add_i32 m0, s1, 0xc000
	ds_read_b128 v[178:181], v166
	ds_read_b128 v[182:185], v221
	ds_read_b128 v[186:189], v166 offset:2048
	ds_read_b128 v[190:193], v221 offset:2048
	ds_read_b128 v[194:197], v166 offset:4096
	ds_read_b128 v[198:201], v221 offset:4096
	ds_read_b128 v[202:205], v166 offset:6144
	ds_read_b128 v[206:209], v221 offset:6144
	global_load_lds_dwordx4 v136, s[16:17]
	s_add_i32 m0, s1, 0xe000
	s_nop 0
	global_load_lds_dwordx4 v138, s[16:17]
	s_waitcnt lgkmcnt(8)
	s_barrier
	s_waitcnt lgkmcnt(0)
	s_waitcnt lgkmcnt(0)
	v_mfma_f32_16x16x32_bf16 v[124:127], v[144:147], v[178:181], v[124:127]
	v_mfma_f32_16x16x32_bf16 v[124:127], v[148:151], v[182:185], v[124:127]
	v_mfma_f32_16x16x32_bf16 v[120:123], v[174:177], v[182:185], v[120:123]
	v_mfma_f32_16x16x32_bf16 v[120:123], v[170:173], v[178:181], v[120:123]
	v_mfma_f32_16x16x32_bf16 v[104:107], v[170:173], v[186:189], v[104:107]
	v_mfma_f32_16x16x32_bf16 v[104:107], v[174:177], v[190:193], v[104:107]
	v_mfma_f32_16x16x32_bf16 v[108:111], v[148:151], v[190:193], v[108:111]
	v_mfma_f32_16x16x32_bf16 v[108:111], v[144:147], v[186:189], v[108:111]
	v_mfma_f32_16x16x32_bf16 v[92:95], v[144:147], v[194:197], v[92:95]
	v_mfma_f32_16x16x32_bf16 v[92:95], v[148:151], v[198:201], v[92:95]
	v_mfma_f32_16x16x32_bf16 v[88:91], v[174:177], v[198:201], v[88:91]
	v_mfma_f32_16x16x32_bf16 v[88:91], v[170:173], v[194:197], v[88:91]
	v_mfma_f32_16x16x32_bf16 v[72:75], v[170:173], v[202:205], v[72:75]
	v_mfma_f32_16x16x32_bf16 v[72:75], v[174:177], v[206:209], v[72:75]
	v_mfma_f32_16x16x32_bf16 v[76:79], v[148:151], v[206:209], v[76:79]
	v_mfma_f32_16x16x32_bf16 v[76:79], v[144:147], v[202:205], v[76:79]
	s_barrier
	s_add_i32 s48, s35, s24
	s_add_u32 s98, s18, s6
	s_addc_u32 s99, s19, s7
	s_mov_b32 m0, s48
	ds_read_b128 v[210:213], v167
	ds_read_b128 v[214:217], v234
	ds_read_b128 v[226:229], v167 offset:2048
	ds_read_b128 v[230:233], v234 offset:2048
	global_load_lds_dwordx4 v132, s[18:19]
	s_add_i32 m0, s48, 0x2000
	s_nop 0
	global_load_lds_dwordx4 v128, s[18:19]
	s_barrier
	s_waitcnt lgkmcnt(0)
	s_waitcnt lgkmcnt(0)
	v_mfma_f32_16x16x32_bf16 v[116:119], v[210:213], v[178:181], v[116:119]
	v_mfma_f32_16x16x32_bf16 v[116:119], v[214:217], v[182:185], v[116:119]
	v_mfma_f32_16x16x32_bf16 v[112:115], v[230:233], v[182:185], v[112:115]
	v_mfma_f32_16x16x32_bf16 v[112:115], v[226:229], v[178:181], v[112:115]
	v_mfma_f32_16x16x32_bf16 v[96:99], v[226:229], v[186:189], v[96:99]
	v_mfma_f32_16x16x32_bf16 v[96:99], v[230:233], v[190:193], v[96:99]
	v_mfma_f32_16x16x32_bf16 v[100:103], v[214:217], v[190:193], v[100:103]
	v_mfma_f32_16x16x32_bf16 v[100:103], v[210:213], v[186:189], v[100:103]
	v_mfma_f32_16x16x32_bf16 v[84:87], v[210:213], v[194:197], v[84:87]
	v_mfma_f32_16x16x32_bf16 v[84:87], v[214:217], v[198:201], v[84:87]
	v_mfma_f32_16x16x32_bf16 v[80:83], v[230:233], v[198:201], v[80:83]
	v_mfma_f32_16x16x32_bf16 v[80:83], v[226:229], v[194:197], v[80:83]
	v_mfma_f32_16x16x32_bf16 v[64:67], v[226:229], v[202:205], v[64:67]
	v_mfma_f32_16x16x32_bf16 v[64:67], v[230:233], v[206:209], v[64:67]
	v_mfma_f32_16x16x32_bf16 v[68:71], v[214:217], v[206:209], v[68:71]
	v_mfma_f32_16x16x32_bf16 v[68:71], v[210:213], v[202:205], v[68:71]
	s_mov_b32 m0, s1
	s_add_u32 s100, s20, s6
	s_addc_u32 s101, s21, s7
	s_barrier
	ds_read_b128 v[178:181], v166 offset:16384
	ds_read_b128 v[182:185], v221 offset:16384
	ds_read_b128 v[186:189], v166 offset:18432
	ds_read_b128 v[190:193], v221 offset:18432
	ds_read_b128 v[194:197], v166 offset:20480
	ds_read_b128 v[198:201], v221 offset:20480
	ds_read_b128 v[202:205], v166 offset:22528
	ds_read_b128 v[206:209], v221 offset:22528
	global_load_lds_dwordx4 v134, s[20:21]
	s_mov_b32 m0, s26
	s_nop 0
	global_load_lds_dwordx4 v130, s[20:21]
	s_barrier
	s_waitcnt lgkmcnt(0)
	s_waitcnt lgkmcnt(0)
	v_mfma_f32_16x16x32_bf16 v[60:63], v[144:147], v[178:181], v[60:63]
	v_mfma_f32_16x16x32_bf16 v[60:63], v[148:151], v[182:185], v[60:63]
	v_mfma_f32_16x16x32_bf16 v[56:59], v[174:177], v[182:185], v[56:59]
	v_mfma_f32_16x16x32_bf16 v[56:59], v[170:173], v[178:181], v[56:59]
	v_mfma_f32_16x16x32_bf16 v[40:43], v[170:173], v[186:189], v[40:43]
	v_mfma_f32_16x16x32_bf16 v[40:43], v[174:177], v[190:193], v[40:43]
	v_mfma_f32_16x16x32_bf16 v[44:47], v[148:151], v[190:193], v[44:47]
	v_mfma_f32_16x16x32_bf16 v[44:47], v[144:147], v[186:189], v[44:47]
	v_mfma_f32_16x16x32_bf16 v[28:31], v[144:147], v[194:197], v[28:31]
	v_mfma_f32_16x16x32_bf16 v[28:31], v[148:151], v[198:201], v[28:31]
	v_mfma_f32_16x16x32_bf16 v[24:27], v[174:177], v[198:201], v[24:27]
	v_mfma_f32_16x16x32_bf16 v[24:27], v[170:173], v[194:197], v[24:27]
	v_mfma_f32_16x16x32_bf16 v[8:11], v[170:173], v[202:205], v[8:11]
	v_mfma_f32_16x16x32_bf16 v[8:11], v[174:177], v[206:209], v[8:11]
	v_mfma_f32_16x16x32_bf16 v[12:15], v[148:151], v[206:209], v[12:15]
	v_mfma_f32_16x16x32_bf16 v[12:15], v[144:147], v[202:205], v[12:15]
	s_barrier
	s_add_u32 s48, s18, 0x80000
	s_addc_u32 s49, s19, 0
	s_add_i32 s52, s38, s24
	s_mov_b32 m0, s52
	s_nop 0
	global_load_lds_dwordx4 v132, s[48:49]
	s_add_i32 m0, s52, 0x2000
	s_nop 0
	global_load_lds_dwordx4 v128, s[48:49]
	s_waitcnt vmcnt(6)
	s_barrier
	v_mfma_f32_16x16x32_bf16 v[52:55], v[210:213], v[178:181], v[52:55]
	v_mfma_f32_16x16x32_bf16 v[52:55], v[214:217], v[182:185], v[52:55]
	v_mfma_f32_16x16x32_bf16 v[48:51], v[230:233], v[182:185], v[48:51]
	v_mfma_f32_16x16x32_bf16 v[48:51], v[226:229], v[178:181], v[48:51]
	v_mfma_f32_16x16x32_bf16 v[32:35], v[226:229], v[186:189], v[32:35]
	v_mfma_f32_16x16x32_bf16 v[32:35], v[230:233], v[190:193], v[32:35]
	v_mfma_f32_16x16x32_bf16 v[36:39], v[214:217], v[190:193], v[36:39]
	v_mfma_f32_16x16x32_bf16 v[36:39], v[210:213], v[186:189], v[36:39]
	v_mfma_f32_16x16x32_bf16 v[20:23], v[210:213], v[194:197], v[20:23]
	v_mfma_f32_16x16x32_bf16 v[20:23], v[214:217], v[198:201], v[20:23]
	v_mfma_f32_16x16x32_bf16 v[16:19], v[230:233], v[198:201], v[16:19]
	v_mfma_f32_16x16x32_bf16 v[16:19], v[226:229], v[194:197], v[16:19]
	v_mfma_f32_16x16x32_bf16 v[0:3], v[226:229], v[202:205], v[0:3]
	v_mfma_f32_16x16x32_bf16 v[0:3], v[230:233], v[206:209], v[0:3]
	v_mfma_f32_16x16x32_bf16 v[4:7], v[214:217], v[206:209], v[4:7]
	v_mfma_f32_16x16x32_bf16 v[4:7], v[210:213], v[202:205], v[4:7]
	s_add_i32 s48, 0, 0x18000
	s_barrier
	ds_read_b128 v[144:147], v235
	ds_read_b128 v[148:151], v236
	ds_read_b128 v[170:173], v235 offset:2048
	ds_read_b128 v[174:177], v236 offset:2048
	s_add_u32 s20, s20, 0x80000
	s_addc_u32 s21, s21, 0
	s_mov_b32 m0, s27
	ds_read_b128 v[178:181], v166 offset:32768
	ds_read_b128 v[182:185], v221 offset:32768
	ds_read_b128 v[186:189], v166 offset:34816
	ds_read_b128 v[190:193], v221 offset:34816
	ds_read_b128 v[194:197], v166 offset:36864
	ds_read_b128 v[198:201], v221 offset:36864
	ds_read_b128 v[202:205], v166 offset:38912
	ds_read_b128 v[206:209], v221 offset:38912
	global_load_lds_dwordx4 v134, s[20:21]
	s_mov_b32 m0, s28
	s_nop 0
	global_load_lds_dwordx4 v130, s[20:21]
	s_waitcnt lgkmcnt(8)
	s_barrier
	s_waitcnt lgkmcnt(0)
	s_waitcnt lgkmcnt(0)
	v_mfma_f32_16x16x32_bf16 v[124:127], v[144:147], v[178:181], v[124:127]
	v_mfma_f32_16x16x32_bf16 v[124:127], v[148:151], v[182:185], v[124:127]
	v_mfma_f32_16x16x32_bf16 v[120:123], v[174:177], v[182:185], v[120:123]
	v_mfma_f32_16x16x32_bf16 v[120:123], v[170:173], v[178:181], v[120:123]
	v_mfma_f32_16x16x32_bf16 v[104:107], v[170:173], v[186:189], v[104:107]
	v_mfma_f32_16x16x32_bf16 v[104:107], v[174:177], v[190:193], v[104:107]
	v_mfma_f32_16x16x32_bf16 v[108:111], v[148:151], v[190:193], v[108:111]
	v_mfma_f32_16x16x32_bf16 v[108:111], v[144:147], v[186:189], v[108:111]
	v_mfma_f32_16x16x32_bf16 v[92:95], v[144:147], v[194:197], v[92:95]
	v_mfma_f32_16x16x32_bf16 v[92:95], v[148:151], v[198:201], v[92:95]
	v_mfma_f32_16x16x32_bf16 v[88:91], v[174:177], v[198:201], v[88:91]
	v_mfma_f32_16x16x32_bf16 v[88:91], v[170:173], v[194:197], v[88:91]
	v_mfma_f32_16x16x32_bf16 v[72:75], v[170:173], v[202:205], v[72:75]
	v_mfma_f32_16x16x32_bf16 v[72:75], v[174:177], v[206:209], v[72:75]
	v_mfma_f32_16x16x32_bf16 v[76:79], v[148:151], v[206:209], v[76:79]
	v_mfma_f32_16x16x32_bf16 v[76:79], v[144:147], v[202:205], v[76:79]
	s_barrier
	s_add_i32 s20, 0, 0x1c000
	s_add_i32 s21, s48, s24
	v_add_u32_e32 v169, s20, v161
	s_mov_b32 m0, s21
	ds_read_b128 v[210:213], v169
	v_xor_b32_e32 v233, 64, v169
	ds_read_b128 v[214:217], v233
	ds_read_b128 v[226:229], v169 offset:2048
	ds_read_b128 v[230:233], v233 offset:2048
	global_load_lds_dwordx4 v132, s[98:99]
	s_add_i32 m0, s21, 0x2000
	s_nop 0
	global_load_lds_dwordx4 v128, s[98:99]
	s_barrier
	s_waitcnt lgkmcnt(0)
	s_waitcnt lgkmcnt(0)
	v_mfma_f32_16x16x32_bf16 v[116:119], v[210:213], v[178:181], v[116:119]
	v_mfma_f32_16x16x32_bf16 v[116:119], v[214:217], v[182:185], v[116:119]
	v_mfma_f32_16x16x32_bf16 v[112:115], v[230:233], v[182:185], v[112:115]
	v_mfma_f32_16x16x32_bf16 v[112:115], v[226:229], v[178:181], v[112:115]
	v_mfma_f32_16x16x32_bf16 v[96:99], v[226:229], v[186:189], v[96:99]
	v_mfma_f32_16x16x32_bf16 v[96:99], v[230:233], v[190:193], v[96:99]
	v_mfma_f32_16x16x32_bf16 v[100:103], v[214:217], v[190:193], v[100:103]
	v_mfma_f32_16x16x32_bf16 v[100:103], v[210:213], v[186:189], v[100:103]
	v_mfma_f32_16x16x32_bf16 v[84:87], v[210:213], v[194:197], v[84:87]
	v_mfma_f32_16x16x32_bf16 v[84:87], v[214:217], v[198:201], v[84:87]
	v_mfma_f32_16x16x32_bf16 v[80:83], v[230:233], v[198:201], v[80:83]
	v_mfma_f32_16x16x32_bf16 v[80:83], v[226:229], v[194:197], v[80:83]
	v_mfma_f32_16x16x32_bf16 v[64:67], v[226:229], v[202:205], v[64:67]
	v_mfma_f32_16x16x32_bf16 v[64:67], v[230:233], v[206:209], v[64:67]
	v_mfma_f32_16x16x32_bf16 v[68:71], v[214:217], v[206:209], v[68:71]
	v_mfma_f32_16x16x32_bf16 v[68:71], v[210:213], v[202:205], v[68:71]
	s_mov_b32 m0, s30
	s_barrier
	ds_read_b128 v[178:181], v166 offset:49152
	ds_read_b128 v[182:185], v221 offset:49152
	ds_read_b128 v[186:189], v166 offset:51200
	ds_read_b128 v[190:193], v221 offset:51200
	ds_read_b128 v[194:197], v166 offset:53248
	ds_read_b128 v[198:201], v221 offset:53248
	ds_read_b128 v[202:205], v166 offset:55296
	ds_read_b128 v[206:209], v221 offset:55296
	global_load_lds_dwordx4 v134, s[100:101]
	s_mov_b32 m0, s31
	s_nop 0
	global_load_lds_dwordx4 v130, s[100:101]
	s_barrier
	s_waitcnt lgkmcnt(0)
	s_waitcnt lgkmcnt(0)
	v_mfma_f32_16x16x32_bf16 v[60:63], v[144:147], v[178:181], v[60:63]
	v_mfma_f32_16x16x32_bf16 v[60:63], v[148:151], v[182:185], v[60:63]
	v_mfma_f32_16x16x32_bf16 v[56:59], v[174:177], v[182:185], v[56:59]
	v_mfma_f32_16x16x32_bf16 v[56:59], v[170:173], v[178:181], v[56:59]
	v_mfma_f32_16x16x32_bf16 v[40:43], v[170:173], v[186:189], v[40:43]
	v_mfma_f32_16x16x32_bf16 v[40:43], v[174:177], v[190:193], v[40:43]
	v_mfma_f32_16x16x32_bf16 v[44:47], v[148:151], v[190:193], v[44:47]
	v_mfma_f32_16x16x32_bf16 v[44:47], v[144:147], v[186:189], v[44:47]
	v_mfma_f32_16x16x32_bf16 v[28:31], v[144:147], v[194:197], v[28:31]
	v_mfma_f32_16x16x32_bf16 v[28:31], v[148:151], v[198:201], v[28:31]
	v_mfma_f32_16x16x32_bf16 v[24:27], v[174:177], v[198:201], v[24:27]
	v_mfma_f32_16x16x32_bf16 v[24:27], v[170:173], v[194:197], v[24:27]
	v_mfma_f32_16x16x32_bf16 v[8:11], v[170:173], v[202:205], v[8:11]
	v_mfma_f32_16x16x32_bf16 v[8:11], v[174:177], v[206:209], v[8:11]
	v_mfma_f32_16x16x32_bf16 v[12:15], v[148:151], v[206:209], v[12:15]
	v_mfma_f32_16x16x32_bf16 v[12:15], v[144:147], v[202:205], v[12:15]
	s_barrier
	s_add_u32 s18, s18, 0x80080
	s_addc_u32 s19, s19, 0
	s_add_i32 s20, s20, s24
	s_mov_b32 m0, s20
	s_nop 0
	global_load_lds_dwordx4 v132, s[18:19]
	s_add_i32 m0, s20, 0x2000
	s_nop 0
	global_load_lds_dwordx4 v128, s[18:19]
	s_waitcnt vmcnt(6)
	s_barrier
	v_mfma_f32_16x16x32_bf16 v[52:55], v[210:213], v[178:181], v[52:55]
	v_mfma_f32_16x16x32_bf16 v[52:55], v[214:217], v[182:185], v[52:55]
	v_mfma_f32_16x16x32_bf16 v[48:51], v[230:233], v[182:185], v[48:51]
	v_mfma_f32_16x16x32_bf16 v[48:51], v[226:229], v[178:181], v[48:51]
	v_mfma_f32_16x16x32_bf16 v[32:35], v[226:229], v[186:189], v[32:35]
	v_mfma_f32_16x16x32_bf16 v[32:35], v[230:233], v[190:193], v[32:35]
	v_mfma_f32_16x16x32_bf16 v[36:39], v[214:217], v[190:193], v[36:39]
	v_mfma_f32_16x16x32_bf16 v[36:39], v[210:213], v[186:189], v[36:39]
	v_mfma_f32_16x16x32_bf16 v[20:23], v[210:213], v[194:197], v[20:23]
	v_mfma_f32_16x16x32_bf16 v[20:23], v[214:217], v[198:201], v[20:23]
	v_mfma_f32_16x16x32_bf16 v[16:19], v[230:233], v[198:201], v[16:19]
	v_mfma_f32_16x16x32_bf16 v[16:19], v[226:229], v[194:197], v[16:19]
	v_mfma_f32_16x16x32_bf16 v[0:3], v[226:229], v[202:205], v[0:3]
	v_mfma_f32_16x16x32_bf16 v[0:3], v[230:233], v[206:209], v[0:3]
	v_mfma_f32_16x16x32_bf16 v[4:7], v[214:217], v[206:209], v[4:7]
	v_mfma_f32_16x16x32_bf16 v[4:7], v[210:213], v[202:205], v[4:7]
	s_add_i32 s47, s47, 2
	s_add_u32 s16, s16, 0x100
	s_addc_u32 s17, s17, 0
	s_add_u32 s45, s45, 0x100
	s_addc_u32 s46, s46, 0
	s_cmp_gt_u32 s47, 29
	s_barrier
	s_cbranch_scc0 .LBB0_147
	s_cmpk_gt_u32 s3, 0xff
	s_cbranch_scc1 .Lst_out_s1
	s_barrier
.Lst_out_s1:
	v_lshl_add_u32 v144, s0, 8, v160
	v_ashrrev_i32_e32 v145, 31, v144
	v_lshl_add_u64 v[150:151], v[144:145], 2, s[92:93]
	global_load_dword v176, v[150:151], off
	global_load_dword v177, v[150:151], off offset:64
	global_load_dword v178, v[150:151], off offset:128
	global_load_dword v179, v[150:151], off offset:192
	global_load_dword v180, v[150:151], off offset:512
	global_load_dword v181, v[150:151], off offset:576
	global_load_dword v182, v[150:151], off offset:640
	global_load_dword v183, v[150:151], off offset:704
	v_lshl_or_b32 v148, s40, 8, v164
	v_mov_b64_e32 v[146:147], s[96:97]
	v_ashrrev_i32_e32 v149, 31, v148
	v_mad_i64_i32 v[172:173], s[16:17], v144, s39, v[146:147]
	v_lshlrev_b64 v[148:149], 1, v[148:149]
	v_lshl_add_u64 v[172:173], v[172:173], 0, v[148:149]
	s_and_b64 vcc, exec, s[4:5]
	s_mov_b32 s40, s8
	s_mov_b32 s0, s10
	s_mov_b64 s[18:19], s[14:15]
	s_waitcnt vmcnt(0)
	v_fmamk_f32 v145, v176, 0x3a000000, v168
	v_rsq_f32_e32 v170, v145
	s_nop 0
	v_pk_mul_f32 v[126:127], v[126:127], v[170:171] op_sel_hi:[1,0]
	v_pk_mul_f32 v[124:125], v[124:125], v[170:171] op_sel_hi:[1,0]
	v_pk_mul_f32 v[122:123], v[122:123], v[170:171] op_sel_hi:[1,0]
	v_pk_mul_f32 v[120:121], v[120:121], v[170:171] op_sel_hi:[1,0]
	v_pk_mul_f32 v[118:119], v[118:119], v[170:171] op_sel_hi:[1,0]
	v_pk_mul_f32 v[116:117], v[116:117], v[170:171] op_sel_hi:[1,0]
	v_pk_mul_f32 v[174:175], v[114:115], v[170:171] op_sel_hi:[1,0]
	v_pk_mul_f32 v[170:171], v[112:113], v[170:171] op_sel_hi:[1,0]
	v_cvt_pk_bf16_f32 v112, v124, v125
	v_cvt_pk_bf16_f32 v113, v126, v127
	v_cvt_pk_bf16_f32 v114, v120, v121
	v_cvt_pk_bf16_f32 v115, v122, v123
	global_store_dwordx4 v[172:173], v[112:115], off
	s_nop 1
	v_cvt_pk_bf16_f32 v112, v116, v117
	v_cvt_pk_bf16_f32 v113, v118, v119
	v_cvt_pk_bf16_f32 v114, v170, v171
	v_cvt_pk_bf16_f32 v115, v174, v175
	global_store_dwordx4 v[172:173], v[112:115], off offset:256
	s_nop 0
	s_nop 0
	v_or_b32_e32 v113, 16, v144
	v_mad_i64_i32 v[114:115], s[16:17], v113, s39, v[146:147]
	v_lshl_add_u64 v[114:115], v[114:115], 0, v[148:149]
	s_nop 0
	v_fmamk_f32 v112, v177, 0x3a000000, v168
	v_rsq_f32_e32 v112, v112
	s_nop 0
	v_pk_mul_f32 v[110:111], v[110:111], v[112:113] op_sel_hi:[1,0]
	v_pk_mul_f32 v[108:109], v[108:109], v[112:113] op_sel_hi:[1,0]
	v_pk_mul_f32 v[106:107], v[106:107], v[112:113] op_sel_hi:[1,0]
	v_pk_mul_f32 v[104:105], v[104:105], v[112:113] op_sel_hi:[1,0]
	v_pk_mul_f32 v[102:103], v[102:103], v[112:113] op_sel_hi:[1,0]
	v_pk_mul_f32 v[100:101], v[100:101], v[112:113] op_sel_hi:[1,0]
	v_pk_mul_f32 v[116:117], v[98:99], v[112:113] op_sel_hi:[1,0]
	v_pk_mul_f32 v[112:113], v[96:97], v[112:113] op_sel_hi:[1,0]
	v_cvt_pk_bf16_f32 v96, v108, v109
	v_cvt_pk_bf16_f32 v97, v110, v111
	v_cvt_pk_bf16_f32 v98, v104, v105
	v_cvt_pk_bf16_f32 v99, v106, v107
	global_store_dwordx4 v[114:115], v[96:99], off
	s_nop 1
	v_cvt_pk_bf16_f32 v96, v100, v101
	v_cvt_pk_bf16_f32 v97, v102, v103
	v_cvt_pk_bf16_f32 v98, v112, v113
	v_cvt_pk_bf16_f32 v99, v116, v117
	global_store_dwordx4 v[114:115], v[96:99], off offset:256
	s_nop 0
	s_nop 0
	v_or_b32_e32 v97, 32, v144
	v_mad_i64_i32 v[98:99], s[16:17], v97, s39, v[146:147]
	v_lshl_add_u64 v[98:99], v[98:99], 0, v[148:149]
	s_nop 0
	v_fmamk_f32 v96, v178, 0x3a000000, v168
	v_rsq_f32_e32 v96, v96
	s_nop 0
	v_pk_mul_f32 v[94:95], v[94:95], v[96:97] op_sel_hi:[1,0]
	v_pk_mul_f32 v[92:93], v[92:93], v[96:97] op_sel_hi:[1,0]
	v_pk_mul_f32 v[90:91], v[90:91], v[96:97] op_sel_hi:[1,0]
	v_pk_mul_f32 v[88:89], v[88:89], v[96:97] op_sel_hi:[1,0]
	v_pk_mul_f32 v[86:87], v[86:87], v[96:97] op_sel_hi:[1,0]
	v_pk_mul_f32 v[84:85], v[84:85], v[96:97] op_sel_hi:[1,0]
	v_pk_mul_f32 v[100:101], v[82:83], v[96:97] op_sel_hi:[1,0]
	v_pk_mul_f32 v[96:97], v[80:81], v[96:97] op_sel_hi:[1,0]
	v_cvt_pk_bf16_f32 v80, v92, v93
	v_cvt_pk_bf16_f32 v81, v94, v95
	v_cvt_pk_bf16_f32 v82, v88, v89
	v_cvt_pk_bf16_f32 v83, v90, v91
	global_store_dwordx4 v[98:99], v[80:83], off
	s_nop 1
	v_cvt_pk_bf16_f32 v80, v84, v85
	v_cvt_pk_bf16_f32 v81, v86, v87
	v_cvt_pk_bf16_f32 v82, v96, v97
	v_cvt_pk_bf16_f32 v83, v100, v101
	global_store_dwordx4 v[98:99], v[80:83], off offset:256
	s_nop 0
	s_nop 0
	v_or_b32_e32 v81, 48, v144
	v_mad_i64_i32 v[82:83], s[16:17], v81, s39, v[146:147]
	v_lshl_add_u64 v[82:83], v[82:83], 0, v[148:149]
	s_nop 0
	v_fmamk_f32 v80, v179, 0x3a000000, v168
	v_rsq_f32_e32 v80, v80
	s_nop 0
	v_pk_mul_f32 v[78:79], v[78:79], v[80:81] op_sel_hi:[1,0]
	v_pk_mul_f32 v[76:77], v[76:77], v[80:81] op_sel_hi:[1,0]
	v_pk_mul_f32 v[74:75], v[74:75], v[80:81] op_sel_hi:[1,0]
	v_pk_mul_f32 v[72:73], v[72:73], v[80:81] op_sel_hi:[1,0]
	v_pk_mul_f32 v[70:71], v[70:71], v[80:81] op_sel_hi:[1,0]
	v_pk_mul_f32 v[68:69], v[68:69], v[80:81] op_sel_hi:[1,0]
	v_pk_mul_f32 v[84:85], v[66:67], v[80:81] op_sel_hi:[1,0]
	v_pk_mul_f32 v[80:81], v[64:65], v[80:81] op_sel_hi:[1,0]
	v_cvt_pk_bf16_f32 v64, v76, v77
	v_cvt_pk_bf16_f32 v65, v78, v79
	v_cvt_pk_bf16_f32 v66, v72, v73
	v_cvt_pk_bf16_f32 v67, v74, v75
	global_store_dwordx4 v[82:83], v[64:67], off
	s_nop 1
	v_cvt_pk_bf16_f32 v64, v68, v69
	v_cvt_pk_bf16_f32 v65, v70, v71
	v_cvt_pk_bf16_f32 v66, v80, v81
	v_cvt_pk_bf16_f32 v67, v84, v85
	global_store_dwordx4 v[82:83], v[64:67], off offset:256
	s_nop 0
	s_nop 0
	v_add_u32_e32 v65, 0x80, v144
	v_mad_i64_i32 v[66:67], s[16:17], v65, s39, v[146:147]
	v_lshl_add_u64 v[66:67], v[66:67], 0, v[148:149]
	s_nop 0
	v_fmamk_f32 v64, v180, 0x3a000000, v168
	v_rsq_f32_e32 v64, v64
	s_nop 0
	v_pk_mul_f32 v[62:63], v[62:63], v[64:65] op_sel_hi:[1,0]
	v_pk_mul_f32 v[60:61], v[60:61], v[64:65] op_sel_hi:[1,0]
	v_pk_mul_f32 v[58:59], v[58:59], v[64:65] op_sel_hi:[1,0]
	v_pk_mul_f32 v[56:57], v[56:57], v[64:65] op_sel_hi:[1,0]
	v_pk_mul_f32 v[54:55], v[54:55], v[64:65] op_sel_hi:[1,0]
	v_pk_mul_f32 v[52:53], v[52:53], v[64:65] op_sel_hi:[1,0]
	v_pk_mul_f32 v[68:69], v[50:51], v[64:65] op_sel_hi:[1,0]
	v_pk_mul_f32 v[64:65], v[48:49], v[64:65] op_sel_hi:[1,0]
	v_cvt_pk_bf16_f32 v48, v60, v61
	v_cvt_pk_bf16_f32 v49, v62, v63
	v_cvt_pk_bf16_f32 v50, v56, v57
	v_cvt_pk_bf16_f32 v51, v58, v59
	global_store_dwordx4 v[66:67], v[48:51], off
	s_nop 1
	v_cvt_pk_bf16_f32 v48, v52, v53
	v_cvt_pk_bf16_f32 v49, v54, v55
	v_cvt_pk_bf16_f32 v50, v64, v65
	v_cvt_pk_bf16_f32 v51, v68, v69
	global_store_dwordx4 v[66:67], v[48:51], off offset:256
	s_nop 0
	s_nop 0
	v_add_u32_e32 v49, 0x90, v144
	v_mad_i64_i32 v[50:51], s[16:17], v49, s39, v[146:147]
	v_lshl_add_u64 v[50:51], v[50:51], 0, v[148:149]
	s_nop 0
	v_fmamk_f32 v48, v181, 0x3a000000, v168
	v_rsq_f32_e32 v48, v48
	s_nop 0
	v_pk_mul_f32 v[46:47], v[46:47], v[48:49] op_sel_hi:[1,0]
	v_pk_mul_f32 v[44:45], v[44:45], v[48:49] op_sel_hi:[1,0]
	v_pk_mul_f32 v[42:43], v[42:43], v[48:49] op_sel_hi:[1,0]
	v_pk_mul_f32 v[40:41], v[40:41], v[48:49] op_sel_hi:[1,0]
	v_pk_mul_f32 v[38:39], v[38:39], v[48:49] op_sel_hi:[1,0]
	v_pk_mul_f32 v[36:37], v[36:37], v[48:49] op_sel_hi:[1,0]
	v_pk_mul_f32 v[52:53], v[34:35], v[48:49] op_sel_hi:[1,0]
	v_pk_mul_f32 v[48:49], v[32:33], v[48:49] op_sel_hi:[1,0]
	v_cvt_pk_bf16_f32 v32, v44, v45
	v_cvt_pk_bf16_f32 v33, v46, v47
	v_cvt_pk_bf16_f32 v34, v40, v41
	v_cvt_pk_bf16_f32 v35, v42, v43
	global_store_dwordx4 v[50:51], v[32:35], off
	s_nop 1
	v_cvt_pk_bf16_f32 v32, v36, v37
	v_cvt_pk_bf16_f32 v33, v38, v39
	v_cvt_pk_bf16_f32 v34, v48, v49
	v_cvt_pk_bf16_f32 v35, v52, v53
	global_store_dwordx4 v[50:51], v[32:35], off offset:256
	s_nop 0
	s_nop 0
	v_add_u32_e32 v33, 0xa0, v144
	v_mad_i64_i32 v[34:35], s[16:17], v33, s39, v[146:147]
	v_lshl_add_u64 v[34:35], v[34:35], 0, v[148:149]
	s_mov_b64 s[16:17], s[12:13]
	s_nop 0
	v_fmamk_f32 v32, v182, 0x3a000000, v168
	v_rsq_f32_e32 v32, v32
	s_nop 0
	v_pk_mul_f32 v[30:31], v[30:31], v[32:33] op_sel_hi:[1,0]
	v_pk_mul_f32 v[28:29], v[28:29], v[32:33] op_sel_hi:[1,0]
	v_pk_mul_f32 v[26:27], v[26:27], v[32:33] op_sel_hi:[1,0]
	v_pk_mul_f32 v[24:25], v[24:25], v[32:33] op_sel_hi:[1,0]
	v_pk_mul_f32 v[22:23], v[22:23], v[32:33] op_sel_hi:[1,0]
	v_pk_mul_f32 v[20:21], v[20:21], v[32:33] op_sel_hi:[1,0]
	v_pk_mul_f32 v[36:37], v[18:19], v[32:33] op_sel_hi:[1,0]
	v_pk_mul_f32 v[32:33], v[16:17], v[32:33] op_sel_hi:[1,0]
	v_cvt_pk_bf16_f32 v16, v28, v29
	v_cvt_pk_bf16_f32 v17, v30, v31
	v_cvt_pk_bf16_f32 v18, v24, v25
	v_cvt_pk_bf16_f32 v19, v26, v27
	global_store_dwordx4 v[34:35], v[16:19], off
	s_nop 1
	v_cvt_pk_bf16_f32 v16, v20, v21
	v_cvt_pk_bf16_f32 v17, v22, v23
	v_cvt_pk_bf16_f32 v18, v32, v33
	v_cvt_pk_bf16_f32 v19, v36, v37
	global_store_dwordx4 v[34:35], v[16:19], off offset:256
	s_nop 0
	s_nop 0
	v_add_u32_e32 v17, 0xb0, v144
	v_mad_i64_i32 v[18:19], s[4:5], v17, s39, v[146:147]
	v_lshl_add_u64 v[18:19], v[18:19], 0, v[148:149]
	s_nop 0
	v_fmamk_f32 v16, v183, 0x3a000000, v168
	v_rsq_f32_e32 v16, v16
	s_nop 0
	v_pk_mul_f32 v[14:15], v[14:15], v[16:17] op_sel_hi:[1,0]
	v_pk_mul_f32 v[12:13], v[12:13], v[16:17] op_sel_hi:[1,0]
	v_pk_mul_f32 v[10:11], v[10:11], v[16:17] op_sel_hi:[1,0]
	v_pk_mul_f32 v[8:9], v[8:9], v[16:17] op_sel_hi:[1,0]
	v_pk_mul_f32 v[6:7], v[6:7], v[16:17] op_sel_hi:[1,0]
	v_pk_mul_f32 v[4:5], v[4:5], v[16:17] op_sel_hi:[1,0]
	v_pk_mul_f32 v[20:21], v[2:3], v[16:17] op_sel_hi:[1,0]
	v_pk_mul_f32 v[16:17], v[0:1], v[16:17] op_sel_hi:[1,0]
	v_cvt_pk_bf16_f32 v0, v12, v13
	v_cvt_pk_bf16_f32 v1, v14, v15
	v_cvt_pk_bf16_f32 v2, v8, v9
	v_cvt_pk_bf16_f32 v3, v10, v11
	global_store_dwordx4 v[18:19], v[0:3], off
	s_nop 1
	v_cvt_pk_bf16_f32 v0, v4, v5
	v_cvt_pk_bf16_f32 v1, v6, v7
	v_cvt_pk_bf16_f32 v2, v16, v17
	v_cvt_pk_bf16_f32 v3, v20, v21
	global_store_dwordx4 v[18:19], v[0:3], off offset:256
	s_cbranch_vccz .LBB0_144
	s_waitcnt vmcnt(0)
	s_cmpk_gt_u32 s3, 0xff
	s_cbranch_scc1 .LBB0_151

.LBB0_269:
	v_and_b32_e32 v0, 24, v158
	v_and_b32_e32 v1, 4, v238
	s_movk_i32 s1, 0x70
	v_or3_b32 v0, v1, v157, v0
	v_and_or_b32 v236, v153, s1, v218
	s_movk_i32 s1, 0x60
	v_add_u32_e32 v233, 0x2000, v156
	v_and_or_b32 v232, v153, s1, v0
	v_lshrrev_b32_e32 v144, 7, v233
	s_movk_i32 s1, 0xf0
	v_and_or_b32 v237, v144, s1, v218
	s_movk_i32 s1, 0xe0
	v_and_or_b32 v240, v144, s1, v0
	v_cndmask_b32_e64 v0, 0, 1, s[4:5]
	v_bitop3_b32 v226, v156, v159, 48 bitop3:0x6c
	v_bfe_u32 v225, v222, 4, 2
	v_cmp_ne_u32_e64 s[6:7], 1, v0
	v_or_b32_e32 v219, v226, v224
	v_lshlrev_b32_e32 v227, 4, v225
	s_add_u32 s12, s92, 0x10000
	v_writelane_b32 v255, s6, 8
	v_lshl_or_b32 v164, v232, 12, v219
	v_lshl_or_b32 v166, v240, 12, v219
	s_addc_u32 s13, s93, 0
	v_writelane_b32 v255, s7, 9
	s_andn2_b64 vcc, exec, s[4:5]
	v_bitop3_b32 v228, v227, v152, v155 bitop3:0x36
	s_cbranch_vccnz .LBB0_303
	s_add_u32 s22, s92, 0x1900000
	s_addc_u32 s23, s93, 0
	s_lshr_b32 s5, s3, 6
	s_ashr_i32 s1, s0, 31
	s_lshr_b32 s4, s3, 8
	s_lshl_b32 s24, s5, 10
	s_lshl_b64 s[6:7], s[0:1], 20
	s_add_u32 s18, s22, s6
	s_addc_u32 s19, s23, s7
	s_add_i32 s25, s24, 0
	s_add_i32 m0, s25, 0x10000
	s_mul_i32 s9, s42, 0x300000
	v_and_b32_e32 v140, 63, v222
	v_lshrrev_b32_e32 v141, 3, v140
	v_lshrrev_b32_e32 v142, 6, v222
	v_lshl_add_u32 v143, v142, 3, v141
	v_and_b32_e32 v150, 7, v140
	v_and_b32_e32 v151, 6, v141
	v_xor_b32_e32 v150, v150, v151
	v_lshlrev_b32_e32 v150, 4, v150
	v_mul_u32_u24_e32 v151, 0x3000, v143
	v_add_u32_e32 v151, v151, v150
	v_mov_b32_e32 v132, v151
	v_mov_b32_e32 v128, v151
	v_add_u32_e32 v134, 0xc0000, v151
	v_add_u32_e32 v130, 0xc0000, v151
	v_add_u32_e32 v134, 0xc0000, v151
	v_add_u32_e32 v130, 0xc0000, v151
	v_and_b32_e32 v151, 31, v143
	v_and_b32_e32 v154, 12, v151
	v_lshlrev_b32_e32 v154, 1, v154
	v_lshrrev_b32_e32 v155, 4, v151
	v_lshlrev_b32_e32 v155, 2, v155
	v_and_b32_e32 v151, 3, v151
	v_or3_b32 v151, v154, v155, v151
	v_and_b32_e32 v154, 0x60, v143
	v_add_u32_e32 v151, v151, v154
	v_mul_u32_u24_e32 v151, 0x1000, v151
	v_add_u32_e32 v151, v151, v150
	v_mov_b32_e32 v164, v151
	v_add_u32_e32 v166, 0x40000, v151
	v_add_u32_e32 v166, 0x40000, v151
	v_and_b32_e32 v151, 15, v140
	v_lshrrev_b32_e32 v154, 4, v140
	v_and_b32_e32 v155, 6, v151
	v_xor_b32_e32 v154, v154, v155
	v_lshlrev_b32_e32 v154, 4, v154
	v_lshl_or_b32 v154, v151, 7, v154
	v_lshrrev_b32_e32 v155, 2, v142
	v_lshl_add_u32 v155, v155, 13, v154
	v_add_u32_e32 v147, 0x0, v155
	v_and_b32_e32 v151, 3, v142
	v_lshl_add_u32 v151, v151, 12, v154
	v_add_u32_e32 v145, 0x0, v151
	v_add_u32_e32 v146, 0x10000, v151
	v_add_u32_e32 v148, 0x14000, v151
	global_load_lds_dwordx4 v164, s[18:19]
	s_add_i32 m0, s25, 0x12000
	v_mul_u32_u24_e32 v9, 0x3000, v236
	s_mul_hi_i32 s8, s42, 0x300000
	s_add_u32 s20, s96, s9
	v_mul_u32_u24_e32 v8, 0x3000, v237
	global_load_lds_dwordx4 v166, s[18:19]
	s_addc_u32 s21, s97, s8
	s_mov_b32 m0, s25
	s_add_i32 s26, s25, 0x2000
	global_load_lds_dwordx4 v128, s[20:21]
	s_mov_b32 m0, s26
	s_add_u32 s6, s18, 0x80000
	global_load_lds_dwordx4 v130, s[20:21]
	s_addc_u32 s7, s19, 0
	s_add_i32 m0, s25, 0x14000
	v_mov_b32_e32 v165, 0
	global_load_lds_dwordx4 v164, s[6:7]
	s_add_i32 m0, s25, 0x16000
	v_mov_b32_e32 v167, v165
	global_load_lds_dwordx4 v166, s[6:7]
	s_add_u32 s6, s20, 0x180000
	s_addc_u32 s7, s21, 0
	s_add_i32 s27, s25, 0x4000
	s_mov_b32 m0, s27
	s_add_i32 s28, s25, 0x6000
	global_load_lds_dwordx4 v128, s[6:7]
	s_mov_b32 m0, s28
	v_mov_b32_e32 v129, v165
	global_load_lds_dwordx4 v130, s[6:7]
	v_mov_b32_e32 v131, v165
	s_mov_b32 s29, 0
	v_lshl_add_u64 v[6:7], s[18:19], 0, v[164:165]
	v_lshl_add_u64 v[4:5], s[18:19], 0, v[166:167]
	v_lshl_add_u64 v[2:3], s[20:21], 0, v[128:129]
	s_cmp_lg_u32 s4, 1
	v_lshl_add_u64 v[0:1], s[20:21], 0, v[130:131]
	s_cbranch_scc1 .LBB0_272
.LBB0_272:
	s_mov_b64 s[8:9], 0x80
	s_lshl_b32 s30, s4, 6
	s_lshl_b32 s1, s4, 13
	s_lshl_b32 s4, s5, 5
	s_add_i32 m0, s25, 0x18000
	v_lshl_add_u64 v[6:7], v[6:7], 0, s[8:9]
	s_and_b32 s31, s4, 0x60
	s_waitcnt vmcnt(4)
	s_barrier
	global_load_lds_dwordx4 v[6:7], off
	v_lshl_add_u64 v[4:5], v[4:5], 0, s[8:9]
	s_add_i32 m0, s25, 0x1a000
	s_add_i32 s33, s25, 0x8000
	s_add_i32 s34, s25, 0xa000
	global_load_lds_dwordx4 v[4:5], off
	v_lshl_add_u64 v[2:3], v[2:3], 0, s[8:9]
	s_mov_b32 m0, s33
	s_add_u32 s4, s18, 0x80080
	global_load_lds_dwordx4 v[2:3], off
	v_lshl_add_u64 v[0:1], v[0:1], 0, s[8:9]
	s_mov_b32 m0, s34
	s_addc_u32 s5, s19, 0
	global_load_lds_dwordx4 v[0:1], off
	s_add_i32 m0, s25, 0x1c000
	v_lshl_add_u64 v[0:1], s[4:5], 0, v[164:165]
	global_load_lds_dwordx4 v[0:1], off
	v_lshl_add_u64 v[0:1], s[4:5], 0, v[166:167]
	s_add_i32 m0, s25, 0x1e000
	global_load_lds_dwordx4 v[0:1], off
	v_lshlrev_b32_e32 v1, 2, v163
	v_lshl_or_b32 v0, v163, 6, v227
	v_and_b32_e32 v1, 32, v1
	v_bitop3_b32 v0, v0, s1, v1 bitop3:0xde
	s_waitcnt vmcnt(6)
	s_add_i32 s39, 0, 0x10000
	s_add_i32 s40, 0, 0x14000
	v_mbcnt_lo_u32_b32 v0, -1, 0
	s_ashr_i32 s35, s94, 31
	s_mov_b32 s38, s94
	v_mov_b32_e32 v133, v165
	v_mov_b32_e32 v135, v165
	v_mov_b64_e32 v[136:137], 0x200
	v_mov_b64_e32 v[138:139], 0x1ff
	v_mbcnt_hi_u32_b32 v149, -1, v0
	s_barrier
	s_branch .LBB0_274

.LBB0_282:
	s_ashr_i32 s11, s10, 31
	s_lshl_b64 s[16:17], s[10:11], 20
	s_add_u32 s16, s22, s16
	s_addc_u32 s17, s23, s17
	s_and_b64 s[6:7], s[6:7], exec
	s_cselect_b32 s1, s17, s19
	s_cselect_b32 s11, s16, s18
	s_add_u32 s6, s20, 0x180080
	s_addc_u32 s7, s21, 0
	s_add_u32 s43, s18, 0x100
	v_mov_b32_e32 v0, 0
	s_addc_u32 s44, s19, 0
	s_mov_b32 s45, -2
	s_waitcnt lgkmcnt(0)
	v_mov_b32_e32 v1, v0
	v_mov_b32_e32 v2, v0
	v_mov_b32_e32 v3, v0
	v_mov_b32_e32 v4, v0
	v_mov_b32_e32 v5, v0
	v_mov_b32_e32 v6, v0
	v_mov_b32_e32 v7, v0
	s_waitcnt vmcnt(0)
	v_mov_b32_e32 v16, v0
	v_mov_b32_e32 v17, v0
	v_mov_b32_e32 v18, v0
	v_mov_b32_e32 v19, v0
	v_mov_b32_e32 v20, v0
	v_mov_b32_e32 v21, v0
	v_mov_b32_e32 v22, v0
	v_mov_b32_e32 v23, v0
	v_mov_b32_e32 v32, v0
	v_mov_b32_e32 v33, v0
	v_mov_b32_e32 v34, v0
	v_mov_b32_e32 v35, v0
	v_mov_b32_e32 v36, v0
	v_mov_b32_e32 v37, v0
	v_mov_b32_e32 v38, v0
	v_mov_b32_e32 v39, v0
	v_mov_b32_e32 v48, v0
	v_mov_b32_e32 v49, v0
	v_mov_b32_e32 v50, v0
	v_mov_b32_e32 v51, v0
	v_mov_b32_e32 v52, v0
	v_mov_b32_e32 v53, v0
	v_mov_b32_e32 v54, v0
	v_mov_b32_e32 v55, v0
	v_mov_b32_e32 v8, v0
	v_mov_b32_e32 v9, v0
	v_mov_b32_e32 v10, v0
	v_mov_b32_e32 v11, v0
	v_mov_b32_e32 v12, v0
	v_mov_b32_e32 v13, v0
	v_mov_b32_e32 v14, v0
	v_mov_b32_e32 v15, v0
	v_mov_b32_e32 v24, v0
	v_mov_b32_e32 v25, v0
	v_mov_b32_e32 v26, v0
	v_mov_b32_e32 v27, v0
	v_mov_b32_e32 v28, v0
	v_mov_b32_e32 v29, v0
	v_mov_b32_e32 v30, v0
	v_mov_b32_e32 v31, v0
	v_mov_b32_e32 v40, v0
	v_mov_b32_e32 v41, v0
	v_mov_b32_e32 v42, v0
	v_mov_b32_e32 v43, v0
	v_mov_b32_e32 v44, v0
	v_mov_b32_e32 v45, v0
	v_mov_b32_e32 v46, v0
	v_mov_b32_e32 v47, v0
	v_mov_b32_e32 v56, v0
	v_mov_b32_e32 v57, v0
	v_mov_b32_e32 v58, v0
	v_mov_b32_e32 v59, v0
	v_mov_b32_e32 v60, v0
	v_mov_b32_e32 v61, v0
	v_mov_b32_e32 v62, v0
	v_mov_b32_e32 v63, v0
	v_mov_b32_e32 v64, v0
	v_mov_b32_e32 v65, v0
	v_mov_b32_e32 v66, v0
	v_mov_b32_e32 v67, v0
	v_mov_b32_e32 v68, v0
	v_mov_b32_e32 v69, v0
	v_mov_b32_e32 v70, v0
	v_mov_b32_e32 v71, v0
	v_mov_b32_e32 v80, v0
	v_mov_b32_e32 v81, v0
	v_mov_b32_e32 v82, v0
	v_mov_b32_e32 v83, v0
	v_mov_b32_e32 v84, v0
	v_mov_b32_e32 v85, v0
	v_mov_b32_e32 v86, v0
	v_mov_b32_e32 v87, v0
	v_mov_b32_e32 v96, v0
	v_mov_b32_e32 v97, v0
	v_mov_b32_e32 v98, v0
	v_mov_b32_e32 v99, v0
	v_mov_b32_e32 v100, v0
	v_mov_b32_e32 v101, v0
	v_mov_b32_e32 v102, v0
	v_mov_b32_e32 v103, v0
	v_mov_b32_e32 v112, v0
	v_mov_b32_e32 v113, v0
	v_mov_b32_e32 v114, v0
	v_mov_b32_e32 v115, v0
	v_mov_b32_e32 v116, v0
	v_mov_b32_e32 v117, v0
	v_mov_b32_e32 v118, v0
	v_mov_b32_e32 v119, v0
	v_mov_b32_e32 v72, v0
	v_mov_b32_e32 v73, v0
	v_mov_b32_e32 v74, v0
	v_mov_b32_e32 v75, v0
	v_mov_b32_e32 v76, v0
	v_mov_b32_e32 v77, v0
	v_mov_b32_e32 v78, v0
	v_mov_b32_e32 v79, v0
	v_mov_b32_e32 v88, v0
	v_mov_b32_e32 v89, v0
	v_mov_b32_e32 v90, v0
	v_mov_b32_e32 v91, v0
	v_mov_b32_e32 v92, v0
	v_mov_b32_e32 v93, v0
	v_mov_b32_e32 v94, v0
	v_mov_b32_e32 v95, v0
	v_mov_b32_e32 v104, v0
	v_mov_b32_e32 v105, v0
	v_mov_b32_e32 v106, v0
	v_mov_b32_e32 v107, v0
	v_mov_b32_e32 v108, v0
	v_mov_b32_e32 v109, v0
	v_mov_b32_e32 v110, v0
	v_mov_b32_e32 v111, v0
	v_mov_b32_e32 v120, v0
	v_mov_b32_e32 v121, v0
	v_mov_b32_e32 v122, v0
	v_mov_b32_e32 v123, v0
	v_mov_b32_e32 v124, v0
	v_mov_b32_e32 v125, v0
	v_mov_b32_e32 v126, v0
	v_mov_b32_e32 v127, v0
	v_xor_b32_e32 v150, 64, v146
	v_xor_b32_e32 v151, 64, v147
	v_xor_b32_e32 v216, 64, v148
	v_add_u32_e32 v217, 0x18000, v145
	v_xor_b32_e32 v220, 64, v217
	s_cmpk_lt_u32 s3, 0x100
	s_cbranch_scc1 .Lst_in_s2
	s_barrier
.Lst_in_s2:
.LBB0_283:
	ds_read_b128 v[140:143], v146
	ds_read_b128 v[154:157], v150
	ds_read_b128 v[158:161], v146 offset:2048
	ds_read_b128 v[168:171], v150 offset:2048
	s_add_u32 s18, s6, 0xffe80080
	s_addc_u32 s19, s7, -1
	s_cmp_eq_u32 s45, 28
	s_cselect_b32 s21, s15, s19
	s_cselect_b32 s20, s14, s18
	s_cselect_b32 s19, s1, s44
	s_cselect_b32 s18, s11, s43
	s_add_i32 m0, s25, 0xc000
	ds_read_b128 v[172:175], v147
	ds_read_b128 v[176:179], v151
	ds_read_b128 v[180:183], v147 offset:2048
	ds_read_b128 v[184:187], v151 offset:2048
	ds_read_b128 v[188:191], v147 offset:4096
	ds_read_b128 v[192:195], v151 offset:4096
	ds_read_b128 v[196:199], v147 offset:6144
	ds_read_b128 v[200:203], v151 offset:6144
	global_load_lds_dwordx4 v132, s[6:7]
	s_add_i32 m0, s25, 0xe000
	s_nop 0
	global_load_lds_dwordx4 v134, s[6:7]
	s_waitcnt lgkmcnt(8)
	s_barrier
	s_waitcnt lgkmcnt(0)
	s_waitcnt lgkmcnt(0)
	v_mfma_f32_16x16x32_bf16 v[124:127], v[140:143], v[172:175], v[124:127]
	v_mfma_f32_16x16x32_bf16 v[124:127], v[154:157], v[176:179], v[124:127]
	v_mfma_f32_16x16x32_bf16 v[120:123], v[168:171], v[176:179], v[120:123]
	v_mfma_f32_16x16x32_bf16 v[120:123], v[158:161], v[172:175], v[120:123]
	v_mfma_f32_16x16x32_bf16 v[104:107], v[158:161], v[180:183], v[104:107]
	v_mfma_f32_16x16x32_bf16 v[104:107], v[168:171], v[184:187], v[104:107]
	v_mfma_f32_16x16x32_bf16 v[108:111], v[154:157], v[184:187], v[108:111]
	v_mfma_f32_16x16x32_bf16 v[108:111], v[140:143], v[180:183], v[108:111]
	v_mfma_f32_16x16x32_bf16 v[92:95], v[140:143], v[188:191], v[92:95]
	v_mfma_f32_16x16x32_bf16 v[92:95], v[154:157], v[192:195], v[92:95]
	v_mfma_f32_16x16x32_bf16 v[88:91], v[168:171], v[192:195], v[88:91]
	v_mfma_f32_16x16x32_bf16 v[88:91], v[158:161], v[188:191], v[88:91]
	v_mfma_f32_16x16x32_bf16 v[72:75], v[158:161], v[196:199], v[72:75]
	v_mfma_f32_16x16x32_bf16 v[72:75], v[168:171], v[200:203], v[72:75]
	v_mfma_f32_16x16x32_bf16 v[76:79], v[154:157], v[200:203], v[76:79]
	v_mfma_f32_16x16x32_bf16 v[76:79], v[140:143], v[196:199], v[76:79]
	s_barrier
	s_add_i32 s46, s39, s24
	s_add_u32 s98, s18, s8
	s_addc_u32 s99, s19, s9
	s_mov_b32 m0, s46
	ds_read_b128 v[204:207], v148
	ds_read_b128 v[208:211], v216
	ds_read_b128 v[212:215], v148 offset:2048
	ds_read_b128 v[242:245], v216 offset:2048
	global_load_lds_dwordx4 v164, s[18:19]
	s_add_i32 m0, s46, 0x2000
	s_nop 0
	global_load_lds_dwordx4 v166, s[18:19]
	s_barrier
	s_waitcnt lgkmcnt(0)
	s_waitcnt lgkmcnt(0)
	v_mfma_f32_16x16x32_bf16 v[116:119], v[204:207], v[172:175], v[116:119]
	v_mfma_f32_16x16x32_bf16 v[116:119], v[208:211], v[176:179], v[116:119]
	v_mfma_f32_16x16x32_bf16 v[112:115], v[242:245], v[176:179], v[112:115]
	v_mfma_f32_16x16x32_bf16 v[112:115], v[212:215], v[172:175], v[112:115]
	v_mfma_f32_16x16x32_bf16 v[96:99], v[212:215], v[180:183], v[96:99]
	v_mfma_f32_16x16x32_bf16 v[96:99], v[242:245], v[184:187], v[96:99]
	v_mfma_f32_16x16x32_bf16 v[100:103], v[208:211], v[184:187], v[100:103]
	v_mfma_f32_16x16x32_bf16 v[100:103], v[204:207], v[180:183], v[100:103]
	v_mfma_f32_16x16x32_bf16 v[84:87], v[204:207], v[188:191], v[84:87]
	v_mfma_f32_16x16x32_bf16 v[84:87], v[208:211], v[192:195], v[84:87]
	v_mfma_f32_16x16x32_bf16 v[80:83], v[242:245], v[192:195], v[80:83]
	v_mfma_f32_16x16x32_bf16 v[80:83], v[212:215], v[188:191], v[80:83]
	v_mfma_f32_16x16x32_bf16 v[64:67], v[212:215], v[196:199], v[64:67]
	v_mfma_f32_16x16x32_bf16 v[64:67], v[242:245], v[200:203], v[64:67]
	v_mfma_f32_16x16x32_bf16 v[68:71], v[208:211], v[200:203], v[68:71]
	v_mfma_f32_16x16x32_bf16 v[68:71], v[204:207], v[196:199], v[68:71]
	s_mov_b32 m0, s25
	s_add_u32 s100, s20, s8
	s_addc_u32 s101, s21, s9
	s_barrier
	ds_read_b128 v[172:175], v147 offset:16384
	ds_read_b128 v[176:179], v151 offset:16384
	ds_read_b128 v[180:183], v147 offset:18432
	ds_read_b128 v[184:187], v151 offset:18432
	ds_read_b128 v[188:191], v147 offset:20480
	ds_read_b128 v[192:195], v151 offset:20480
	ds_read_b128 v[196:199], v147 offset:22528
	ds_read_b128 v[200:203], v151 offset:22528
	global_load_lds_dwordx4 v128, s[20:21]
	s_mov_b32 m0, s26
	s_nop 0
	global_load_lds_dwordx4 v130, s[20:21]
	s_barrier
	s_waitcnt lgkmcnt(0)
	s_waitcnt lgkmcnt(0)
	v_mfma_f32_16x16x32_bf16 v[60:63], v[140:143], v[172:175], v[60:63]
	v_mfma_f32_16x16x32_bf16 v[60:63], v[154:157], v[176:179], v[60:63]
	v_mfma_f32_16x16x32_bf16 v[56:59], v[168:171], v[176:179], v[56:59]
	v_mfma_f32_16x16x32_bf16 v[56:59], v[158:161], v[172:175], v[56:59]
	v_mfma_f32_16x16x32_bf16 v[40:43], v[158:161], v[180:183], v[40:43]
	v_mfma_f32_16x16x32_bf16 v[40:43], v[168:171], v[184:187], v[40:43]
	v_mfma_f32_16x16x32_bf16 v[44:47], v[154:157], v[184:187], v[44:47]
	v_mfma_f32_16x16x32_bf16 v[44:47], v[140:143], v[180:183], v[44:47]
	v_mfma_f32_16x16x32_bf16 v[28:31], v[140:143], v[188:191], v[28:31]
	v_mfma_f32_16x16x32_bf16 v[28:31], v[154:157], v[192:195], v[28:31]
	v_mfma_f32_16x16x32_bf16 v[24:27], v[168:171], v[192:195], v[24:27]
	v_mfma_f32_16x16x32_bf16 v[24:27], v[158:161], v[188:191], v[24:27]
	v_mfma_f32_16x16x32_bf16 v[8:11], v[158:161], v[196:199], v[8:11]
	v_mfma_f32_16x16x32_bf16 v[8:11], v[168:171], v[200:203], v[8:11]
	v_mfma_f32_16x16x32_bf16 v[12:15], v[154:157], v[200:203], v[12:15]
	v_mfma_f32_16x16x32_bf16 v[12:15], v[140:143], v[196:199], v[12:15]
	s_barrier
	s_add_u32 s46, s18, 0x80000
	s_addc_u32 s47, s19, 0
	s_add_i32 s48, s40, s24
	s_mov_b32 m0, s48
	s_nop 0
	global_load_lds_dwordx4 v164, s[46:47]
	s_add_i32 m0, s48, 0x2000
	s_nop 0
	global_load_lds_dwordx4 v166, s[46:47]
	s_waitcnt vmcnt(6)
	s_barrier
	v_mfma_f32_16x16x32_bf16 v[52:55], v[204:207], v[172:175], v[52:55]
	v_mfma_f32_16x16x32_bf16 v[52:55], v[208:211], v[176:179], v[52:55]
	v_mfma_f32_16x16x32_bf16 v[48:51], v[242:245], v[176:179], v[48:51]
	v_mfma_f32_16x16x32_bf16 v[48:51], v[212:215], v[172:175], v[48:51]
	v_mfma_f32_16x16x32_bf16 v[32:35], v[212:215], v[180:183], v[32:35]
	v_mfma_f32_16x16x32_bf16 v[32:35], v[242:245], v[184:187], v[32:35]
	v_mfma_f32_16x16x32_bf16 v[36:39], v[208:211], v[184:187], v[36:39]
	v_mfma_f32_16x16x32_bf16 v[36:39], v[204:207], v[180:183], v[36:39]
	v_mfma_f32_16x16x32_bf16 v[20:23], v[204:207], v[188:191], v[20:23]
	v_mfma_f32_16x16x32_bf16 v[20:23], v[208:211], v[192:195], v[20:23]
	v_mfma_f32_16x16x32_bf16 v[16:19], v[242:245], v[192:195], v[16:19]
	v_mfma_f32_16x16x32_bf16 v[16:19], v[212:215], v[188:191], v[16:19]
	v_mfma_f32_16x16x32_bf16 v[0:3], v[212:215], v[196:199], v[0:3]
	v_mfma_f32_16x16x32_bf16 v[0:3], v[242:245], v[200:203], v[0:3]
	v_mfma_f32_16x16x32_bf16 v[4:7], v[208:211], v[200:203], v[4:7]
	v_mfma_f32_16x16x32_bf16 v[4:7], v[204:207], v[196:199], v[4:7]
	s_add_i32 s46, 0, 0x18000
	s_barrier
	ds_read_b128 v[140:143], v217
	ds_read_b128 v[154:157], v220
	ds_read_b128 v[158:161], v217 offset:2048
	ds_read_b128 v[168:171], v220 offset:2048
	s_add_u32 s20, s20, 0x180000
	s_addc_u32 s21, s21, 0
	s_mov_b32 m0, s27
	ds_read_b128 v[172:175], v147 offset:32768
	ds_read_b128 v[176:179], v151 offset:32768
	ds_read_b128 v[180:183], v147 offset:34816
	ds_read_b128 v[184:187], v151 offset:34816
	ds_read_b128 v[188:191], v147 offset:36864
	ds_read_b128 v[192:195], v151 offset:36864
	ds_read_b128 v[196:199], v147 offset:38912
	ds_read_b128 v[200:203], v151 offset:38912
	global_load_lds_dwordx4 v128, s[20:21]
	s_mov_b32 m0, s28
	s_nop 0
	global_load_lds_dwordx4 v130, s[20:21]
	s_waitcnt lgkmcnt(8)
	s_barrier
	s_waitcnt lgkmcnt(0)
	s_waitcnt lgkmcnt(0)
	v_mfma_f32_16x16x32_bf16 v[124:127], v[140:143], v[172:175], v[124:127]
	v_mfma_f32_16x16x32_bf16 v[124:127], v[154:157], v[176:179], v[124:127]
	v_mfma_f32_16x16x32_bf16 v[120:123], v[168:171], v[176:179], v[120:123]
	v_mfma_f32_16x16x32_bf16 v[120:123], v[158:161], v[172:175], v[120:123]
	v_mfma_f32_16x16x32_bf16 v[104:107], v[158:161], v[180:183], v[104:107]
	v_mfma_f32_16x16x32_bf16 v[104:107], v[168:171], v[184:187], v[104:107]
	v_mfma_f32_16x16x32_bf16 v[108:111], v[154:157], v[184:187], v[108:111]
	v_mfma_f32_16x16x32_bf16 v[108:111], v[140:143], v[180:183], v[108:111]
	v_mfma_f32_16x16x32_bf16 v[92:95], v[140:143], v[188:191], v[92:95]
	v_mfma_f32_16x16x32_bf16 v[92:95], v[154:157], v[192:195], v[92:95]
	v_mfma_f32_16x16x32_bf16 v[88:91], v[168:171], v[192:195], v[88:91]
	v_mfma_f32_16x16x32_bf16 v[88:91], v[158:161], v[188:191], v[88:91]
	v_mfma_f32_16x16x32_bf16 v[72:75], v[158:161], v[196:199], v[72:75]
	v_mfma_f32_16x16x32_bf16 v[72:75], v[168:171], v[200:203], v[72:75]
	v_mfma_f32_16x16x32_bf16 v[76:79], v[154:157], v[200:203], v[76:79]
	v_mfma_f32_16x16x32_bf16 v[76:79], v[140:143], v[196:199], v[76:79]
	s_barrier
	s_add_i32 s20, 0, 0x1c000
	s_add_i32 s21, s46, s24
	v_add_u32_e32 v223, s20, v145
	s_mov_b32 m0, s21
	ds_read_b128 v[204:207], v223
	v_xor_b32_e32 v245, 64, v223
	ds_read_b128 v[208:211], v245
	ds_read_b128 v[212:215], v223 offset:2048
	ds_read_b128 v[242:245], v245 offset:2048
	global_load_lds_dwordx4 v164, s[98:99]
	s_add_i32 m0, s21, 0x2000
	s_nop 0
	global_load_lds_dwordx4 v166, s[98:99]
	s_barrier
	s_waitcnt lgkmcnt(0)
	s_waitcnt lgkmcnt(0)
	v_mfma_f32_16x16x32_bf16 v[116:119], v[204:207], v[172:175], v[116:119]
	v_mfma_f32_16x16x32_bf16 v[116:119], v[208:211], v[176:179], v[116:119]
	v_mfma_f32_16x16x32_bf16 v[112:115], v[242:245], v[176:179], v[112:115]
	v_mfma_f32_16x16x32_bf16 v[112:115], v[212:215], v[172:175], v[112:115]
	v_mfma_f32_16x16x32_bf16 v[96:99], v[212:215], v[180:183], v[96:99]
	v_mfma_f32_16x16x32_bf16 v[96:99], v[242:245], v[184:187], v[96:99]
	v_mfma_f32_16x16x32_bf16 v[100:103], v[208:211], v[184:187], v[100:103]
	v_mfma_f32_16x16x32_bf16 v[100:103], v[204:207], v[180:183], v[100:103]
	v_mfma_f32_16x16x32_bf16 v[84:87], v[204:207], v[188:191], v[84:87]
	v_mfma_f32_16x16x32_bf16 v[84:87], v[208:211], v[192:195], v[84:87]
	v_mfma_f32_16x16x32_bf16 v[80:83], v[242:245], v[192:195], v[80:83]
	v_mfma_f32_16x16x32_bf16 v[80:83], v[212:215], v[188:191], v[80:83]
	v_mfma_f32_16x16x32_bf16 v[64:67], v[212:215], v[196:199], v[64:67]
	v_mfma_f32_16x16x32_bf16 v[64:67], v[242:245], v[200:203], v[64:67]
	v_mfma_f32_16x16x32_bf16 v[68:71], v[208:211], v[200:203], v[68:71]
	v_mfma_f32_16x16x32_bf16 v[68:71], v[204:207], v[196:199], v[68:71]
	s_mov_b32 m0, s33
	s_barrier
	ds_read_b128 v[172:175], v147 offset:49152
	ds_read_b128 v[176:179], v151 offset:49152
	ds_read_b128 v[180:183], v147 offset:51200
	ds_read_b128 v[184:187], v151 offset:51200
	ds_read_b128 v[188:191], v147 offset:53248
	ds_read_b128 v[192:195], v151 offset:53248
	ds_read_b128 v[196:199], v147 offset:55296
	ds_read_b128 v[200:203], v151 offset:55296
	global_load_lds_dwordx4 v128, s[100:101]
	s_mov_b32 m0, s34
	s_nop 0
	global_load_lds_dwordx4 v130, s[100:101]
	s_barrier
	s_waitcnt lgkmcnt(0)
	s_waitcnt lgkmcnt(0)
	v_mfma_f32_16x16x32_bf16 v[60:63], v[140:143], v[172:175], v[60:63]
	v_mfma_f32_16x16x32_bf16 v[60:63], v[154:157], v[176:179], v[60:63]
	v_mfma_f32_16x16x32_bf16 v[56:59], v[168:171], v[176:179], v[56:59]
	v_mfma_f32_16x16x32_bf16 v[56:59], v[158:161], v[172:175], v[56:59]
	v_mfma_f32_16x16x32_bf16 v[40:43], v[158:161], v[180:183], v[40:43]
	v_mfma_f32_16x16x32_bf16 v[40:43], v[168:171], v[184:187], v[40:43]
	v_mfma_f32_16x16x32_bf16 v[44:47], v[154:157], v[184:187], v[44:47]
	v_mfma_f32_16x16x32_bf16 v[44:47], v[140:143], v[180:183], v[44:47]
	v_mfma_f32_16x16x32_bf16 v[28:31], v[140:143], v[188:191], v[28:31]
	v_mfma_f32_16x16x32_bf16 v[28:31], v[154:157], v[192:195], v[28:31]
	v_mfma_f32_16x16x32_bf16 v[24:27], v[168:171], v[192:195], v[24:27]
	v_mfma_f32_16x16x32_bf16 v[24:27], v[158:161], v[188:191], v[24:27]
	v_mfma_f32_16x16x32_bf16 v[8:11], v[158:161], v[196:199], v[8:11]
	v_mfma_f32_16x16x32_bf16 v[8:11], v[168:171], v[200:203], v[8:11]
	v_mfma_f32_16x16x32_bf16 v[12:15], v[154:157], v[200:203], v[12:15]
	v_mfma_f32_16x16x32_bf16 v[12:15], v[140:143], v[196:199], v[12:15]
	s_barrier
	s_add_u32 s18, s18, 0x80080
	s_addc_u32 s19, s19, 0
	s_add_i32 s20, s20, s24
	s_mov_b32 m0, s20
	s_nop 0
	global_load_lds_dwordx4 v164, s[18:19]
	s_add_i32 m0, s20, 0x2000
	s_nop 0
	global_load_lds_dwordx4 v166, s[18:19]
	s_waitcnt vmcnt(6)
	s_barrier
	v_mfma_f32_16x16x32_bf16 v[52:55], v[204:207], v[172:175], v[52:55]
	v_mfma_f32_16x16x32_bf16 v[52:55], v[208:211], v[176:179], v[52:55]
	v_mfma_f32_16x16x32_bf16 v[48:51], v[242:245], v[176:179], v[48:51]
	v_mfma_f32_16x16x32_bf16 v[48:51], v[212:215], v[172:175], v[48:51]
	v_mfma_f32_16x16x32_bf16 v[32:35], v[212:215], v[180:183], v[32:35]
	v_mfma_f32_16x16x32_bf16 v[32:35], v[242:245], v[184:187], v[32:35]
	v_mfma_f32_16x16x32_bf16 v[36:39], v[208:211], v[184:187], v[36:39]
	v_mfma_f32_16x16x32_bf16 v[36:39], v[204:207], v[180:183], v[36:39]
	v_mfma_f32_16x16x32_bf16 v[20:23], v[204:207], v[188:191], v[20:23]
	v_mfma_f32_16x16x32_bf16 v[20:23], v[208:211], v[192:195], v[20:23]
	v_mfma_f32_16x16x32_bf16 v[16:19], v[242:245], v[192:195], v[16:19]
	v_mfma_f32_16x16x32_bf16 v[16:19], v[212:215], v[188:191], v[16:19]
	v_mfma_f32_16x16x32_bf16 v[0:3], v[212:215], v[196:199], v[0:3]
	v_mfma_f32_16x16x32_bf16 v[0:3], v[242:245], v[200:203], v[0:3]
	v_mfma_f32_16x16x32_bf16 v[4:7], v[208:211], v[200:203], v[4:7]
	v_mfma_f32_16x16x32_bf16 v[4:7], v[204:207], v[196:199], v[4:7]
	s_add_i32 s45, s45, 2
	s_add_u32 s6, s6, 0x100
	s_addc_u32 s7, s7, 0
	s_add_u32 s43, s43, 0x100
	s_addc_u32 s44, s44, 0
	s_cmp_gt_u32 s45, 29
	s_barrier
	s_cbranch_scc0 .LBB0_283
	s_cmpk_gt_u32 s3, 0xff
	s_cbranch_scc1 .Lst_out_s2
	s_barrier
.Lst_out_s2:
	v_lshl_add_u32 v217, s42, 8, v163
	v_add_u32_e32 v217, s30, v217
	v_lshlrev_b32_e32 v208, 2, v217
	v_lshl_add_u32 v214, v225, 3, s31
	v_lshl_add_u32 v214, s0, 8, v214
	v_lshl_add_u32 v209, v217, 11, v214
	v_lshlrev_b32_e32 v209, 1, v209
	v_lshlrev_b32_e32 v210, 1, v209
	v_lshl_add_u32 v217, v225, 4, v163
	v_xor_b32_e32 v215, 16, v217
	v_lshlrev_b32_e32 v215, 2, v215
	v_xor_b32_e32 v216, 32, v217
	v_lshlrev_b32_e32 v216, 2, v216
	v_add_u32_e32 v212, 0x0, v210
	global_load_dwordx4 v[176:179], v212, s[36:37]
	global_load_dwordx4 v[180:183], v212, s[36:37] offset:16
	global_load_dwordx4 v[184:187], v212, s[36:37] offset:512
	global_load_dwordx4 v[188:191], v212, s[36:37] offset:528
	v_add_u32_e32 v212, 0x20000, v210
	global_load_dwordx4 v[192:195], v212, s[36:37]
	global_load_dwordx4 v[196:199], v212, s[36:37] offset:16
	global_load_dwordx4 v[200:203], v212, s[36:37] offset:512
	global_load_dwordx4 v[204:207], v212, s[36:37] offset:528
	s_waitcnt vmcnt(4)
	v_pk_add_f32 v[124:125], v[124:125], v[176:177]
	v_pk_add_f32 v[126:127], v[126:127], v[178:179]
	v_pk_add_f32 v[120:121], v[120:121], v[180:181]
	v_pk_add_f32 v[122:123], v[122:123], v[182:183]
	v_mul_f32_e32 v213, v124, v124
	v_fmac_f32_e32 v213, v125, v125
	v_fmac_f32_e32 v213, v126, v126
	v_fmac_f32_e32 v213, v127, v127
	v_fmac_f32_e32 v213, v120, v120
	v_fmac_f32_e32 v213, v121, v121
	v_fmac_f32_e32 v213, v122, v122
	v_fmac_f32_e32 v213, v123, v123
	v_cvt_pk_bf16_f32 v176, v124, v125
	v_cvt_pk_bf16_f32 v177, v126, v127
	v_cvt_pk_bf16_f32 v178, v120, v121
	v_cvt_pk_bf16_f32 v179, v122, v123
	v_add_u32_e32 v217, 0x0, v209
	global_store_dwordx4 v217, v[176:179], s[80:81]
	v_pk_add_f32 v[116:117], v[116:117], v[184:185]
	v_pk_add_f32 v[118:119], v[118:119], v[186:187]
	v_pk_add_f32 v[112:113], v[112:113], v[188:189]
	v_pk_add_f32 v[114:115], v[114:115], v[190:191]
	v_fmac_f32_e32 v213, v116, v116
	v_fmac_f32_e32 v213, v117, v117
	v_fmac_f32_e32 v213, v118, v118
	v_fmac_f32_e32 v213, v119, v119
	v_fmac_f32_e32 v213, v112, v112
	v_fmac_f32_e32 v213, v113, v113
	v_fmac_f32_e32 v213, v114, v114
	v_fmac_f32_e32 v213, v115, v115
	v_cvt_pk_bf16_f32 v184, v116, v117
	v_cvt_pk_bf16_f32 v185, v118, v119
	v_cvt_pk_bf16_f32 v186, v112, v113
	v_cvt_pk_bf16_f32 v187, v114, v115
	global_store_dwordx4 v217, v[184:187], s[80:81] offset:256
	ds_bpermute_b32 v214, v215, v213
	s_waitcnt lgkmcnt(0)
	v_add_f32_e32 v213, v213, v214
	ds_bpermute_b32 v214, v216, v213
	s_waitcnt lgkmcnt(0)
	v_add_f32_e32 v213, v213, v214
	s_mov_b64 exec, 0xffff
	global_atomic_add_f32 v208, v213, s[12:13]
	s_mov_b64 exec, -1
	v_add_u32_e32 v212, 0x40000, v210
	global_load_dwordx4 v[176:179], v212, s[36:37]
	global_load_dwordx4 v[180:183], v212, s[36:37] offset:16
	global_load_dwordx4 v[184:187], v212, s[36:37] offset:512
	global_load_dwordx4 v[188:191], v212, s[36:37] offset:528
	s_waitcnt vmcnt(7)
	v_pk_add_f32 v[108:109], v[108:109], v[192:193]
	v_pk_add_f32 v[110:111], v[110:111], v[194:195]
	v_pk_add_f32 v[104:105], v[104:105], v[196:197]
	v_pk_add_f32 v[106:107], v[106:107], v[198:199]
	v_mul_f32_e32 v213, v108, v108
	v_fmac_f32_e32 v213, v109, v109
	v_fmac_f32_e32 v213, v110, v110
	v_fmac_f32_e32 v213, v111, v111
	v_fmac_f32_e32 v213, v104, v104
	v_fmac_f32_e32 v213, v105, v105
	v_fmac_f32_e32 v213, v106, v106
	v_fmac_f32_e32 v213, v107, v107
	v_cvt_pk_bf16_f32 v192, v108, v109
	v_cvt_pk_bf16_f32 v193, v110, v111
	v_cvt_pk_bf16_f32 v194, v104, v105
	v_cvt_pk_bf16_f32 v195, v106, v107
	v_add_u32_e32 v217, 0x10000, v209
	global_store_dwordx4 v217, v[192:195], s[80:81]
	v_pk_add_f32 v[100:101], v[100:101], v[200:201]
	v_pk_add_f32 v[102:103], v[102:103], v[202:203]
	v_pk_add_f32 v[96:97], v[96:97], v[204:205]
	v_pk_add_f32 v[98:99], v[98:99], v[206:207]
	v_fmac_f32_e32 v213, v100, v100
	v_fmac_f32_e32 v213, v101, v101
	v_fmac_f32_e32 v213, v102, v102
	v_fmac_f32_e32 v213, v103, v103
	v_fmac_f32_e32 v213, v96, v96
	v_fmac_f32_e32 v213, v97, v97
	v_fmac_f32_e32 v213, v98, v98
	v_fmac_f32_e32 v213, v99, v99
	v_cvt_pk_bf16_f32 v200, v100, v101
	v_cvt_pk_bf16_f32 v201, v102, v103
	v_cvt_pk_bf16_f32 v202, v96, v97
	v_cvt_pk_bf16_f32 v203, v98, v99
	global_store_dwordx4 v217, v[200:203], s[80:81] offset:256
	ds_bpermute_b32 v214, v215, v213
	s_waitcnt lgkmcnt(0)
	v_add_f32_e32 v213, v213, v214
	ds_bpermute_b32 v214, v216, v213
	s_waitcnt lgkmcnt(0)
	v_add_f32_e32 v213, v213, v214
	s_mov_b64 exec, 0xffff
	global_atomic_add_f32 v208, v213, s[12:13] offset:64
	s_mov_b64 exec, -1
	v_add_u32_e32 v212, 0x60000, v210
	global_load_dwordx4 v[192:195], v212, s[36:37]
	global_load_dwordx4 v[196:199], v212, s[36:37] offset:16
	global_load_dwordx4 v[200:203], v212, s[36:37] offset:512
	global_load_dwordx4 v[204:207], v212, s[36:37] offset:528
	s_waitcnt vmcnt(7)
	v_pk_add_f32 v[92:93], v[92:93], v[176:177]
	v_pk_add_f32 v[94:95], v[94:95], v[178:179]
	v_pk_add_f32 v[88:89], v[88:89], v[180:181]
	v_pk_add_f32 v[90:91], v[90:91], v[182:183]
	v_mul_f32_e32 v213, v92, v92
	v_fmac_f32_e32 v213, v93, v93
	v_fmac_f32_e32 v213, v94, v94
	v_fmac_f32_e32 v213, v95, v95
	v_fmac_f32_e32 v213, v88, v88
	v_fmac_f32_e32 v213, v89, v89
	v_fmac_f32_e32 v213, v90, v90
	v_fmac_f32_e32 v213, v91, v91
	v_cvt_pk_bf16_f32 v176, v92, v93
	v_cvt_pk_bf16_f32 v177, v94, v95
	v_cvt_pk_bf16_f32 v178, v88, v89
	v_cvt_pk_bf16_f32 v179, v90, v91
	v_add_u32_e32 v217, 0x20000, v209
	global_store_dwordx4 v217, v[176:179], s[80:81]
	v_pk_add_f32 v[84:85], v[84:85], v[184:185]
	v_pk_add_f32 v[86:87], v[86:87], v[186:187]
	v_pk_add_f32 v[80:81], v[80:81], v[188:189]
	v_pk_add_f32 v[82:83], v[82:83], v[190:191]
	v_fmac_f32_e32 v213, v84, v84
	v_fmac_f32_e32 v213, v85, v85
	v_fmac_f32_e32 v213, v86, v86
	v_fmac_f32_e32 v213, v87, v87
	v_fmac_f32_e32 v213, v80, v80
	v_fmac_f32_e32 v213, v81, v81
	v_fmac_f32_e32 v213, v82, v82
	v_fmac_f32_e32 v213, v83, v83
	v_cvt_pk_bf16_f32 v184, v84, v85
	v_cvt_pk_bf16_f32 v185, v86, v87
	v_cvt_pk_bf16_f32 v186, v80, v81
	v_cvt_pk_bf16_f32 v187, v82, v83
	global_store_dwordx4 v217, v[184:187], s[80:81] offset:256
	ds_bpermute_b32 v214, v215, v213
	s_waitcnt lgkmcnt(0)
	v_add_f32_e32 v213, v213, v214
	ds_bpermute_b32 v214, v216, v213
	s_waitcnt lgkmcnt(0)
	v_add_f32_e32 v213, v213, v214
	s_mov_b64 exec, 0xffff
	global_atomic_add_f32 v208, v213, s[12:13] offset:128
	s_mov_b64 exec, -1
	v_add_u32_e32 v212, 0x100000, v210
	global_load_dwordx4 v[176:179], v212, s[36:37]
	global_load_dwordx4 v[180:183], v212, s[36:37] offset:16
	global_load_dwordx4 v[184:187], v212, s[36:37] offset:512
	global_load_dwordx4 v[188:191], v212, s[36:37] offset:528
	s_waitcnt vmcnt(7)
	v_pk_add_f32 v[76:77], v[76:77], v[192:193]
	v_pk_add_f32 v[78:79], v[78:79], v[194:195]
	v_pk_add_f32 v[72:73], v[72:73], v[196:197]
	v_pk_add_f32 v[74:75], v[74:75], v[198:199]
	v_mul_f32_e32 v213, v76, v76
	v_fmac_f32_e32 v213, v77, v77
	v_fmac_f32_e32 v213, v78, v78
	v_fmac_f32_e32 v213, v79, v79
	v_fmac_f32_e32 v213, v72, v72
	v_fmac_f32_e32 v213, v73, v73
	v_fmac_f32_e32 v213, v74, v74
	v_fmac_f32_e32 v213, v75, v75
	v_cvt_pk_bf16_f32 v192, v76, v77
	v_cvt_pk_bf16_f32 v193, v78, v79
	v_cvt_pk_bf16_f32 v194, v72, v73
	v_cvt_pk_bf16_f32 v195, v74, v75
	v_add_u32_e32 v217, 0x30000, v209
	global_store_dwordx4 v217, v[192:195], s[80:81]
	v_pk_add_f32 v[68:69], v[68:69], v[200:201]
	v_pk_add_f32 v[70:71], v[70:71], v[202:203]
	v_pk_add_f32 v[64:65], v[64:65], v[204:205]
	v_pk_add_f32 v[66:67], v[66:67], v[206:207]
	v_fmac_f32_e32 v213, v68, v68
	v_fmac_f32_e32 v213, v69, v69
	v_fmac_f32_e32 v213, v70, v70
	v_fmac_f32_e32 v213, v71, v71
	v_fmac_f32_e32 v213, v64, v64
	v_fmac_f32_e32 v213, v65, v65
	v_fmac_f32_e32 v213, v66, v66
	v_fmac_f32_e32 v213, v67, v67
	v_cvt_pk_bf16_f32 v200, v68, v69
	v_cvt_pk_bf16_f32 v201, v70, v71
	v_cvt_pk_bf16_f32 v202, v64, v65
	v_cvt_pk_bf16_f32 v203, v66, v67
	global_store_dwordx4 v217, v[200:203], s[80:81] offset:256
	ds_bpermute_b32 v214, v215, v213
	s_waitcnt lgkmcnt(0)
	v_add_f32_e32 v213, v213, v214
	ds_bpermute_b32 v214, v216, v213
	s_waitcnt lgkmcnt(0)
	v_add_f32_e32 v213, v213, v214
	s_mov_b64 exec, 0xffff
	global_atomic_add_f32 v208, v213, s[12:13] offset:192
	s_mov_b64 exec, -1
	v_add_u32_e32 v212, 0x120000, v210
	global_load_dwordx4 v[192:195], v212, s[36:37]
	global_load_dwordx4 v[196:199], v212, s[36:37] offset:16
	global_load_dwordx4 v[200:203], v212, s[36:37] offset:512
	global_load_dwordx4 v[204:207], v212, s[36:37] offset:528
	s_waitcnt vmcnt(7)
	v_pk_add_f32 v[60:61], v[60:61], v[176:177]
	v_pk_add_f32 v[62:63], v[62:63], v[178:179]
	v_pk_add_f32 v[56:57], v[56:57], v[180:181]
	v_pk_add_f32 v[58:59], v[58:59], v[182:183]
	v_mul_f32_e32 v213, v60, v60
	v_fmac_f32_e32 v213, v61, v61
	v_fmac_f32_e32 v213, v62, v62
	v_fmac_f32_e32 v213, v63, v63
	v_fmac_f32_e32 v213, v56, v56
	v_fmac_f32_e32 v213, v57, v57
	v_fmac_f32_e32 v213, v58, v58
	v_fmac_f32_e32 v213, v59, v59
	v_cvt_pk_bf16_f32 v176, v60, v61
	v_cvt_pk_bf16_f32 v177, v62, v63
	v_cvt_pk_bf16_f32 v178, v56, v57
	v_cvt_pk_bf16_f32 v179, v58, v59
	v_add_u32_e32 v217, 0x80000, v209
	global_store_dwordx4 v217, v[176:179], s[80:81]
	v_pk_add_f32 v[52:53], v[52:53], v[184:185]
	v_pk_add_f32 v[54:55], v[54:55], v[186:187]
	v_pk_add_f32 v[48:49], v[48:49], v[188:189]
	v_pk_add_f32 v[50:51], v[50:51], v[190:191]
	v_fmac_f32_e32 v213, v52, v52
	v_fmac_f32_e32 v213, v53, v53
	v_fmac_f32_e32 v213, v54, v54
	v_fmac_f32_e32 v213, v55, v55
	v_fmac_f32_e32 v213, v48, v48
	v_fmac_f32_e32 v213, v49, v49
	v_fmac_f32_e32 v213, v50, v50
	v_fmac_f32_e32 v213, v51, v51
	v_cvt_pk_bf16_f32 v184, v52, v53
	v_cvt_pk_bf16_f32 v185, v54, v55
	v_cvt_pk_bf16_f32 v186, v48, v49
	v_cvt_pk_bf16_f32 v187, v50, v51
	global_store_dwordx4 v217, v[184:187], s[80:81] offset:256
	ds_bpermute_b32 v214, v215, v213
	s_waitcnt lgkmcnt(0)
	v_add_f32_e32 v213, v213, v214
	ds_bpermute_b32 v214, v216, v213
	s_waitcnt lgkmcnt(0)
	v_add_f32_e32 v213, v213, v214
	s_mov_b64 exec, 0xffff
	global_atomic_add_f32 v208, v213, s[12:13] offset:512
	s_mov_b64 exec, -1
	v_add_u32_e32 v212, 0x140000, v210
	global_load_dwordx4 v[176:179], v212, s[36:37]
	global_load_dwordx4 v[180:183], v212, s[36:37] offset:16
	global_load_dwordx4 v[184:187], v212, s[36:37] offset:512
	global_load_dwordx4 v[188:191], v212, s[36:37] offset:528
	s_waitcnt vmcnt(7)
	v_pk_add_f32 v[44:45], v[44:45], v[192:193]
	v_pk_add_f32 v[46:47], v[46:47], v[194:195]
	v_pk_add_f32 v[40:41], v[40:41], v[196:197]
	v_pk_add_f32 v[42:43], v[42:43], v[198:199]
	v_mul_f32_e32 v213, v44, v44
	v_fmac_f32_e32 v213, v45, v45
	v_fmac_f32_e32 v213, v46, v46
	v_fmac_f32_e32 v213, v47, v47
	v_fmac_f32_e32 v213, v40, v40
	v_fmac_f32_e32 v213, v41, v41
	v_fmac_f32_e32 v213, v42, v42
	v_fmac_f32_e32 v213, v43, v43
	v_cvt_pk_bf16_f32 v192, v44, v45
	v_cvt_pk_bf16_f32 v193, v46, v47
	v_cvt_pk_bf16_f32 v194, v40, v41
	v_cvt_pk_bf16_f32 v195, v42, v43
	v_add_u32_e32 v217, 0x90000, v209
	global_store_dwordx4 v217, v[192:195], s[80:81]
	v_pk_add_f32 v[36:37], v[36:37], v[200:201]
	v_pk_add_f32 v[38:39], v[38:39], v[202:203]
	v_pk_add_f32 v[32:33], v[32:33], v[204:205]
	v_pk_add_f32 v[34:35], v[34:35], v[206:207]
	v_fmac_f32_e32 v213, v36, v36
	v_fmac_f32_e32 v213, v37, v37
	v_fmac_f32_e32 v213, v38, v38
	v_fmac_f32_e32 v213, v39, v39
	v_fmac_f32_e32 v213, v32, v32
	v_fmac_f32_e32 v213, v33, v33
	v_fmac_f32_e32 v213, v34, v34
	v_fmac_f32_e32 v213, v35, v35
	v_cvt_pk_bf16_f32 v200, v36, v37
	v_cvt_pk_bf16_f32 v201, v38, v39
	v_cvt_pk_bf16_f32 v202, v32, v33
	v_cvt_pk_bf16_f32 v203, v34, v35
	global_store_dwordx4 v217, v[200:203], s[80:81] offset:256
	ds_bpermute_b32 v214, v215, v213
	s_waitcnt lgkmcnt(0)
	v_add_f32_e32 v213, v213, v214
	ds_bpermute_b32 v214, v216, v213
	s_waitcnt lgkmcnt(0)
	v_add_f32_e32 v213, v213, v214
	s_mov_b64 exec, 0xffff
	global_atomic_add_f32 v208, v213, s[12:13] offset:576
	s_mov_b64 exec, -1
	v_add_u32_e32 v212, 0x160000, v210
	global_load_dwordx4 v[192:195], v212, s[36:37]
	global_load_dwordx4 v[196:199], v212, s[36:37] offset:16
	global_load_dwordx4 v[200:203], v212, s[36:37] offset:512
	global_load_dwordx4 v[204:207], v212, s[36:37] offset:528
	s_waitcnt vmcnt(7)
	v_pk_add_f32 v[28:29], v[28:29], v[176:177]
	v_pk_add_f32 v[30:31], v[30:31], v[178:179]
	v_pk_add_f32 v[24:25], v[24:25], v[180:181]
	v_pk_add_f32 v[26:27], v[26:27], v[182:183]
	v_mul_f32_e32 v213, v28, v28
	v_fmac_f32_e32 v213, v29, v29
	v_fmac_f32_e32 v213, v30, v30
	v_fmac_f32_e32 v213, v31, v31
	v_fmac_f32_e32 v213, v24, v24
	v_fmac_f32_e32 v213, v25, v25
	v_fmac_f32_e32 v213, v26, v26
	v_fmac_f32_e32 v213, v27, v27
	v_cvt_pk_bf16_f32 v176, v28, v29
	v_cvt_pk_bf16_f32 v177, v30, v31
	v_cvt_pk_bf16_f32 v178, v24, v25
	v_cvt_pk_bf16_f32 v179, v26, v27
	v_add_u32_e32 v217, 0xa0000, v209
	global_store_dwordx4 v217, v[176:179], s[80:81]
	v_pk_add_f32 v[20:21], v[20:21], v[184:185]
	v_pk_add_f32 v[22:23], v[22:23], v[186:187]
	v_pk_add_f32 v[16:17], v[16:17], v[188:189]
	v_pk_add_f32 v[18:19], v[18:19], v[190:191]
	v_fmac_f32_e32 v213, v20, v20
	v_fmac_f32_e32 v213, v21, v21
	v_fmac_f32_e32 v213, v22, v22
	v_fmac_f32_e32 v213, v23, v23
	v_fmac_f32_e32 v213, v16, v16
	v_fmac_f32_e32 v213, v17, v17
	v_fmac_f32_e32 v213, v18, v18
	v_fmac_f32_e32 v213, v19, v19
	v_cvt_pk_bf16_f32 v184, v20, v21
	v_cvt_pk_bf16_f32 v185, v22, v23
	v_cvt_pk_bf16_f32 v186, v16, v17
	v_cvt_pk_bf16_f32 v187, v18, v19
	global_store_dwordx4 v217, v[184:187], s[80:81] offset:256
	ds_bpermute_b32 v214, v215, v213
	s_waitcnt lgkmcnt(0)
	v_add_f32_e32 v213, v213, v214
	ds_bpermute_b32 v214, v216, v213
	s_waitcnt lgkmcnt(0)
	v_add_f32_e32 v213, v213, v214
	s_mov_b64 exec, 0xffff
	global_atomic_add_f32 v208, v213, s[12:13] offset:640
	s_mov_b64 exec, -1
	s_waitcnt vmcnt(3)
	v_pk_add_f32 v[12:13], v[12:13], v[192:193]
	v_pk_add_f32 v[14:15], v[14:15], v[194:195]
	v_pk_add_f32 v[8:9], v[8:9], v[196:197]
	v_pk_add_f32 v[10:11], v[10:11], v[198:199]
	v_mul_f32_e32 v213, v12, v12
	v_fmac_f32_e32 v213, v13, v13
	v_fmac_f32_e32 v213, v14, v14
	v_fmac_f32_e32 v213, v15, v15
	v_fmac_f32_e32 v213, v8, v8
	v_fmac_f32_e32 v213, v9, v9
	v_fmac_f32_e32 v213, v10, v10
	v_fmac_f32_e32 v213, v11, v11
	v_cvt_pk_bf16_f32 v192, v12, v13
	v_cvt_pk_bf16_f32 v193, v14, v15
	v_cvt_pk_bf16_f32 v194, v8, v9
	v_cvt_pk_bf16_f32 v195, v10, v11
	v_add_u32_e32 v217, 0xb0000, v209
	global_store_dwordx4 v217, v[192:195], s[80:81]
	v_pk_add_f32 v[4:5], v[4:5], v[200:201]
	v_pk_add_f32 v[6:7], v[6:7], v[202:203]
	v_pk_add_f32 v[0:1], v[0:1], v[204:205]
	v_pk_add_f32 v[2:3], v[2:3], v[206:207]
	v_fmac_f32_e32 v213, v4, v4
	v_fmac_f32_e32 v213, v5, v5
	v_fmac_f32_e32 v213, v6, v6
	v_fmac_f32_e32 v213, v7, v7
	v_fmac_f32_e32 v213, v0, v0
	v_fmac_f32_e32 v213, v1, v1
	v_fmac_f32_e32 v213, v2, v2
	v_fmac_f32_e32 v213, v3, v3
	v_cvt_pk_bf16_f32 v200, v4, v5
	v_cvt_pk_bf16_f32 v201, v6, v7
	v_cvt_pk_bf16_f32 v202, v0, v1
	v_cvt_pk_bf16_f32 v203, v2, v3
	global_store_dwordx4 v217, v[200:203], s[80:81] offset:256
	ds_bpermute_b32 v214, v215, v213
	s_waitcnt lgkmcnt(0)
	v_add_f32_e32 v213, v213, v214
	ds_bpermute_b32 v214, v216, v213
	s_waitcnt lgkmcnt(0)
	v_add_f32_e32 v213, v213, v214
	s_mov_b64 exec, 0xffff
	global_atomic_add_f32 v208, v213, s[12:13] offset:704
	s_mov_b64 exec, -1
	s_branch .LBB0_273
.LBB0_300:
	s_waitcnt vmcnt(0)
	s_cmpk_gt_u32 s3, 0xff
	s_cbranch_scc1 .LBB0_302
.LBB0_302:
	s_barrier

.LBB0_355:
	s_or_b64 exec, exec, s[0:1]
	s_add_u32 s70, s92, 0x1bd00000
	s_addc_u32 s71, s93, 0
	s_cmpk_lt_i32 s2, 0xb00
	s_cselect_b64 s[0:1], -1, 0
	s_waitcnt lgkmcnt(0)
	v_lshlrev_b32_e32 v0, 6, v163
	v_writelane_b32 v255, s0, 10
	v_readfirstlane_b32 s3, v222
	v_bitop3_b32 v230, v227, v152, v0 bitop3:0x36
	v_writelane_b32 v255, s1, 11
	s_cmpk_gt_i32 s2, 0xaff
	v_and_b32_e32 v220, 48, v144
	v_lshlrev_b32_e32 v223, 1, v144
	v_and_b32_e32 v221, 48, v153
	v_lshlrev_b32_e32 v254, 1, v153
	s_barrier
	s_cbranch_scc1 .LBB0_377
	s_add_u32 s40, s92, 0x2100000
	s_addc_u32 s41, s93, 0
	s_lshr_b32 s0, s77, 29
	s_add_i32 s0, s2, s0
	s_lshr_b32 s10, s3, 6
	s_ashr_i32 s1, s0, 3
	s_and_b32 s0, s0, -8
	s_lshr_b32 s5, s3, 8
	s_lshl_b32 s42, s10, 10
	s_sub_i32 s0, s2, s0
	s_cmp_lt_i32 s0, 0
	s_movk_i32 s43, 0x161
	s_cselect_b32 s4, s43, 0x160
	s_mul_i32 s0, s4, s0
	s_add_i32 s0, s0, s1
	s_mul_hi_i32 s1, s0, 0x2e8ba2e9
	s_lshr_b32 s4, s1, 31
	s_ashr_i32 s1, s1, 5
	s_add_i32 s1, s1, s4
	s_lshl_b32 s6, s1, 2
	s_mulk_i32 s1, 0xb0
	s_sub_i32 s0, s0, s1
	s_sext_i32_i16 s1, s0
	s_bfe_u32 s1, s1, 0x2001d
	s_add_i32 s1, s0, s1
	s_sext_i32_i16 s4, s1
	s_and_b32 s1, s1, 0xfffc
	s_sub_i32 s0, s0, s1
	s_sext_i32_i16 s0, s0
	s_lshr_b32 s4, s4, 2
	s_add_i32 s0, s6, s0
	s_ashr_i32 s1, s0, 31
	s_bfe_i64 s[8:9], s[4:5], 0x100000
	s_lshl_b64 s[6:7], s[0:1], 20
	s_lshl_b64 s[8:9], s[8:9], 19
	s_add_u32 s8, s40, s8
	s_addc_u32 s9, s41, s9
	s_add_i32 s44, s42, 0
	v_and_b32_e32 v8, 0x180, v223
	s_add_i32 m0, s44, 0x10000
	v_or3_b32 v0, v220, v8, v218
	v_and_b32_e32 v9, 0x80, v254
	v_and_b32_e32 v183, 63, v222
	v_lshrrev_b32_e32 v184, 3, v183
	v_lshrrev_b32_e32 v185, 6, v222
	v_lshl_add_u32 v186, v185, 3, v184
	v_and_b32_e32 v187, 7, v183
	v_and_b32_e32 v188, 6, v184
	v_xor_b32_e32 v187, v187, v188
	v_lshlrev_b32_e32 v187, 4, v187
	v_mul_u32_u24_e32 v188, 0x1000, v186
	v_add_u32_e32 v188, v188, v187
	v_add_u32_e32 v168, 0x80000, v188
	v_mov_b32_e32 v170, v188
	v_add_u32_e32 v172, 0x40080, v188
	v_add_u32_e32 v174, 0xc0080, v188
	v_add_u32_e32 v168, 0x80000, v188
	v_add_u32_e32 v174, 0xc0080, v188
	v_and_b32_e32 v188, 31, v186
	v_and_b32_e32 v189, 12, v188
	v_lshlrev_b32_e32 v189, 1, v189
	v_lshrrev_b32_e32 v190, 4, v188
	v_lshlrev_b32_e32 v190, 2, v190
	v_and_b32_e32 v188, 3, v188
	v_or3_b32 v188, v189, v190, v188
	v_and_b32_e32 v189, 0x60, v186
	v_add_u32_e32 v188, v188, v189
	v_mul_u32_u24_e32 v188, 0x1000, v188
	v_add_u32_e32 v188, v188, v187
	v_mov_b32_e32 v164, v188
	v_add_u32_e32 v166, 0x40000, v188
	v_add_u32_e32 v166, 0x40000, v188
	v_and_b32_e32 v188, 15, v183
	v_lshrrev_b32_e32 v189, 4, v183
	v_and_b32_e32 v190, 6, v188
	v_xor_b32_e32 v189, v189, v190
	v_lshlrev_b32_e32 v189, 4, v189
	v_lshl_or_b32 v189, v188, 7, v189
	v_lshrrev_b32_e32 v190, 2, v185
	v_lshl_add_u32 v190, v190, 13, v189
	v_add_u32_e32 v241, 0x0, v190
	v_and_b32_e32 v188, 3, v185
	v_lshl_add_u32 v188, v188, 12, v189
	v_add_u32_e32 v229, 0x0, v188
	v_add_u32_e32 v231, 0x10000, v188
	v_add_u32_e32 v242, 0x14000, v188
	v_mov_b32_e32 v173, 0x0
	v_mov_b32_e32 v175, 0x0
	global_load_lds_dwordx4 v164, s[8:9]
	s_add_i32 m0, s44, 0x12000
	v_or3_b32 v0, v221, v9, v218
	s_add_u32 s6, s80, s6
	global_load_lds_dwordx4 v166, s[8:9]
	s_addc_u32 s7, s81, s7
	s_mov_b32 m0, s44
	s_add_i32 s45, s44, 0x2000
	global_load_lds_dwordx4 v170, s[6:7]
	s_mov_b32 m0, s45
	s_add_u32 s14, s8, 0x1600000
	global_load_lds_dwordx4 v168, s[6:7]
	s_addc_u32 s15, s9, 0
	s_add_i32 m0, s44, 0x14000
	v_mov_b32_e32 v165, 0
	global_load_lds_dwordx4 v164, s[14:15]
	s_add_i32 m0, s44, 0x16000
	v_mov_b32_e32 v167, v165
	global_load_lds_dwordx4 v166, s[14:15]
	s_add_u32 s14, s6, 0x40000
	s_addc_u32 s15, s7, 0
	s_add_i32 s46, s44, 0x4000
	s_mov_b32 m0, s46
	s_add_i32 s47, s44, 0x6000
	global_load_lds_dwordx4 v170, s[14:15]
	s_mov_b32 m0, s47
	v_mov_b32_e32 v171, v165
	global_load_lds_dwordx4 v168, s[14:15]
	v_mov_b32_e32 v169, v165
	s_mov_b32 s48, 0
	v_lshl_add_u64 v[6:7], s[8:9], 0, v[164:165]
	v_lshl_add_u64 v[4:5], s[8:9], 0, v[166:167]
	v_lshl_add_u64 v[2:3], s[6:7], 0, v[170:171]
	s_cmp_lg_u32 s5, 1
	v_lshl_add_u64 v[0:1], s[6:7], 0, v[168:169]
	s_cbranch_scc1 .LBB0_358
.LBB0_358:
	s_mov_b64 s[14:15], 0x80
	s_lshl_b32 s1, s10, 5
	s_add_i32 m0, s44, 0x18000
	v_lshl_add_u64 v[6:7], v[6:7], 0, s[14:15]
	s_and_b32 s49, s1, 0x60
	s_waitcnt vmcnt(4)
	s_barrier
	global_load_lds_dwordx4 v[6:7], off
	v_lshl_add_u64 v[4:5], v[4:5], 0, s[14:15]
	s_add_i32 m0, s44, 0x1a000
	s_add_i32 s52, s44, 0x8000
	s_add_i32 s53, s44, 0xa000
	global_load_lds_dwordx4 v[4:5], off
	v_lshl_add_u64 v[2:3], v[2:3], 0, s[14:15]
	s_mov_b32 m0, s52
	s_add_u32 s10, s8, 0x1600080
	global_load_lds_dwordx4 v[2:3], off
	v_lshl_add_u64 v[0:1], v[0:1], 0, s[14:15]
	s_mov_b32 m0, s53
	s_addc_u32 s11, s9, 0
	global_load_lds_dwordx4 v[0:1], off
	s_add_i32 m0, s44, 0x1c000
	v_lshl_add_u64 v[0:1], s[10:11], 0, v[164:165]
	global_load_lds_dwordx4 v[0:1], off
	v_lshl_add_u64 v[0:1], s[10:11], 0, v[166:167]
	s_add_i32 m0, s44, 0x1e000
	s_ashr_i32 s54, s94, 31
	global_load_lds_dwordx4 v[0:1], off
	s_lshl_b32 s56, s5, 7
	s_lshl_b32 s57, s5, 2
	s_add_u32 s16, s82, 0xb000
	s_addc_u32 s17, s83, 0
	s_add_u32 s18, s82, 0x16000
	s_addc_u32 s19, s83, 0
	s_add_u32 s20, s82, 0x5800
	s_addc_u32 s21, s83, 0
	s_add_u32 s22, s82, 0x10800
	v_add3_u32 v0, v9, v221, v218
	s_addc_u32 s23, s83, 0
	v_lshl_or_b32 v0, v0, 12, v226
	s_sext_i32_i16 s1, s4
	v_lshl_or_b32 v2, s5, 13, v230
	s_add_u32 s24, s82, 0x1b800
	v_add_u32_e32 v0, v0, v224
	v_mov_b32_e32 v1, v165
	s_mov_b64 s[4:5], 0x40080
	s_addc_u32 s25, s83, 0
	v_add3_u32 v0, v8, v220, v218
	s_waitcnt vmcnt(6)
	s_add_u32 s26, s84, 0x5800
	v_lshl_or_b32 v0, v0, 12, v226
	s_addc_u32 s27, s85, 0
	v_add_u32_e32 v0, v0, v224
	s_add_i32 s58, 0, 0x10000
	s_add_i32 s59, 0, 0x14000
	s_mov_b32 s55, s94
	v_mov_b64_e32 v[176:177], 0xb00
	v_mov_b64_e32 v[178:179], 0xaff
	v_mov_b32_e32 v243, 0x3727c5ac
	s_mov_b32 s60, 0xb000
	s_movk_i32 s61, 0x2c00
	s_barrier
	s_branch .LBB0_360

.LBB0_362:
	s_ashr_i32 s31, s30, 31
	v_cmp_lt_i64_e32 vcc, s[10:11], v[176:177]
	s_lshl_b64 s[10:11], s[30:31], 20
	s_add_u32 s34, s80, s10
	s_addc_u32 s35, s81, s11
	s_and_b64 s[10:11], vcc, exec
	s_cselect_b32 s31, s35, s7
	s_cselect_b32 s33, s34, s6
	s_ashr_i32 s29, s28, 31
	s_lshl_b64 s[10:11], s[28:29], 19
	s_add_u32 s36, s40, s10
	s_addc_u32 s37, s41, s11
	s_and_b64 s[10:11], vcc, exec
	s_cselect_b32 s29, s37, s9
	s_cselect_b32 s62, s36, s8
	s_add_u32 s63, s8, 0x100
	v_mov_b32_e32 v0, 0
	s_addc_u32 s64, s9, 0
	s_mov_b32 s65, -2
	v_mov_b32_e32 v1, v0
	v_mov_b32_e32 v2, v0
	v_mov_b32_e32 v3, v0
	v_mov_b32_e32 v64, v0
	v_mov_b32_e32 v65, v0
	v_mov_b32_e32 v66, v0
	v_mov_b32_e32 v67, v0
	v_mov_b32_e32 v8, v0
	v_mov_b32_e32 v9, v0
	s_waitcnt vmcnt(0)
	v_mov_b32_e32 v10, v0
	v_mov_b32_e32 v11, v0
	v_mov_b32_e32 v68, v0
	v_mov_b32_e32 v69, v0
	v_mov_b32_e32 v70, v0
	v_mov_b32_e32 v71, v0
	v_mov_b32_e32 v12, v0
	v_mov_b32_e32 v13, v0
	v_mov_b32_e32 v14, v0
	v_mov_b32_e32 v15, v0
	v_mov_b32_e32 v110, v0
	v_mov_b32_e32 v111, v0
	v_mov_b32_e32 v112, v0
	v_mov_b32_e32 v113, v0
	v_mov_b32_e32 v16, v0
	v_mov_b32_e32 v17, v0
	v_mov_b32_e32 v18, v0
	v_mov_b32_e32 v19, v0
	v_mov_b32_e32 v118, v0
	v_mov_b32_e32 v119, v0
	v_mov_b32_e32 v120, v0
	v_mov_b32_e32 v121, v0
	v_mov_b32_e32 v4, v0
	v_mov_b32_e32 v5, v0
	v_mov_b32_e32 v6, v0
	v_mov_b32_e32 v7, v0
	v_mov_b32_e32 v72, v0
	v_mov_b32_e32 v73, v0
	v_mov_b32_e32 v74, v0
	v_mov_b32_e32 v75, v0
	v_mov_b32_e32 v20, v0
	v_mov_b32_e32 v21, v0
	v_mov_b32_e32 v22, v0
	v_mov_b32_e32 v23, v0
	v_mov_b32_e32 v114, v0
	v_mov_b32_e32 v115, v0
	v_mov_b32_e32 v116, v0
	v_mov_b32_e32 v117, v0
	v_mov_b32_e32 v24, v0
	v_mov_b32_e32 v25, v0
	v_mov_b32_e32 v26, v0
	v_mov_b32_e32 v27, v0
	v_mov_b32_e32 v122, v0
	v_mov_b32_e32 v123, v0
	v_mov_b32_e32 v124, v0
	v_mov_b32_e32 v125, v0
	v_mov_b32_e32 v28, v0
	v_mov_b32_e32 v29, v0
	v_mov_b32_e32 v30, v0
	v_mov_b32_e32 v31, v0
	v_mov_b32_e32 v126, v0
	v_mov_b32_e32 v127, v0
	v_mov_b32_e32 v128, v0
	v_mov_b32_e32 v129, v0
	v_mov_b32_e32 v32, v0
	v_mov_b32_e32 v33, v0
	v_mov_b32_e32 v34, v0
	v_mov_b32_e32 v35, v0
	v_mov_b32_e32 v130, v0
	v_mov_b32_e32 v131, v0
	v_mov_b32_e32 v132, v0
	v_mov_b32_e32 v133, v0
	v_mov_b32_e32 v36, v0
	v_mov_b32_e32 v37, v0
	v_mov_b32_e32 v38, v0
	v_mov_b32_e32 v39, v0
	v_mov_b32_e32 v134, v0
	v_mov_b32_e32 v135, v0
	v_mov_b32_e32 v136, v0
	v_mov_b32_e32 v137, v0
	v_mov_b32_e32 v44, v0
	v_mov_b32_e32 v45, v0
	v_mov_b32_e32 v46, v0
	v_mov_b32_e32 v47, v0
	v_mov_b32_e32 v142, v0
	v_mov_b32_e32 v143, v0
	v_mov_b32_e32 v144, v0
	v_mov_b32_e32 v145, v0
	v_mov_b32_e32 v56, v0
	v_mov_b32_e32 v57, v0
	v_mov_b32_e32 v58, v0
	v_mov_b32_e32 v59, v0
	v_mov_b32_e32 v154, v0
	v_mov_b32_e32 v155, v0
	v_mov_b32_e32 v156, v0
	v_mov_b32_e32 v157, v0
	v_mov_b32_e32 v40, v0
	v_mov_b32_e32 v41, v0
	v_mov_b32_e32 v42, v0
	v_mov_b32_e32 v43, v0
	v_mov_b32_e32 v138, v0
	v_mov_b32_e32 v139, v0
	v_mov_b32_e32 v140, v0
	v_mov_b32_e32 v141, v0
	v_mov_b32_e32 v48, v0
	v_mov_b32_e32 v49, v0
	v_mov_b32_e32 v50, v0
	v_mov_b32_e32 v51, v0
	v_mov_b32_e32 v146, v0
	v_mov_b32_e32 v147, v0
	v_mov_b32_e32 v148, v0
	v_mov_b32_e32 v149, v0
	v_mov_b32_e32 v52, v0
	v_mov_b32_e32 v53, v0
	v_mov_b32_e32 v54, v0
	v_mov_b32_e32 v55, v0
	v_mov_b32_e32 v150, v0
	v_mov_b32_e32 v151, v0
	v_mov_b32_e32 v152, v0
	v_mov_b32_e32 v153, v0
	v_mov_b32_e32 v60, v0
	v_mov_b32_e32 v61, v0
	v_mov_b32_e32 v62, v0
	v_mov_b32_e32 v63, v0
	v_mov_b32_e32 v158, v0
	v_mov_b32_e32 v159, v0
	v_mov_b32_e32 v160, v0
	v_mov_b32_e32 v161, v0
	v_xor_b32_e32 v216, 64, v231
	v_xor_b32_e32 v217, 64, v241
	v_xor_b32_e32 v244, 64, v242
	v_add_u32_e32 v245, 0x18000, v229
	v_xor_b32_e32 v246, 64, v245
	v_add_u32_e32 v247, 0x1c000, v229
	v_xor_b32_e32 v248, 64, v247
	s_cmpk_lt_u32 s3, 0x100
	s_cbranch_scc1 .Lst_in_s3
	s_barrier
.Lst_in_s3:
.LBB0_363:
	ds_read_b128 v[76:79], v231
	ds_read_b128 v[80:83], v216
	ds_read_b128 v[84:87], v231 offset:2048
	ds_read_b128 v[88:91], v216 offset:2048
	s_add_u32 s8, s6, 0x100
	s_addc_u32 s9, s7, 0
	s_cmp_eq_u32 s65, 28
	s_cselect_b32 s39, s31, s9
	s_cselect_b32 s38, s33, s8
	s_cselect_b32 s11, s29, s64
	s_cselect_b32 s10, s62, s63
	s_add_i32 m0, s44, 0xc000
	ds_read_b128 v[92:95], v241
	ds_read_b128 v[96:99], v217
	ds_read_b128 v[100:103], v241 offset:2048
	ds_read_b128 v[104:107], v217 offset:2048
	ds_read_b128 v[180:183], v241 offset:4096
	ds_read_b128 v[184:187], v217 offset:4096
	ds_read_b128 v[188:191], v241 offset:6144
	ds_read_b128 v[192:195], v217 offset:6144
	global_load_lds_dwordx4 v172, s[6:7]
	s_add_i32 m0, s44, 0xe000
	s_nop 0
	global_load_lds_dwordx4 v174, s[6:7]
	s_waitcnt lgkmcnt(8)
	s_barrier
	s_waitcnt lgkmcnt(0)
	s_waitcnt lgkmcnt(0)
	v_mfma_f32_16x16x32_bf16 v[158:161], v[76:79], v[92:95], v[158:161]
	v_mfma_f32_16x16x32_bf16 v[158:161], v[80:83], v[96:99], v[158:161]
	v_mfma_f32_16x16x32_bf16 v[60:63], v[88:91], v[96:99], v[60:63]
	v_mfma_f32_16x16x32_bf16 v[60:63], v[84:87], v[92:95], v[60:63]
	v_mfma_f32_16x16x32_bf16 v[52:55], v[84:87], v[100:103], v[52:55]
	v_mfma_f32_16x16x32_bf16 v[52:55], v[88:91], v[104:107], v[52:55]
	v_mfma_f32_16x16x32_bf16 v[150:153], v[80:83], v[104:107], v[150:153]
	v_mfma_f32_16x16x32_bf16 v[150:153], v[76:79], v[100:103], v[150:153]
	v_mfma_f32_16x16x32_bf16 v[146:149], v[76:79], v[180:183], v[146:149]
	v_mfma_f32_16x16x32_bf16 v[146:149], v[80:83], v[184:187], v[146:149]
	v_mfma_f32_16x16x32_bf16 v[48:51], v[88:91], v[184:187], v[48:51]
	v_mfma_f32_16x16x32_bf16 v[48:51], v[84:87], v[180:183], v[48:51]
	v_mfma_f32_16x16x32_bf16 v[40:43], v[84:87], v[188:191], v[40:43]
	v_mfma_f32_16x16x32_bf16 v[40:43], v[88:91], v[192:195], v[40:43]
	v_mfma_f32_16x16x32_bf16 v[138:141], v[80:83], v[192:195], v[138:141]
	v_mfma_f32_16x16x32_bf16 v[138:141], v[76:79], v[188:191], v[138:141]
	s_barrier
	s_add_i32 s6, s58, s42
	s_add_u32 s98, s10, s14
	s_addc_u32 s99, s11, s15
	s_mov_b32 m0, s6
	ds_read_b128 v[196:199], v242
	ds_read_b128 v[200:203], v244
	ds_read_b128 v[204:207], v242 offset:2048
	ds_read_b128 v[208:211], v244 offset:2048
	global_load_lds_dwordx4 v164, s[10:11]
	s_add_i32 m0, s6, 0x2000
	s_nop 0
	global_load_lds_dwordx4 v166, s[10:11]
	s_barrier
	s_waitcnt lgkmcnt(0)
	s_waitcnt lgkmcnt(0)
	v_mfma_f32_16x16x32_bf16 v[154:157], v[196:199], v[92:95], v[154:157]
	v_mfma_f32_16x16x32_bf16 v[154:157], v[200:203], v[96:99], v[154:157]
	v_mfma_f32_16x16x32_bf16 v[56:59], v[208:211], v[96:99], v[56:59]
	v_mfma_f32_16x16x32_bf16 v[56:59], v[204:207], v[92:95], v[56:59]
	v_mfma_f32_16x16x32_bf16 v[44:47], v[204:207], v[100:103], v[44:47]
	v_mfma_f32_16x16x32_bf16 v[44:47], v[208:211], v[104:107], v[44:47]
	v_mfma_f32_16x16x32_bf16 v[36:39], v[208:211], v[184:187], v[36:39]
	v_mfma_f32_16x16x32_bf16 v[36:39], v[204:207], v[180:183], v[36:39]
	v_mfma_f32_16x16x32_bf16 v[32:35], v[204:207], v[188:191], v[32:35]
	v_mfma_f32_16x16x32_bf16 v[32:35], v[208:211], v[192:195], v[32:35]
	v_mfma_f32_16x16x32_bf16 v[92:95], v[196:199], v[100:103], v[142:145]
	v_mfma_f32_16x16x32_bf16 v[92:95], v[200:203], v[104:107], v[92:95]
	v_mfma_f32_16x16x32_bf16 v[96:99], v[200:203], v[184:187], v[134:137]
	v_mfma_f32_16x16x32_bf16 v[96:99], v[196:199], v[180:183], v[96:99]
	v_mfma_f32_16x16x32_bf16 v[100:103], v[196:199], v[188:191], v[130:133]
	v_mfma_f32_16x16x32_bf16 v[100:103], v[200:203], v[192:195], v[100:103]
	s_mov_b32 m0, s44
	s_add_u32 s100, s38, s14
	s_addc_u32 s101, s39, s15
	s_barrier
	ds_read_b128 v[104:107], v241 offset:16384
	ds_read_b128 v[130:133], v217 offset:16384
	ds_read_b128 v[134:137], v241 offset:18432
	ds_read_b128 v[142:145], v217 offset:18432
	ds_read_b128 v[180:183], v241 offset:20480
	ds_read_b128 v[184:187], v217 offset:20480
	ds_read_b128 v[188:191], v241 offset:22528
	ds_read_b128 v[192:195], v217 offset:22528
	global_load_lds_dwordx4 v170, s[38:39]
	s_mov_b32 m0, s45
	s_nop 0
	global_load_lds_dwordx4 v168, s[38:39]
	s_barrier
	s_waitcnt lgkmcnt(0)
	s_waitcnt lgkmcnt(0)
	v_mfma_f32_16x16x32_bf16 v[126:129], v[76:79], v[104:107], v[126:129]
	v_mfma_f32_16x16x32_bf16 v[126:129], v[80:83], v[130:133], v[126:129]
	v_mfma_f32_16x16x32_bf16 v[28:31], v[88:91], v[130:133], v[28:31]
	v_mfma_f32_16x16x32_bf16 v[28:31], v[84:87], v[104:107], v[28:31]
	v_mfma_f32_16x16x32_bf16 v[24:27], v[84:87], v[134:137], v[24:27]
	v_mfma_f32_16x16x32_bf16 v[24:27], v[88:91], v[142:145], v[24:27]
	v_mfma_f32_16x16x32_bf16 v[122:125], v[80:83], v[142:145], v[122:125]
	v_mfma_f32_16x16x32_bf16 v[122:125], v[76:79], v[134:137], v[122:125]
	v_mfma_f32_16x16x32_bf16 v[114:117], v[76:79], v[180:183], v[114:117]
	v_mfma_f32_16x16x32_bf16 v[114:117], v[80:83], v[184:187], v[114:117]
	v_mfma_f32_16x16x32_bf16 v[20:23], v[88:91], v[184:187], v[20:23]
	v_mfma_f32_16x16x32_bf16 v[20:23], v[84:87], v[180:183], v[20:23]
	v_mfma_f32_16x16x32_bf16 v[4:7], v[84:87], v[188:191], v[4:7]
	v_mfma_f32_16x16x32_bf16 v[4:7], v[88:91], v[192:195], v[4:7]
	v_mfma_f32_16x16x32_bf16 v[72:75], v[80:83], v[192:195], v[72:75]
	v_mfma_f32_16x16x32_bf16 v[72:75], v[76:79], v[188:191], v[72:75]
	s_barrier
	s_add_u32 s6, s10, 0x1600000
	s_addc_u32 s7, s11, 0
	s_add_i32 s66, s59, s42
	s_mov_b32 m0, s66
	s_nop 0
	global_load_lds_dwordx4 v164, s[6:7]
	s_add_i32 m0, s66, 0x2000
	s_nop 0
	global_load_lds_dwordx4 v166, s[6:7]
	s_waitcnt vmcnt(6)
	s_barrier
	v_mfma_f32_16x16x32_bf16 v[16:19], v[204:207], v[104:107], v[16:19]
	v_mfma_f32_16x16x32_bf16 v[16:19], v[208:211], v[130:133], v[16:19]
	v_mfma_f32_16x16x32_bf16 v[12:15], v[208:211], v[142:145], v[12:15]
	v_mfma_f32_16x16x32_bf16 v[12:15], v[204:207], v[134:137], v[12:15]
	v_mfma_f32_16x16x32_bf16 v[8:11], v[204:207], v[180:183], v[8:11]
	v_mfma_f32_16x16x32_bf16 v[8:11], v[208:211], v[184:187], v[8:11]
	v_mfma_f32_16x16x32_bf16 v[68:71], v[200:203], v[184:187], v[68:71]
	v_mfma_f32_16x16x32_bf16 v[68:71], v[196:199], v[180:183], v[68:71]
	v_mfma_f32_16x16x32_bf16 v[64:67], v[196:199], v[188:191], v[64:67]
	v_mfma_f32_16x16x32_bf16 v[64:67], v[200:203], v[192:195], v[64:67]
	v_mfma_f32_16x16x32_bf16 v[0:3], v[208:211], v[192:195], v[0:3]
	v_mfma_f32_16x16x32_bf16 v[0:3], v[204:207], v[188:191], v[0:3]
	v_mfma_f32_16x16x32_bf16 v[76:79], v[196:199], v[104:107], v[118:121]
	v_mfma_f32_16x16x32_bf16 v[76:79], v[200:203], v[130:133], v[76:79]
	v_mfma_f32_16x16x32_bf16 v[80:83], v[200:203], v[142:145], v[110:113]
	v_mfma_f32_16x16x32_bf16 v[80:83], v[196:199], v[134:137], v[80:83]
	s_add_i32 s66, 0, 0x18000
	s_barrier
	ds_read_b128 v[84:87], v245
	ds_read_b128 v[88:91], v246
	ds_read_b128 v[104:107], v245 offset:2048
	ds_read_b128 v[108:111], v246 offset:2048
	s_add_u32 s6, s38, 0x40000
	s_addc_u32 s7, s39, 0
	s_mov_b32 m0, s46
	ds_read_b128 v[118:121], v241 offset:32768
	ds_read_b128 v[130:133], v217 offset:32768
	ds_read_b128 v[134:137], v241 offset:34816
	ds_read_b128 v[180:183], v217 offset:34816
	ds_read_b128 v[184:187], v241 offset:36864
	ds_read_b128 v[188:191], v217 offset:36864
	ds_read_b128 v[192:195], v241 offset:38912
	ds_read_b128 v[196:199], v217 offset:38912
	global_load_lds_dwordx4 v170, s[6:7]
	s_mov_b32 m0, s47
	s_nop 0
	global_load_lds_dwordx4 v168, s[6:7]
	s_waitcnt lgkmcnt(8)
	s_barrier
	s_waitcnt lgkmcnt(0)
	s_waitcnt lgkmcnt(0)
	v_mfma_f32_16x16x32_bf16 v[142:145], v[84:87], v[118:121], v[158:161]
	v_mfma_f32_16x16x32_bf16 v[158:161], v[88:91], v[130:133], v[142:145]
	v_mfma_f32_16x16x32_bf16 v[60:63], v[108:111], v[130:133], v[60:63]
	v_mfma_f32_16x16x32_bf16 v[60:63], v[104:107], v[118:121], v[60:63]
	v_mfma_f32_16x16x32_bf16 v[52:55], v[104:107], v[134:137], v[52:55]
	v_mfma_f32_16x16x32_bf16 v[52:55], v[108:111], v[180:183], v[52:55]
	v_mfma_f32_16x16x32_bf16 v[48:51], v[108:111], v[188:191], v[48:51]
	v_mfma_f32_16x16x32_bf16 v[48:51], v[104:107], v[184:187], v[48:51]
	v_mfma_f32_16x16x32_bf16 v[40:43], v[104:107], v[192:195], v[40:43]
	v_mfma_f32_16x16x32_bf16 v[40:43], v[108:111], v[196:199], v[40:43]
	v_mfma_f32_16x16x32_bf16 v[138:141], v[88:91], v[196:199], v[138:141]
	v_mfma_f32_16x16x32_bf16 v[138:141], v[84:87], v[192:195], v[138:141]
	v_mfma_f32_16x16x32_bf16 v[142:145], v[84:87], v[134:137], v[150:153]
	v_mfma_f32_16x16x32_bf16 v[150:153], v[88:91], v[180:183], v[142:145]
	v_mfma_f32_16x16x32_bf16 v[142:145], v[84:87], v[184:187], v[146:149]
	v_mfma_f32_16x16x32_bf16 v[146:149], v[88:91], v[188:191], v[142:145]
	s_barrier
	s_add_i32 s38, 0, 0x1c000
	s_add_i32 s6, s66, s42
	ds_read_b128 v[200:203], v247
	ds_read_b128 v[204:207], v248
	ds_read_b128 v[208:211], v247 offset:2048
	ds_read_b128 v[212:215], v248 offset:2048
	s_mov_b32 m0, s6
	s_nop 0
	global_load_lds_dwordx4 v164, s[98:99]
	s_add_i32 m0, s6, 0x2000
	s_nop 0
	global_load_lds_dwordx4 v166, s[98:99]
	s_barrier
	s_waitcnt lgkmcnt(0)
	s_waitcnt lgkmcnt(0)
	v_mfma_f32_16x16x32_bf16 v[142:145], v[200:203], v[118:121], v[154:157]
	v_mfma_f32_16x16x32_bf16 v[154:157], v[204:207], v[130:133], v[142:145]
	v_mfma_f32_16x16x32_bf16 v[56:59], v[212:215], v[130:133], v[56:59]
	v_mfma_f32_16x16x32_bf16 v[56:59], v[208:211], v[118:121], v[56:59]
	v_mfma_f32_16x16x32_bf16 v[44:47], v[208:211], v[134:137], v[44:47]
	v_mfma_f32_16x16x32_bf16 v[44:47], v[212:215], v[180:183], v[44:47]
	v_mfma_f32_16x16x32_bf16 v[36:39], v[212:215], v[188:191], v[36:39]
	v_mfma_f32_16x16x32_bf16 v[36:39], v[208:211], v[184:187], v[36:39]
	v_mfma_f32_16x16x32_bf16 v[32:35], v[208:211], v[192:195], v[32:35]
	v_mfma_f32_16x16x32_bf16 v[32:35], v[212:215], v[196:199], v[32:35]
	v_mfma_f32_16x16x32_bf16 v[92:95], v[200:203], v[134:137], v[92:95]
	v_mfma_f32_16x16x32_bf16 v[142:145], v[204:207], v[180:183], v[92:95]
	v_mfma_f32_16x16x32_bf16 v[92:95], v[200:203], v[184:187], v[96:99]
	v_mfma_f32_16x16x32_bf16 v[134:137], v[204:207], v[188:191], v[92:95]
	v_mfma_f32_16x16x32_bf16 v[92:95], v[200:203], v[192:195], v[100:103]
	v_mfma_f32_16x16x32_bf16 v[130:133], v[204:207], v[196:199], v[92:95]
	s_mov_b32 m0, s52
	s_barrier
	ds_read_b128 v[92:95], v241 offset:49152
	ds_read_b128 v[96:99], v217 offset:49152
	ds_read_b128 v[100:103], v241 offset:51200
	ds_read_b128 v[180:183], v217 offset:51200
	ds_read_b128 v[184:187], v241 offset:53248
	ds_read_b128 v[188:191], v217 offset:53248
	ds_read_b128 v[192:195], v241 offset:55296
	ds_read_b128 v[196:199], v217 offset:55296
	global_load_lds_dwordx4 v170, s[100:101]
	s_mov_b32 m0, s53
	s_nop 0
	global_load_lds_dwordx4 v168, s[100:101]
	s_barrier
	s_waitcnt lgkmcnt(0)
	s_waitcnt lgkmcnt(0)
	v_mfma_f32_16x16x32_bf16 v[118:121], v[84:87], v[92:95], v[126:129]
	v_mfma_f32_16x16x32_bf16 v[126:129], v[88:91], v[96:99], v[118:121]
	v_mfma_f32_16x16x32_bf16 v[28:31], v[108:111], v[96:99], v[28:31]
	v_mfma_f32_16x16x32_bf16 v[28:31], v[104:107], v[92:95], v[28:31]
	v_mfma_f32_16x16x32_bf16 v[24:27], v[104:107], v[100:103], v[24:27]
	v_mfma_f32_16x16x32_bf16 v[24:27], v[108:111], v[180:183], v[24:27]
	v_mfma_f32_16x16x32_bf16 v[20:23], v[108:111], v[188:191], v[20:23]
	v_mfma_f32_16x16x32_bf16 v[20:23], v[104:107], v[184:187], v[20:23]
	v_mfma_f32_16x16x32_bf16 v[112:115], v[84:87], v[184:187], v[114:117]
	v_mfma_f32_16x16x32_bf16 v[114:117], v[88:91], v[188:191], v[112:115]
	v_mfma_f32_16x16x32_bf16 v[72:75], v[88:91], v[196:199], v[72:75]
	v_mfma_f32_16x16x32_bf16 v[72:75], v[84:87], v[192:195], v[72:75]
	v_mfma_f32_16x16x32_bf16 v[118:121], v[84:87], v[100:103], v[122:125]
	v_mfma_f32_16x16x32_bf16 v[122:125], v[88:91], v[180:183], v[118:121]
	v_mfma_f32_16x16x32_bf16 v[4:7], v[104:107], v[192:195], v[4:7]
	v_mfma_f32_16x16x32_bf16 v[4:7], v[108:111], v[196:199], v[4:7]
	s_barrier
	s_add_u32 s6, s10, 0x1600080
	s_addc_u32 s7, s11, 0
	s_add_i32 s10, s38, s42
	s_mov_b32 m0, s10
	s_nop 0
	global_load_lds_dwordx4 v164, s[6:7]
	s_add_i32 m0, s10, 0x2000
	s_nop 0
	global_load_lds_dwordx4 v166, s[6:7]
	s_waitcnt vmcnt(6)
	s_barrier
	v_mfma_f32_16x16x32_bf16 v[76:79], v[200:203], v[92:95], v[76:79]
	v_mfma_f32_16x16x32_bf16 v[118:121], v[204:207], v[96:99], v[76:79]
	v_mfma_f32_16x16x32_bf16 v[16:19], v[212:215], v[96:99], v[16:19]
	v_mfma_f32_16x16x32_bf16 v[16:19], v[208:211], v[92:95], v[16:19]
	v_mfma_f32_16x16x32_bf16 v[12:15], v[208:211], v[100:103], v[12:15]
	v_mfma_f32_16x16x32_bf16 v[12:15], v[212:215], v[180:183], v[12:15]
	v_mfma_f32_16x16x32_bf16 v[8:11], v[212:215], v[188:191], v[8:11]
	v_mfma_f32_16x16x32_bf16 v[8:11], v[208:211], v[184:187], v[8:11]
	v_mfma_f32_16x16x32_bf16 v[68:71], v[200:203], v[184:187], v[68:71]
	v_mfma_f32_16x16x32_bf16 v[68:71], v[204:207], v[188:191], v[68:71]
	v_mfma_f32_16x16x32_bf16 v[64:67], v[204:207], v[196:199], v[64:67]
	v_mfma_f32_16x16x32_bf16 v[64:67], v[200:203], v[192:195], v[64:67]
	v_mfma_f32_16x16x32_bf16 v[76:79], v[200:203], v[100:103], v[80:83]
	v_mfma_f32_16x16x32_bf16 v[110:113], v[204:207], v[180:183], v[76:79]
	v_mfma_f32_16x16x32_bf16 v[0:3], v[208:211], v[192:195], v[0:3]
	v_mfma_f32_16x16x32_bf16 v[0:3], v[212:215], v[196:199], v[0:3]
	s_add_i32 s65, s65, 2
	s_add_u32 s63, s63, 0x100
	s_addc_u32 s64, s64, 0
	s_cmp_gt_u32 s65, 29
	s_mov_b64 s[6:7], s[8:9]
	s_barrier
	s_cbranch_scc0 .LBB0_363
	s_cmpk_gt_u32 s3, 0xff
	s_cbranch_scc1 .Lst_out_s3
	s_barrier
.Lst_out_s3:
	s_lshl_b32 s8, s0, 8
	s_add_i32 s8, s8, s56
	s_lshl_b32 s9, s1, 7
	s_add_i32 s9, s9, s49
	s_lshl_b32 s10, s0, 3
	s_lshr_b32 s11, s56, 5
	s_add_i32 s10, s10, s11
	v_add_u32_e32 v200, s8, v163
	v_lshlrev_b32_e32 v213, 2, v200
	global_load_dword v188, v213, s[12:13]
	global_load_dword v189, v213, s[12:13] offset:64
	global_load_dword v190, v213, s[12:13] offset:128
	global_load_dword v191, v213, s[12:13] offset:192
	global_load_dword v192, v213, s[12:13] offset:256
	global_load_dword v193, v213, s[12:13] offset:320
	global_load_dword v194, v213, s[12:13] offset:384
	global_load_dword v195, v213, s[12:13] offset:448
	v_lshl_add_u32 v201, v225, 3, s9
	v_lshlrev_b32_e32 v212, 2, v201
	global_load_dwordx4 v[76:79], v212, s[82:83]
	v_add_u32_e32 v213, 0xb000, v212
	global_load_dwordx4 v[80:83], v213, s[82:83]
	v_add_u32_e32 v213, 0x16000, v212
	global_load_dwordx4 v[84:87], v213, s[82:83]
	global_load_dwordx4 v[88:91], v212, s[84:85]
	v_add_u32_e32 v213, 0x5800, v212
	global_load_dwordx4 v[92:95], v213, s[82:83]
	v_add_u32_e32 v213, 0x10800, v212
	global_load_dwordx4 v[96:99], v213, s[82:83]
	v_add_u32_e32 v213, 0x1b800, v212
	global_load_dwordx4 v[100:103], v213, s[82:83]
	v_add_u32_e32 v213, 0x5800, v212
	global_load_dwordx4 v[104:107], v213, s[84:85]
	v_mul_u32_u24_e32 v215, 0x2c00, v200
	v_lshl_add_u32 v215, v201, 1, v215
	v_add_u32_e32 v213, s10, v163
	v_mul_u32_u24_e32 v217, 0xb000, v213
	v_add_u32_e32 v217, v217, v212
	v_cmp_gt_u32_e64 s[8:9], 2, v163
	v_cmp_lt_u32_e64 s[10:11], 13, v163
	v_cmp_lt_u32_e32 vcc, 1, v163
	v_mov_b32_e32 v214, 1.0
	v_mov_b32_e32 v216, 0xbfb8aa3b
	v_mov_b32_e32 v108, 0x3727c5ac
	s_waitcnt vmcnt(8)
	v_fmamk_f32 v188, v188, 0x3a000000, v108
	v_fmamk_f32 v189, v189, 0x3a000000, v108
	v_fmamk_f32 v190, v190, 0x3a000000, v108
	v_fmamk_f32 v191, v191, 0x3a000000, v108
	v_fmamk_f32 v192, v192, 0x3a000000, v108
	v_fmamk_f32 v193, v193, 0x3a000000, v108
	v_fmamk_f32 v194, v194, 0x3a000000, v108
	v_fmamk_f32 v195, v195, 0x3a000000, v108
	v_rsq_f32_e32 v188, v188
	v_rsq_f32_e32 v189, v189
	v_rsq_f32_e32 v190, v190
	v_rsq_f32_e32 v191, v191
	v_rsq_f32_e32 v192, v192
	v_rsq_f32_e32 v193, v193
	v_rsq_f32_e32 v194, v194
	v_rsq_f32_e32 v195, v195
	v_pk_mul_f32 v[158:159], v[158:159], v[188:189] op_sel_hi:[1,0]
	v_pk_mul_f32 v[160:161], v[160:161], v[188:189] op_sel_hi:[1,0]
	v_pk_mul_f32 v[60:61], v[60:61], v[188:189] op_sel_hi:[1,0]
	v_pk_mul_f32 v[62:63], v[62:63], v[188:189] op_sel_hi:[1,0]
	v_pk_mul_f32 v[154:155], v[154:155], v[188:189] op_sel_hi:[1,0]
	v_pk_mul_f32 v[156:157], v[156:157], v[188:189] op_sel_hi:[1,0]
	v_pk_mul_f32 v[56:57], v[56:57], v[188:189] op_sel_hi:[1,0]
	v_pk_mul_f32 v[58:59], v[58:59], v[188:189] op_sel_hi:[1,0]
	v_pk_mul_f32 v[150:151], v[150:151], v[188:189] op_sel:[0,1] op_sel_hi:[1,1]
	v_pk_mul_f32 v[152:153], v[152:153], v[188:189] op_sel:[0,1] op_sel_hi:[1,1]
	v_pk_mul_f32 v[52:53], v[52:53], v[188:189] op_sel:[0,1] op_sel_hi:[1,1]
	v_pk_mul_f32 v[54:55], v[54:55], v[188:189] op_sel:[0,1] op_sel_hi:[1,1]
	v_pk_mul_f32 v[142:143], v[142:143], v[188:189] op_sel:[0,1] op_sel_hi:[1,1]
	v_pk_mul_f32 v[144:145], v[144:145], v[188:189] op_sel:[0,1] op_sel_hi:[1,1]
	v_pk_mul_f32 v[44:45], v[44:45], v[188:189] op_sel:[0,1] op_sel_hi:[1,1]
	v_pk_mul_f32 v[46:47], v[46:47], v[188:189] op_sel:[0,1] op_sel_hi:[1,1]
	v_pk_mul_f32 v[146:147], v[146:147], v[190:191] op_sel_hi:[1,0]
	v_pk_mul_f32 v[148:149], v[148:149], v[190:191] op_sel_hi:[1,0]
	v_pk_mul_f32 v[48:49], v[48:49], v[190:191] op_sel_hi:[1,0]
	v_pk_mul_f32 v[50:51], v[50:51], v[190:191] op_sel_hi:[1,0]
	v_pk_mul_f32 v[134:135], v[134:135], v[190:191] op_sel_hi:[1,0]
	v_pk_mul_f32 v[136:137], v[136:137], v[190:191] op_sel_hi:[1,0]
	v_pk_mul_f32 v[36:37], v[36:37], v[190:191] op_sel_hi:[1,0]
	v_pk_mul_f32 v[38:39], v[38:39], v[190:191] op_sel_hi:[1,0]
	v_pk_mul_f32 v[138:139], v[138:139], v[190:191] op_sel:[0,1] op_sel_hi:[1,1]
	v_pk_mul_f32 v[140:141], v[140:141], v[190:191] op_sel:[0,1] op_sel_hi:[1,1]
	v_pk_mul_f32 v[40:41], v[40:41], v[190:191] op_sel:[0,1] op_sel_hi:[1,1]
	v_pk_mul_f32 v[42:43], v[42:43], v[190:191] op_sel:[0,1] op_sel_hi:[1,1]
	v_pk_mul_f32 v[130:131], v[130:131], v[190:191] op_sel:[0,1] op_sel_hi:[1,1]
	v_pk_mul_f32 v[132:133], v[132:133], v[190:191] op_sel:[0,1] op_sel_hi:[1,1]
	v_pk_mul_f32 v[32:33], v[32:33], v[190:191] op_sel:[0,1] op_sel_hi:[1,1]
	v_pk_mul_f32 v[34:35], v[34:35], v[190:191] op_sel:[0,1] op_sel_hi:[1,1]
	v_pk_mul_f32 v[126:127], v[126:127], v[192:193] op_sel_hi:[1,0]
	v_pk_mul_f32 v[128:129], v[128:129], v[192:193] op_sel_hi:[1,0]
	v_pk_mul_f32 v[28:29], v[28:29], v[192:193] op_sel_hi:[1,0]
	v_pk_mul_f32 v[30:31], v[30:31], v[192:193] op_sel_hi:[1,0]
	v_pk_mul_f32 v[118:119], v[118:119], v[192:193] op_sel_hi:[1,0]
	v_pk_mul_f32 v[120:121], v[120:121], v[192:193] op_sel_hi:[1,0]
	v_pk_mul_f32 v[16:17], v[16:17], v[192:193] op_sel_hi:[1,0]
	v_pk_mul_f32 v[18:19], v[18:19], v[192:193] op_sel_hi:[1,0]
	v_pk_mul_f32 v[122:123], v[122:123], v[192:193] op_sel:[0,1] op_sel_hi:[1,1]
	v_pk_mul_f32 v[124:125], v[124:125], v[192:193] op_sel:[0,1] op_sel_hi:[1,1]
	v_pk_mul_f32 v[24:25], v[24:25], v[192:193] op_sel:[0,1] op_sel_hi:[1,1]
	v_pk_mul_f32 v[26:27], v[26:27], v[192:193] op_sel:[0,1] op_sel_hi:[1,1]
	v_pk_mul_f32 v[110:111], v[110:111], v[192:193] op_sel:[0,1] op_sel_hi:[1,1]
	v_pk_mul_f32 v[112:113], v[112:113], v[192:193] op_sel:[0,1] op_sel_hi:[1,1]
	v_pk_mul_f32 v[12:13], v[12:13], v[192:193] op_sel:[0,1] op_sel_hi:[1,1]
	v_pk_mul_f32 v[14:15], v[14:15], v[192:193] op_sel:[0,1] op_sel_hi:[1,1]
	v_pk_mul_f32 v[114:115], v[114:115], v[194:195] op_sel_hi:[1,0]
	v_pk_mul_f32 v[116:117], v[116:117], v[194:195] op_sel_hi:[1,0]
	v_pk_mul_f32 v[20:21], v[20:21], v[194:195] op_sel_hi:[1,0]
	v_pk_mul_f32 v[22:23], v[22:23], v[194:195] op_sel_hi:[1,0]
	v_pk_mul_f32 v[68:69], v[68:69], v[194:195] op_sel_hi:[1,0]
	v_pk_mul_f32 v[70:71], v[70:71], v[194:195] op_sel_hi:[1,0]
	v_pk_mul_f32 v[8:9], v[8:9], v[194:195] op_sel_hi:[1,0]
	v_pk_mul_f32 v[10:11], v[10:11], v[194:195] op_sel_hi:[1,0]
	v_pk_mul_f32 v[72:73], v[72:73], v[194:195] op_sel:[0,1] op_sel_hi:[1,1]
	v_pk_mul_f32 v[74:75], v[74:75], v[194:195] op_sel:[0,1] op_sel_hi:[1,1]
	v_pk_mul_f32 v[4:5], v[4:5], v[194:195] op_sel:[0,1] op_sel_hi:[1,1]
	v_pk_mul_f32 v[6:7], v[6:7], v[194:195] op_sel:[0,1] op_sel_hi:[1,1]
	v_pk_mul_f32 v[64:65], v[64:65], v[194:195] op_sel:[0,1] op_sel_hi:[1,1]
	v_pk_mul_f32 v[66:67], v[66:67], v[194:195] op_sel:[0,1] op_sel_hi:[1,1]
	v_pk_mul_f32 v[0:1], v[0:1], v[194:195] op_sel:[0,1] op_sel_hi:[1,1]
	v_pk_mul_f32 v[2:3], v[2:3], v[194:195] op_sel:[0,1] op_sel_hi:[1,1]
	s_nop 1
	s_mov_b64 exec, s[8:9]
	v_add_u32_e32 v213, 0x5800, v217
	global_store_dwordx4 v217, v[158:161], s[70:71]
	global_store_dwordx4 v213, v[154:157], s[70:71]
	global_store_dwordx4 v217, v[60:63], s[70:71] offset:16
	global_store_dwordx4 v213, v[56:59], s[70:71] offset:16
	s_mov_b64 exec, s[10:11]
	v_add_u32_e32 v213, 0xfff7c000, v217
	global_store_dwordx4 v213, v[72:75], s[70:71]
	global_store_dwordx4 v213, v[4:7], s[70:71] offset:16
	v_add_u32_e32 v213, 0xfff81800, v217
	global_store_dwordx4 v213, v[64:67], s[70:71]
	global_store_dwordx4 v213, v[0:3], s[70:71] offset:16
	s_mov_b64 exec, -1
	v_add_u32_e32 v213, 0x1b800, v212
	global_load_dwordx4 v[204:207], v213, s[82:83] offset:16
	v_add_u32_e32 v213, 0x5800, v212
	global_load_dwordx4 v[208:211], v213, s[84:85] offset:16
	s_waitcnt vmcnt(10)
	v_pk_fma_f32 v[188:189], v[158:159], v[84:85], v[88:89]
	v_pk_fma_f32 v[190:191], v[160:161], v[86:87], v[90:91]
	v_pk_fma_f32 v[192:193], v[154:155], v[100:101], v[104:105]
	v_pk_fma_f32 v[194:195], v[156:157], v[102:103], v[106:107]
	v_fmac_f32_dpp v188, v158, v80 row_shr:1 row_mask:0xf bank_mask:0xf
	v_fmac_f32_dpp v189, v159, v81 row_shr:1 row_mask:0xf bank_mask:0xf
	v_fmac_f32_dpp v190, v160, v82 row_shr:1 row_mask:0xf bank_mask:0xf
	v_fmac_f32_dpp v191, v161, v83 row_shr:1 row_mask:0xf bank_mask:0xf
	v_fmac_f32_dpp v192, v154, v96 row_shr:1 row_mask:0xf bank_mask:0xf
	v_fmac_f32_dpp v193, v155, v97 row_shr:1 row_mask:0xf bank_mask:0xf
	v_fmac_f32_dpp v194, v156, v98 row_shr:1 row_mask:0xf bank_mask:0xf
	v_fmac_f32_dpp v195, v157, v99 row_shr:1 row_mask:0xf bank_mask:0xf
	v_fmac_f32_dpp v188, v158, v76 row_shr:2 row_mask:0xf bank_mask:0xf
	v_fmac_f32_dpp v189, v159, v77 row_shr:2 row_mask:0xf bank_mask:0xf
	v_fmac_f32_dpp v190, v160, v78 row_shr:2 row_mask:0xf bank_mask:0xf
	v_fmac_f32_dpp v191, v161, v79 row_shr:2 row_mask:0xf bank_mask:0xf
	v_fmac_f32_dpp v192, v154, v92 row_shr:2 row_mask:0xf bank_mask:0xf
	v_fmac_f32_dpp v193, v155, v93 row_shr:2 row_mask:0xf bank_mask:0xf
	v_fmac_f32_dpp v194, v156, v94 row_shr:2 row_mask:0xf bank_mask:0xf
	v_fmac_f32_dpp v195, v157, v95 row_shr:2 row_mask:0xf bank_mask:0xf
	v_pk_mul_f32 v[196:197], v[188:189], v[216:217] op_sel_hi:[1,0]
	v_pk_mul_f32 v[198:199], v[190:191], v[216:217] op_sel_hi:[1,0]
	v_exp_f32_e32 v196, v196
	v_exp_f32_e32 v197, v197
	v_exp_f32_e32 v198, v198
	v_exp_f32_e32 v199, v199
	v_pk_add_f32 v[196:197], v[196:197], v[214:215] op_sel_hi:[1,0]
	v_pk_add_f32 v[198:199], v[198:199], v[214:215] op_sel_hi:[1,0]
	v_rcp_f32_e32 v196, v196
	v_rcp_f32_e32 v197, v197
	v_rcp_f32_e32 v198, v198
	v_rcp_f32_e32 v199, v199
	v_pk_mul_f32 v[188:189], v[188:189], v[196:197]
	v_pk_mul_f32 v[190:191], v[190:191], v[198:199]
	v_pk_mul_f32 v[188:189], v[188:189], v[192:193]
	v_pk_mul_f32 v[190:191], v[190:191], v[194:195]
	v_cvt_pk_bf16_f32 v200, v188, v189
	v_cvt_pk_bf16_f32 v201, v190, v191
	v_pk_fma_f32 v[188:189], v[150:151], v[84:85], v[88:89]
	v_pk_fma_f32 v[190:191], v[152:153], v[86:87], v[90:91]
	v_pk_fma_f32 v[192:193], v[142:143], v[100:101], v[104:105]
	v_pk_fma_f32 v[194:195], v[144:145], v[102:103], v[106:107]
	v_fmac_f32_dpp v188, v150, v80 row_shr:1 row_mask:0xf bank_mask:0xf
	v_fmac_f32_dpp v189, v151, v81 row_shr:1 row_mask:0xf bank_mask:0xf
	v_fmac_f32_dpp v190, v152, v82 row_shr:1 row_mask:0xf bank_mask:0xf
	v_fmac_f32_dpp v191, v153, v83 row_shr:1 row_mask:0xf bank_mask:0xf
	v_fmac_f32_dpp v192, v142, v96 row_shr:1 row_mask:0xf bank_mask:0xf
	v_fmac_f32_dpp v193, v143, v97 row_shr:1 row_mask:0xf bank_mask:0xf
	v_fmac_f32_dpp v194, v144, v98 row_shr:1 row_mask:0xf bank_mask:0xf
	v_fmac_f32_dpp v195, v145, v99 row_shr:1 row_mask:0xf bank_mask:0xf
	v_fmac_f32_dpp v188, v150, v76 row_shr:2 row_mask:0xf bank_mask:0xf
	v_fmac_f32_dpp v189, v151, v77 row_shr:2 row_mask:0xf bank_mask:0xf
	v_fmac_f32_dpp v190, v152, v78 row_shr:2 row_mask:0xf bank_mask:0xf
	v_fmac_f32_dpp v191, v153, v79 row_shr:2 row_mask:0xf bank_mask:0xf
	v_fmac_f32_dpp v192, v142, v92 row_shr:2 row_mask:0xf bank_mask:0xf
	v_fmac_f32_dpp v193, v143, v93 row_shr:2 row_mask:0xf bank_mask:0xf
	v_fmac_f32_dpp v194, v144, v94 row_shr:2 row_mask:0xf bank_mask:0xf
	v_fmac_f32_dpp v195, v145, v95 row_shr:2 row_mask:0xf bank_mask:0xf
	v_fmac_f32_dpp v188, v158, v80 row_shl:15 row_mask:0xf bank_mask:0xf
	v_fmac_f32_dpp v189, v159, v81 row_shl:15 row_mask:0xf bank_mask:0xf
	v_fmac_f32_dpp v190, v160, v82 row_shl:15 row_mask:0xf bank_mask:0xf
	v_fmac_f32_dpp v191, v161, v83 row_shl:15 row_mask:0xf bank_mask:0xf
	v_fmac_f32_dpp v192, v154, v96 row_shl:15 row_mask:0xf bank_mask:0xf
	v_fmac_f32_dpp v193, v155, v97 row_shl:15 row_mask:0xf bank_mask:0xf
	v_fmac_f32_dpp v194, v156, v98 row_shl:15 row_mask:0xf bank_mask:0xf
	v_fmac_f32_dpp v195, v157, v99 row_shl:15 row_mask:0xf bank_mask:0xf
	v_fmac_f32_dpp v188, v158, v76 row_shl:14 row_mask:0xf bank_mask:0xf
	v_fmac_f32_dpp v189, v159, v77 row_shl:14 row_mask:0xf bank_mask:0xf
	v_fmac_f32_dpp v190, v160, v78 row_shl:14 row_mask:0xf bank_mask:0xf
	v_fmac_f32_dpp v191, v161, v79 row_shl:14 row_mask:0xf bank_mask:0xf
	v_fmac_f32_dpp v192, v154, v92 row_shl:14 row_mask:0xf bank_mask:0xf
	v_fmac_f32_dpp v193, v155, v93 row_shl:14 row_mask:0xf bank_mask:0xf
	v_fmac_f32_dpp v194, v156, v94 row_shl:14 row_mask:0xf bank_mask:0xf
	v_fmac_f32_dpp v195, v157, v95 row_shl:14 row_mask:0xf bank_mask:0xf
	v_pk_mul_f32 v[196:197], v[188:189], v[216:217] op_sel_hi:[1,0]
	v_pk_mul_f32 v[198:199], v[190:191], v[216:217] op_sel_hi:[1,0]
	v_exp_f32_e32 v196, v196
	v_exp_f32_e32 v197, v197
	v_exp_f32_e32 v198, v198
	v_exp_f32_e32 v199, v199
	v_pk_add_f32 v[196:197], v[196:197], v[214:215] op_sel_hi:[1,0]
	v_pk_add_f32 v[198:199], v[198:199], v[214:215] op_sel_hi:[1,0]
	v_rcp_f32_e32 v196, v196
	v_rcp_f32_e32 v197, v197
	v_rcp_f32_e32 v198, v198
	v_rcp_f32_e32 v199, v199
	v_pk_mul_f32 v[188:189], v[188:189], v[196:197]
	v_pk_mul_f32 v[190:191], v[190:191], v[198:199]
	v_pk_mul_f32 v[188:189], v[188:189], v[192:193]
	v_pk_mul_f32 v[190:191], v[190:191], v[194:195]
	v_cvt_pk_bf16_f32 v158, v188, v189
	v_cvt_pk_bf16_f32 v159, v190, v191
	global_load_dwordx4 v[154:157], v212, s[82:83] offset:16
	v_pk_fma_f32 v[188:189], v[146:147], v[84:85], v[88:89]
	v_pk_fma_f32 v[190:191], v[148:149], v[86:87], v[90:91]
	v_pk_fma_f32 v[192:193], v[134:135], v[100:101], v[104:105]
	v_pk_fma_f32 v[194:195], v[136:137], v[102:103], v[106:107]
	v_fmac_f32_dpp v188, v146, v80 row_shr:1 row_mask:0xf bank_mask:0xf
	v_fmac_f32_dpp v189, v147, v81 row_shr:1 row_mask:0xf bank_mask:0xf
	v_fmac_f32_dpp v190, v148, v82 row_shr:1 row_mask:0xf bank_mask:0xf
	v_fmac_f32_dpp v191, v149, v83 row_shr:1 row_mask:0xf bank_mask:0xf
	v_fmac_f32_dpp v192, v134, v96 row_shr:1 row_mask:0xf bank_mask:0xf
	v_fmac_f32_dpp v193, v135, v97 row_shr:1 row_mask:0xf bank_mask:0xf
	v_fmac_f32_dpp v194, v136, v98 row_shr:1 row_mask:0xf bank_mask:0xf
	v_fmac_f32_dpp v195, v137, v99 row_shr:1 row_mask:0xf bank_mask:0xf
	v_fmac_f32_dpp v188, v146, v76 row_shr:2 row_mask:0xf bank_mask:0xf
	v_fmac_f32_dpp v189, v147, v77 row_shr:2 row_mask:0xf bank_mask:0xf
	v_fmac_f32_dpp v190, v148, v78 row_shr:2 row_mask:0xf bank_mask:0xf
	v_fmac_f32_dpp v191, v149, v79 row_shr:2 row_mask:0xf bank_mask:0xf
	v_fmac_f32_dpp v192, v134, v92 row_shr:2 row_mask:0xf bank_mask:0xf
	v_fmac_f32_dpp v193, v135, v93 row_shr:2 row_mask:0xf bank_mask:0xf
	v_fmac_f32_dpp v194, v136, v94 row_shr:2 row_mask:0xf bank_mask:0xf
	v_fmac_f32_dpp v195, v137, v95 row_shr:2 row_mask:0xf bank_mask:0xf
	v_fmac_f32_dpp v188, v150, v80 row_shl:15 row_mask:0xf bank_mask:0xf
	v_fmac_f32_dpp v189, v151, v81 row_shl:15 row_mask:0xf bank_mask:0xf
	v_fmac_f32_dpp v190, v152, v82 row_shl:15 row_mask:0xf bank_mask:0xf
	v_fmac_f32_dpp v191, v153, v83 row_shl:15 row_mask:0xf bank_mask:0xf
	v_fmac_f32_dpp v192, v142, v96 row_shl:15 row_mask:0xf bank_mask:0xf
	v_fmac_f32_dpp v193, v143, v97 row_shl:15 row_mask:0xf bank_mask:0xf
	v_fmac_f32_dpp v194, v144, v98 row_shl:15 row_mask:0xf bank_mask:0xf
	v_fmac_f32_dpp v195, v145, v99 row_shl:15 row_mask:0xf bank_mask:0xf
	v_fmac_f32_dpp v188, v150, v76 row_shl:14 row_mask:0xf bank_mask:0xf
	v_fmac_f32_dpp v189, v151, v77 row_shl:14 row_mask:0xf bank_mask:0xf
	v_fmac_f32_dpp v190, v152, v78 row_shl:14 row_mask:0xf bank_mask:0xf
	v_fmac_f32_dpp v191, v153, v79 row_shl:14 row_mask:0xf bank_mask:0xf
	v_fmac_f32_dpp v192, v142, v92 row_shl:14 row_mask:0xf bank_mask:0xf
	v_fmac_f32_dpp v193, v143, v93 row_shl:14 row_mask:0xf bank_mask:0xf
	v_fmac_f32_dpp v194, v144, v94 row_shl:14 row_mask:0xf bank_mask:0xf
	v_fmac_f32_dpp v195, v145, v95 row_shl:14 row_mask:0xf bank_mask:0xf
	v_pk_mul_f32 v[196:197], v[188:189], v[216:217] op_sel_hi:[1,0]
	v_pk_mul_f32 v[198:199], v[190:191], v[216:217] op_sel_hi:[1,0]
	v_exp_f32_e32 v196, v196
	v_exp_f32_e32 v197, v197
	v_exp_f32_e32 v198, v198
	v_exp_f32_e32 v199, v199
	v_pk_add_f32 v[196:197], v[196:197], v[214:215] op_sel_hi:[1,0]
	v_pk_add_f32 v[198:199], v[198:199], v[214:215] op_sel_hi:[1,0]
	v_rcp_f32_e32 v196, v196
	v_rcp_f32_e32 v197, v197
	v_rcp_f32_e32 v198, v198
	v_rcp_f32_e32 v199, v199
	v_pk_mul_f32 v[188:189], v[188:189], v[196:197]
	v_pk_mul_f32 v[190:191], v[190:191], v[198:199]
	v_pk_mul_f32 v[188:189], v[188:189], v[192:193]
	v_pk_mul_f32 v[190:191], v[190:191], v[194:195]
	v_cvt_pk_bf16_f32 v150, v188, v189
	v_cvt_pk_bf16_f32 v151, v190, v191
	v_add_u32_e32 v213, 0xb000, v212
	global_load_dwordx4 v[142:145], v213, s[82:83] offset:16
	v_pk_fma_f32 v[188:189], v[138:139], v[84:85], v[88:89]
	v_pk_fma_f32 v[190:191], v[140:141], v[86:87], v[90:91]
	v_pk_fma_f32 v[192:193], v[130:131], v[100:101], v[104:105]
	v_pk_fma_f32 v[194:195], v[132:133], v[102:103], v[106:107]
	v_fmac_f32_dpp v188, v138, v80 row_shr:1 row_mask:0xf bank_mask:0xf
	v_fmac_f32_dpp v189, v139, v81 row_shr:1 row_mask:0xf bank_mask:0xf
	v_fmac_f32_dpp v190, v140, v82 row_shr:1 row_mask:0xf bank_mask:0xf
	v_fmac_f32_dpp v191, v141, v83 row_shr:1 row_mask:0xf bank_mask:0xf
	v_fmac_f32_dpp v192, v130, v96 row_shr:1 row_mask:0xf bank_mask:0xf
	v_fmac_f32_dpp v193, v131, v97 row_shr:1 row_mask:0xf bank_mask:0xf
	v_fmac_f32_dpp v194, v132, v98 row_shr:1 row_mask:0xf bank_mask:0xf
	v_fmac_f32_dpp v195, v133, v99 row_shr:1 row_mask:0xf bank_mask:0xf
	v_fmac_f32_dpp v188, v138, v76 row_shr:2 row_mask:0xf bank_mask:0xf
	v_fmac_f32_dpp v189, v139, v77 row_shr:2 row_mask:0xf bank_mask:0xf
	v_fmac_f32_dpp v190, v140, v78 row_shr:2 row_mask:0xf bank_mask:0xf
	v_fmac_f32_dpp v191, v141, v79 row_shr:2 row_mask:0xf bank_mask:0xf
	v_fmac_f32_dpp v192, v130, v92 row_shr:2 row_mask:0xf bank_mask:0xf
	v_fmac_f32_dpp v193, v131, v93 row_shr:2 row_mask:0xf bank_mask:0xf
	v_fmac_f32_dpp v194, v132, v94 row_shr:2 row_mask:0xf bank_mask:0xf
	v_fmac_f32_dpp v195, v133, v95 row_shr:2 row_mask:0xf bank_mask:0xf
	v_fmac_f32_dpp v188, v146, v80 row_shl:15 row_mask:0xf bank_mask:0xf
	v_fmac_f32_dpp v189, v147, v81 row_shl:15 row_mask:0xf bank_mask:0xf
	v_fmac_f32_dpp v190, v148, v82 row_shl:15 row_mask:0xf bank_mask:0xf
	v_fmac_f32_dpp v191, v149, v83 row_shl:15 row_mask:0xf bank_mask:0xf
	v_fmac_f32_dpp v192, v134, v96 row_shl:15 row_mask:0xf bank_mask:0xf
	v_fmac_f32_dpp v193, v135, v97 row_shl:15 row_mask:0xf bank_mask:0xf
	v_fmac_f32_dpp v194, v136, v98 row_shl:15 row_mask:0xf bank_mask:0xf
	v_fmac_f32_dpp v195, v137, v99 row_shl:15 row_mask:0xf bank_mask:0xf
	v_fmac_f32_dpp v188, v146, v76 row_shl:14 row_mask:0xf bank_mask:0xf
	v_fmac_f32_dpp v189, v147, v77 row_shl:14 row_mask:0xf bank_mask:0xf
	v_fmac_f32_dpp v190, v148, v78 row_shl:14 row_mask:0xf bank_mask:0xf
	v_fmac_f32_dpp v191, v149, v79 row_shl:14 row_mask:0xf bank_mask:0xf
	v_fmac_f32_dpp v192, v134, v92 row_shl:14 row_mask:0xf bank_mask:0xf
	v_fmac_f32_dpp v193, v135, v93 row_shl:14 row_mask:0xf bank_mask:0xf
	v_fmac_f32_dpp v194, v136, v94 row_shl:14 row_mask:0xf bank_mask:0xf
	v_fmac_f32_dpp v195, v137, v95 row_shl:14 row_mask:0xf bank_mask:0xf
	v_pk_mul_f32 v[196:197], v[188:189], v[216:217] op_sel_hi:[1,0]
	v_pk_mul_f32 v[198:199], v[190:191], v[216:217] op_sel_hi:[1,0]
	v_exp_f32_e32 v196, v196
	v_exp_f32_e32 v197, v197
	v_exp_f32_e32 v198, v198
	v_exp_f32_e32 v199, v199
	v_pk_add_f32 v[196:197], v[196:197], v[214:215] op_sel_hi:[1,0]
	v_pk_add_f32 v[198:199], v[198:199], v[214:215] op_sel_hi:[1,0]
	v_rcp_f32_e32 v196, v196
	v_rcp_f32_e32 v197, v197
	v_rcp_f32_e32 v198, v198
	v_rcp_f32_e32 v199, v199
	v_pk_mul_f32 v[188:189], v[188:189], v[196:197]
	v_pk_mul_f32 v[190:191], v[190:191], v[198:199]
	v_pk_mul_f32 v[188:189], v[188:189], v[192:193]
	v_pk_mul_f32 v[190:191], v[190:191], v[194:195]
	v_cvt_pk_bf16_f32 v146, v188, v189
	v_cvt_pk_bf16_f32 v147, v190, v191
	v_add_u32_e32 v213, 0x16000, v212
	global_load_dwordx4 v[134:137], v213, s[82:83] offset:16
	v_pk_fma_f32 v[188:189], v[126:127], v[84:85], v[88:89]
	v_pk_fma_f32 v[190:191], v[128:129], v[86:87], v[90:91]
	v_pk_fma_f32 v[192:193], v[118:119], v[100:101], v[104:105]
	v_pk_fma_f32 v[194:195], v[120:121], v[102:103], v[106:107]
	v_fmac_f32_dpp v188, v126, v80 row_shr:1 row_mask:0xf bank_mask:0xf
	v_fmac_f32_dpp v189, v127, v81 row_shr:1 row_mask:0xf bank_mask:0xf
	v_fmac_f32_dpp v190, v128, v82 row_shr:1 row_mask:0xf bank_mask:0xf
	v_fmac_f32_dpp v191, v129, v83 row_shr:1 row_mask:0xf bank_mask:0xf
	v_fmac_f32_dpp v192, v118, v96 row_shr:1 row_mask:0xf bank_mask:0xf
	v_fmac_f32_dpp v193, v119, v97 row_shr:1 row_mask:0xf bank_mask:0xf
	v_fmac_f32_dpp v194, v120, v98 row_shr:1 row_mask:0xf bank_mask:0xf
	v_fmac_f32_dpp v195, v121, v99 row_shr:1 row_mask:0xf bank_mask:0xf
	v_fmac_f32_dpp v188, v126, v76 row_shr:2 row_mask:0xf bank_mask:0xf
	v_fmac_f32_dpp v189, v127, v77 row_shr:2 row_mask:0xf bank_mask:0xf
	v_fmac_f32_dpp v190, v128, v78 row_shr:2 row_mask:0xf bank_mask:0xf
	v_fmac_f32_dpp v191, v129, v79 row_shr:2 row_mask:0xf bank_mask:0xf
	v_fmac_f32_dpp v192, v118, v92 row_shr:2 row_mask:0xf bank_mask:0xf
	v_fmac_f32_dpp v193, v119, v93 row_shr:2 row_mask:0xf bank_mask:0xf
	v_fmac_f32_dpp v194, v120, v94 row_shr:2 row_mask:0xf bank_mask:0xf
	v_fmac_f32_dpp v195, v121, v95 row_shr:2 row_mask:0xf bank_mask:0xf
	v_fmac_f32_dpp v188, v138, v80 row_shl:15 row_mask:0xf bank_mask:0xf
	v_fmac_f32_dpp v189, v139, v81 row_shl:15 row_mask:0xf bank_mask:0xf
	v_fmac_f32_dpp v190, v140, v82 row_shl:15 row_mask:0xf bank_mask:0xf
	v_fmac_f32_dpp v191, v141, v83 row_shl:15 row_mask:0xf bank_mask:0xf
	v_fmac_f32_dpp v192, v130, v96 row_shl:15 row_mask:0xf bank_mask:0xf
	v_fmac_f32_dpp v193, v131, v97 row_shl:15 row_mask:0xf bank_mask:0xf
	v_fmac_f32_dpp v194, v132, v98 row_shl:15 row_mask:0xf bank_mask:0xf
	v_fmac_f32_dpp v195, v133, v99 row_shl:15 row_mask:0xf bank_mask:0xf
	v_fmac_f32_dpp v188, v138, v76 row_shl:14 row_mask:0xf bank_mask:0xf
	v_fmac_f32_dpp v189, v139, v77 row_shl:14 row_mask:0xf bank_mask:0xf
	v_fmac_f32_dpp v190, v140, v78 row_shl:14 row_mask:0xf bank_mask:0xf
	v_fmac_f32_dpp v191, v141, v79 row_shl:14 row_mask:0xf bank_mask:0xf
	v_fmac_f32_dpp v192, v130, v92 row_shl:14 row_mask:0xf bank_mask:0xf
	v_fmac_f32_dpp v193, v131, v93 row_shl:14 row_mask:0xf bank_mask:0xf
	v_fmac_f32_dpp v194, v132, v94 row_shl:14 row_mask:0xf bank_mask:0xf
	v_fmac_f32_dpp v195, v133, v95 row_shl:14 row_mask:0xf bank_mask:0xf
	v_pk_mul_f32 v[196:197], v[188:189], v[216:217] op_sel_hi:[1,0]
	v_pk_mul_f32 v[198:199], v[190:191], v[216:217] op_sel_hi:[1,0]
	v_exp_f32_e32 v196, v196
	v_exp_f32_e32 v197, v197
	v_exp_f32_e32 v198, v198
	v_exp_f32_e32 v199, v199
	v_pk_add_f32 v[196:197], v[196:197], v[214:215] op_sel_hi:[1,0]
	v_pk_add_f32 v[198:199], v[198:199], v[214:215] op_sel_hi:[1,0]
	v_rcp_f32_e32 v196, v196
	v_rcp_f32_e32 v197, v197
	v_rcp_f32_e32 v198, v198
	v_rcp_f32_e32 v199, v199
	v_pk_mul_f32 v[188:189], v[188:189], v[196:197]
	v_pk_mul_f32 v[190:191], v[190:191], v[198:199]
	v_pk_mul_f32 v[188:189], v[188:189], v[192:193]
	v_pk_mul_f32 v[190:191], v[190:191], v[194:195]
	v_cvt_pk_bf16_f32 v138, v188, v189
	v_cvt_pk_bf16_f32 v139, v190, v191
	global_load_dwordx4 v[130:133], v212, s[84:85] offset:16
	v_pk_fma_f32 v[188:189], v[122:123], v[84:85], v[88:89]
	v_pk_fma_f32 v[190:191], v[124:125], v[86:87], v[90:91]
	v_pk_fma_f32 v[192:193], v[110:111], v[100:101], v[104:105]
	v_pk_fma_f32 v[194:195], v[112:113], v[102:103], v[106:107]
	v_fmac_f32_dpp v188, v122, v80 row_shr:1 row_mask:0xf bank_mask:0xf
	v_fmac_f32_dpp v189, v123, v81 row_shr:1 row_mask:0xf bank_mask:0xf
	v_fmac_f32_dpp v190, v124, v82 row_shr:1 row_mask:0xf bank_mask:0xf
	v_fmac_f32_dpp v191, v125, v83 row_shr:1 row_mask:0xf bank_mask:0xf
	v_fmac_f32_dpp v192, v110, v96 row_shr:1 row_mask:0xf bank_mask:0xf
	v_fmac_f32_dpp v193, v111, v97 row_shr:1 row_mask:0xf bank_mask:0xf
	v_fmac_f32_dpp v194, v112, v98 row_shr:1 row_mask:0xf bank_mask:0xf
	v_fmac_f32_dpp v195, v113, v99 row_shr:1 row_mask:0xf bank_mask:0xf
	v_fmac_f32_dpp v188, v122, v76 row_shr:2 row_mask:0xf bank_mask:0xf
	v_fmac_f32_dpp v189, v123, v77 row_shr:2 row_mask:0xf bank_mask:0xf
	v_fmac_f32_dpp v190, v124, v78 row_shr:2 row_mask:0xf bank_mask:0xf
	v_fmac_f32_dpp v191, v125, v79 row_shr:2 row_mask:0xf bank_mask:0xf
	v_fmac_f32_dpp v192, v110, v92 row_shr:2 row_mask:0xf bank_mask:0xf
	v_fmac_f32_dpp v193, v111, v93 row_shr:2 row_mask:0xf bank_mask:0xf
	v_fmac_f32_dpp v194, v112, v94 row_shr:2 row_mask:0xf bank_mask:0xf
	v_fmac_f32_dpp v195, v113, v95 row_shr:2 row_mask:0xf bank_mask:0xf
	v_fmac_f32_dpp v188, v126, v80 row_shl:15 row_mask:0xf bank_mask:0xf
	v_fmac_f32_dpp v189, v127, v81 row_shl:15 row_mask:0xf bank_mask:0xf
	v_fmac_f32_dpp v190, v128, v82 row_shl:15 row_mask:0xf bank_mask:0xf
	v_fmac_f32_dpp v191, v129, v83 row_shl:15 row_mask:0xf bank_mask:0xf
	v_fmac_f32_dpp v192, v118, v96 row_shl:15 row_mask:0xf bank_mask:0xf
	v_fmac_f32_dpp v193, v119, v97 row_shl:15 row_mask:0xf bank_mask:0xf
	v_fmac_f32_dpp v194, v120, v98 row_shl:15 row_mask:0xf bank_mask:0xf
	v_fmac_f32_dpp v195, v121, v99 row_shl:15 row_mask:0xf bank_mask:0xf
	v_fmac_f32_dpp v188, v126, v76 row_shl:14 row_mask:0xf bank_mask:0xf
	v_fmac_f32_dpp v189, v127, v77 row_shl:14 row_mask:0xf bank_mask:0xf
	v_fmac_f32_dpp v190, v128, v78 row_shl:14 row_mask:0xf bank_mask:0xf
	v_fmac_f32_dpp v191, v129, v79 row_shl:14 row_mask:0xf bank_mask:0xf
	v_fmac_f32_dpp v192, v118, v92 row_shl:14 row_mask:0xf bank_mask:0xf
	v_fmac_f32_dpp v193, v119, v93 row_shl:14 row_mask:0xf bank_mask:0xf
	v_fmac_f32_dpp v194, v120, v94 row_shl:14 row_mask:0xf bank_mask:0xf
	v_fmac_f32_dpp v195, v121, v95 row_shl:14 row_mask:0xf bank_mask:0xf
	v_pk_mul_f32 v[196:197], v[188:189], v[216:217] op_sel_hi:[1,0]
	v_pk_mul_f32 v[198:199], v[190:191], v[216:217] op_sel_hi:[1,0]
	v_exp_f32_e32 v196, v196
	v_exp_f32_e32 v197, v197
	v_exp_f32_e32 v198, v198
	v_exp_f32_e32 v199, v199
	v_pk_add_f32 v[196:197], v[196:197], v[214:215] op_sel_hi:[1,0]
	v_pk_add_f32 v[198:199], v[198:199], v[214:215] op_sel_hi:[1,0]
	v_rcp_f32_e32 v196, v196
	v_rcp_f32_e32 v197, v197
	v_rcp_f32_e32 v198, v198
	v_rcp_f32_e32 v199, v199
	v_pk_mul_f32 v[188:189], v[188:189], v[196:197]
	v_pk_mul_f32 v[190:191], v[190:191], v[198:199]
	v_pk_mul_f32 v[188:189], v[188:189], v[192:193]
	v_pk_mul_f32 v[190:191], v[190:191], v[194:195]
	v_cvt_pk_bf16_f32 v126, v188, v189
	v_cvt_pk_bf16_f32 v127, v190, v191
	v_add_u32_e32 v213, 0x5800, v212
	global_load_dwordx4 v[118:121], v213, s[82:83] offset:16
	v_pk_fma_f32 v[188:189], v[114:115], v[84:85], v[88:89]
	v_pk_fma_f32 v[190:191], v[116:117], v[86:87], v[90:91]
	v_pk_fma_f32 v[192:193], v[68:69], v[100:101], v[104:105]
	v_pk_fma_f32 v[194:195], v[70:71], v[102:103], v[106:107]
	v_fmac_f32_dpp v188, v114, v80 row_shr:1 row_mask:0xf bank_mask:0xf
	v_fmac_f32_dpp v189, v115, v81 row_shr:1 row_mask:0xf bank_mask:0xf
	v_fmac_f32_dpp v190, v116, v82 row_shr:1 row_mask:0xf bank_mask:0xf
	v_fmac_f32_dpp v191, v117, v83 row_shr:1 row_mask:0xf bank_mask:0xf
	v_fmac_f32_dpp v192, v68, v96 row_shr:1 row_mask:0xf bank_mask:0xf
	v_fmac_f32_dpp v193, v69, v97 row_shr:1 row_mask:0xf bank_mask:0xf
	v_fmac_f32_dpp v194, v70, v98 row_shr:1 row_mask:0xf bank_mask:0xf
	v_fmac_f32_dpp v195, v71, v99 row_shr:1 row_mask:0xf bank_mask:0xf
	v_fmac_f32_dpp v188, v114, v76 row_shr:2 row_mask:0xf bank_mask:0xf
	v_fmac_f32_dpp v189, v115, v77 row_shr:2 row_mask:0xf bank_mask:0xf
	v_fmac_f32_dpp v190, v116, v78 row_shr:2 row_mask:0xf bank_mask:0xf
	v_fmac_f32_dpp v191, v117, v79 row_shr:2 row_mask:0xf bank_mask:0xf
	v_fmac_f32_dpp v192, v68, v92 row_shr:2 row_mask:0xf bank_mask:0xf
	v_fmac_f32_dpp v193, v69, v93 row_shr:2 row_mask:0xf bank_mask:0xf
	v_fmac_f32_dpp v194, v70, v94 row_shr:2 row_mask:0xf bank_mask:0xf
	v_fmac_f32_dpp v195, v71, v95 row_shr:2 row_mask:0xf bank_mask:0xf
	v_fmac_f32_dpp v188, v122, v80 row_shl:15 row_mask:0xf bank_mask:0xf
	v_fmac_f32_dpp v189, v123, v81 row_shl:15 row_mask:0xf bank_mask:0xf
	v_fmac_f32_dpp v190, v124, v82 row_shl:15 row_mask:0xf bank_mask:0xf
	v_fmac_f32_dpp v191, v125, v83 row_shl:15 row_mask:0xf bank_mask:0xf
	v_fmac_f32_dpp v192, v110, v96 row_shl:15 row_mask:0xf bank_mask:0xf
	v_fmac_f32_dpp v193, v111, v97 row_shl:15 row_mask:0xf bank_mask:0xf
	v_fmac_f32_dpp v194, v112, v98 row_shl:15 row_mask:0xf bank_mask:0xf
	v_fmac_f32_dpp v195, v113, v99 row_shl:15 row_mask:0xf bank_mask:0xf
	v_fmac_f32_dpp v188, v122, v76 row_shl:14 row_mask:0xf bank_mask:0xf
	v_fmac_f32_dpp v189, v123, v77 row_shl:14 row_mask:0xf bank_mask:0xf
	v_fmac_f32_dpp v190, v124, v78 row_shl:14 row_mask:0xf bank_mask:0xf
	v_fmac_f32_dpp v191, v125, v79 row_shl:14 row_mask:0xf bank_mask:0xf
	v_fmac_f32_dpp v192, v110, v92 row_shl:14 row_mask:0xf bank_mask:0xf
	v_fmac_f32_dpp v193, v111, v93 row_shl:14 row_mask:0xf bank_mask:0xf
	v_fmac_f32_dpp v194, v112, v94 row_shl:14 row_mask:0xf bank_mask:0xf
	v_fmac_f32_dpp v195, v113, v95 row_shl:14 row_mask:0xf bank_mask:0xf
	v_pk_mul_f32 v[196:197], v[188:189], v[216:217] op_sel_hi:[1,0]
	v_pk_mul_f32 v[198:199], v[190:191], v[216:217] op_sel_hi:[1,0]
	v_exp_f32_e32 v196, v196
	v_exp_f32_e32 v197, v197
	v_exp_f32_e32 v198, v198
	v_exp_f32_e32 v199, v199
	v_pk_add_f32 v[196:197], v[196:197], v[214:215] op_sel_hi:[1,0]
	v_pk_add_f32 v[198:199], v[198:199], v[214:215] op_sel_hi:[1,0]
	v_rcp_f32_e32 v196, v196
	v_rcp_f32_e32 v197, v197
	v_rcp_f32_e32 v198, v198
	v_rcp_f32_e32 v199, v199
	v_pk_mul_f32 v[188:189], v[188:189], v[196:197]
	v_pk_mul_f32 v[190:191], v[190:191], v[198:199]
	v_pk_mul_f32 v[188:189], v[188:189], v[192:193]
	v_pk_mul_f32 v[190:191], v[190:191], v[194:195]
	v_cvt_pk_bf16_f32 v122, v188, v189
	v_cvt_pk_bf16_f32 v123, v190, v191
	v_add_u32_e32 v213, 0x10800, v212
	global_load_dwordx4 v[110:113], v213, s[82:83] offset:16
	v_pk_fma_f32 v[188:189], v[72:73], v[84:85], v[88:89]
	v_pk_fma_f32 v[190:191], v[74:75], v[86:87], v[90:91]
	v_pk_fma_f32 v[192:193], v[64:65], v[100:101], v[104:105]
	v_pk_fma_f32 v[194:195], v[66:67], v[102:103], v[106:107]
	v_fmac_f32_dpp v188, v72, v80 row_shr:1 row_mask:0xf bank_mask:0xf
	v_fmac_f32_dpp v189, v73, v81 row_shr:1 row_mask:0xf bank_mask:0xf
	v_fmac_f32_dpp v190, v74, v82 row_shr:1 row_mask:0xf bank_mask:0xf
	v_fmac_f32_dpp v191, v75, v83 row_shr:1 row_mask:0xf bank_mask:0xf
	v_fmac_f32_dpp v192, v64, v96 row_shr:1 row_mask:0xf bank_mask:0xf
	v_fmac_f32_dpp v193, v65, v97 row_shr:1 row_mask:0xf bank_mask:0xf
	v_fmac_f32_dpp v194, v66, v98 row_shr:1 row_mask:0xf bank_mask:0xf
	v_fmac_f32_dpp v195, v67, v99 row_shr:1 row_mask:0xf bank_mask:0xf
	v_fmac_f32_dpp v188, v72, v76 row_shr:2 row_mask:0xf bank_mask:0xf
	v_fmac_f32_dpp v189, v73, v77 row_shr:2 row_mask:0xf bank_mask:0xf
	v_fmac_f32_dpp v190, v74, v78 row_shr:2 row_mask:0xf bank_mask:0xf
	v_fmac_f32_dpp v191, v75, v79 row_shr:2 row_mask:0xf bank_mask:0xf
	v_fmac_f32_dpp v192, v64, v92 row_shr:2 row_mask:0xf bank_mask:0xf
	v_fmac_f32_dpp v193, v65, v93 row_shr:2 row_mask:0xf bank_mask:0xf
	v_fmac_f32_dpp v194, v66, v94 row_shr:2 row_mask:0xf bank_mask:0xf
	v_fmac_f32_dpp v195, v67, v95 row_shr:2 row_mask:0xf bank_mask:0xf
	v_fmac_f32_dpp v188, v114, v80 row_shl:15 row_mask:0xf bank_mask:0xf
	v_fmac_f32_dpp v189, v115, v81 row_shl:15 row_mask:0xf bank_mask:0xf
	v_fmac_f32_dpp v190, v116, v82 row_shl:15 row_mask:0xf bank_mask:0xf
	v_fmac_f32_dpp v191, v117, v83 row_shl:15 row_mask:0xf bank_mask:0xf
	v_fmac_f32_dpp v192, v68, v96 row_shl:15 row_mask:0xf bank_mask:0xf
	v_fmac_f32_dpp v193, v69, v97 row_shl:15 row_mask:0xf bank_mask:0xf
	v_fmac_f32_dpp v194, v70, v98 row_shl:15 row_mask:0xf bank_mask:0xf
	v_fmac_f32_dpp v195, v71, v99 row_shl:15 row_mask:0xf bank_mask:0xf
	v_fmac_f32_dpp v188, v114, v76 row_shl:14 row_mask:0xf bank_mask:0xf
	v_fmac_f32_dpp v189, v115, v77 row_shl:14 row_mask:0xf bank_mask:0xf
	v_fmac_f32_dpp v190, v116, v78 row_shl:14 row_mask:0xf bank_mask:0xf
	v_fmac_f32_dpp v191, v117, v79 row_shl:14 row_mask:0xf bank_mask:0xf
	v_fmac_f32_dpp v192, v68, v92 row_shl:14 row_mask:0xf bank_mask:0xf
	v_fmac_f32_dpp v193, v69, v93 row_shl:14 row_mask:0xf bank_mask:0xf
	v_fmac_f32_dpp v194, v70, v94 row_shl:14 row_mask:0xf bank_mask:0xf
	v_fmac_f32_dpp v195, v71, v95 row_shl:14 row_mask:0xf bank_mask:0xf
	v_pk_mul_f32 v[196:197], v[188:189], v[216:217] op_sel_hi:[1,0]
	v_pk_mul_f32 v[198:199], v[190:191], v[216:217] op_sel_hi:[1,0]
	v_exp_f32_e32 v196, v196
	v_exp_f32_e32 v197, v197
	v_exp_f32_e32 v198, v198
	v_exp_f32_e32 v199, v199
	v_pk_add_f32 v[196:197], v[196:197], v[214:215] op_sel_hi:[1,0]
	v_pk_add_f32 v[198:199], v[198:199], v[214:215] op_sel_hi:[1,0]
	v_rcp_f32_e32 v196, v196
	v_rcp_f32_e32 v197, v197
	v_rcp_f32_e32 v198, v198
	v_rcp_f32_e32 v199, v199
	v_pk_mul_f32 v[188:189], v[188:189], v[196:197]
	v_pk_mul_f32 v[190:191], v[190:191], v[198:199]
	v_pk_mul_f32 v[188:189], v[188:189], v[192:193]
	v_pk_mul_f32 v[190:191], v[190:191], v[194:195]
	v_cvt_pk_bf16_f32 v114, v188, v189
	v_cvt_pk_bf16_f32 v115, v190, v191
	s_waitcnt vmcnt(0)
	v_pk_fma_f32 v[188:189], v[60:61], v[134:135], v[130:131]
	v_pk_fma_f32 v[190:191], v[62:63], v[136:137], v[132:133]
	v_pk_fma_f32 v[192:193], v[56:57], v[204:205], v[208:209]
	v_pk_fma_f32 v[194:195], v[58:59], v[206:207], v[210:211]
	v_fmac_f32_dpp v188, v60, v142 row_shr:1 row_mask:0xf bank_mask:0xf
	v_fmac_f32_dpp v189, v61, v143 row_shr:1 row_mask:0xf bank_mask:0xf
	v_fmac_f32_dpp v190, v62, v144 row_shr:1 row_mask:0xf bank_mask:0xf
	v_fmac_f32_dpp v191, v63, v145 row_shr:1 row_mask:0xf bank_mask:0xf
	v_fmac_f32_dpp v192, v56, v110 row_shr:1 row_mask:0xf bank_mask:0xf
	v_fmac_f32_dpp v193, v57, v111 row_shr:1 row_mask:0xf bank_mask:0xf
	v_fmac_f32_dpp v194, v58, v112 row_shr:1 row_mask:0xf bank_mask:0xf
	v_fmac_f32_dpp v195, v59, v113 row_shr:1 row_mask:0xf bank_mask:0xf
	v_fmac_f32_dpp v188, v60, v154 row_shr:2 row_mask:0xf bank_mask:0xf
	v_fmac_f32_dpp v189, v61, v155 row_shr:2 row_mask:0xf bank_mask:0xf
	v_fmac_f32_dpp v190, v62, v156 row_shr:2 row_mask:0xf bank_mask:0xf
	v_fmac_f32_dpp v191, v63, v157 row_shr:2 row_mask:0xf bank_mask:0xf
	v_fmac_f32_dpp v192, v56, v118 row_shr:2 row_mask:0xf bank_mask:0xf
	v_fmac_f32_dpp v193, v57, v119 row_shr:2 row_mask:0xf bank_mask:0xf
	v_fmac_f32_dpp v194, v58, v120 row_shr:2 row_mask:0xf bank_mask:0xf
	v_fmac_f32_dpp v195, v59, v121 row_shr:2 row_mask:0xf bank_mask:0xf
	v_pk_mul_f32 v[196:197], v[188:189], v[216:217] op_sel_hi:[1,0]
	v_pk_mul_f32 v[198:199], v[190:191], v[216:217] op_sel_hi:[1,0]
	v_exp_f32_e32 v196, v196
	v_exp_f32_e32 v197, v197
	v_exp_f32_e32 v198, v198
	v_exp_f32_e32 v199, v199
	v_pk_add_f32 v[196:197], v[196:197], v[214:215] op_sel_hi:[1,0]
	v_pk_add_f32 v[198:199], v[198:199], v[214:215] op_sel_hi:[1,0]
	v_rcp_f32_e32 v196, v196
	v_rcp_f32_e32 v197, v197
	v_rcp_f32_e32 v198, v198
	v_rcp_f32_e32 v199, v199
	v_pk_mul_f32 v[188:189], v[188:189], v[196:197]
	v_pk_mul_f32 v[190:191], v[190:191], v[198:199]
	v_pk_mul_f32 v[188:189], v[188:189], v[192:193]
	v_pk_mul_f32 v[190:191], v[190:191], v[194:195]
	v_cvt_pk_bf16_f32 v202, v188, v189
	v_cvt_pk_bf16_f32 v203, v190, v191
	s_mov_b64 exec, vcc
	global_store_dwordx4 v215, v[200:203], s[96:97]
	s_mov_b64 exec, -1
	v_pk_fma_f32 v[188:189], v[52:53], v[134:135], v[130:131]
	v_pk_fma_f32 v[190:191], v[54:55], v[136:137], v[132:133]
	v_pk_fma_f32 v[192:193], v[44:45], v[204:205], v[208:209]
	v_pk_fma_f32 v[194:195], v[46:47], v[206:207], v[210:211]
	v_fmac_f32_dpp v188, v52, v142 row_shr:1 row_mask:0xf bank_mask:0xf
	v_fmac_f32_dpp v189, v53, v143 row_shr:1 row_mask:0xf bank_mask:0xf
	v_fmac_f32_dpp v190, v54, v144 row_shr:1 row_mask:0xf bank_mask:0xf
	v_fmac_f32_dpp v191, v55, v145 row_shr:1 row_mask:0xf bank_mask:0xf
	v_fmac_f32_dpp v192, v44, v110 row_shr:1 row_mask:0xf bank_mask:0xf
	v_fmac_f32_dpp v193, v45, v111 row_shr:1 row_mask:0xf bank_mask:0xf
	v_fmac_f32_dpp v194, v46, v112 row_shr:1 row_mask:0xf bank_mask:0xf
	v_fmac_f32_dpp v195, v47, v113 row_shr:1 row_mask:0xf bank_mask:0xf
	v_fmac_f32_dpp v188, v52, v154 row_shr:2 row_mask:0xf bank_mask:0xf
	v_fmac_f32_dpp v189, v53, v155 row_shr:2 row_mask:0xf bank_mask:0xf
	v_fmac_f32_dpp v190, v54, v156 row_shr:2 row_mask:0xf bank_mask:0xf
	v_fmac_f32_dpp v191, v55, v157 row_shr:2 row_mask:0xf bank_mask:0xf
	v_fmac_f32_dpp v192, v44, v118 row_shr:2 row_mask:0xf bank_mask:0xf
	v_fmac_f32_dpp v193, v45, v119 row_shr:2 row_mask:0xf bank_mask:0xf
	v_fmac_f32_dpp v194, v46, v120 row_shr:2 row_mask:0xf bank_mask:0xf
	v_fmac_f32_dpp v195, v47, v121 row_shr:2 row_mask:0xf bank_mask:0xf
	v_fmac_f32_dpp v188, v60, v142 row_shl:15 row_mask:0xf bank_mask:0xf
	v_fmac_f32_dpp v189, v61, v143 row_shl:15 row_mask:0xf bank_mask:0xf
	v_fmac_f32_dpp v190, v62, v144 row_shl:15 row_mask:0xf bank_mask:0xf
	v_fmac_f32_dpp v191, v63, v145 row_shl:15 row_mask:0xf bank_mask:0xf
	v_fmac_f32_dpp v192, v56, v110 row_shl:15 row_mask:0xf bank_mask:0xf
	v_fmac_f32_dpp v193, v57, v111 row_shl:15 row_mask:0xf bank_mask:0xf
	v_fmac_f32_dpp v194, v58, v112 row_shl:15 row_mask:0xf bank_mask:0xf
	v_fmac_f32_dpp v195, v59, v113 row_shl:15 row_mask:0xf bank_mask:0xf
	v_fmac_f32_dpp v188, v60, v154 row_shl:14 row_mask:0xf bank_mask:0xf
	v_fmac_f32_dpp v189, v61, v155 row_shl:14 row_mask:0xf bank_mask:0xf
	v_fmac_f32_dpp v190, v62, v156 row_shl:14 row_mask:0xf bank_mask:0xf
	v_fmac_f32_dpp v191, v63, v157 row_shl:14 row_mask:0xf bank_mask:0xf
	v_fmac_f32_dpp v192, v56, v118 row_shl:14 row_mask:0xf bank_mask:0xf
	v_fmac_f32_dpp v193, v57, v119 row_shl:14 row_mask:0xf bank_mask:0xf
	v_fmac_f32_dpp v194, v58, v120 row_shl:14 row_mask:0xf bank_mask:0xf
	v_fmac_f32_dpp v195, v59, v121 row_shl:14 row_mask:0xf bank_mask:0xf
	v_pk_mul_f32 v[196:197], v[188:189], v[216:217] op_sel_hi:[1,0]
	v_pk_mul_f32 v[198:199], v[190:191], v[216:217] op_sel_hi:[1,0]
	v_exp_f32_e32 v196, v196
	v_exp_f32_e32 v197, v197
	v_exp_f32_e32 v198, v198
	v_exp_f32_e32 v199, v199
	v_pk_add_f32 v[196:197], v[196:197], v[214:215] op_sel_hi:[1,0]
	v_pk_add_f32 v[198:199], v[198:199], v[214:215] op_sel_hi:[1,0]
	v_rcp_f32_e32 v196, v196
	v_rcp_f32_e32 v197, v197
	v_rcp_f32_e32 v198, v198
	v_rcp_f32_e32 v199, v199
	v_pk_mul_f32 v[188:189], v[188:189], v[196:197]
	v_pk_mul_f32 v[190:191], v[190:191], v[198:199]
	v_pk_mul_f32 v[188:189], v[188:189], v[192:193]
	v_pk_mul_f32 v[190:191], v[190:191], v[194:195]
	v_cvt_pk_bf16_f32 v160, v188, v189
	v_cvt_pk_bf16_f32 v161, v190, v191
	v_add_u32_e32 v213, 0x2c000, v215
	global_store_dwordx4 v213, v[158:161], s[96:97]
	v_pk_fma_f32 v[188:189], v[48:49], v[134:135], v[130:131]
	v_pk_fma_f32 v[190:191], v[50:51], v[136:137], v[132:133]
	v_pk_fma_f32 v[192:193], v[36:37], v[204:205], v[208:209]
	v_pk_fma_f32 v[194:195], v[38:39], v[206:207], v[210:211]
	v_fmac_f32_dpp v188, v48, v142 row_shr:1 row_mask:0xf bank_mask:0xf
	v_fmac_f32_dpp v189, v49, v143 row_shr:1 row_mask:0xf bank_mask:0xf
	v_fmac_f32_dpp v190, v50, v144 row_shr:1 row_mask:0xf bank_mask:0xf
	v_fmac_f32_dpp v191, v51, v145 row_shr:1 row_mask:0xf bank_mask:0xf
	v_fmac_f32_dpp v192, v36, v110 row_shr:1 row_mask:0xf bank_mask:0xf
	v_fmac_f32_dpp v193, v37, v111 row_shr:1 row_mask:0xf bank_mask:0xf
	v_fmac_f32_dpp v194, v38, v112 row_shr:1 row_mask:0xf bank_mask:0xf
	v_fmac_f32_dpp v195, v39, v113 row_shr:1 row_mask:0xf bank_mask:0xf
	v_fmac_f32_dpp v188, v48, v154 row_shr:2 row_mask:0xf bank_mask:0xf
	v_fmac_f32_dpp v189, v49, v155 row_shr:2 row_mask:0xf bank_mask:0xf
	v_fmac_f32_dpp v190, v50, v156 row_shr:2 row_mask:0xf bank_mask:0xf
	v_fmac_f32_dpp v191, v51, v157 row_shr:2 row_mask:0xf bank_mask:0xf
	v_fmac_f32_dpp v192, v36, v118 row_shr:2 row_mask:0xf bank_mask:0xf
	v_fmac_f32_dpp v193, v37, v119 row_shr:2 row_mask:0xf bank_mask:0xf
	v_fmac_f32_dpp v194, v38, v120 row_shr:2 row_mask:0xf bank_mask:0xf
	v_fmac_f32_dpp v195, v39, v121 row_shr:2 row_mask:0xf bank_mask:0xf
	v_fmac_f32_dpp v188, v52, v142 row_shl:15 row_mask:0xf bank_mask:0xf
	v_fmac_f32_dpp v189, v53, v143 row_shl:15 row_mask:0xf bank_mask:0xf
	v_fmac_f32_dpp v190, v54, v144 row_shl:15 row_mask:0xf bank_mask:0xf
	v_fmac_f32_dpp v191, v55, v145 row_shl:15 row_mask:0xf bank_mask:0xf
	v_fmac_f32_dpp v192, v44, v110 row_shl:15 row_mask:0xf bank_mask:0xf
	v_fmac_f32_dpp v193, v45, v111 row_shl:15 row_mask:0xf bank_mask:0xf
	v_fmac_f32_dpp v194, v46, v112 row_shl:15 row_mask:0xf bank_mask:0xf
	v_fmac_f32_dpp v195, v47, v113 row_shl:15 row_mask:0xf bank_mask:0xf
	v_fmac_f32_dpp v188, v52, v154 row_shl:14 row_mask:0xf bank_mask:0xf
	v_fmac_f32_dpp v189, v53, v155 row_shl:14 row_mask:0xf bank_mask:0xf
	v_fmac_f32_dpp v190, v54, v156 row_shl:14 row_mask:0xf bank_mask:0xf
	v_fmac_f32_dpp v191, v55, v157 row_shl:14 row_mask:0xf bank_mask:0xf
	v_fmac_f32_dpp v192, v44, v118 row_shl:14 row_mask:0xf bank_mask:0xf
	v_fmac_f32_dpp v193, v45, v119 row_shl:14 row_mask:0xf bank_mask:0xf
	v_fmac_f32_dpp v194, v46, v120 row_shl:14 row_mask:0xf bank_mask:0xf
	v_fmac_f32_dpp v195, v47, v121 row_shl:14 row_mask:0xf bank_mask:0xf
	v_pk_mul_f32 v[196:197], v[188:189], v[216:217] op_sel_hi:[1,0]
	v_pk_mul_f32 v[198:199], v[190:191], v[216:217] op_sel_hi:[1,0]
	v_exp_f32_e32 v196, v196
	v_exp_f32_e32 v197, v197
	v_exp_f32_e32 v198, v198
	v_exp_f32_e32 v199, v199
	v_pk_add_f32 v[196:197], v[196:197], v[214:215] op_sel_hi:[1,0]
	v_pk_add_f32 v[198:199], v[198:199], v[214:215] op_sel_hi:[1,0]
	v_rcp_f32_e32 v196, v196
	v_rcp_f32_e32 v197, v197
	v_rcp_f32_e32 v198, v198
	v_rcp_f32_e32 v199, v199
	v_pk_mul_f32 v[188:189], v[188:189], v[196:197]
	v_pk_mul_f32 v[190:191], v[190:191], v[198:199]
	v_pk_mul_f32 v[188:189], v[188:189], v[192:193]
	v_pk_mul_f32 v[190:191], v[190:191], v[194:195]
	v_cvt_pk_bf16_f32 v152, v188, v189
	v_cvt_pk_bf16_f32 v153, v190, v191
	v_add_u32_e32 v213, 0x58000, v215
	global_store_dwordx4 v213, v[150:153], s[96:97]
	v_pk_fma_f32 v[188:189], v[40:41], v[134:135], v[130:131]
	v_pk_fma_f32 v[190:191], v[42:43], v[136:137], v[132:133]
	v_pk_fma_f32 v[192:193], v[32:33], v[204:205], v[208:209]
	v_pk_fma_f32 v[194:195], v[34:35], v[206:207], v[210:211]
	v_fmac_f32_dpp v188, v40, v142 row_shr:1 row_mask:0xf bank_mask:0xf
	v_fmac_f32_dpp v189, v41, v143 row_shr:1 row_mask:0xf bank_mask:0xf
	v_fmac_f32_dpp v190, v42, v144 row_shr:1 row_mask:0xf bank_mask:0xf
	v_fmac_f32_dpp v191, v43, v145 row_shr:1 row_mask:0xf bank_mask:0xf
	v_fmac_f32_dpp v192, v32, v110 row_shr:1 row_mask:0xf bank_mask:0xf
	v_fmac_f32_dpp v193, v33, v111 row_shr:1 row_mask:0xf bank_mask:0xf
	v_fmac_f32_dpp v194, v34, v112 row_shr:1 row_mask:0xf bank_mask:0xf
	v_fmac_f32_dpp v195, v35, v113 row_shr:1 row_mask:0xf bank_mask:0xf
	v_fmac_f32_dpp v188, v40, v154 row_shr:2 row_mask:0xf bank_mask:0xf
	v_fmac_f32_dpp v189, v41, v155 row_shr:2 row_mask:0xf bank_mask:0xf
	v_fmac_f32_dpp v190, v42, v156 row_shr:2 row_mask:0xf bank_mask:0xf
	v_fmac_f32_dpp v191, v43, v157 row_shr:2 row_mask:0xf bank_mask:0xf
	v_fmac_f32_dpp v192, v32, v118 row_shr:2 row_mask:0xf bank_mask:0xf
	v_fmac_f32_dpp v193, v33, v119 row_shr:2 row_mask:0xf bank_mask:0xf
	v_fmac_f32_dpp v194, v34, v120 row_shr:2 row_mask:0xf bank_mask:0xf
	v_fmac_f32_dpp v195, v35, v121 row_shr:2 row_mask:0xf bank_mask:0xf
	v_fmac_f32_dpp v188, v48, v142 row_shl:15 row_mask:0xf bank_mask:0xf
	v_fmac_f32_dpp v189, v49, v143 row_shl:15 row_mask:0xf bank_mask:0xf
	v_fmac_f32_dpp v190, v50, v144 row_shl:15 row_mask:0xf bank_mask:0xf
	v_fmac_f32_dpp v191, v51, v145 row_shl:15 row_mask:0xf bank_mask:0xf
	v_fmac_f32_dpp v192, v36, v110 row_shl:15 row_mask:0xf bank_mask:0xf
	v_fmac_f32_dpp v193, v37, v111 row_shl:15 row_mask:0xf bank_mask:0xf
	v_fmac_f32_dpp v194, v38, v112 row_shl:15 row_mask:0xf bank_mask:0xf
	v_fmac_f32_dpp v195, v39, v113 row_shl:15 row_mask:0xf bank_mask:0xf
	v_fmac_f32_dpp v188, v48, v154 row_shl:14 row_mask:0xf bank_mask:0xf
	v_fmac_f32_dpp v189, v49, v155 row_shl:14 row_mask:0xf bank_mask:0xf
	v_fmac_f32_dpp v190, v50, v156 row_shl:14 row_mask:0xf bank_mask:0xf
	v_fmac_f32_dpp v191, v51, v157 row_shl:14 row_mask:0xf bank_mask:0xf
	v_fmac_f32_dpp v192, v36, v118 row_shl:14 row_mask:0xf bank_mask:0xf
	v_fmac_f32_dpp v193, v37, v119 row_shl:14 row_mask:0xf bank_mask:0xf
	v_fmac_f32_dpp v194, v38, v120 row_shl:14 row_mask:0xf bank_mask:0xf
	v_fmac_f32_dpp v195, v39, v121 row_shl:14 row_mask:0xf bank_mask:0xf
	v_pk_mul_f32 v[196:197], v[188:189], v[216:217] op_sel_hi:[1,0]
	v_pk_mul_f32 v[198:199], v[190:191], v[216:217] op_sel_hi:[1,0]
	v_exp_f32_e32 v196, v196
	v_exp_f32_e32 v197, v197
	v_exp_f32_e32 v198, v198
	v_exp_f32_e32 v199, v199
	v_pk_add_f32 v[196:197], v[196:197], v[214:215] op_sel_hi:[1,0]
	v_pk_add_f32 v[198:199], v[198:199], v[214:215] op_sel_hi:[1,0]
	v_rcp_f32_e32 v196, v196
	v_rcp_f32_e32 v197, v197
	v_rcp_f32_e32 v198, v198
	v_rcp_f32_e32 v199, v199
	v_pk_mul_f32 v[188:189], v[188:189], v[196:197]
	v_pk_mul_f32 v[190:191], v[190:191], v[198:199]
	v_pk_mul_f32 v[188:189], v[188:189], v[192:193]
	v_pk_mul_f32 v[190:191], v[190:191], v[194:195]
	v_cvt_pk_bf16_f32 v148, v188, v189
	v_cvt_pk_bf16_f32 v149, v190, v191
	v_add_u32_e32 v213, 0x84000, v215
	global_store_dwordx4 v213, v[146:149], s[96:97]
	v_pk_fma_f32 v[188:189], v[28:29], v[134:135], v[130:131]
	v_pk_fma_f32 v[190:191], v[30:31], v[136:137], v[132:133]
	v_pk_fma_f32 v[192:193], v[16:17], v[204:205], v[208:209]
	v_pk_fma_f32 v[194:195], v[18:19], v[206:207], v[210:211]
	v_fmac_f32_dpp v188, v28, v142 row_shr:1 row_mask:0xf bank_mask:0xf
	v_fmac_f32_dpp v189, v29, v143 row_shr:1 row_mask:0xf bank_mask:0xf
	v_fmac_f32_dpp v190, v30, v144 row_shr:1 row_mask:0xf bank_mask:0xf
	v_fmac_f32_dpp v191, v31, v145 row_shr:1 row_mask:0xf bank_mask:0xf
	v_fmac_f32_dpp v192, v16, v110 row_shr:1 row_mask:0xf bank_mask:0xf
	v_fmac_f32_dpp v193, v17, v111 row_shr:1 row_mask:0xf bank_mask:0xf
	v_fmac_f32_dpp v194, v18, v112 row_shr:1 row_mask:0xf bank_mask:0xf
	v_fmac_f32_dpp v195, v19, v113 row_shr:1 row_mask:0xf bank_mask:0xf
	v_fmac_f32_dpp v188, v28, v154 row_shr:2 row_mask:0xf bank_mask:0xf
	v_fmac_f32_dpp v189, v29, v155 row_shr:2 row_mask:0xf bank_mask:0xf
	v_fmac_f32_dpp v190, v30, v156 row_shr:2 row_mask:0xf bank_mask:0xf
	v_fmac_f32_dpp v191, v31, v157 row_shr:2 row_mask:0xf bank_mask:0xf
	v_fmac_f32_dpp v192, v16, v118 row_shr:2 row_mask:0xf bank_mask:0xf
	v_fmac_f32_dpp v193, v17, v119 row_shr:2 row_mask:0xf bank_mask:0xf
	v_fmac_f32_dpp v194, v18, v120 row_shr:2 row_mask:0xf bank_mask:0xf
	v_fmac_f32_dpp v195, v19, v121 row_shr:2 row_mask:0xf bank_mask:0xf
	v_fmac_f32_dpp v188, v40, v142 row_shl:15 row_mask:0xf bank_mask:0xf
	v_fmac_f32_dpp v189, v41, v143 row_shl:15 row_mask:0xf bank_mask:0xf
	v_fmac_f32_dpp v190, v42, v144 row_shl:15 row_mask:0xf bank_mask:0xf
	v_fmac_f32_dpp v191, v43, v145 row_shl:15 row_mask:0xf bank_mask:0xf
	v_fmac_f32_dpp v192, v32, v110 row_shl:15 row_mask:0xf bank_mask:0xf
	v_fmac_f32_dpp v193, v33, v111 row_shl:15 row_mask:0xf bank_mask:0xf
	v_fmac_f32_dpp v194, v34, v112 row_shl:15 row_mask:0xf bank_mask:0xf
	v_fmac_f32_dpp v195, v35, v113 row_shl:15 row_mask:0xf bank_mask:0xf
	v_fmac_f32_dpp v188, v40, v154 row_shl:14 row_mask:0xf bank_mask:0xf
	v_fmac_f32_dpp v189, v41, v155 row_shl:14 row_mask:0xf bank_mask:0xf
	v_fmac_f32_dpp v190, v42, v156 row_shl:14 row_mask:0xf bank_mask:0xf
	v_fmac_f32_dpp v191, v43, v157 row_shl:14 row_mask:0xf bank_mask:0xf
	v_fmac_f32_dpp v192, v32, v118 row_shl:14 row_mask:0xf bank_mask:0xf
	v_fmac_f32_dpp v193, v33, v119 row_shl:14 row_mask:0xf bank_mask:0xf
	v_fmac_f32_dpp v194, v34, v120 row_shl:14 row_mask:0xf bank_mask:0xf
	v_fmac_f32_dpp v195, v35, v121 row_shl:14 row_mask:0xf bank_mask:0xf
	v_pk_mul_f32 v[196:197], v[188:189], v[216:217] op_sel_hi:[1,0]
	v_pk_mul_f32 v[198:199], v[190:191], v[216:217] op_sel_hi:[1,0]
	v_exp_f32_e32 v196, v196
	v_exp_f32_e32 v197, v197
	v_exp_f32_e32 v198, v198
	v_exp_f32_e32 v199, v199
	v_pk_add_f32 v[196:197], v[196:197], v[214:215] op_sel_hi:[1,0]
	v_pk_add_f32 v[198:199], v[198:199], v[214:215] op_sel_hi:[1,0]
	v_rcp_f32_e32 v196, v196
	v_rcp_f32_e32 v197, v197
	v_rcp_f32_e32 v198, v198
	v_rcp_f32_e32 v199, v199
	v_pk_mul_f32 v[188:189], v[188:189], v[196:197]
	v_pk_mul_f32 v[190:191], v[190:191], v[198:199]
	v_pk_mul_f32 v[188:189], v[188:189], v[192:193]
	v_pk_mul_f32 v[190:191], v[190:191], v[194:195]
	v_cvt_pk_bf16_f32 v140, v188, v189
	v_cvt_pk_bf16_f32 v141, v190, v191
	v_add_u32_e32 v213, 0xb0000, v215
	global_store_dwordx4 v213, v[138:141], s[96:97]
	v_pk_fma_f32 v[188:189], v[24:25], v[134:135], v[130:131]
	v_pk_fma_f32 v[190:191], v[26:27], v[136:137], v[132:133]
	v_pk_fma_f32 v[192:193], v[12:13], v[204:205], v[208:209]
	v_pk_fma_f32 v[194:195], v[14:15], v[206:207], v[210:211]
	v_fmac_f32_dpp v188, v24, v142 row_shr:1 row_mask:0xf bank_mask:0xf
	v_fmac_f32_dpp v189, v25, v143 row_shr:1 row_mask:0xf bank_mask:0xf
	v_fmac_f32_dpp v190, v26, v144 row_shr:1 row_mask:0xf bank_mask:0xf
	v_fmac_f32_dpp v191, v27, v145 row_shr:1 row_mask:0xf bank_mask:0xf
	v_fmac_f32_dpp v192, v12, v110 row_shr:1 row_mask:0xf bank_mask:0xf
	v_fmac_f32_dpp v193, v13, v111 row_shr:1 row_mask:0xf bank_mask:0xf
	v_fmac_f32_dpp v194, v14, v112 row_shr:1 row_mask:0xf bank_mask:0xf
	v_fmac_f32_dpp v195, v15, v113 row_shr:1 row_mask:0xf bank_mask:0xf
	v_fmac_f32_dpp v188, v24, v154 row_shr:2 row_mask:0xf bank_mask:0xf
	v_fmac_f32_dpp v189, v25, v155 row_shr:2 row_mask:0xf bank_mask:0xf
	v_fmac_f32_dpp v190, v26, v156 row_shr:2 row_mask:0xf bank_mask:0xf
	v_fmac_f32_dpp v191, v27, v157 row_shr:2 row_mask:0xf bank_mask:0xf
	v_fmac_f32_dpp v192, v12, v118 row_shr:2 row_mask:0xf bank_mask:0xf
	v_fmac_f32_dpp v193, v13, v119 row_shr:2 row_mask:0xf bank_mask:0xf
	v_fmac_f32_dpp v194, v14, v120 row_shr:2 row_mask:0xf bank_mask:0xf
	v_fmac_f32_dpp v195, v15, v121 row_shr:2 row_mask:0xf bank_mask:0xf
	v_fmac_f32_dpp v188, v28, v142 row_shl:15 row_mask:0xf bank_mask:0xf
	v_fmac_f32_dpp v189, v29, v143 row_shl:15 row_mask:0xf bank_mask:0xf
	v_fmac_f32_dpp v190, v30, v144 row_shl:15 row_mask:0xf bank_mask:0xf
	v_fmac_f32_dpp v191, v31, v145 row_shl:15 row_mask:0xf bank_mask:0xf
	v_fmac_f32_dpp v192, v16, v110 row_shl:15 row_mask:0xf bank_mask:0xf
	v_fmac_f32_dpp v193, v17, v111 row_shl:15 row_mask:0xf bank_mask:0xf
	v_fmac_f32_dpp v194, v18, v112 row_shl:15 row_mask:0xf bank_mask:0xf
	v_fmac_f32_dpp v195, v19, v113 row_shl:15 row_mask:0xf bank_mask:0xf
	v_fmac_f32_dpp v188, v28, v154 row_shl:14 row_mask:0xf bank_mask:0xf
	v_fmac_f32_dpp v189, v29, v155 row_shl:14 row_mask:0xf bank_mask:0xf
	v_fmac_f32_dpp v190, v30, v156 row_shl:14 row_mask:0xf bank_mask:0xf
	v_fmac_f32_dpp v191, v31, v157 row_shl:14 row_mask:0xf bank_mask:0xf
	v_fmac_f32_dpp v192, v16, v118 row_shl:14 row_mask:0xf bank_mask:0xf
	v_fmac_f32_dpp v193, v17, v119 row_shl:14 row_mask:0xf bank_mask:0xf
	v_fmac_f32_dpp v194, v18, v120 row_shl:14 row_mask:0xf bank_mask:0xf
	v_fmac_f32_dpp v195, v19, v121 row_shl:14 row_mask:0xf bank_mask:0xf
	v_pk_mul_f32 v[196:197], v[188:189], v[216:217] op_sel_hi:[1,0]
	v_pk_mul_f32 v[198:199], v[190:191], v[216:217] op_sel_hi:[1,0]
	v_exp_f32_e32 v196, v196
	v_exp_f32_e32 v197, v197
	v_exp_f32_e32 v198, v198
	v_exp_f32_e32 v199, v199
	v_pk_add_f32 v[196:197], v[196:197], v[214:215] op_sel_hi:[1,0]
	v_pk_add_f32 v[198:199], v[198:199], v[214:215] op_sel_hi:[1,0]
	v_rcp_f32_e32 v196, v196
	v_rcp_f32_e32 v197, v197
	v_rcp_f32_e32 v198, v198
	v_rcp_f32_e32 v199, v199
	v_pk_mul_f32 v[188:189], v[188:189], v[196:197]
	v_pk_mul_f32 v[190:191], v[190:191], v[198:199]
	v_pk_mul_f32 v[188:189], v[188:189], v[192:193]
	v_pk_mul_f32 v[190:191], v[190:191], v[194:195]
	v_cvt_pk_bf16_f32 v128, v188, v189
	v_cvt_pk_bf16_f32 v129, v190, v191
	v_add_u32_e32 v213, 0xdc000, v215
	global_store_dwordx4 v213, v[126:129], s[96:97]
	v_pk_fma_f32 v[188:189], v[20:21], v[134:135], v[130:131]
	v_pk_fma_f32 v[190:191], v[22:23], v[136:137], v[132:133]
	v_pk_fma_f32 v[192:193], v[8:9], v[204:205], v[208:209]
	v_pk_fma_f32 v[194:195], v[10:11], v[206:207], v[210:211]
	v_fmac_f32_dpp v188, v20, v142 row_shr:1 row_mask:0xf bank_mask:0xf
	v_fmac_f32_dpp v189, v21, v143 row_shr:1 row_mask:0xf bank_mask:0xf
	v_fmac_f32_dpp v190, v22, v144 row_shr:1 row_mask:0xf bank_mask:0xf
	v_fmac_f32_dpp v191, v23, v145 row_shr:1 row_mask:0xf bank_mask:0xf
	v_fmac_f32_dpp v192, v8, v110 row_shr:1 row_mask:0xf bank_mask:0xf
	v_fmac_f32_dpp v193, v9, v111 row_shr:1 row_mask:0xf bank_mask:0xf
	v_fmac_f32_dpp v194, v10, v112 row_shr:1 row_mask:0xf bank_mask:0xf
	v_fmac_f32_dpp v195, v11, v113 row_shr:1 row_mask:0xf bank_mask:0xf
	v_fmac_f32_dpp v188, v20, v154 row_shr:2 row_mask:0xf bank_mask:0xf
	v_fmac_f32_dpp v189, v21, v155 row_shr:2 row_mask:0xf bank_mask:0xf
	v_fmac_f32_dpp v190, v22, v156 row_shr:2 row_mask:0xf bank_mask:0xf
	v_fmac_f32_dpp v191, v23, v157 row_shr:2 row_mask:0xf bank_mask:0xf
	v_fmac_f32_dpp v192, v8, v118 row_shr:2 row_mask:0xf bank_mask:0xf
	v_fmac_f32_dpp v193, v9, v119 row_shr:2 row_mask:0xf bank_mask:0xf
	v_fmac_f32_dpp v194, v10, v120 row_shr:2 row_mask:0xf bank_mask:0xf
	v_fmac_f32_dpp v195, v11, v121 row_shr:2 row_mask:0xf bank_mask:0xf
	v_fmac_f32_dpp v188, v24, v142 row_shl:15 row_mask:0xf bank_mask:0xf
	v_fmac_f32_dpp v189, v25, v143 row_shl:15 row_mask:0xf bank_mask:0xf
	v_fmac_f32_dpp v190, v26, v144 row_shl:15 row_mask:0xf bank_mask:0xf
	v_fmac_f32_dpp v191, v27, v145 row_shl:15 row_mask:0xf bank_mask:0xf
	v_fmac_f32_dpp v192, v12, v110 row_shl:15 row_mask:0xf bank_mask:0xf
	v_fmac_f32_dpp v193, v13, v111 row_shl:15 row_mask:0xf bank_mask:0xf
	v_fmac_f32_dpp v194, v14, v112 row_shl:15 row_mask:0xf bank_mask:0xf
	v_fmac_f32_dpp v195, v15, v113 row_shl:15 row_mask:0xf bank_mask:0xf
	v_fmac_f32_dpp v188, v24, v154 row_shl:14 row_mask:0xf bank_mask:0xf
	v_fmac_f32_dpp v189, v25, v155 row_shl:14 row_mask:0xf bank_mask:0xf
	v_fmac_f32_dpp v190, v26, v156 row_shl:14 row_mask:0xf bank_mask:0xf
	v_fmac_f32_dpp v191, v27, v157 row_shl:14 row_mask:0xf bank_mask:0xf
	v_fmac_f32_dpp v192, v12, v118 row_shl:14 row_mask:0xf bank_mask:0xf
	v_fmac_f32_dpp v193, v13, v119 row_shl:14 row_mask:0xf bank_mask:0xf
	v_fmac_f32_dpp v194, v14, v120 row_shl:14 row_mask:0xf bank_mask:0xf
	v_fmac_f32_dpp v195, v15, v121 row_shl:14 row_mask:0xf bank_mask:0xf
	v_pk_mul_f32 v[196:197], v[188:189], v[216:217] op_sel_hi:[1,0]
	v_pk_mul_f32 v[198:199], v[190:191], v[216:217] op_sel_hi:[1,0]
	v_exp_f32_e32 v196, v196
	v_exp_f32_e32 v197, v197
	v_exp_f32_e32 v198, v198
	v_exp_f32_e32 v199, v199
	v_pk_add_f32 v[196:197], v[196:197], v[214:215] op_sel_hi:[1,0]
	v_pk_add_f32 v[198:199], v[198:199], v[214:215] op_sel_hi:[1,0]
	v_rcp_f32_e32 v196, v196
	v_rcp_f32_e32 v197, v197
	v_rcp_f32_e32 v198, v198
	v_rcp_f32_e32 v199, v199
	v_pk_mul_f32 v[188:189], v[188:189], v[196:197]
	v_pk_mul_f32 v[190:191], v[190:191], v[198:199]
	v_pk_mul_f32 v[188:189], v[188:189], v[192:193]
	v_pk_mul_f32 v[190:191], v[190:191], v[194:195]
	v_cvt_pk_bf16_f32 v124, v188, v189
	v_cvt_pk_bf16_f32 v125, v190, v191
	v_add_u32_e32 v213, 0x108000, v215
	global_store_dwordx4 v213, v[122:125], s[96:97]
	v_pk_fma_f32 v[188:189], v[4:5], v[134:135], v[130:131]
	v_pk_fma_f32 v[190:191], v[6:7], v[136:137], v[132:133]
	v_pk_fma_f32 v[192:193], v[0:1], v[204:205], v[208:209]
	v_pk_fma_f32 v[194:195], v[2:3], v[206:207], v[210:211]
	v_fmac_f32_dpp v188, v4, v142 row_shr:1 row_mask:0xf bank_mask:0xf
	v_fmac_f32_dpp v189, v5, v143 row_shr:1 row_mask:0xf bank_mask:0xf
	v_fmac_f32_dpp v190, v6, v144 row_shr:1 row_mask:0xf bank_mask:0xf
	v_fmac_f32_dpp v191, v7, v145 row_shr:1 row_mask:0xf bank_mask:0xf
	v_fmac_f32_dpp v192, v0, v110 row_shr:1 row_mask:0xf bank_mask:0xf
	v_fmac_f32_dpp v193, v1, v111 row_shr:1 row_mask:0xf bank_mask:0xf
	v_fmac_f32_dpp v194, v2, v112 row_shr:1 row_mask:0xf bank_mask:0xf
	v_fmac_f32_dpp v195, v3, v113 row_shr:1 row_mask:0xf bank_mask:0xf
	v_fmac_f32_dpp v188, v4, v154 row_shr:2 row_mask:0xf bank_mask:0xf
	v_fmac_f32_dpp v189, v5, v155 row_shr:2 row_mask:0xf bank_mask:0xf
	v_fmac_f32_dpp v190, v6, v156 row_shr:2 row_mask:0xf bank_mask:0xf
	v_fmac_f32_dpp v191, v7, v157 row_shr:2 row_mask:0xf bank_mask:0xf
	v_fmac_f32_dpp v192, v0, v118 row_shr:2 row_mask:0xf bank_mask:0xf
	v_fmac_f32_dpp v193, v1, v119 row_shr:2 row_mask:0xf bank_mask:0xf
	v_fmac_f32_dpp v194, v2, v120 row_shr:2 row_mask:0xf bank_mask:0xf
	v_fmac_f32_dpp v195, v3, v121 row_shr:2 row_mask:0xf bank_mask:0xf
	v_fmac_f32_dpp v188, v20, v142 row_shl:15 row_mask:0xf bank_mask:0xf
	v_fmac_f32_dpp v189, v21, v143 row_shl:15 row_mask:0xf bank_mask:0xf
	v_fmac_f32_dpp v190, v22, v144 row_shl:15 row_mask:0xf bank_mask:0xf
	v_fmac_f32_dpp v191, v23, v145 row_shl:15 row_mask:0xf bank_mask:0xf
	v_fmac_f32_dpp v192, v8, v110 row_shl:15 row_mask:0xf bank_mask:0xf
	v_fmac_f32_dpp v193, v9, v111 row_shl:15 row_mask:0xf bank_mask:0xf
	v_fmac_f32_dpp v194, v10, v112 row_shl:15 row_mask:0xf bank_mask:0xf
	v_fmac_f32_dpp v195, v11, v113 row_shl:15 row_mask:0xf bank_mask:0xf
	v_fmac_f32_dpp v188, v20, v154 row_shl:14 row_mask:0xf bank_mask:0xf
	v_fmac_f32_dpp v189, v21, v155 row_shl:14 row_mask:0xf bank_mask:0xf
	v_fmac_f32_dpp v190, v22, v156 row_shl:14 row_mask:0xf bank_mask:0xf
	v_fmac_f32_dpp v191, v23, v157 row_shl:14 row_mask:0xf bank_mask:0xf
	v_fmac_f32_dpp v192, v8, v118 row_shl:14 row_mask:0xf bank_mask:0xf
	v_fmac_f32_dpp v193, v9, v119 row_shl:14 row_mask:0xf bank_mask:0xf
	v_fmac_f32_dpp v194, v10, v120 row_shl:14 row_mask:0xf bank_mask:0xf
	v_fmac_f32_dpp v195, v11, v121 row_shl:14 row_mask:0xf bank_mask:0xf
	v_pk_mul_f32 v[196:197], v[188:189], v[216:217] op_sel_hi:[1,0]
	v_pk_mul_f32 v[198:199], v[190:191], v[216:217] op_sel_hi:[1,0]
	v_exp_f32_e32 v196, v196
	v_exp_f32_e32 v197, v197
	v_exp_f32_e32 v198, v198
	v_exp_f32_e32 v199, v199
	v_pk_add_f32 v[196:197], v[196:197], v[214:215] op_sel_hi:[1,0]
	v_pk_add_f32 v[198:199], v[198:199], v[214:215] op_sel_hi:[1,0]
	v_rcp_f32_e32 v196, v196
	v_rcp_f32_e32 v197, v197
	v_rcp_f32_e32 v198, v198
	v_rcp_f32_e32 v199, v199
	v_pk_mul_f32 v[188:189], v[188:189], v[196:197]
	v_pk_mul_f32 v[190:191], v[190:191], v[198:199]
	v_pk_mul_f32 v[188:189], v[188:189], v[192:193]
	v_pk_mul_f32 v[190:191], v[190:191], v[194:195]
	v_cvt_pk_bf16_f32 v116, v188, v189
	v_cvt_pk_bf16_f32 v117, v190, v191
	v_add_u32_e32 v213, 0x134000, v215
	global_store_dwordx4 v213, v[114:117], s[96:97]
	s_branch .LBB0_359
.LBB0_374:
	s_waitcnt vmcnt(0)
	s_cmpk_gt_u32 s3, 0xff
	s_cbranch_scc1 .LBB0_376
.LBB0_376:
	s_barrier

.LBB0_492:
	v_lshrrev_b32_e32 v0, 1, v219
	v_mul_u32_u24_e32 v231, 0x1600, v236
	v_or_b32_e32 v1, v0, v231
	v_lshlrev_b32_e32 v168, 1, v1
	v_mul_u32_u24_e32 v1, 0x1600, v232
	v_or_b32_e32 v1, v1, v0
	v_mul_u32_u24_e32 v232, 0x1600, v237
	v_lshlrev_b32_e32 v170, 1, v1
	v_or_b32_e32 v1, v232, v0
	v_lshlrev_b32_e32 v172, 1, v1
	v_mul_u32_u24_e32 v1, 0x1600, v240
	v_readlane_b32 s0, v255, 8
	v_or_b32_e32 v0, v1, v0
	s_add_u32 s14, s92, 0x20000
	v_readlane_b32 s1, v255, 9
	s_addc_u32 s15, s93, 0
	s_and_b64 vcc, exec, s[0:1]
	v_lshlrev_b32_e32 v174, 1, v0
	s_cbranch_vccnz .LBB0_528
	s_add_u32 s18, s92, 0x4d00000
	s_addc_u32 s19, s93, 0
	s_lshr_b32 s4, s3, 6
	s_lshr_b32 s5, s3, 8
	s_lshl_b32 s20, s4, 10
	s_mul_i32 s7, s37, 0x2c0000
	s_mul_hi_i32 s6, s37, 0x2c0000
	s_add_u32 s16, s18, s7
	s_addc_u32 s17, s19, s6
	s_add_i32 s21, s20, 0
	s_add_i32 m0, s21, 0x10000
	s_mul_i32 s0, s38, 0x2c0000
	v_and_b32_e32 v136, 63, v222
	v_lshrrev_b32_e32 v137, 3, v136
	v_lshrrev_b32_e32 v138, 6, v222
	v_lshl_add_u32 v139, v138, 3, v137
	v_and_b32_e32 v146, 7, v136
	v_and_b32_e32 v147, 6, v137
	v_xor_b32_e32 v146, v146, v147
	v_lshlrev_b32_e32 v146, 4, v146
	v_mul_u32_u24_e32 v147, 0x2c00, v139
	v_add_u32_e32 v147, v147, v146
	v_mov_b32_e32 v128, v147
	v_add_u32_e32 v130, 0xb0000, v147
	v_mov_b32_e32 v168, v147
	v_add_u32_e32 v172, 0xb0000, v147
	v_add_u32_e32 v130, 0xb0000, v147
	v_add_u32_e32 v172, 0xb0000, v147
	v_and_b32_e32 v147, 31, v139
	v_and_b32_e32 v148, 12, v147
	v_lshlrev_b32_e32 v148, 1, v148
	v_lshrrev_b32_e32 v149, 4, v147
	v_lshlrev_b32_e32 v149, 2, v149
	v_and_b32_e32 v147, 3, v147
	v_or3_b32 v147, v148, v149, v147
	v_and_b32_e32 v148, 0x60, v139
	v_add_u32_e32 v147, v147, v148
	v_mul_u32_u24_e32 v147, 0x2c00, v147
	v_add_u32_e32 v147, v147, v146
	v_mov_b32_e32 v170, v147
	v_add_u32_e32 v174, 0xb0000, v147
	v_add_u32_e32 v174, 0xb0000, v147
	v_and_b32_e32 v147, 15, v136
	v_lshrrev_b32_e32 v148, 4, v136
	v_and_b32_e32 v149, 6, v147
	v_xor_b32_e32 v148, v148, v149
	v_lshlrev_b32_e32 v148, 4, v148
	v_lshl_or_b32 v148, v147, 7, v148
	v_lshrrev_b32_e32 v149, 2, v138
	v_lshl_add_u32 v149, v149, 13, v148
	v_add_u32_e32 v142, 0x0, v149
	v_and_b32_e32 v147, 3, v138
	v_lshl_add_u32 v147, v147, 12, v148
	v_add_u32_e32 v140, 0x0, v147
	v_add_u32_e32 v141, 0x10000, v147
	v_add_u32_e32 v143, 0x14000, v147
	v_add_u32_e32 v145, 0x0, v147
	global_load_lds_dwordx4 v170, s[16:17]
	s_add_i32 m0, s21, 0x12000
	s_mul_hi_i32 s1, s38, 0x2c0000
	s_add_u32 s0, s96, s0
	global_load_lds_dwordx4 v174, s[16:17]
	s_addc_u32 s1, s97, s1
	s_mov_b32 m0, s21
	s_add_i32 s22, s21, 0x2000
	global_load_lds_dwordx4 v168, s[0:1]
	s_mov_b32 m0, s22
	s_add_u32 s6, s16, 0x160000
	global_load_lds_dwordx4 v172, s[0:1]
	s_addc_u32 s7, s17, 0
	s_add_i32 m0, s21, 0x14000
	v_mov_b32_e32 v171, 0
	global_load_lds_dwordx4 v170, s[6:7]
	s_add_i32 m0, s21, 0x16000
	v_mov_b32_e32 v175, v171
	global_load_lds_dwordx4 v174, s[6:7]
	s_add_u32 s6, s0, 0x160000
	s_addc_u32 s7, s1, 0
	s_add_i32 s23, s21, 0x4000
	s_mov_b32 m0, s23
	s_add_i32 s24, s21, 0x6000
	global_load_lds_dwordx4 v168, s[6:7]
	s_mov_b32 m0, s24
	v_mov_b32_e32 v169, v171
	global_load_lds_dwordx4 v172, s[6:7]
	v_mov_b32_e32 v173, v171
	s_mov_b32 s25, 0
	v_lshl_add_u64 v[6:7], s[16:17], 0, v[170:171]
	v_lshl_add_u64 v[4:5], s[16:17], 0, v[174:175]
	v_lshl_add_u64 v[2:3], s[0:1], 0, v[168:169]
	s_cmp_lg_u32 s5, 1
	v_lshl_add_u64 v[0:1], s[0:1], 0, v[172:173]
	s_cbranch_scc1 .LBB0_495
.LBB0_495:
	s_lshl_b32 s4, s4, 5
	s_lshl_b32 s26, s5, 6
	s_lshl_b32 s8, s5, 13
	s_and_b32 s27, s4, 0x60
	s_mov_b64 s[4:5], 0x80
	s_add_i32 m0, s21, 0x18000
	v_lshl_add_u64 v[6:7], v[6:7], 0, s[4:5]
	s_waitcnt vmcnt(4)
	s_barrier
	global_load_lds_dwordx4 v[6:7], off
	v_lshl_add_u64 v[4:5], v[4:5], 0, s[4:5]
	s_add_i32 m0, s21, 0x1a000
	s_add_i32 s28, s21, 0x8000
	s_add_i32 s29, s21, 0xa000
	global_load_lds_dwordx4 v[4:5], off
	v_lshl_add_u64 v[2:3], v[2:3], 0, s[4:5]
	s_mov_b32 m0, s28
	s_add_u32 s6, s16, 0x160080
	global_load_lds_dwordx4 v[2:3], off
	v_lshl_add_u64 v[0:1], v[0:1], 0, s[4:5]
	s_mov_b32 m0, s29
	s_addc_u32 s7, s17, 0
	global_load_lds_dwordx4 v[0:1], off
	s_add_i32 m0, s21, 0x1c000
	v_lshl_add_u64 v[0:1], s[6:7], 0, v[170:171]
	global_load_lds_dwordx4 v[0:1], off
	v_lshl_add_u64 v[0:1], s[6:7], 0, v[174:175]
	s_add_i32 m0, s21, 0x1e000
	global_load_lds_dwordx4 v[0:1], off
	v_lshlrev_b32_e32 v1, 2, v163
	v_lshl_or_b32 v0, v163, 6, v227
	v_and_b32_e32 v1, 32, v1
	v_bitop3_b32 v0, v0, s8, v1 bitop3:0xde
	s_waitcnt vmcnt(6)
	v_add_u16_e32 v1, v226, v224
	v_lshrrev_b16_e32 v1, 1, v1
	s_add_i32 s33, 0, 0x10000
	s_add_i32 s34, 0, 0x14000
	v_mbcnt_lo_u32_b32 v0, -1, 0
	s_ashr_i32 s30, s94, 31
	s_mov_b32 s31, s94
	v_mov_b32_e32 v129, v171
	v_mov_b32_e32 v131, v171
	v_mov_b64_e32 v[132:133], 0x200
	v_mov_b64_e32 v[134:135], 0x1ff
	v_mbcnt_hi_u32_b32 v144, -1, v0
	s_barrier
	s_branch .LBB0_497

.LBB0_507:
	s_add_u32 s0, s0, 0x160080
	s_addc_u32 s1, s1, 0
	s_add_u32 s39, s16, 0x100
	v_mov_b32_e32 v0, 0
	s_addc_u32 s40, s17, 0
	s_mov_b32 s41, -2
	s_waitcnt lgkmcnt(0)
	v_mov_b32_e32 v1, v0
	v_mov_b32_e32 v2, v0
	v_mov_b32_e32 v3, v0
	v_mov_b32_e32 v4, v0
	v_mov_b32_e32 v5, v0
	v_mov_b32_e32 v6, v0
	v_mov_b32_e32 v7, v0
	s_waitcnt vmcnt(0)
	v_mov_b32_e32 v16, v0
	v_mov_b32_e32 v17, v0
	v_mov_b32_e32 v18, v0
	v_mov_b32_e32 v19, v0
	v_mov_b32_e32 v20, v0
	v_mov_b32_e32 v21, v0
	v_mov_b32_e32 v22, v0
	v_mov_b32_e32 v23, v0
	v_mov_b32_e32 v32, v0
	v_mov_b32_e32 v33, v0
	v_mov_b32_e32 v34, v0
	v_mov_b32_e32 v35, v0
	v_mov_b32_e32 v36, v0
	v_mov_b32_e32 v37, v0
	v_mov_b32_e32 v38, v0
	v_mov_b32_e32 v39, v0
	v_mov_b32_e32 v48, v0
	v_mov_b32_e32 v49, v0
	v_mov_b32_e32 v50, v0
	v_mov_b32_e32 v51, v0
	v_mov_b32_e32 v52, v0
	v_mov_b32_e32 v53, v0
	v_mov_b32_e32 v54, v0
	v_mov_b32_e32 v55, v0
	v_mov_b32_e32 v8, v0
	v_mov_b32_e32 v9, v0
	v_mov_b32_e32 v10, v0
	v_mov_b32_e32 v11, v0
	v_mov_b32_e32 v12, v0
	v_mov_b32_e32 v13, v0
	v_mov_b32_e32 v14, v0
	v_mov_b32_e32 v15, v0
	v_mov_b32_e32 v24, v0
	v_mov_b32_e32 v25, v0
	v_mov_b32_e32 v26, v0
	v_mov_b32_e32 v27, v0
	v_mov_b32_e32 v28, v0
	v_mov_b32_e32 v29, v0
	v_mov_b32_e32 v30, v0
	v_mov_b32_e32 v31, v0
	v_mov_b32_e32 v40, v0
	v_mov_b32_e32 v41, v0
	v_mov_b32_e32 v42, v0
	v_mov_b32_e32 v43, v0
	v_mov_b32_e32 v44, v0
	v_mov_b32_e32 v45, v0
	v_mov_b32_e32 v46, v0
	v_mov_b32_e32 v47, v0
	v_mov_b32_e32 v56, v0
	v_mov_b32_e32 v57, v0
	v_mov_b32_e32 v58, v0
	v_mov_b32_e32 v59, v0
	v_mov_b32_e32 v60, v0
	v_mov_b32_e32 v61, v0
	v_mov_b32_e32 v62, v0
	v_mov_b32_e32 v63, v0
	v_mov_b32_e32 v64, v0
	v_mov_b32_e32 v65, v0
	v_mov_b32_e32 v66, v0
	v_mov_b32_e32 v67, v0
	v_mov_b32_e32 v68, v0
	v_mov_b32_e32 v69, v0
	v_mov_b32_e32 v70, v0
	v_mov_b32_e32 v71, v0
	v_mov_b32_e32 v80, v0
	v_mov_b32_e32 v81, v0
	v_mov_b32_e32 v82, v0
	v_mov_b32_e32 v83, v0
	v_mov_b32_e32 v84, v0
	v_mov_b32_e32 v85, v0
	v_mov_b32_e32 v86, v0
	v_mov_b32_e32 v87, v0
	v_mov_b32_e32 v96, v0
	v_mov_b32_e32 v97, v0
	v_mov_b32_e32 v98, v0
	v_mov_b32_e32 v99, v0
	v_mov_b32_e32 v100, v0
	v_mov_b32_e32 v101, v0
	v_mov_b32_e32 v102, v0
	v_mov_b32_e32 v103, v0
	v_mov_b32_e32 v112, v0
	v_mov_b32_e32 v113, v0
	v_mov_b32_e32 v114, v0
	v_mov_b32_e32 v115, v0
	v_mov_b32_e32 v116, v0
	v_mov_b32_e32 v117, v0
	v_mov_b32_e32 v118, v0
	v_mov_b32_e32 v119, v0
	v_mov_b32_e32 v72, v0
	v_mov_b32_e32 v73, v0
	v_mov_b32_e32 v74, v0
	v_mov_b32_e32 v75, v0
	v_mov_b32_e32 v76, v0
	v_mov_b32_e32 v77, v0
	v_mov_b32_e32 v78, v0
	v_mov_b32_e32 v79, v0
	v_mov_b32_e32 v88, v0
	v_mov_b32_e32 v89, v0
	v_mov_b32_e32 v90, v0
	v_mov_b32_e32 v91, v0
	v_mov_b32_e32 v92, v0
	v_mov_b32_e32 v93, v0
	v_mov_b32_e32 v94, v0
	v_mov_b32_e32 v95, v0
	v_mov_b32_e32 v104, v0
	v_mov_b32_e32 v105, v0
	v_mov_b32_e32 v106, v0
	v_mov_b32_e32 v107, v0
	v_mov_b32_e32 v108, v0
	v_mov_b32_e32 v109, v0
	v_mov_b32_e32 v110, v0
	v_mov_b32_e32 v111, v0
	v_mov_b32_e32 v120, v0
	v_mov_b32_e32 v121, v0
	v_mov_b32_e32 v122, v0
	v_mov_b32_e32 v123, v0
	v_mov_b32_e32 v124, v0
	v_mov_b32_e32 v125, v0
	v_mov_b32_e32 v126, v0
	v_mov_b32_e32 v127, v0
	v_xor_b32_e32 v216, 64, v141
	v_xor_b32_e32 v217, 64, v142
	v_xor_b32_e32 v244, 64, v143
	v_add_u32_e32 v245, 0x18000, v140
	v_xor_b32_e32 v246, 64, v245
	s_cmpk_lt_u32 s3, 0x100
	s_cbranch_scc1 .Lst_in_s4
	s_barrier
.Lst_in_s4:
.LBB0_508:
	ds_read_b128 v[136:139], v141
	ds_read_b128 v[146:149], v216
	ds_read_b128 v[150:153], v141 offset:2048
	ds_read_b128 v[154:157], v216 offset:2048
	s_add_u32 s8, s0, 0xffea0080
	s_addc_u32 s9, s1, -1
	s_cmpk_eq_i32 s41, 0x54
	s_cselect_b32 s17, s13, s9
	s_cselect_b32 s16, s12, s8
	s_cselect_b32 s9, s11, s40
	s_cselect_b32 s8, s10, s39
	s_add_i32 m0, s21, 0xc000
	ds_read_b128 v[158:161], v142
	ds_read_b128 v[176:179], v217
	ds_read_b128 v[180:183], v142 offset:2048
	ds_read_b128 v[184:187], v217 offset:2048
	ds_read_b128 v[188:191], v142 offset:4096
	ds_read_b128 v[192:195], v217 offset:4096
	ds_read_b128 v[196:199], v142 offset:6144
	ds_read_b128 v[200:203], v217 offset:6144
	global_load_lds_dwordx4 v128, s[0:1]
	s_add_i32 m0, s21, 0xe000
	s_nop 0
	global_load_lds_dwordx4 v130, s[0:1]
	s_waitcnt lgkmcnt(8)
	s_barrier
	s_waitcnt lgkmcnt(0)
	s_waitcnt lgkmcnt(0)
	v_mfma_f32_16x16x32_bf16 v[124:127], v[136:139], v[158:161], v[124:127]
	v_mfma_f32_16x16x32_bf16 v[124:127], v[146:149], v[176:179], v[124:127]
	v_mfma_f32_16x16x32_bf16 v[120:123], v[154:157], v[176:179], v[120:123]
	v_mfma_f32_16x16x32_bf16 v[120:123], v[150:153], v[158:161], v[120:123]
	v_mfma_f32_16x16x32_bf16 v[104:107], v[150:153], v[180:183], v[104:107]
	v_mfma_f32_16x16x32_bf16 v[104:107], v[154:157], v[184:187], v[104:107]
	v_mfma_f32_16x16x32_bf16 v[108:111], v[146:149], v[184:187], v[108:111]
	v_mfma_f32_16x16x32_bf16 v[108:111], v[136:139], v[180:183], v[108:111]
	v_mfma_f32_16x16x32_bf16 v[92:95], v[136:139], v[188:191], v[92:95]
	v_mfma_f32_16x16x32_bf16 v[92:95], v[146:149], v[192:195], v[92:95]
	v_mfma_f32_16x16x32_bf16 v[88:91], v[154:157], v[192:195], v[88:91]
	v_mfma_f32_16x16x32_bf16 v[88:91], v[150:153], v[188:191], v[88:91]
	v_mfma_f32_16x16x32_bf16 v[72:75], v[150:153], v[196:199], v[72:75]
	v_mfma_f32_16x16x32_bf16 v[72:75], v[154:157], v[200:203], v[72:75]
	v_mfma_f32_16x16x32_bf16 v[76:79], v[146:149], v[200:203], v[76:79]
	v_mfma_f32_16x16x32_bf16 v[76:79], v[136:139], v[196:199], v[76:79]
	s_barrier
	s_add_i32 s42, s33, s20
	s_add_u32 s98, s8, s4
	s_addc_u32 s99, s9, s5
	s_mov_b32 m0, s42
	ds_read_b128 v[204:207], v143
	ds_read_b128 v[208:211], v244
	ds_read_b128 v[212:215], v143 offset:2048
	ds_read_b128 v[240:243], v244 offset:2048
	global_load_lds_dwordx4 v170, s[8:9]
	s_add_i32 m0, s42, 0x2000
	s_nop 0
	global_load_lds_dwordx4 v174, s[8:9]
	s_barrier
	s_waitcnt lgkmcnt(0)
	s_waitcnt lgkmcnt(0)
	v_mfma_f32_16x16x32_bf16 v[116:119], v[204:207], v[158:161], v[116:119]
	v_mfma_f32_16x16x32_bf16 v[116:119], v[208:211], v[176:179], v[116:119]
	v_mfma_f32_16x16x32_bf16 v[112:115], v[240:243], v[176:179], v[112:115]
	v_mfma_f32_16x16x32_bf16 v[112:115], v[212:215], v[158:161], v[112:115]
	v_mfma_f32_16x16x32_bf16 v[96:99], v[212:215], v[180:183], v[96:99]
	v_mfma_f32_16x16x32_bf16 v[96:99], v[240:243], v[184:187], v[96:99]
	v_mfma_f32_16x16x32_bf16 v[100:103], v[208:211], v[184:187], v[100:103]
	v_mfma_f32_16x16x32_bf16 v[100:103], v[204:207], v[180:183], v[100:103]
	v_mfma_f32_16x16x32_bf16 v[84:87], v[204:207], v[188:191], v[84:87]
	v_mfma_f32_16x16x32_bf16 v[84:87], v[208:211], v[192:195], v[84:87]
	v_mfma_f32_16x16x32_bf16 v[80:83], v[240:243], v[192:195], v[80:83]
	v_mfma_f32_16x16x32_bf16 v[80:83], v[212:215], v[188:191], v[80:83]
	v_mfma_f32_16x16x32_bf16 v[64:67], v[212:215], v[196:199], v[64:67]
	v_mfma_f32_16x16x32_bf16 v[64:67], v[240:243], v[200:203], v[64:67]
	v_mfma_f32_16x16x32_bf16 v[68:71], v[208:211], v[200:203], v[68:71]
	v_mfma_f32_16x16x32_bf16 v[68:71], v[204:207], v[196:199], v[68:71]
	s_mov_b32 m0, s21
	s_add_u32 s100, s16, s4
	s_addc_u32 s101, s17, s5
	s_barrier
	ds_read_b128 v[158:161], v142 offset:16384
	ds_read_b128 v[176:179], v217 offset:16384
	ds_read_b128 v[180:183], v142 offset:18432
	ds_read_b128 v[184:187], v217 offset:18432
	ds_read_b128 v[188:191], v142 offset:20480
	ds_read_b128 v[192:195], v217 offset:20480
	ds_read_b128 v[196:199], v142 offset:22528
	ds_read_b128 v[200:203], v217 offset:22528
	global_load_lds_dwordx4 v168, s[16:17]
	s_mov_b32 m0, s22
	s_nop 0
	global_load_lds_dwordx4 v172, s[16:17]
	s_barrier
	s_waitcnt lgkmcnt(0)
	s_waitcnt lgkmcnt(0)
	v_mfma_f32_16x16x32_bf16 v[60:63], v[136:139], v[158:161], v[60:63]
	v_mfma_f32_16x16x32_bf16 v[60:63], v[146:149], v[176:179], v[60:63]
	v_mfma_f32_16x16x32_bf16 v[56:59], v[154:157], v[176:179], v[56:59]
	v_mfma_f32_16x16x32_bf16 v[56:59], v[150:153], v[158:161], v[56:59]
	v_mfma_f32_16x16x32_bf16 v[40:43], v[150:153], v[180:183], v[40:43]
	v_mfma_f32_16x16x32_bf16 v[40:43], v[154:157], v[184:187], v[40:43]
	v_mfma_f32_16x16x32_bf16 v[44:47], v[146:149], v[184:187], v[44:47]
	v_mfma_f32_16x16x32_bf16 v[44:47], v[136:139], v[180:183], v[44:47]
	v_mfma_f32_16x16x32_bf16 v[28:31], v[136:139], v[188:191], v[28:31]
	v_mfma_f32_16x16x32_bf16 v[28:31], v[146:149], v[192:195], v[28:31]
	v_mfma_f32_16x16x32_bf16 v[24:27], v[154:157], v[192:195], v[24:27]
	v_mfma_f32_16x16x32_bf16 v[24:27], v[150:153], v[188:191], v[24:27]
	v_mfma_f32_16x16x32_bf16 v[8:11], v[150:153], v[196:199], v[8:11]
	v_mfma_f32_16x16x32_bf16 v[8:11], v[154:157], v[200:203], v[8:11]
	v_mfma_f32_16x16x32_bf16 v[12:15], v[146:149], v[200:203], v[12:15]
	v_mfma_f32_16x16x32_bf16 v[12:15], v[136:139], v[196:199], v[12:15]
	s_barrier
	s_add_u32 s42, s8, 0x160000
	s_addc_u32 s43, s9, 0
	s_add_i32 s44, s34, s20
	s_mov_b32 m0, s44
	s_nop 0
	global_load_lds_dwordx4 v170, s[42:43]
	s_add_i32 m0, s44, 0x2000
	s_nop 0
	global_load_lds_dwordx4 v174, s[42:43]
	s_waitcnt vmcnt(6)
	s_barrier
	v_mfma_f32_16x16x32_bf16 v[52:55], v[204:207], v[158:161], v[52:55]
	v_mfma_f32_16x16x32_bf16 v[52:55], v[208:211], v[176:179], v[52:55]
	v_mfma_f32_16x16x32_bf16 v[48:51], v[240:243], v[176:179], v[48:51]
	v_mfma_f32_16x16x32_bf16 v[48:51], v[212:215], v[158:161], v[48:51]
	v_mfma_f32_16x16x32_bf16 v[32:35], v[212:215], v[180:183], v[32:35]
	v_mfma_f32_16x16x32_bf16 v[32:35], v[240:243], v[184:187], v[32:35]
	v_mfma_f32_16x16x32_bf16 v[36:39], v[208:211], v[184:187], v[36:39]
	v_mfma_f32_16x16x32_bf16 v[36:39], v[204:207], v[180:183], v[36:39]
	v_mfma_f32_16x16x32_bf16 v[20:23], v[204:207], v[188:191], v[20:23]
	v_mfma_f32_16x16x32_bf16 v[20:23], v[208:211], v[192:195], v[20:23]
	v_mfma_f32_16x16x32_bf16 v[16:19], v[240:243], v[192:195], v[16:19]
	v_mfma_f32_16x16x32_bf16 v[16:19], v[212:215], v[188:191], v[16:19]
	v_mfma_f32_16x16x32_bf16 v[0:3], v[212:215], v[196:199], v[0:3]
	v_mfma_f32_16x16x32_bf16 v[0:3], v[240:243], v[200:203], v[0:3]
	v_mfma_f32_16x16x32_bf16 v[4:7], v[208:211], v[200:203], v[4:7]
	v_mfma_f32_16x16x32_bf16 v[4:7], v[204:207], v[196:199], v[4:7]
	s_add_i32 s42, 0, 0x18000
	s_barrier
	ds_read_b128 v[136:139], v245
	ds_read_b128 v[146:149], v246
	ds_read_b128 v[150:153], v245 offset:2048
	ds_read_b128 v[154:157], v246 offset:2048
	s_add_u32 s16, s16, 0x160000
	s_addc_u32 s17, s17, 0
	s_mov_b32 m0, s23
	ds_read_b128 v[158:161], v142 offset:32768
	ds_read_b128 v[176:179], v217 offset:32768
	ds_read_b128 v[180:183], v142 offset:34816
	ds_read_b128 v[184:187], v217 offset:34816
	ds_read_b128 v[188:191], v142 offset:36864
	ds_read_b128 v[192:195], v217 offset:36864
	ds_read_b128 v[196:199], v142 offset:38912
	ds_read_b128 v[200:203], v217 offset:38912
	global_load_lds_dwordx4 v168, s[16:17]
	s_mov_b32 m0, s24
	s_nop 0
	global_load_lds_dwordx4 v172, s[16:17]
	s_waitcnt lgkmcnt(8)
	s_barrier
	s_waitcnt lgkmcnt(0)
	s_waitcnt lgkmcnt(0)
	v_mfma_f32_16x16x32_bf16 v[124:127], v[136:139], v[158:161], v[124:127]
	v_mfma_f32_16x16x32_bf16 v[124:127], v[146:149], v[176:179], v[124:127]
	v_mfma_f32_16x16x32_bf16 v[120:123], v[154:157], v[176:179], v[120:123]
	v_mfma_f32_16x16x32_bf16 v[120:123], v[150:153], v[158:161], v[120:123]
	v_mfma_f32_16x16x32_bf16 v[104:107], v[150:153], v[180:183], v[104:107]
	v_mfma_f32_16x16x32_bf16 v[104:107], v[154:157], v[184:187], v[104:107]
	v_mfma_f32_16x16x32_bf16 v[108:111], v[146:149], v[184:187], v[108:111]
	v_mfma_f32_16x16x32_bf16 v[108:111], v[136:139], v[180:183], v[108:111]
	v_mfma_f32_16x16x32_bf16 v[92:95], v[136:139], v[188:191], v[92:95]
	v_mfma_f32_16x16x32_bf16 v[92:95], v[146:149], v[192:195], v[92:95]
	v_mfma_f32_16x16x32_bf16 v[88:91], v[154:157], v[192:195], v[88:91]
	v_mfma_f32_16x16x32_bf16 v[88:91], v[150:153], v[188:191], v[88:91]
	v_mfma_f32_16x16x32_bf16 v[72:75], v[150:153], v[196:199], v[72:75]
	v_mfma_f32_16x16x32_bf16 v[72:75], v[154:157], v[200:203], v[72:75]
	v_mfma_f32_16x16x32_bf16 v[76:79], v[146:149], v[200:203], v[76:79]
	v_mfma_f32_16x16x32_bf16 v[76:79], v[136:139], v[196:199], v[76:79]
	s_barrier
	s_add_i32 s16, 0, 0x1c000
	s_add_i32 s17, s42, s20
	v_add_u32_e32 v145, s16, v140
	s_mov_b32 m0, s17
	ds_read_b128 v[204:207], v145
	v_xor_b32_e32 v243, 64, v145
	ds_read_b128 v[208:211], v243
	ds_read_b128 v[212:215], v145 offset:2048
	ds_read_b128 v[240:243], v243 offset:2048
	global_load_lds_dwordx4 v170, s[98:99]
	s_add_i32 m0, s17, 0x2000
	s_nop 0
	global_load_lds_dwordx4 v174, s[98:99]
	s_barrier
	s_waitcnt lgkmcnt(0)
	s_waitcnt lgkmcnt(0)
	v_mfma_f32_16x16x32_bf16 v[116:119], v[204:207], v[158:161], v[116:119]
	v_mfma_f32_16x16x32_bf16 v[116:119], v[208:211], v[176:179], v[116:119]
	v_mfma_f32_16x16x32_bf16 v[112:115], v[240:243], v[176:179], v[112:115]
	v_mfma_f32_16x16x32_bf16 v[112:115], v[212:215], v[158:161], v[112:115]
	v_mfma_f32_16x16x32_bf16 v[96:99], v[212:215], v[180:183], v[96:99]
	v_mfma_f32_16x16x32_bf16 v[96:99], v[240:243], v[184:187], v[96:99]
	v_mfma_f32_16x16x32_bf16 v[100:103], v[208:211], v[184:187], v[100:103]
	v_mfma_f32_16x16x32_bf16 v[100:103], v[204:207], v[180:183], v[100:103]
	v_mfma_f32_16x16x32_bf16 v[84:87], v[204:207], v[188:191], v[84:87]
	v_mfma_f32_16x16x32_bf16 v[84:87], v[208:211], v[192:195], v[84:87]
	v_mfma_f32_16x16x32_bf16 v[80:83], v[240:243], v[192:195], v[80:83]
	v_mfma_f32_16x16x32_bf16 v[80:83], v[212:215], v[188:191], v[80:83]
	v_mfma_f32_16x16x32_bf16 v[64:67], v[212:215], v[196:199], v[64:67]
	v_mfma_f32_16x16x32_bf16 v[64:67], v[240:243], v[200:203], v[64:67]
	v_mfma_f32_16x16x32_bf16 v[68:71], v[208:211], v[200:203], v[68:71]
	v_mfma_f32_16x16x32_bf16 v[68:71], v[204:207], v[196:199], v[68:71]
	s_mov_b32 m0, s28
	s_barrier
	ds_read_b128 v[158:161], v142 offset:49152
	ds_read_b128 v[176:179], v217 offset:49152
	ds_read_b128 v[180:183], v142 offset:51200
	ds_read_b128 v[184:187], v217 offset:51200
	ds_read_b128 v[188:191], v142 offset:53248
	ds_read_b128 v[192:195], v217 offset:53248
	ds_read_b128 v[196:199], v142 offset:55296
	ds_read_b128 v[200:203], v217 offset:55296
	global_load_lds_dwordx4 v168, s[100:101]
	s_mov_b32 m0, s29
	s_nop 0
	global_load_lds_dwordx4 v172, s[100:101]
	s_barrier
	s_waitcnt lgkmcnt(0)
	s_waitcnt lgkmcnt(0)
	v_mfma_f32_16x16x32_bf16 v[60:63], v[136:139], v[158:161], v[60:63]
	v_mfma_f32_16x16x32_bf16 v[60:63], v[146:149], v[176:179], v[60:63]
	v_mfma_f32_16x16x32_bf16 v[56:59], v[154:157], v[176:179], v[56:59]
	v_mfma_f32_16x16x32_bf16 v[56:59], v[150:153], v[158:161], v[56:59]
	v_mfma_f32_16x16x32_bf16 v[40:43], v[150:153], v[180:183], v[40:43]
	v_mfma_f32_16x16x32_bf16 v[40:43], v[154:157], v[184:187], v[40:43]
	v_mfma_f32_16x16x32_bf16 v[44:47], v[146:149], v[184:187], v[44:47]
	v_mfma_f32_16x16x32_bf16 v[44:47], v[136:139], v[180:183], v[44:47]
	v_mfma_f32_16x16x32_bf16 v[28:31], v[136:139], v[188:191], v[28:31]
	v_mfma_f32_16x16x32_bf16 v[28:31], v[146:149], v[192:195], v[28:31]
	v_mfma_f32_16x16x32_bf16 v[24:27], v[154:157], v[192:195], v[24:27]
	v_mfma_f32_16x16x32_bf16 v[24:27], v[150:153], v[188:191], v[24:27]
	v_mfma_f32_16x16x32_bf16 v[8:11], v[150:153], v[196:199], v[8:11]
	v_mfma_f32_16x16x32_bf16 v[8:11], v[154:157], v[200:203], v[8:11]
	v_mfma_f32_16x16x32_bf16 v[12:15], v[146:149], v[200:203], v[12:15]
	v_mfma_f32_16x16x32_bf16 v[12:15], v[136:139], v[196:199], v[12:15]
	s_barrier
	s_add_u32 s8, s8, 0x160080
	s_addc_u32 s9, s9, 0
	s_add_i32 s16, s16, s20
	s_mov_b32 m0, s16
	s_nop 0
	global_load_lds_dwordx4 v170, s[8:9]
	s_add_i32 m0, s16, 0x2000
	s_nop 0
	global_load_lds_dwordx4 v174, s[8:9]
	s_waitcnt vmcnt(6)
	s_barrier
	v_mfma_f32_16x16x32_bf16 v[52:55], v[204:207], v[158:161], v[52:55]
	v_mfma_f32_16x16x32_bf16 v[52:55], v[208:211], v[176:179], v[52:55]
	v_mfma_f32_16x16x32_bf16 v[48:51], v[240:243], v[176:179], v[48:51]
	v_mfma_f32_16x16x32_bf16 v[48:51], v[212:215], v[158:161], v[48:51]
	v_mfma_f32_16x16x32_bf16 v[32:35], v[212:215], v[180:183], v[32:35]
	v_mfma_f32_16x16x32_bf16 v[32:35], v[240:243], v[184:187], v[32:35]
	v_mfma_f32_16x16x32_bf16 v[36:39], v[208:211], v[184:187], v[36:39]
	v_mfma_f32_16x16x32_bf16 v[36:39], v[204:207], v[180:183], v[36:39]
	v_mfma_f32_16x16x32_bf16 v[20:23], v[204:207], v[188:191], v[20:23]
	v_mfma_f32_16x16x32_bf16 v[20:23], v[208:211], v[192:195], v[20:23]
	v_mfma_f32_16x16x32_bf16 v[16:19], v[240:243], v[192:195], v[16:19]
	v_mfma_f32_16x16x32_bf16 v[16:19], v[212:215], v[188:191], v[16:19]
	v_mfma_f32_16x16x32_bf16 v[0:3], v[212:215], v[196:199], v[0:3]
	v_mfma_f32_16x16x32_bf16 v[0:3], v[240:243], v[200:203], v[0:3]
	v_mfma_f32_16x16x32_bf16 v[4:7], v[208:211], v[200:203], v[4:7]
	v_mfma_f32_16x16x32_bf16 v[4:7], v[204:207], v[196:199], v[4:7]
	s_add_i32 s41, s41, 2
	s_add_u32 s0, s0, 0x100
	s_addc_u32 s1, s1, 0
	s_add_u32 s39, s39, 0x100
	s_addc_u32 s40, s40, 0
	s_cmpk_gt_u32 s41, 0x55
	s_barrier
	s_cbranch_scc0 .LBB0_508
	s_cmpk_gt_u32 s3, 0xff
	s_cbranch_scc1 .Lst_out_s4
	s_barrier
.Lst_out_s4:
	v_lshl_add_u32 v217, s38, 8, v163
	v_add_u32_e32 v217, s26, v217
	v_lshlrev_b32_e32 v208, 2, v217
	v_lshl_add_u32 v214, v225, 3, s27
	v_lshl_add_u32 v214, s37, 8, v214
	v_lshl_add_u32 v209, v217, 11, v214
	v_lshlrev_b32_e32 v209, 1, v209
	v_lshlrev_b32_e32 v210, 1, v209
	v_lshl_add_u32 v217, v225, 4, v163
	v_xor_b32_e32 v215, 16, v217
	v_lshlrev_b32_e32 v215, 2, v215
	v_xor_b32_e32 v216, 32, v217
	v_lshlrev_b32_e32 v216, 2, v216
	v_add_u32_e32 v211, 0x0, v209
	global_load_dwordx4 v[176:179], v211, s[80:81]
	global_load_dwordx4 v[180:183], v211, s[80:81] offset:256
	v_add_u32_e32 v211, 0x10000, v209
	global_load_dwordx4 v[192:195], v211, s[80:81]
	global_load_dwordx4 v[196:199], v211, s[80:81] offset:256
	s_waitcnt vmcnt(2)
	v_lshlrev_b32_e32 v184, 16, v176
	v_and_b32_e32 v185, 0xffff0000, v176
	v_lshlrev_b32_e32 v186, 16, v177
	v_and_b32_e32 v187, 0xffff0000, v177
	v_lshlrev_b32_e32 v188, 16, v178
	v_and_b32_e32 v189, 0xffff0000, v178
	v_lshlrev_b32_e32 v190, 16, v179
	v_and_b32_e32 v191, 0xffff0000, v179
	v_pk_add_f32 v[124:125], v[124:125], v[184:185]
	v_pk_add_f32 v[126:127], v[126:127], v[186:187]
	v_pk_add_f32 v[120:121], v[120:121], v[188:189]
	v_pk_add_f32 v[122:123], v[122:123], v[190:191]
	v_mul_f32_e32 v213, v124, v124
	v_fmac_f32_e32 v213, v125, v125
	v_fmac_f32_e32 v213, v126, v126
	v_fmac_f32_e32 v213, v127, v127
	v_fmac_f32_e32 v213, v120, v120
	v_fmac_f32_e32 v213, v121, v121
	v_fmac_f32_e32 v213, v122, v122
	v_fmac_f32_e32 v213, v123, v123
	v_cvt_pk_bf16_f32 v176, v124, v125
	v_cvt_pk_bf16_f32 v177, v126, v127
	v_cvt_pk_bf16_f32 v178, v120, v121
	v_cvt_pk_bf16_f32 v179, v122, v123
	v_add_u32_e32 v217, 0x0, v209
	global_store_dwordx4 v217, v[176:179], s[80:81]
	v_lshlrev_b32_e32 v184, 16, v180
	v_and_b32_e32 v185, 0xffff0000, v180
	v_lshlrev_b32_e32 v186, 16, v181
	v_and_b32_e32 v187, 0xffff0000, v181
	v_lshlrev_b32_e32 v188, 16, v182
	v_and_b32_e32 v189, 0xffff0000, v182
	v_lshlrev_b32_e32 v190, 16, v183
	v_and_b32_e32 v191, 0xffff0000, v183
	v_pk_add_f32 v[116:117], v[116:117], v[184:185]
	v_pk_add_f32 v[118:119], v[118:119], v[186:187]
	v_pk_add_f32 v[112:113], v[112:113], v[188:189]
	v_pk_add_f32 v[114:115], v[114:115], v[190:191]
	v_fmac_f32_e32 v213, v116, v116
	v_fmac_f32_e32 v213, v117, v117
	v_fmac_f32_e32 v213, v118, v118
	v_fmac_f32_e32 v213, v119, v119
	v_fmac_f32_e32 v213, v112, v112
	v_fmac_f32_e32 v213, v113, v113
	v_fmac_f32_e32 v213, v114, v114
	v_fmac_f32_e32 v213, v115, v115
	v_cvt_pk_bf16_f32 v180, v116, v117
	v_cvt_pk_bf16_f32 v181, v118, v119
	v_cvt_pk_bf16_f32 v182, v112, v113
	v_cvt_pk_bf16_f32 v183, v114, v115
	global_store_dwordx4 v217, v[180:183], s[80:81] offset:256
	ds_bpermute_b32 v214, v215, v213
	s_waitcnt lgkmcnt(0)
	v_add_f32_e32 v213, v213, v214
	ds_bpermute_b32 v214, v216, v213
	s_waitcnt lgkmcnt(0)
	v_add_f32_e32 v213, v213, v214
	s_mov_b64 exec, 0xffff
	global_atomic_add_f32 v208, v213, s[14:15]
	s_mov_b64 exec, -1
	v_add_u32_e32 v211, 0x20000, v209
	global_load_dwordx4 v[176:179], v211, s[80:81]
	global_load_dwordx4 v[180:183], v211, s[80:81] offset:256
	s_waitcnt vmcnt(5)
	v_lshlrev_b32_e32 v200, 16, v192
	v_and_b32_e32 v201, 0xffff0000, v192
	v_lshlrev_b32_e32 v202, 16, v193
	v_and_b32_e32 v203, 0xffff0000, v193
	v_lshlrev_b32_e32 v204, 16, v194
	v_and_b32_e32 v205, 0xffff0000, v194
	v_lshlrev_b32_e32 v206, 16, v195
	v_and_b32_e32 v207, 0xffff0000, v195
	v_pk_add_f32 v[108:109], v[108:109], v[200:201]
	v_pk_add_f32 v[110:111], v[110:111], v[202:203]
	v_pk_add_f32 v[104:105], v[104:105], v[204:205]
	v_pk_add_f32 v[106:107], v[106:107], v[206:207]
	v_mul_f32_e32 v213, v108, v108
	v_fmac_f32_e32 v213, v109, v109
	v_fmac_f32_e32 v213, v110, v110
	v_fmac_f32_e32 v213, v111, v111
	v_fmac_f32_e32 v213, v104, v104
	v_fmac_f32_e32 v213, v105, v105
	v_fmac_f32_e32 v213, v106, v106
	v_fmac_f32_e32 v213, v107, v107
	v_cvt_pk_bf16_f32 v192, v108, v109
	v_cvt_pk_bf16_f32 v193, v110, v111
	v_cvt_pk_bf16_f32 v194, v104, v105
	v_cvt_pk_bf16_f32 v195, v106, v107
	v_add_u32_e32 v217, 0x10000, v209
	global_store_dwordx4 v217, v[192:195], s[80:81]
	v_lshlrev_b32_e32 v200, 16, v196
	v_and_b32_e32 v201, 0xffff0000, v196
	v_lshlrev_b32_e32 v202, 16, v197
	v_and_b32_e32 v203, 0xffff0000, v197
	v_lshlrev_b32_e32 v204, 16, v198
	v_and_b32_e32 v205, 0xffff0000, v198
	v_lshlrev_b32_e32 v206, 16, v199
	v_and_b32_e32 v207, 0xffff0000, v199
	v_pk_add_f32 v[100:101], v[100:101], v[200:201]
	v_pk_add_f32 v[102:103], v[102:103], v[202:203]
	v_pk_add_f32 v[96:97], v[96:97], v[204:205]
	v_pk_add_f32 v[98:99], v[98:99], v[206:207]
	v_fmac_f32_e32 v213, v100, v100
	v_fmac_f32_e32 v213, v101, v101
	v_fmac_f32_e32 v213, v102, v102
	v_fmac_f32_e32 v213, v103, v103
	v_fmac_f32_e32 v213, v96, v96
	v_fmac_f32_e32 v213, v97, v97
	v_fmac_f32_e32 v213, v98, v98
	v_fmac_f32_e32 v213, v99, v99
	v_cvt_pk_bf16_f32 v196, v100, v101
	v_cvt_pk_bf16_f32 v197, v102, v103
	v_cvt_pk_bf16_f32 v198, v96, v97
	v_cvt_pk_bf16_f32 v199, v98, v99
	global_store_dwordx4 v217, v[196:199], s[80:81] offset:256
	ds_bpermute_b32 v214, v215, v213
	s_waitcnt lgkmcnt(0)
	v_add_f32_e32 v213, v213, v214
	ds_bpermute_b32 v214, v216, v213
	s_waitcnt lgkmcnt(0)
	v_add_f32_e32 v213, v213, v214
	s_mov_b64 exec, 0xffff
	global_atomic_add_f32 v208, v213, s[14:15] offset:64
	s_mov_b64 exec, -1
	v_add_u32_e32 v211, 0x30000, v209
	global_load_dwordx4 v[192:195], v211, s[80:81]
	global_load_dwordx4 v[196:199], v211, s[80:81] offset:256
	s_waitcnt vmcnt(5)
	v_lshlrev_b32_e32 v184, 16, v176
	v_and_b32_e32 v185, 0xffff0000, v176
	v_lshlrev_b32_e32 v186, 16, v177
	v_and_b32_e32 v187, 0xffff0000, v177
	v_lshlrev_b32_e32 v188, 16, v178
	v_and_b32_e32 v189, 0xffff0000, v178
	v_lshlrev_b32_e32 v190, 16, v179
	v_and_b32_e32 v191, 0xffff0000, v179
	v_pk_add_f32 v[92:93], v[92:93], v[184:185]
	v_pk_add_f32 v[94:95], v[94:95], v[186:187]
	v_pk_add_f32 v[88:89], v[88:89], v[188:189]
	v_pk_add_f32 v[90:91], v[90:91], v[190:191]
	v_mul_f32_e32 v213, v92, v92
	v_fmac_f32_e32 v213, v93, v93
	v_fmac_f32_e32 v213, v94, v94
	v_fmac_f32_e32 v213, v95, v95
	v_fmac_f32_e32 v213, v88, v88
	v_fmac_f32_e32 v213, v89, v89
	v_fmac_f32_e32 v213, v90, v90
	v_fmac_f32_e32 v213, v91, v91
	v_cvt_pk_bf16_f32 v176, v92, v93
	v_cvt_pk_bf16_f32 v177, v94, v95
	v_cvt_pk_bf16_f32 v178, v88, v89
	v_cvt_pk_bf16_f32 v179, v90, v91
	v_add_u32_e32 v217, 0x20000, v209
	global_store_dwordx4 v217, v[176:179], s[80:81]
	v_lshlrev_b32_e32 v184, 16, v180
	v_and_b32_e32 v185, 0xffff0000, v180
	v_lshlrev_b32_e32 v186, 16, v181
	v_and_b32_e32 v187, 0xffff0000, v181
	v_lshlrev_b32_e32 v188, 16, v182
	v_and_b32_e32 v189, 0xffff0000, v182
	v_lshlrev_b32_e32 v190, 16, v183
	v_and_b32_e32 v191, 0xffff0000, v183
	v_pk_add_f32 v[84:85], v[84:85], v[184:185]
	v_pk_add_f32 v[86:87], v[86:87], v[186:187]
	v_pk_add_f32 v[80:81], v[80:81], v[188:189]
	v_pk_add_f32 v[82:83], v[82:83], v[190:191]
	v_fmac_f32_e32 v213, v84, v84
	v_fmac_f32_e32 v213, v85, v85
	v_fmac_f32_e32 v213, v86, v86
	v_fmac_f32_e32 v213, v87, v87
	v_fmac_f32_e32 v213, v80, v80
	v_fmac_f32_e32 v213, v81, v81
	v_fmac_f32_e32 v213, v82, v82
	v_fmac_f32_e32 v213, v83, v83
	v_cvt_pk_bf16_f32 v180, v84, v85
	v_cvt_pk_bf16_f32 v181, v86, v87
	v_cvt_pk_bf16_f32 v182, v80, v81
	v_cvt_pk_bf16_f32 v183, v82, v83
	global_store_dwordx4 v217, v[180:183], s[80:81] offset:256
	ds_bpermute_b32 v214, v215, v213
	s_waitcnt lgkmcnt(0)
	v_add_f32_e32 v213, v213, v214
	ds_bpermute_b32 v214, v216, v213
	s_waitcnt lgkmcnt(0)
	v_add_f32_e32 v213, v213, v214
	s_mov_b64 exec, 0xffff
	global_atomic_add_f32 v208, v213, s[14:15] offset:128
	s_mov_b64 exec, -1
	v_add_u32_e32 v211, 0x80000, v209
	global_load_dwordx4 v[176:179], v211, s[80:81]
	global_load_dwordx4 v[180:183], v211, s[80:81] offset:256
	s_waitcnt vmcnt(5)
	v_lshlrev_b32_e32 v200, 16, v192
	v_and_b32_e32 v201, 0xffff0000, v192
	v_lshlrev_b32_e32 v202, 16, v193
	v_and_b32_e32 v203, 0xffff0000, v193
	v_lshlrev_b32_e32 v204, 16, v194
	v_and_b32_e32 v205, 0xffff0000, v194
	v_lshlrev_b32_e32 v206, 16, v195
	v_and_b32_e32 v207, 0xffff0000, v195
	v_pk_add_f32 v[76:77], v[76:77], v[200:201]
	v_pk_add_f32 v[78:79], v[78:79], v[202:203]
	v_pk_add_f32 v[72:73], v[72:73], v[204:205]
	v_pk_add_f32 v[74:75], v[74:75], v[206:207]
	v_mul_f32_e32 v213, v76, v76
	v_fmac_f32_e32 v213, v77, v77
	v_fmac_f32_e32 v213, v78, v78
	v_fmac_f32_e32 v213, v79, v79
	v_fmac_f32_e32 v213, v72, v72
	v_fmac_f32_e32 v213, v73, v73
	v_fmac_f32_e32 v213, v74, v74
	v_fmac_f32_e32 v213, v75, v75
	v_cvt_pk_bf16_f32 v192, v76, v77
	v_cvt_pk_bf16_f32 v193, v78, v79
	v_cvt_pk_bf16_f32 v194, v72, v73
	v_cvt_pk_bf16_f32 v195, v74, v75
	v_add_u32_e32 v217, 0x30000, v209
	global_store_dwordx4 v217, v[192:195], s[80:81]
	v_lshlrev_b32_e32 v200, 16, v196
	v_and_b32_e32 v201, 0xffff0000, v196
	v_lshlrev_b32_e32 v202, 16, v197
	v_and_b32_e32 v203, 0xffff0000, v197
	v_lshlrev_b32_e32 v204, 16, v198
	v_and_b32_e32 v205, 0xffff0000, v198
	v_lshlrev_b32_e32 v206, 16, v199
	v_and_b32_e32 v207, 0xffff0000, v199
	v_pk_add_f32 v[68:69], v[68:69], v[200:201]
	v_pk_add_f32 v[70:71], v[70:71], v[202:203]
	v_pk_add_f32 v[64:65], v[64:65], v[204:205]
	v_pk_add_f32 v[66:67], v[66:67], v[206:207]
	v_fmac_f32_e32 v213, v68, v68
	v_fmac_f32_e32 v213, v69, v69
	v_fmac_f32_e32 v213, v70, v70
	v_fmac_f32_e32 v213, v71, v71
	v_fmac_f32_e32 v213, v64, v64
	v_fmac_f32_e32 v213, v65, v65
	v_fmac_f32_e32 v213, v66, v66
	v_fmac_f32_e32 v213, v67, v67
	v_cvt_pk_bf16_f32 v196, v68, v69
	v_cvt_pk_bf16_f32 v197, v70, v71
	v_cvt_pk_bf16_f32 v198, v64, v65
	v_cvt_pk_bf16_f32 v199, v66, v67
	global_store_dwordx4 v217, v[196:199], s[80:81] offset:256
	ds_bpermute_b32 v214, v215, v213
	s_waitcnt lgkmcnt(0)
	v_add_f32_e32 v213, v213, v214
	ds_bpermute_b32 v214, v216, v213
	s_waitcnt lgkmcnt(0)
	v_add_f32_e32 v213, v213, v214
	s_mov_b64 exec, 0xffff
	global_atomic_add_f32 v208, v213, s[14:15] offset:192
	s_mov_b64 exec, -1
	v_add_u32_e32 v211, 0x90000, v209
	global_load_dwordx4 v[192:195], v211, s[80:81]
	global_load_dwordx4 v[196:199], v211, s[80:81] offset:256
	s_waitcnt vmcnt(5)
	v_lshlrev_b32_e32 v184, 16, v176
	v_and_b32_e32 v185, 0xffff0000, v176
	v_lshlrev_b32_e32 v186, 16, v177
	v_and_b32_e32 v187, 0xffff0000, v177
	v_lshlrev_b32_e32 v188, 16, v178
	v_and_b32_e32 v189, 0xffff0000, v178
	v_lshlrev_b32_e32 v190, 16, v179
	v_and_b32_e32 v191, 0xffff0000, v179
	v_pk_add_f32 v[60:61], v[60:61], v[184:185]
	v_pk_add_f32 v[62:63], v[62:63], v[186:187]
	v_pk_add_f32 v[56:57], v[56:57], v[188:189]
	v_pk_add_f32 v[58:59], v[58:59], v[190:191]
	v_mul_f32_e32 v213, v60, v60
	v_fmac_f32_e32 v213, v61, v61
	v_fmac_f32_e32 v213, v62, v62
	v_fmac_f32_e32 v213, v63, v63
	v_fmac_f32_e32 v213, v56, v56
	v_fmac_f32_e32 v213, v57, v57
	v_fmac_f32_e32 v213, v58, v58
	v_fmac_f32_e32 v213, v59, v59
	v_cvt_pk_bf16_f32 v176, v60, v61
	v_cvt_pk_bf16_f32 v177, v62, v63
	v_cvt_pk_bf16_f32 v178, v56, v57
	v_cvt_pk_bf16_f32 v179, v58, v59
	v_add_u32_e32 v217, 0x80000, v209
	global_store_dwordx4 v217, v[176:179], s[80:81]
	v_lshlrev_b32_e32 v184, 16, v180
	v_and_b32_e32 v185, 0xffff0000, v180
	v_lshlrev_b32_e32 v186, 16, v181
	v_and_b32_e32 v187, 0xffff0000, v181
	v_lshlrev_b32_e32 v188, 16, v182
	v_and_b32_e32 v189, 0xffff0000, v182
	v_lshlrev_b32_e32 v190, 16, v183
	v_and_b32_e32 v191, 0xffff0000, v183
	v_pk_add_f32 v[52:53], v[52:53], v[184:185]
	v_pk_add_f32 v[54:55], v[54:55], v[186:187]
	v_pk_add_f32 v[48:49], v[48:49], v[188:189]
	v_pk_add_f32 v[50:51], v[50:51], v[190:191]
	v_fmac_f32_e32 v213, v52, v52
	v_fmac_f32_e32 v213, v53, v53
	v_fmac_f32_e32 v213, v54, v54
	v_fmac_f32_e32 v213, v55, v55
	v_fmac_f32_e32 v213, v48, v48
	v_fmac_f32_e32 v213, v49, v49
	v_fmac_f32_e32 v213, v50, v50
	v_fmac_f32_e32 v213, v51, v51
	v_cvt_pk_bf16_f32 v180, v52, v53
	v_cvt_pk_bf16_f32 v181, v54, v55
	v_cvt_pk_bf16_f32 v182, v48, v49
	v_cvt_pk_bf16_f32 v183, v50, v51
	global_store_dwordx4 v217, v[180:183], s[80:81] offset:256
	ds_bpermute_b32 v214, v215, v213
	s_waitcnt lgkmcnt(0)
	v_add_f32_e32 v213, v213, v214
	ds_bpermute_b32 v214, v216, v213
	s_waitcnt lgkmcnt(0)
	v_add_f32_e32 v213, v213, v214
	s_mov_b64 exec, 0xffff
	global_atomic_add_f32 v208, v213, s[14:15] offset:512
	s_mov_b64 exec, -1
	v_add_u32_e32 v211, 0xa0000, v209
	global_load_dwordx4 v[176:179], v211, s[80:81]
	global_load_dwordx4 v[180:183], v211, s[80:81] offset:256
	s_waitcnt vmcnt(5)
	v_lshlrev_b32_e32 v200, 16, v192
	v_and_b32_e32 v201, 0xffff0000, v192
	v_lshlrev_b32_e32 v202, 16, v193
	v_and_b32_e32 v203, 0xffff0000, v193
	v_lshlrev_b32_e32 v204, 16, v194
	v_and_b32_e32 v205, 0xffff0000, v194
	v_lshlrev_b32_e32 v206, 16, v195
	v_and_b32_e32 v207, 0xffff0000, v195
	v_pk_add_f32 v[44:45], v[44:45], v[200:201]
	v_pk_add_f32 v[46:47], v[46:47], v[202:203]
	v_pk_add_f32 v[40:41], v[40:41], v[204:205]
	v_pk_add_f32 v[42:43], v[42:43], v[206:207]
	v_mul_f32_e32 v213, v44, v44
	v_fmac_f32_e32 v213, v45, v45
	v_fmac_f32_e32 v213, v46, v46
	v_fmac_f32_e32 v213, v47, v47
	v_fmac_f32_e32 v213, v40, v40
	v_fmac_f32_e32 v213, v41, v41
	v_fmac_f32_e32 v213, v42, v42
	v_fmac_f32_e32 v213, v43, v43
	v_cvt_pk_bf16_f32 v192, v44, v45
	v_cvt_pk_bf16_f32 v193, v46, v47
	v_cvt_pk_bf16_f32 v194, v40, v41
	v_cvt_pk_bf16_f32 v195, v42, v43
	v_add_u32_e32 v217, 0x90000, v209
	global_store_dwordx4 v217, v[192:195], s[80:81]
	v_lshlrev_b32_e32 v200, 16, v196
	v_and_b32_e32 v201, 0xffff0000, v196
	v_lshlrev_b32_e32 v202, 16, v197
	v_and_b32_e32 v203, 0xffff0000, v197
	v_lshlrev_b32_e32 v204, 16, v198
	v_and_b32_e32 v205, 0xffff0000, v198
	v_lshlrev_b32_e32 v206, 16, v199
	v_and_b32_e32 v207, 0xffff0000, v199
	v_pk_add_f32 v[36:37], v[36:37], v[200:201]
	v_pk_add_f32 v[38:39], v[38:39], v[202:203]
	v_pk_add_f32 v[32:33], v[32:33], v[204:205]
	v_pk_add_f32 v[34:35], v[34:35], v[206:207]
	v_fmac_f32_e32 v213, v36, v36
	v_fmac_f32_e32 v213, v37, v37
	v_fmac_f32_e32 v213, v38, v38
	v_fmac_f32_e32 v213, v39, v39
	v_fmac_f32_e32 v213, v32, v32
	v_fmac_f32_e32 v213, v33, v33
	v_fmac_f32_e32 v213, v34, v34
	v_fmac_f32_e32 v213, v35, v35
	v_cvt_pk_bf16_f32 v196, v36, v37
	v_cvt_pk_bf16_f32 v197, v38, v39
	v_cvt_pk_bf16_f32 v198, v32, v33
	v_cvt_pk_bf16_f32 v199, v34, v35
	global_store_dwordx4 v217, v[196:199], s[80:81] offset:256
	ds_bpermute_b32 v214, v215, v213
	s_waitcnt lgkmcnt(0)
	v_add_f32_e32 v213, v213, v214
	ds_bpermute_b32 v214, v216, v213
	s_waitcnt lgkmcnt(0)
	v_add_f32_e32 v213, v213, v214
	s_mov_b64 exec, 0xffff
	global_atomic_add_f32 v208, v213, s[14:15] offset:576
	s_mov_b64 exec, -1
	v_add_u32_e32 v211, 0xb0000, v209
	global_load_dwordx4 v[192:195], v211, s[80:81]
	global_load_dwordx4 v[196:199], v211, s[80:81] offset:256
	s_waitcnt vmcnt(5)
	v_lshlrev_b32_e32 v184, 16, v176
	v_and_b32_e32 v185, 0xffff0000, v176
	v_lshlrev_b32_e32 v186, 16, v177
	v_and_b32_e32 v187, 0xffff0000, v177
	v_lshlrev_b32_e32 v188, 16, v178
	v_and_b32_e32 v189, 0xffff0000, v178
	v_lshlrev_b32_e32 v190, 16, v179
	v_and_b32_e32 v191, 0xffff0000, v179
	v_pk_add_f32 v[28:29], v[28:29], v[184:185]
	v_pk_add_f32 v[30:31], v[30:31], v[186:187]
	v_pk_add_f32 v[24:25], v[24:25], v[188:189]
	v_pk_add_f32 v[26:27], v[26:27], v[190:191]
	v_mul_f32_e32 v213, v28, v28
	v_fmac_f32_e32 v213, v29, v29
	v_fmac_f32_e32 v213, v30, v30
	v_fmac_f32_e32 v213, v31, v31
	v_fmac_f32_e32 v213, v24, v24
	v_fmac_f32_e32 v213, v25, v25
	v_fmac_f32_e32 v213, v26, v26
	v_fmac_f32_e32 v213, v27, v27
	v_cvt_pk_bf16_f32 v176, v28, v29
	v_cvt_pk_bf16_f32 v177, v30, v31
	v_cvt_pk_bf16_f32 v178, v24, v25
	v_cvt_pk_bf16_f32 v179, v26, v27
	v_add_u32_e32 v217, 0xa0000, v209
	global_store_dwordx4 v217, v[176:179], s[80:81]
	v_lshlrev_b32_e32 v184, 16, v180
	v_and_b32_e32 v185, 0xffff0000, v180
	v_lshlrev_b32_e32 v186, 16, v181
	v_and_b32_e32 v187, 0xffff0000, v181
	v_lshlrev_b32_e32 v188, 16, v182
	v_and_b32_e32 v189, 0xffff0000, v182
	v_lshlrev_b32_e32 v190, 16, v183
	v_and_b32_e32 v191, 0xffff0000, v183
	v_pk_add_f32 v[20:21], v[20:21], v[184:185]
	v_pk_add_f32 v[22:23], v[22:23], v[186:187]
	v_pk_add_f32 v[16:17], v[16:17], v[188:189]
	v_pk_add_f32 v[18:19], v[18:19], v[190:191]
	v_fmac_f32_e32 v213, v20, v20
	v_fmac_f32_e32 v213, v21, v21
	v_fmac_f32_e32 v213, v22, v22
	v_fmac_f32_e32 v213, v23, v23
	v_fmac_f32_e32 v213, v16, v16
	v_fmac_f32_e32 v213, v17, v17
	v_fmac_f32_e32 v213, v18, v18
	v_fmac_f32_e32 v213, v19, v19
	v_cvt_pk_bf16_f32 v180, v20, v21
	v_cvt_pk_bf16_f32 v181, v22, v23
	v_cvt_pk_bf16_f32 v182, v16, v17
	v_cvt_pk_bf16_f32 v183, v18, v19
	global_store_dwordx4 v217, v[180:183], s[80:81] offset:256
	ds_bpermute_b32 v214, v215, v213
	s_waitcnt lgkmcnt(0)
	v_add_f32_e32 v213, v213, v214
	ds_bpermute_b32 v214, v216, v213
	s_waitcnt lgkmcnt(0)
	v_add_f32_e32 v213, v213, v214
	s_mov_b64 exec, 0xffff
	global_atomic_add_f32 v208, v213, s[14:15] offset:640
	s_mov_b64 exec, -1
	s_waitcnt vmcnt(3)
	v_lshlrev_b32_e32 v200, 16, v192
	v_and_b32_e32 v201, 0xffff0000, v192
	v_lshlrev_b32_e32 v202, 16, v193
	v_and_b32_e32 v203, 0xffff0000, v193
	v_lshlrev_b32_e32 v204, 16, v194
	v_and_b32_e32 v205, 0xffff0000, v194
	v_lshlrev_b32_e32 v206, 16, v195
	v_and_b32_e32 v207, 0xffff0000, v195
	v_pk_add_f32 v[12:13], v[12:13], v[200:201]
	v_pk_add_f32 v[14:15], v[14:15], v[202:203]
	v_pk_add_f32 v[8:9], v[8:9], v[204:205]
	v_pk_add_f32 v[10:11], v[10:11], v[206:207]
	v_mul_f32_e32 v213, v12, v12
	v_fmac_f32_e32 v213, v13, v13
	v_fmac_f32_e32 v213, v14, v14
	v_fmac_f32_e32 v213, v15, v15
	v_fmac_f32_e32 v213, v8, v8
	v_fmac_f32_e32 v213, v9, v9
	v_fmac_f32_e32 v213, v10, v10
	v_fmac_f32_e32 v213, v11, v11
	v_cvt_pk_bf16_f32 v192, v12, v13
	v_cvt_pk_bf16_f32 v193, v14, v15
	v_cvt_pk_bf16_f32 v194, v8, v9
	v_cvt_pk_bf16_f32 v195, v10, v11
	v_add_u32_e32 v217, 0xb0000, v209
	global_store_dwordx4 v217, v[192:195], s[80:81]
	v_lshlrev_b32_e32 v200, 16, v196
	v_and_b32_e32 v201, 0xffff0000, v196
	v_lshlrev_b32_e32 v202, 16, v197
	v_and_b32_e32 v203, 0xffff0000, v197
	v_lshlrev_b32_e32 v204, 16, v198
	v_and_b32_e32 v205, 0xffff0000, v198
	v_lshlrev_b32_e32 v206, 16, v199
	v_and_b32_e32 v207, 0xffff0000, v199
	v_pk_add_f32 v[4:5], v[4:5], v[200:201]
	v_pk_add_f32 v[6:7], v[6:7], v[202:203]
	v_pk_add_f32 v[0:1], v[0:1], v[204:205]
	v_pk_add_f32 v[2:3], v[2:3], v[206:207]
	v_fmac_f32_e32 v213, v4, v4
	v_fmac_f32_e32 v213, v5, v5
	v_fmac_f32_e32 v213, v6, v6
	v_fmac_f32_e32 v213, v7, v7
	v_fmac_f32_e32 v213, v0, v0
	v_fmac_f32_e32 v213, v1, v1
	v_fmac_f32_e32 v213, v2, v2
	v_fmac_f32_e32 v213, v3, v3
	v_cvt_pk_bf16_f32 v196, v4, v5
	v_cvt_pk_bf16_f32 v197, v6, v7
	v_cvt_pk_bf16_f32 v198, v0, v1
	v_cvt_pk_bf16_f32 v199, v2, v3
	global_store_dwordx4 v217, v[196:199], s[80:81] offset:256
	ds_bpermute_b32 v214, v215, v213
	s_waitcnt lgkmcnt(0)
	v_add_f32_e32 v213, v213, v214
	ds_bpermute_b32 v214, v216, v213
	s_waitcnt lgkmcnt(0)
	v_add_f32_e32 v213, v213, v214
	s_mov_b64 exec, 0xffff
	global_atomic_add_f32 v208, v213, s[14:15] offset:704
	s_mov_b64 exec, -1
	s_branch .LBB0_496
.LBB0_525:
	s_waitcnt vmcnt(0)
	s_cmpk_gt_u32 s3, 0xff
	s_cbranch_scc1 .LBB0_527
.LBB0_527:
	s_barrier

.LBB0_586:
	s_add_u32 s4, s92, 0x30000
	v_cndmask_b32_e64 v0, 0, 1, s[8:9]
	s_addc_u32 s5, s93, 0
	v_cmp_ne_u32_e64 s[6:7], 1, v0
	s_andn2_b64 vcc, exec, s[8:9]
	s_cbranch_vccnz .LBB0_634
	s_add_u32 s34, s92, 0x6300000
	s_addc_u32 s35, s93, 0
	s_lshr_b32 s9, s3, 6
	s_ashr_i32 s13, s12, 31
	s_ashr_i32 s1, s0, 31
	s_lshr_b32 s8, s3, 8
	s_lshl_b32 s36, s9, 10
	s_lshl_b64 s[10:11], s[12:13], 20
	s_lshl_b64 s[16:17], s[0:1], 20
	s_add_u32 s28, s34, s16
	s_addc_u32 s29, s35, s17
	s_add_i32 s37, s36, 0
	s_add_i32 m0, s37, 0x10000
	v_lshl_or_b32 v128, v236, 12, v219
	v_and_b32_e32 v140, 63, v222
	v_lshrrev_b32_e32 v141, 3, v140
	v_lshrrev_b32_e32 v142, 6, v222
	v_lshl_add_u32 v143, v142, 3, v141
	v_and_b32_e32 v144, 7, v140
	v_and_b32_e32 v145, 6, v141
	v_xor_b32_e32 v144, v144, v145
	v_lshlrev_b32_e32 v144, 4, v144
	v_mul_u32_u24_e32 v145, 0x1000, v143
	v_add_u32_e32 v145, v145, v144
	v_mov_b32_e32 v132, v145
	v_mov_b32_e32 v128, v145
	v_add_u32_e32 v134, 0x40000, v145
	v_add_u32_e32 v130, 0x40000, v145
	v_add_u32_e32 v134, 0x40000, v145
	v_add_u32_e32 v130, 0x40000, v145
	v_and_b32_e32 v145, 31, v143
	v_and_b32_e32 v154, 12, v145
	v_lshlrev_b32_e32 v154, 1, v154
	v_lshrrev_b32_e32 v155, 4, v145
	v_lshlrev_b32_e32 v155, 2, v155
	v_and_b32_e32 v145, 3, v145
	v_or3_b32 v145, v154, v155, v145
	v_and_b32_e32 v154, 0x60, v143
	v_add_u32_e32 v145, v145, v154
	v_mul_u32_u24_e32 v145, 0x1000, v145
	v_add_u32_e32 v145, v145, v144
	v_mov_b32_e32 v164, v145
	v_add_u32_e32 v166, 0x40000, v145
	v_add_u32_e32 v166, 0x40000, v145
	v_and_b32_e32 v145, 15, v140
	v_lshrrev_b32_e32 v154, 4, v140
	v_and_b32_e32 v155, 6, v145
	v_xor_b32_e32 v154, v154, v155
	v_lshlrev_b32_e32 v154, 4, v154
	v_lshl_or_b32 v154, v145, 7, v154
	v_lshrrev_b32_e32 v155, 2, v142
	v_lshl_add_u32 v155, v155, 13, v154
	v_add_u32_e32 v150, 0x0, v155
	v_and_b32_e32 v145, 3, v142
	v_lshl_add_u32 v145, v145, 12, v154
	v_add_u32_e32 v147, 0x0, v145
	v_add_u32_e32 v149, 0x10000, v145
	v_add_u32_e32 v151, 0x14000, v145
	global_load_lds_dwordx4 v164, s[28:29]
	s_add_i32 m0, s37, 0x12000
	s_add_u32 s26, s80, s10
	global_load_lds_dwordx4 v166, s[28:29]
	s_addc_u32 s27, s81, s11
	s_mov_b32 m0, s37
	s_add_i32 s38, s37, 0x2000
	global_load_lds_dwordx4 v128, s[26:27]
	s_mov_b32 m0, s38
	s_add_u32 s10, s28, 0x80000
	global_load_lds_dwordx4 v130, s[26:27]
	s_addc_u32 s11, s29, 0
	s_add_i32 m0, s37, 0x14000
	v_mov_b32_e32 v165, 0
	global_load_lds_dwordx4 v164, s[10:11]
	s_add_i32 m0, s37, 0x16000
	v_mov_b32_e32 v167, v165
	global_load_lds_dwordx4 v166, s[10:11]
	s_add_u32 s10, s26, 0x80000
	s_addc_u32 s11, s27, 0
	s_add_i32 s39, s37, 0x4000
	s_mov_b32 m0, s39
	s_add_i32 s40, s37, 0x6000
	global_load_lds_dwordx4 v128, s[10:11]
	s_mov_b32 m0, s40
	v_mov_b32_e32 v129, v165
	global_load_lds_dwordx4 v130, s[10:11]
	v_mov_b32_e32 v131, v165
	s_mov_b32 s41, 0
	v_lshl_add_u64 v[6:7], s[28:29], 0, v[164:165]
	v_lshl_add_u64 v[4:5], s[28:29], 0, v[166:167]
	v_lshl_add_u64 v[2:3], s[26:27], 0, v[128:129]
	s_cmp_lg_u32 s8, 1
	v_lshl_add_u64 v[0:1], s[26:27], 0, v[130:131]
	s_cbranch_scc1 .LBB0_589
.LBB0_589:
	s_mov_b64 s[16:17], 0x80
	s_lshl_b32 s9, s9, 5
	s_add_i32 m0, s37, 0x18000
	v_lshl_add_u64 v[6:7], v[6:7], 0, s[16:17]
	s_lshl_b32 s1, s8, 13
	s_and_b32 s13, s9, 0x60
	s_waitcnt vmcnt(4)
	s_barrier
	global_load_lds_dwordx4 v[6:7], off
	v_lshl_add_u64 v[4:5], v[4:5], 0, s[16:17]
	s_add_i32 m0, s37, 0x1a000
	s_add_i32 s42, s37, 0x8000
	s_add_i32 s43, s37, 0xa000
	global_load_lds_dwordx4 v[4:5], off
	v_lshl_add_u64 v[2:3], v[2:3], 0, s[16:17]
	s_mov_b32 m0, s42
	s_add_u32 s10, s28, 0x80080
	global_load_lds_dwordx4 v[2:3], off
	v_lshl_add_u64 v[0:1], v[0:1], 0, s[16:17]
	s_mov_b32 m0, s43
	s_addc_u32 s11, s29, 0
	global_load_lds_dwordx4 v[0:1], off
	s_add_i32 m0, s37, 0x1c000
	v_lshl_add_u64 v[0:1], s[10:11], 0, v[164:165]
	global_load_lds_dwordx4 v[0:1], off
	v_lshl_add_u64 v[0:1], s[10:11], 0, v[166:167]
	s_add_i32 m0, s37, 0x1e000
	v_lshlrev_b32_e32 v2, 12, v218
	global_load_lds_dwordx4 v[0:1], off
	v_lshlrev_b32_e32 v1, 2, v163
	v_lshl_or_b32 v0, v163, 6, v227
	v_and_b32_e32 v1, 32, v1
	v_bitop3_b32 v0, v0, s1, v1 bitop3:0xde
	v_lshlrev_b32_e32 v1, 9, v222
	v_and_b32_e32 v1, 0x70000, v1
	v_or3_b32 v1, v226, v1, v2
	v_lshlrev_b32_e32 v1, 5, v233
	s_waitcnt vmcnt(6)
	v_and_b32_e32 v1, 0xf0000, v1
	v_or3_b32 v1, v226, v1, v2
	s_add_i32 s46, 0, 0x10000
	s_add_i32 s47, 0, 0x14000
	v_mbcnt_lo_u32_b32 v0, -1, 0
	v_lshl_or_b32 v146, s8, 6, v163
	s_ashr_i32 s44, s94, 31
	s_mov_b32 s45, s94
	v_cmp_eq_u32_e64 s[8:9], 0, v225
	v_lshl_or_b32 v148, v225, 3, s13
	v_mov_b32_e32 v133, v165
	v_mov_b32_e32 v135, v165
	v_mov_b64_e32 v[136:137], 0x400
	v_mov_b64_e32 v[138:139], 0x3ff
	v_mov_b32_e32 v152, 0x3727c5ac
	v_mbcnt_hi_u32_b32 v153, -1, v0
	s_barrier
	s_branch .LBB0_592

.LBB0_598:
	s_ashr_i32 s21, s20, 31
	v_cmp_lt_i64_e32 vcc, s[22:23], v[136:137]
	s_lshl_b64 s[22:23], s[20:21], 20
	s_add_u32 s22, s80, s22
	s_addc_u32 s23, s81, s23
	s_and_b64 s[24:25], vcc, exec
	s_cselect_b32 s1, s23, s27
	s_cselect_b32 s13, s22, s26
	s_ashr_i32 s19, s18, 31
	s_lshl_b64 s[24:25], s[18:19], 20
	s_add_u32 s24, s34, s24
	s_addc_u32 s25, s35, s25
	s_and_b64 s[30:31], vcc, exec
	s_cselect_b32 s19, s25, s29
	s_cselect_b32 s21, s24, s28
	s_add_u32 s26, s26, 0x80080
	s_addc_u32 s27, s27, 0
	s_add_u32 s33, s28, 0x100
	v_mov_b32_e32 v0, 0
	s_addc_u32 s48, s29, 0
	s_mov_b32 s49, -2
	s_waitcnt lgkmcnt(0)
	v_mov_b32_e32 v1, v0
	v_mov_b32_e32 v2, v0
	v_mov_b32_e32 v3, v0
	v_mov_b32_e32 v4, v0
	v_mov_b32_e32 v5, v0
	v_mov_b32_e32 v6, v0
	v_mov_b32_e32 v7, v0
	s_waitcnt vmcnt(0)
	v_mov_b32_e32 v16, v0
	v_mov_b32_e32 v17, v0
	v_mov_b32_e32 v18, v0
	v_mov_b32_e32 v19, v0
	v_mov_b32_e32 v20, v0
	v_mov_b32_e32 v21, v0
	v_mov_b32_e32 v22, v0
	v_mov_b32_e32 v23, v0
	v_mov_b32_e32 v32, v0
	v_mov_b32_e32 v33, v0
	v_mov_b32_e32 v34, v0
	v_mov_b32_e32 v35, v0
	v_mov_b32_e32 v36, v0
	v_mov_b32_e32 v37, v0
	v_mov_b32_e32 v38, v0
	v_mov_b32_e32 v39, v0
	v_mov_b32_e32 v48, v0
	v_mov_b32_e32 v49, v0
	v_mov_b32_e32 v50, v0
	v_mov_b32_e32 v51, v0
	v_mov_b32_e32 v52, v0
	v_mov_b32_e32 v53, v0
	v_mov_b32_e32 v54, v0
	v_mov_b32_e32 v55, v0
	v_mov_b32_e32 v8, v0
	v_mov_b32_e32 v9, v0
	v_mov_b32_e32 v10, v0
	v_mov_b32_e32 v11, v0
	v_mov_b32_e32 v12, v0
	v_mov_b32_e32 v13, v0
	v_mov_b32_e32 v14, v0
	v_mov_b32_e32 v15, v0
	v_mov_b32_e32 v24, v0
	v_mov_b32_e32 v25, v0
	v_mov_b32_e32 v26, v0
	v_mov_b32_e32 v27, v0
	v_mov_b32_e32 v28, v0
	v_mov_b32_e32 v29, v0
	v_mov_b32_e32 v30, v0
	v_mov_b32_e32 v31, v0
	v_mov_b32_e32 v40, v0
	v_mov_b32_e32 v41, v0
	v_mov_b32_e32 v42, v0
	v_mov_b32_e32 v43, v0
	v_mov_b32_e32 v44, v0
	v_mov_b32_e32 v45, v0
	v_mov_b32_e32 v46, v0
	v_mov_b32_e32 v47, v0
	v_mov_b32_e32 v56, v0
	v_mov_b32_e32 v57, v0
	v_mov_b32_e32 v58, v0
	v_mov_b32_e32 v59, v0
	v_mov_b32_e32 v60, v0
	v_mov_b32_e32 v61, v0
	v_mov_b32_e32 v62, v0
	v_mov_b32_e32 v63, v0
	v_mov_b32_e32 v64, v0
	v_mov_b32_e32 v65, v0
	v_mov_b32_e32 v66, v0
	v_mov_b32_e32 v67, v0
	v_mov_b32_e32 v68, v0
	v_mov_b32_e32 v69, v0
	v_mov_b32_e32 v70, v0
	v_mov_b32_e32 v71, v0
	v_mov_b32_e32 v80, v0
	v_mov_b32_e32 v81, v0
	v_mov_b32_e32 v82, v0
	v_mov_b32_e32 v83, v0
	v_mov_b32_e32 v84, v0
	v_mov_b32_e32 v85, v0
	v_mov_b32_e32 v86, v0
	v_mov_b32_e32 v87, v0
	v_mov_b32_e32 v96, v0
	v_mov_b32_e32 v97, v0
	v_mov_b32_e32 v98, v0
	v_mov_b32_e32 v99, v0
	v_mov_b32_e32 v100, v0
	v_mov_b32_e32 v101, v0
	v_mov_b32_e32 v102, v0
	v_mov_b32_e32 v103, v0
	v_mov_b32_e32 v112, v0
	v_mov_b32_e32 v113, v0
	v_mov_b32_e32 v114, v0
	v_mov_b32_e32 v115, v0
	v_mov_b32_e32 v116, v0
	v_mov_b32_e32 v117, v0
	v_mov_b32_e32 v118, v0
	v_mov_b32_e32 v119, v0
	v_mov_b32_e32 v72, v0
	v_mov_b32_e32 v73, v0
	v_mov_b32_e32 v74, v0
	v_mov_b32_e32 v75, v0
	v_mov_b32_e32 v76, v0
	v_mov_b32_e32 v77, v0
	v_mov_b32_e32 v78, v0
	v_mov_b32_e32 v79, v0
	v_mov_b32_e32 v88, v0
	v_mov_b32_e32 v89, v0
	v_mov_b32_e32 v90, v0
	v_mov_b32_e32 v91, v0
	v_mov_b32_e32 v92, v0
	v_mov_b32_e32 v93, v0
	v_mov_b32_e32 v94, v0
	v_mov_b32_e32 v95, v0
	v_mov_b32_e32 v104, v0
	v_mov_b32_e32 v105, v0
	v_mov_b32_e32 v106, v0
	v_mov_b32_e32 v107, v0
	v_mov_b32_e32 v108, v0
	v_mov_b32_e32 v109, v0
	v_mov_b32_e32 v110, v0
	v_mov_b32_e32 v111, v0
	v_mov_b32_e32 v120, v0
	v_mov_b32_e32 v121, v0
	v_mov_b32_e32 v122, v0
	v_mov_b32_e32 v123, v0
	v_mov_b32_e32 v124, v0
	v_mov_b32_e32 v125, v0
	v_mov_b32_e32 v126, v0
	v_mov_b32_e32 v127, v0
	v_xor_b32_e32 v144, 64, v149
	v_xor_b32_e32 v145, 64, v150
	v_xor_b32_e32 v216, 64, v151
	v_add_u32_e32 v217, 0x18000, v147
	v_xor_b32_e32 v234, 64, v217
	v_add_u32_e32 v235, 0x1c000, v147
	v_xor_b32_e32 v252, 64, v235
	s_cmpk_lt_u32 s3, 0x100
	s_cbranch_scc1 .Lst_in_s5
	s_barrier
.Lst_in_s5:
.LBB0_599:
	ds_read_b128 v[140:143], v149
	ds_read_b128 v[154:157], v144
	ds_read_b128 v[158:161], v149 offset:2048
	ds_read_b128 v[176:179], v144 offset:2048
	s_add_u32 s28, s26, 0xfff80080
	s_addc_u32 s29, s27, -1
	s_cmp_eq_u32 s49, 28
	s_cselect_b32 s31, s1, s29
	s_cselect_b32 s30, s13, s28
	s_cselect_b32 s29, s19, s48
	s_cselect_b32 s28, s21, s33
	s_add_i32 m0, s37, 0xc000
	ds_read_b128 v[180:183], v150
	ds_read_b128 v[184:187], v145
	ds_read_b128 v[188:191], v150 offset:2048
	ds_read_b128 v[192:195], v145 offset:2048
	ds_read_b128 v[196:199], v150 offset:4096
	ds_read_b128 v[200:203], v145 offset:4096
	ds_read_b128 v[204:207], v150 offset:6144
	ds_read_b128 v[208:211], v145 offset:6144
	global_load_lds_dwordx4 v132, s[26:27]
	s_add_i32 m0, s37, 0xe000
	s_nop 0
	global_load_lds_dwordx4 v134, s[26:27]
	s_waitcnt lgkmcnt(8)
	s_barrier
	s_waitcnt lgkmcnt(0)
	s_waitcnt lgkmcnt(0)
	v_mfma_f32_16x16x32_bf16 v[124:127], v[140:143], v[180:183], v[124:127]
	v_mfma_f32_16x16x32_bf16 v[124:127], v[154:157], v[184:187], v[124:127]
	v_mfma_f32_16x16x32_bf16 v[120:123], v[176:179], v[184:187], v[120:123]
	v_mfma_f32_16x16x32_bf16 v[120:123], v[158:161], v[180:183], v[120:123]
	v_mfma_f32_16x16x32_bf16 v[104:107], v[158:161], v[188:191], v[104:107]
	v_mfma_f32_16x16x32_bf16 v[104:107], v[176:179], v[192:195], v[104:107]
	v_mfma_f32_16x16x32_bf16 v[108:111], v[154:157], v[192:195], v[108:111]
	v_mfma_f32_16x16x32_bf16 v[108:111], v[140:143], v[188:191], v[108:111]
	v_mfma_f32_16x16x32_bf16 v[92:95], v[140:143], v[196:199], v[92:95]
	v_mfma_f32_16x16x32_bf16 v[92:95], v[154:157], v[200:203], v[92:95]
	v_mfma_f32_16x16x32_bf16 v[88:91], v[176:179], v[200:203], v[88:91]
	v_mfma_f32_16x16x32_bf16 v[88:91], v[158:161], v[196:199], v[88:91]
	v_mfma_f32_16x16x32_bf16 v[72:75], v[158:161], v[204:207], v[72:75]
	v_mfma_f32_16x16x32_bf16 v[72:75], v[176:179], v[208:211], v[72:75]
	v_mfma_f32_16x16x32_bf16 v[76:79], v[154:157], v[208:211], v[76:79]
	v_mfma_f32_16x16x32_bf16 v[76:79], v[140:143], v[204:207], v[76:79]
	s_barrier
	s_add_i32 s52, s46, s36
	s_add_u32 s98, s28, s16
	s_addc_u32 s99, s29, s17
	s_mov_b32 m0, s52
	ds_read_b128 v[212:215], v151
	ds_read_b128 v[240:243], v216
	ds_read_b128 v[244:247], v151 offset:2048
	ds_read_b128 v[248:251], v216 offset:2048
	global_load_lds_dwordx4 v164, s[28:29]
	s_add_i32 m0, s52, 0x2000
	s_nop 0
	global_load_lds_dwordx4 v166, s[28:29]
	s_barrier
	s_waitcnt lgkmcnt(0)
	s_waitcnt lgkmcnt(0)
	v_mfma_f32_16x16x32_bf16 v[116:119], v[212:215], v[180:183], v[116:119]
	v_mfma_f32_16x16x32_bf16 v[116:119], v[240:243], v[184:187], v[116:119]
	v_mfma_f32_16x16x32_bf16 v[112:115], v[248:251], v[184:187], v[112:115]
	v_mfma_f32_16x16x32_bf16 v[112:115], v[244:247], v[180:183], v[112:115]
	v_mfma_f32_16x16x32_bf16 v[96:99], v[244:247], v[188:191], v[96:99]
	v_mfma_f32_16x16x32_bf16 v[96:99], v[248:251], v[192:195], v[96:99]
	v_mfma_f32_16x16x32_bf16 v[100:103], v[240:243], v[192:195], v[100:103]
	v_mfma_f32_16x16x32_bf16 v[100:103], v[212:215], v[188:191], v[100:103]
	v_mfma_f32_16x16x32_bf16 v[84:87], v[212:215], v[196:199], v[84:87]
	v_mfma_f32_16x16x32_bf16 v[84:87], v[240:243], v[200:203], v[84:87]
	v_mfma_f32_16x16x32_bf16 v[80:83], v[248:251], v[200:203], v[80:83]
	v_mfma_f32_16x16x32_bf16 v[80:83], v[244:247], v[196:199], v[80:83]
	v_mfma_f32_16x16x32_bf16 v[64:67], v[244:247], v[204:207], v[64:67]
	v_mfma_f32_16x16x32_bf16 v[64:67], v[248:251], v[208:211], v[64:67]
	v_mfma_f32_16x16x32_bf16 v[68:71], v[240:243], v[208:211], v[68:71]
	v_mfma_f32_16x16x32_bf16 v[68:71], v[212:215], v[204:207], v[68:71]
	s_mov_b32 m0, s37
	s_add_u32 s100, s30, s16
	s_addc_u32 s101, s31, s17
	s_barrier
	ds_read_b128 v[180:183], v150 offset:16384
	ds_read_b128 v[184:187], v145 offset:16384
	ds_read_b128 v[188:191], v150 offset:18432
	ds_read_b128 v[192:195], v145 offset:18432
	ds_read_b128 v[196:199], v150 offset:20480
	ds_read_b128 v[200:203], v145 offset:20480
	ds_read_b128 v[204:207], v150 offset:22528
	ds_read_b128 v[208:211], v145 offset:22528
	global_load_lds_dwordx4 v128, s[30:31]
	s_mov_b32 m0, s38
	s_nop 0
	global_load_lds_dwordx4 v130, s[30:31]
	s_barrier
	s_waitcnt lgkmcnt(0)
	s_waitcnt lgkmcnt(0)
	v_mfma_f32_16x16x32_bf16 v[60:63], v[140:143], v[180:183], v[60:63]
	v_mfma_f32_16x16x32_bf16 v[60:63], v[154:157], v[184:187], v[60:63]
	v_mfma_f32_16x16x32_bf16 v[56:59], v[176:179], v[184:187], v[56:59]
	v_mfma_f32_16x16x32_bf16 v[56:59], v[158:161], v[180:183], v[56:59]
	v_mfma_f32_16x16x32_bf16 v[40:43], v[158:161], v[188:191], v[40:43]
	v_mfma_f32_16x16x32_bf16 v[40:43], v[176:179], v[192:195], v[40:43]
	v_mfma_f32_16x16x32_bf16 v[44:47], v[154:157], v[192:195], v[44:47]
	v_mfma_f32_16x16x32_bf16 v[44:47], v[140:143], v[188:191], v[44:47]
	v_mfma_f32_16x16x32_bf16 v[28:31], v[140:143], v[196:199], v[28:31]
	v_mfma_f32_16x16x32_bf16 v[28:31], v[154:157], v[200:203], v[28:31]
	v_mfma_f32_16x16x32_bf16 v[24:27], v[176:179], v[200:203], v[24:27]
	v_mfma_f32_16x16x32_bf16 v[24:27], v[158:161], v[196:199], v[24:27]
	v_mfma_f32_16x16x32_bf16 v[8:11], v[158:161], v[204:207], v[8:11]
	v_mfma_f32_16x16x32_bf16 v[8:11], v[176:179], v[208:211], v[8:11]
	v_mfma_f32_16x16x32_bf16 v[12:15], v[154:157], v[208:211], v[12:15]
	v_mfma_f32_16x16x32_bf16 v[12:15], v[140:143], v[204:207], v[12:15]
	s_barrier
	s_add_u32 s52, s28, 0x80000
	s_addc_u32 s53, s29, 0
	s_add_i32 s54, s47, s36
	s_mov_b32 m0, s54
	s_nop 0
	global_load_lds_dwordx4 v164, s[52:53]
	s_add_i32 m0, s54, 0x2000
	s_nop 0
	global_load_lds_dwordx4 v166, s[52:53]
	s_waitcnt vmcnt(6)
	s_barrier
	v_mfma_f32_16x16x32_bf16 v[52:55], v[212:215], v[180:183], v[52:55]
	v_mfma_f32_16x16x32_bf16 v[52:55], v[240:243], v[184:187], v[52:55]
	v_mfma_f32_16x16x32_bf16 v[48:51], v[248:251], v[184:187], v[48:51]
	v_mfma_f32_16x16x32_bf16 v[48:51], v[244:247], v[180:183], v[48:51]
	v_mfma_f32_16x16x32_bf16 v[32:35], v[244:247], v[188:191], v[32:35]
	v_mfma_f32_16x16x32_bf16 v[32:35], v[248:251], v[192:195], v[32:35]
	v_mfma_f32_16x16x32_bf16 v[36:39], v[240:243], v[192:195], v[36:39]
	v_mfma_f32_16x16x32_bf16 v[36:39], v[212:215], v[188:191], v[36:39]
	v_mfma_f32_16x16x32_bf16 v[20:23], v[212:215], v[196:199], v[20:23]
	v_mfma_f32_16x16x32_bf16 v[20:23], v[240:243], v[200:203], v[20:23]
	v_mfma_f32_16x16x32_bf16 v[16:19], v[248:251], v[200:203], v[16:19]
	v_mfma_f32_16x16x32_bf16 v[16:19], v[244:247], v[196:199], v[16:19]
	v_mfma_f32_16x16x32_bf16 v[0:3], v[244:247], v[204:207], v[0:3]
	v_mfma_f32_16x16x32_bf16 v[0:3], v[248:251], v[208:211], v[0:3]
	v_mfma_f32_16x16x32_bf16 v[4:7], v[240:243], v[208:211], v[4:7]
	v_mfma_f32_16x16x32_bf16 v[4:7], v[212:215], v[204:207], v[4:7]
	s_add_i32 s52, 0, 0x18000
	s_barrier
	ds_read_b128 v[140:143], v217
	ds_read_b128 v[154:157], v234
	ds_read_b128 v[158:161], v217 offset:2048
	ds_read_b128 v[176:179], v234 offset:2048
	s_add_u32 s30, s30, 0x80000
	s_addc_u32 s31, s31, 0
	s_mov_b32 m0, s39
	ds_read_b128 v[180:183], v150 offset:32768
	ds_read_b128 v[184:187], v145 offset:32768
	ds_read_b128 v[188:191], v150 offset:34816
	ds_read_b128 v[192:195], v145 offset:34816
	ds_read_b128 v[196:199], v150 offset:36864
	ds_read_b128 v[200:203], v145 offset:36864
	ds_read_b128 v[204:207], v150 offset:38912
	ds_read_b128 v[208:211], v145 offset:38912
	global_load_lds_dwordx4 v128, s[30:31]
	s_mov_b32 m0, s40
	s_nop 0
	global_load_lds_dwordx4 v130, s[30:31]
	s_waitcnt lgkmcnt(8)
	s_barrier
	s_waitcnt lgkmcnt(0)
	s_waitcnt lgkmcnt(0)
	v_mfma_f32_16x16x32_bf16 v[124:127], v[140:143], v[180:183], v[124:127]
	v_mfma_f32_16x16x32_bf16 v[124:127], v[154:157], v[184:187], v[124:127]
	v_mfma_f32_16x16x32_bf16 v[120:123], v[176:179], v[184:187], v[120:123]
	v_mfma_f32_16x16x32_bf16 v[120:123], v[158:161], v[180:183], v[120:123]
	v_mfma_f32_16x16x32_bf16 v[104:107], v[158:161], v[188:191], v[104:107]
	v_mfma_f32_16x16x32_bf16 v[104:107], v[176:179], v[192:195], v[104:107]
	v_mfma_f32_16x16x32_bf16 v[108:111], v[154:157], v[192:195], v[108:111]
	v_mfma_f32_16x16x32_bf16 v[108:111], v[140:143], v[188:191], v[108:111]
	v_mfma_f32_16x16x32_bf16 v[92:95], v[140:143], v[196:199], v[92:95]
	v_mfma_f32_16x16x32_bf16 v[92:95], v[154:157], v[200:203], v[92:95]
	v_mfma_f32_16x16x32_bf16 v[88:91], v[176:179], v[200:203], v[88:91]
	v_mfma_f32_16x16x32_bf16 v[88:91], v[158:161], v[196:199], v[88:91]
	v_mfma_f32_16x16x32_bf16 v[72:75], v[158:161], v[204:207], v[72:75]
	v_mfma_f32_16x16x32_bf16 v[72:75], v[176:179], v[208:211], v[72:75]
	v_mfma_f32_16x16x32_bf16 v[76:79], v[154:157], v[208:211], v[76:79]
	v_mfma_f32_16x16x32_bf16 v[76:79], v[140:143], v[204:207], v[76:79]
	s_barrier
	s_add_i32 s30, 0, 0x1c000
	s_add_i32 s31, s52, s36
	s_mov_b32 m0, s31
	ds_read_b128 v[212:215], v235
	ds_read_b128 v[240:243], v252
	ds_read_b128 v[244:247], v235 offset:2048
	ds_read_b128 v[248:251], v252 offset:2048
	global_load_lds_dwordx4 v164, s[98:99]
	s_add_i32 m0, s31, 0x2000
	s_nop 0
	global_load_lds_dwordx4 v166, s[98:99]
	s_barrier
	s_waitcnt lgkmcnt(0)
	s_waitcnt lgkmcnt(0)
	v_mfma_f32_16x16x32_bf16 v[116:119], v[212:215], v[180:183], v[116:119]
	v_mfma_f32_16x16x32_bf16 v[116:119], v[240:243], v[184:187], v[116:119]
	v_mfma_f32_16x16x32_bf16 v[112:115], v[248:251], v[184:187], v[112:115]
	v_mfma_f32_16x16x32_bf16 v[112:115], v[244:247], v[180:183], v[112:115]
	v_mfma_f32_16x16x32_bf16 v[96:99], v[244:247], v[188:191], v[96:99]
	v_mfma_f32_16x16x32_bf16 v[96:99], v[248:251], v[192:195], v[96:99]
	v_mfma_f32_16x16x32_bf16 v[100:103], v[240:243], v[192:195], v[100:103]
	v_mfma_f32_16x16x32_bf16 v[100:103], v[212:215], v[188:191], v[100:103]
	v_mfma_f32_16x16x32_bf16 v[84:87], v[212:215], v[196:199], v[84:87]
	v_mfma_f32_16x16x32_bf16 v[84:87], v[240:243], v[200:203], v[84:87]
	v_mfma_f32_16x16x32_bf16 v[80:83], v[248:251], v[200:203], v[80:83]
	v_mfma_f32_16x16x32_bf16 v[80:83], v[244:247], v[196:199], v[80:83]
	v_mfma_f32_16x16x32_bf16 v[64:67], v[244:247], v[204:207], v[64:67]
	v_mfma_f32_16x16x32_bf16 v[64:67], v[248:251], v[208:211], v[64:67]
	v_mfma_f32_16x16x32_bf16 v[68:71], v[240:243], v[208:211], v[68:71]
	v_mfma_f32_16x16x32_bf16 v[68:71], v[212:215], v[204:207], v[68:71]
	s_mov_b32 m0, s42
	s_barrier
	ds_read_b128 v[180:183], v150 offset:49152
	ds_read_b128 v[184:187], v145 offset:49152
	ds_read_b128 v[188:191], v150 offset:51200
	ds_read_b128 v[192:195], v145 offset:51200
	ds_read_b128 v[196:199], v150 offset:53248
	ds_read_b128 v[200:203], v145 offset:53248
	ds_read_b128 v[204:207], v150 offset:55296
	ds_read_b128 v[208:211], v145 offset:55296
	global_load_lds_dwordx4 v128, s[100:101]
	s_mov_b32 m0, s43
	s_nop 0
	global_load_lds_dwordx4 v130, s[100:101]
	s_barrier
	s_waitcnt lgkmcnt(0)
	s_waitcnt lgkmcnt(0)
	v_mfma_f32_16x16x32_bf16 v[60:63], v[140:143], v[180:183], v[60:63]
	v_mfma_f32_16x16x32_bf16 v[60:63], v[154:157], v[184:187], v[60:63]
	v_mfma_f32_16x16x32_bf16 v[56:59], v[176:179], v[184:187], v[56:59]
	v_mfma_f32_16x16x32_bf16 v[56:59], v[158:161], v[180:183], v[56:59]
	v_mfma_f32_16x16x32_bf16 v[40:43], v[158:161], v[188:191], v[40:43]
	v_mfma_f32_16x16x32_bf16 v[40:43], v[176:179], v[192:195], v[40:43]
	v_mfma_f32_16x16x32_bf16 v[44:47], v[154:157], v[192:195], v[44:47]
	v_mfma_f32_16x16x32_bf16 v[44:47], v[140:143], v[188:191], v[44:47]
	v_mfma_f32_16x16x32_bf16 v[28:31], v[140:143], v[196:199], v[28:31]
	v_mfma_f32_16x16x32_bf16 v[28:31], v[154:157], v[200:203], v[28:31]
	v_mfma_f32_16x16x32_bf16 v[24:27], v[176:179], v[200:203], v[24:27]
	v_mfma_f32_16x16x32_bf16 v[24:27], v[158:161], v[196:199], v[24:27]
	v_mfma_f32_16x16x32_bf16 v[8:11], v[158:161], v[204:207], v[8:11]
	v_mfma_f32_16x16x32_bf16 v[8:11], v[176:179], v[208:211], v[8:11]
	v_mfma_f32_16x16x32_bf16 v[12:15], v[154:157], v[208:211], v[12:15]
	v_mfma_f32_16x16x32_bf16 v[12:15], v[140:143], v[204:207], v[12:15]
	s_barrier
	s_add_u32 s28, s28, 0x80080
	s_addc_u32 s29, s29, 0
	s_add_i32 s30, s30, s36
	s_mov_b32 m0, s30
	s_nop 0
	global_load_lds_dwordx4 v164, s[28:29]
	s_add_i32 m0, s30, 0x2000
	s_nop 0
	global_load_lds_dwordx4 v166, s[28:29]
	s_waitcnt vmcnt(6)
	s_barrier
	v_mfma_f32_16x16x32_bf16 v[52:55], v[212:215], v[180:183], v[52:55]
	v_mfma_f32_16x16x32_bf16 v[52:55], v[240:243], v[184:187], v[52:55]
	v_mfma_f32_16x16x32_bf16 v[48:51], v[248:251], v[184:187], v[48:51]
	v_mfma_f32_16x16x32_bf16 v[48:51], v[244:247], v[180:183], v[48:51]
	v_mfma_f32_16x16x32_bf16 v[32:35], v[244:247], v[188:191], v[32:35]
	v_mfma_f32_16x16x32_bf16 v[32:35], v[248:251], v[192:195], v[32:35]
	v_mfma_f32_16x16x32_bf16 v[36:39], v[240:243], v[192:195], v[36:39]
	v_mfma_f32_16x16x32_bf16 v[36:39], v[212:215], v[188:191], v[36:39]
	v_mfma_f32_16x16x32_bf16 v[20:23], v[212:215], v[196:199], v[20:23]
	v_mfma_f32_16x16x32_bf16 v[20:23], v[240:243], v[200:203], v[20:23]
	v_mfma_f32_16x16x32_bf16 v[16:19], v[248:251], v[200:203], v[16:19]
	v_mfma_f32_16x16x32_bf16 v[16:19], v[244:247], v[196:199], v[16:19]
	v_mfma_f32_16x16x32_bf16 v[0:3], v[244:247], v[204:207], v[0:3]
	v_mfma_f32_16x16x32_bf16 v[0:3], v[248:251], v[208:211], v[0:3]
	v_mfma_f32_16x16x32_bf16 v[4:7], v[240:243], v[208:211], v[4:7]
	v_mfma_f32_16x16x32_bf16 v[4:7], v[212:215], v[204:207], v[4:7]
	s_add_i32 s49, s49, 2
	s_add_u32 s26, s26, 0x100
	s_addc_u32 s27, s27, 0
	s_add_u32 s33, s33, 0x100
	s_addc_u32 s48, s48, 0
	s_cmp_gt_u32 s49, 29
	s_barrier
	s_cbranch_scc0 .LBB0_599
	s_cmpk_gt_u32 s3, 0xff
	s_cbranch_scc1 .Lst_out_s5
	s_barrier
.Lst_out_s5:
	v_lshl_add_u32 v143, s12, 8, v146
	v_lshlrev_b32_e32 v145, 2, v143
	global_load_dword v154, v145, s[14:15]
	global_load_dword v155, v145, s[14:15] offset:64
	global_load_dword v156, v145, s[14:15] offset:128
	global_load_dword v157, v145, s[14:15] offset:192
	global_load_dword v158, v145, s[14:15] offset:512
	global_load_dword v159, v145, s[14:15] offset:576
	global_load_dword v160, v145, s[14:15] offset:640
	global_load_dword v161, v145, s[14:15] offset:704
	v_lshlrev_b32_e32 v141, 13, v143
	v_lshl_or_b32 v143, s0, 8, v148
	v_lshl_add_u32 v141, v143, 1, v141
	v_xor_b32_e32 v169, 16, v153
	v_lshlrev_b32_e32 v169, 2, v169
	v_xor_b32_e32 v171, 32, v153
	v_lshlrev_b32_e32 v171, 2, v171
	v_mov_b32_e32 v140, 0xbdd2d3e8
	v_mov_b32_e32 v142, 0xc0135761
	v_mov_b32_e32 v144, 1.0
	s_waitcnt vmcnt(0)
	v_fmamk_f32 v154, v154, 0x3a000000, v152
	v_fmamk_f32 v155, v155, 0x3a000000, v152
	v_fmamk_f32 v156, v156, 0x3a000000, v152
	v_fmamk_f32 v157, v157, 0x3a000000, v152
	v_fmamk_f32 v158, v158, 0x3a000000, v152
	v_fmamk_f32 v159, v159, 0x3a000000, v152
	v_fmamk_f32 v160, v160, 0x3a000000, v152
	v_fmamk_f32 v161, v161, 0x3a000000, v152
	v_rsq_f32_e32 v154, v154
	v_rsq_f32_e32 v155, v155
	v_rsq_f32_e32 v156, v156
	v_rsq_f32_e32 v157, v157
	v_rsq_f32_e32 v158, v158
	v_rsq_f32_e32 v159, v159
	v_rsq_f32_e32 v160, v160
	v_rsq_f32_e32 v161, v161
	v_pk_mul_f32 v[124:125], v[124:125], v[154:155] op_sel:[0,0] op_sel_hi:[1,0]
	v_pk_mul_f32 v[126:127], v[126:127], v[154:155] op_sel:[0,0] op_sel_hi:[1,0]
	v_pk_mul_f32 v[120:121], v[120:121], v[154:155] op_sel:[0,0] op_sel_hi:[1,0]
	v_pk_mul_f32 v[122:123], v[122:123], v[154:155] op_sel:[0,0] op_sel_hi:[1,0]
	v_pk_mul_f32 v[176:177], v[124:125], v[124:125]
	v_pk_mul_f32 v[178:179], v[126:127], v[126:127]
	v_pk_mul_f32 v[180:181], v[120:121], v[120:121]
	v_pk_mul_f32 v[182:183], v[122:123], v[122:123]
	v_pk_fma_f32 v[176:177], v[176:177], v[140:141], v[142:143] op_sel_hi:[1,0,0]
	v_pk_fma_f32 v[178:179], v[178:179], v[140:141], v[142:143] op_sel_hi:[1,0,0]
	v_pk_fma_f32 v[180:181], v[180:181], v[140:141], v[142:143] op_sel_hi:[1,0,0]
	v_pk_fma_f32 v[182:183], v[182:183], v[140:141], v[142:143] op_sel_hi:[1,0,0]
	v_pk_mul_f32 v[176:177], v[124:125], v[176:177]
	v_pk_mul_f32 v[178:179], v[126:127], v[178:179]
	v_pk_mul_f32 v[180:181], v[120:121], v[180:181]
	v_pk_mul_f32 v[182:183], v[122:123], v[182:183]
	v_exp_f32_e32 v176, v176
	v_exp_f32_e32 v177, v177
	v_exp_f32_e32 v178, v178
	v_exp_f32_e32 v179, v179
	v_exp_f32_e32 v180, v180
	v_exp_f32_e32 v181, v181
	v_exp_f32_e32 v182, v182
	v_exp_f32_e32 v183, v183
	v_pk_add_f32 v[176:177], v[176:177], v[144:145] op_sel_hi:[1,0]
	v_pk_add_f32 v[178:179], v[178:179], v[144:145] op_sel_hi:[1,0]
	v_pk_add_f32 v[180:181], v[180:181], v[144:145] op_sel_hi:[1,0]
	v_pk_add_f32 v[182:183], v[182:183], v[144:145] op_sel_hi:[1,0]
	v_rcp_f32_e32 v176, v176
	v_rcp_f32_e32 v177, v177
	v_rcp_f32_e32 v178, v178
	v_rcp_f32_e32 v179, v179
	v_rcp_f32_e32 v180, v180
	v_rcp_f32_e32 v181, v181
	v_rcp_f32_e32 v182, v182
	v_rcp_f32_e32 v183, v183
	v_pk_mul_f32 v[124:125], v[124:125], v[176:177]
	v_pk_mul_f32 v[126:127], v[126:127], v[178:179]
	v_pk_mul_f32 v[120:121], v[120:121], v[180:181]
	v_pk_mul_f32 v[122:123], v[122:123], v[182:183]
	v_pk_mul_f32 v[184:185], v[124:125], v[124:125]
	v_pk_fma_f32 v[184:185], v[126:127], v[126:127], v[184:185]
	v_pk_fma_f32 v[184:185], v[120:121], v[120:121], v[184:185]
	v_pk_fma_f32 v[184:185], v[122:123], v[122:123], v[184:185]
	v_cvt_pk_bf16_f32 v124, v124, v125
	v_cvt_pk_bf16_f32 v125, v126, v127
	v_cvt_pk_bf16_f32 v126, v120, v121
	v_cvt_pk_bf16_f32 v127, v122, v123
	global_store_dwordx4 v141, v[124:127], s[96:97]
	v_pk_mul_f32 v[116:117], v[116:117], v[154:155] op_sel:[0,0] op_sel_hi:[1,0]
	v_pk_mul_f32 v[118:119], v[118:119], v[154:155] op_sel:[0,0] op_sel_hi:[1,0]
	v_pk_mul_f32 v[112:113], v[112:113], v[154:155] op_sel:[0,0] op_sel_hi:[1,0]
	v_pk_mul_f32 v[114:115], v[114:115], v[154:155] op_sel:[0,0] op_sel_hi:[1,0]
	v_pk_mul_f32 v[176:177], v[116:117], v[116:117]
	v_pk_mul_f32 v[178:179], v[118:119], v[118:119]
	v_pk_mul_f32 v[180:181], v[112:113], v[112:113]
	v_pk_mul_f32 v[182:183], v[114:115], v[114:115]
	v_pk_fma_f32 v[176:177], v[176:177], v[140:141], v[142:143] op_sel_hi:[1,0,0]
	v_pk_fma_f32 v[178:179], v[178:179], v[140:141], v[142:143] op_sel_hi:[1,0,0]
	v_pk_fma_f32 v[180:181], v[180:181], v[140:141], v[142:143] op_sel_hi:[1,0,0]
	v_pk_fma_f32 v[182:183], v[182:183], v[140:141], v[142:143] op_sel_hi:[1,0,0]
	v_pk_mul_f32 v[176:177], v[116:117], v[176:177]
	v_pk_mul_f32 v[178:179], v[118:119], v[178:179]
	v_pk_mul_f32 v[180:181], v[112:113], v[180:181]
	v_pk_mul_f32 v[182:183], v[114:115], v[182:183]
	v_exp_f32_e32 v176, v176
	v_exp_f32_e32 v177, v177
	v_exp_f32_e32 v178, v178
	v_exp_f32_e32 v179, v179
	v_exp_f32_e32 v180, v180
	v_exp_f32_e32 v181, v181
	v_exp_f32_e32 v182, v182
	v_exp_f32_e32 v183, v183
	v_pk_add_f32 v[176:177], v[176:177], v[144:145] op_sel_hi:[1,0]
	v_pk_add_f32 v[178:179], v[178:179], v[144:145] op_sel_hi:[1,0]
	v_pk_add_f32 v[180:181], v[180:181], v[144:145] op_sel_hi:[1,0]
	v_pk_add_f32 v[182:183], v[182:183], v[144:145] op_sel_hi:[1,0]
	v_rcp_f32_e32 v176, v176
	v_rcp_f32_e32 v177, v177
	v_rcp_f32_e32 v178, v178
	v_rcp_f32_e32 v179, v179
	v_rcp_f32_e32 v180, v180
	v_rcp_f32_e32 v181, v181
	v_rcp_f32_e32 v182, v182
	v_rcp_f32_e32 v183, v183
	v_pk_mul_f32 v[116:117], v[116:117], v[176:177]
	v_pk_mul_f32 v[118:119], v[118:119], v[178:179]
	v_pk_mul_f32 v[112:113], v[112:113], v[180:181]
	v_pk_mul_f32 v[114:115], v[114:115], v[182:183]
	v_pk_fma_f32 v[184:185], v[116:117], v[116:117], v[184:185]
	v_pk_fma_f32 v[184:185], v[118:119], v[118:119], v[184:185]
	v_pk_fma_f32 v[184:185], v[112:113], v[112:113], v[184:185]
	v_pk_fma_f32 v[184:185], v[114:115], v[114:115], v[184:185]
	v_cvt_pk_bf16_f32 v116, v116, v117
	v_cvt_pk_bf16_f32 v117, v118, v119
	v_cvt_pk_bf16_f32 v118, v112, v113
	v_cvt_pk_bf16_f32 v119, v114, v115
	global_store_dwordx4 v141, v[116:119], s[96:97] offset:256
	s_cmp_lt_i32 s0, 8
	s_cbranch_scc1 .Le2_skip0
	v_add_f32_e32 v184, v184, v185
	ds_bpermute_b32 v173, v169, v184
	s_waitcnt lgkmcnt(0)
	v_add_f32_e32 v184, v184, v173
	ds_bpermute_b32 v173, v171, v184
	s_waitcnt lgkmcnt(0)
	v_add_f32_e32 v184, v184, v173
	s_mov_b64 exec, s[8:9]
	global_atomic_add_f32 v145, v184, s[4:5]
	s_mov_b64 exec, -1

.LBB0_631:
	s_waitcnt vmcnt(0)
	s_cmpk_gt_u32 s3, 0xff
	s_cbranch_scc1 .LBB0_633
.LBB0_633:
	s_barrier

.LBB0_748:
	v_readlane_b32 s6, v255, 8
	s_add_u32 s4, s92, 0x40000
	v_readlane_b32 s7, v255, 9
	s_addc_u32 s5, s93, 0
	s_and_b64 vcc, exec, s[6:7]
	s_cbranch_vccnz .LBB0_780
	s_add_u32 s26, s92, 0x7300000
	s_addc_u32 s27, s93, 0
	s_lshr_b32 s6, s3, 6
	s_ashr_i32 s9, s8, 31
	s_ashr_i32 s1, s0, 31
	s_lshr_b32 s7, s3, 8
	s_lshl_b32 s28, s6, 10
	s_lshl_b64 s[10:11], s[8:9], 21
	s_lshl_b64 s[12:13], s[0:1], 20
	s_add_u32 s22, s26, s12
	s_addc_u32 s23, s27, s13
	s_add_i32 s29, s28, 0
	s_add_i32 m0, s29, 0x10000
	v_lshl_or_b32 v128, v236, 13, v219
	v_and_b32_e32 v140, 63, v222
	v_lshrrev_b32_e32 v141, 3, v140
	v_lshrrev_b32_e32 v142, 6, v222
	v_lshl_add_u32 v143, v142, 3, v141
	v_and_b32_e32 v150, 7, v140
	v_and_b32_e32 v151, 6, v141
	v_xor_b32_e32 v150, v150, v151
	v_lshlrev_b32_e32 v150, 4, v150
	v_mul_u32_u24_e32 v151, 0x2000, v143
	v_add_u32_e32 v151, v151, v150
	v_mov_b32_e32 v132, v151
	v_mov_b32_e32 v128, v151
	v_add_u32_e32 v134, 0x80000, v151
	v_add_u32_e32 v130, 0x80000, v151
	v_add_u32_e32 v134, 0x80000, v151
	v_add_u32_e32 v130, 0x80000, v151
	v_and_b32_e32 v151, 31, v143
	v_and_b32_e32 v152, 12, v151
	v_lshlrev_b32_e32 v152, 1, v152
	v_lshrrev_b32_e32 v153, 4, v151
	v_lshlrev_b32_e32 v153, 2, v153
	v_and_b32_e32 v151, 3, v151
	v_or3_b32 v151, v152, v153, v151
	v_and_b32_e32 v152, 0x60, v143
	v_add_u32_e32 v151, v151, v152
	v_mul_u32_u24_e32 v151, 0x1000, v151
	v_add_u32_e32 v151, v151, v150
	v_mov_b32_e32 v164, v151
	v_add_u32_e32 v166, 0x40000, v151
	v_add_u32_e32 v166, 0x40000, v151
	v_and_b32_e32 v151, 15, v140
	v_lshrrev_b32_e32 v152, 4, v140
	v_and_b32_e32 v153, 6, v151
	v_xor_b32_e32 v152, v152, v153
	v_lshlrev_b32_e32 v152, 4, v152
	v_lshl_or_b32 v152, v151, 7, v152
	v_lshrrev_b32_e32 v153, 2, v142
	v_lshl_add_u32 v153, v153, 13, v152
	v_add_u32_e32 v146, 0x0, v153
	v_and_b32_e32 v151, 3, v142
	v_lshl_add_u32 v151, v151, 12, v152
	v_add_u32_e32 v144, 0x0, v151
	v_add_u32_e32 v145, 0x10000, v151
	v_add_u32_e32 v147, 0x14000, v151
	v_add_u32_e32 v149, 0x10000, v151
	global_load_lds_dwordx4 v164, s[22:23]
	s_add_i32 m0, s29, 0x12000
	s_add_u32 s20, s96, s10
	global_load_lds_dwordx4 v166, s[22:23]
	s_addc_u32 s21, s97, s11
	s_mov_b32 m0, s29
	s_add_i32 s30, s29, 0x2000
	global_load_lds_dwordx4 v128, s[20:21]
	s_mov_b32 m0, s30
	s_add_u32 s10, s22, 0x80000
	global_load_lds_dwordx4 v130, s[20:21]
	s_addc_u32 s11, s23, 0
	s_add_i32 m0, s29, 0x14000
	v_mov_b32_e32 v165, 0
	global_load_lds_dwordx4 v164, s[10:11]
	s_add_i32 m0, s29, 0x16000
	v_mov_b32_e32 v167, v165
	global_load_lds_dwordx4 v166, s[10:11]
	s_add_u32 s10, s20, 0x100000
	s_addc_u32 s11, s21, 0
	s_add_i32 s31, s29, 0x4000
	s_mov_b32 m0, s31
	s_add_i32 s33, s29, 0x6000
	global_load_lds_dwordx4 v128, s[10:11]
	s_mov_b32 m0, s33
	v_mov_b32_e32 v129, v165
	global_load_lds_dwordx4 v130, s[10:11]
	v_mov_b32_e32 v131, v165
	s_mov_b32 s34, 0
	v_lshl_add_u64 v[6:7], s[22:23], 0, v[164:165]
	v_lshl_add_u64 v[4:5], s[22:23], 0, v[166:167]
	v_lshl_add_u64 v[2:3], s[20:21], 0, v[128:129]
	s_cmp_lg_u32 s7, 1
	v_lshl_add_u64 v[0:1], s[20:21], 0, v[130:131]
	s_cbranch_scc1 .LBB0_751
.LBB0_751:
	s_mov_b64 s[10:11], 0x80
	s_lshl_b32 s6, s6, 5
	s_add_i32 m0, s29, 0x18000
	v_lshl_add_u64 v[6:7], v[6:7], 0, s[10:11]
	s_lshl_b32 s35, s7, 6
	s_lshl_b32 s1, s7, 13
	s_and_b32 s36, s6, 0x60
	s_waitcnt vmcnt(4)
	s_barrier
	global_load_lds_dwordx4 v[6:7], off
	v_lshl_add_u64 v[4:5], v[4:5], 0, s[10:11]
	s_add_i32 m0, s29, 0x1a000
	s_add_i32 s37, s29, 0x8000
	s_add_i32 s38, s29, 0xa000
	global_load_lds_dwordx4 v[4:5], off
	v_lshl_add_u64 v[2:3], v[2:3], 0, s[10:11]
	s_mov_b32 m0, s37
	s_add_u32 s6, s22, 0x80080
	global_load_lds_dwordx4 v[2:3], off
	v_lshl_add_u64 v[0:1], v[0:1], 0, s[10:11]
	s_mov_b32 m0, s38
	s_addc_u32 s7, s23, 0
	global_load_lds_dwordx4 v[0:1], off
	s_add_i32 m0, s29, 0x1c000
	v_lshl_add_u64 v[0:1], s[6:7], 0, v[164:165]
	global_load_lds_dwordx4 v[0:1], off
	v_lshl_add_u64 v[0:1], s[6:7], 0, v[166:167]
	s_add_i32 m0, s29, 0x1e000
	v_lshlrev_b32_e32 v2, 13, v218
	global_load_lds_dwordx4 v[0:1], off
	v_lshlrev_b32_e32 v1, 2, v163
	v_lshl_or_b32 v0, v163, 6, v227
	v_and_b32_e32 v1, 32, v1
	v_bitop3_b32 v0, v0, s1, v1 bitop3:0xde
	v_lshlrev_b32_e32 v1, 10, v222
	v_and_b32_e32 v1, 0xe0000, v1
	v_or3_b32 v1, v226, v1, v2
	v_lshlrev_b32_e32 v1, 6, v233
	s_waitcnt vmcnt(6)
	v_and_b32_e32 v1, 0x1e0000, v1
	v_or3_b32 v1, v226, v1, v2
	s_add_i32 s41, 0, 0x10000
	s_add_i32 s42, 0, 0x14000
	v_mbcnt_lo_u32_b32 v0, -1, 0
	s_ashr_i32 s39, s94, 31
	s_mov_b32 s40, s94
	v_mov_b32_e32 v133, v165
	v_mov_b32_e32 v135, v165
	v_mov_b64_e32 v[136:137], 0x200
	v_mov_b64_e32 v[138:139], 0x1ff
	v_mbcnt_hi_u32_b32 v148, -1, v0
	s_barrier
	s_branch .LBB0_753

.LBB0_759:
	s_ashr_i32 s15, s14, 31
	v_cmp_lt_i64_e32 vcc, s[16:17], v[136:137]
	s_lshl_b64 s[16:17], s[14:15], 21
	s_add_u32 s16, s96, s16
	s_addc_u32 s17, s97, s17
	s_and_b64 s[18:19], vcc, exec
	s_cselect_b32 s1, s17, s21
	s_cselect_b32 s9, s16, s20
	s_ashr_i32 s13, s12, 31
	s_lshl_b64 s[18:19], s[12:13], 20
	s_add_u32 s18, s26, s18
	s_addc_u32 s19, s27, s19
	s_and_b64 s[24:25], vcc, exec
	s_cselect_b32 s13, s19, s23
	s_cselect_b32 s15, s18, s22
	s_add_u32 s20, s20, 0x100080
	s_addc_u32 s21, s21, 0
	s_add_u32 s43, s22, 0x100
	v_mov_b32_e32 v0, 0
	s_addc_u32 s44, s23, 0
	s_mov_b32 s45, -2
	s_waitcnt lgkmcnt(0)
	v_mov_b32_e32 v1, v0
	v_mov_b32_e32 v2, v0
	v_mov_b32_e32 v3, v0
	v_mov_b32_e32 v4, v0
	v_mov_b32_e32 v5, v0
	v_mov_b32_e32 v6, v0
	v_mov_b32_e32 v7, v0
	s_waitcnt vmcnt(0)
	v_mov_b32_e32 v16, v0
	v_mov_b32_e32 v17, v0
	v_mov_b32_e32 v18, v0
	v_mov_b32_e32 v19, v0
	v_mov_b32_e32 v20, v0
	v_mov_b32_e32 v21, v0
	v_mov_b32_e32 v22, v0
	v_mov_b32_e32 v23, v0
	v_mov_b32_e32 v32, v0
	v_mov_b32_e32 v33, v0
	v_mov_b32_e32 v34, v0
	v_mov_b32_e32 v35, v0
	v_mov_b32_e32 v36, v0
	v_mov_b32_e32 v37, v0
	v_mov_b32_e32 v38, v0
	v_mov_b32_e32 v39, v0
	v_mov_b32_e32 v48, v0
	v_mov_b32_e32 v49, v0
	v_mov_b32_e32 v50, v0
	v_mov_b32_e32 v51, v0
	v_mov_b32_e32 v52, v0
	v_mov_b32_e32 v53, v0
	v_mov_b32_e32 v54, v0
	v_mov_b32_e32 v55, v0
	v_mov_b32_e32 v8, v0
	v_mov_b32_e32 v9, v0
	v_mov_b32_e32 v10, v0
	v_mov_b32_e32 v11, v0
	v_mov_b32_e32 v12, v0
	v_mov_b32_e32 v13, v0
	v_mov_b32_e32 v14, v0
	v_mov_b32_e32 v15, v0
	v_mov_b32_e32 v24, v0
	v_mov_b32_e32 v25, v0
	v_mov_b32_e32 v26, v0
	v_mov_b32_e32 v27, v0
	v_mov_b32_e32 v28, v0
	v_mov_b32_e32 v29, v0
	v_mov_b32_e32 v30, v0
	v_mov_b32_e32 v31, v0
	v_mov_b32_e32 v40, v0
	v_mov_b32_e32 v41, v0
	v_mov_b32_e32 v42, v0
	v_mov_b32_e32 v43, v0
	v_mov_b32_e32 v44, v0
	v_mov_b32_e32 v45, v0
	v_mov_b32_e32 v46, v0
	v_mov_b32_e32 v47, v0
	v_mov_b32_e32 v56, v0
	v_mov_b32_e32 v57, v0
	v_mov_b32_e32 v58, v0
	v_mov_b32_e32 v59, v0
	v_mov_b32_e32 v60, v0
	v_mov_b32_e32 v61, v0
	v_mov_b32_e32 v62, v0
	v_mov_b32_e32 v63, v0
	v_mov_b32_e32 v64, v0
	v_mov_b32_e32 v65, v0
	v_mov_b32_e32 v66, v0
	v_mov_b32_e32 v67, v0
	v_mov_b32_e32 v68, v0
	v_mov_b32_e32 v69, v0
	v_mov_b32_e32 v70, v0
	v_mov_b32_e32 v71, v0
	v_mov_b32_e32 v80, v0
	v_mov_b32_e32 v81, v0
	v_mov_b32_e32 v82, v0
	v_mov_b32_e32 v83, v0
	v_mov_b32_e32 v84, v0
	v_mov_b32_e32 v85, v0
	v_mov_b32_e32 v86, v0
	v_mov_b32_e32 v87, v0
	v_mov_b32_e32 v96, v0
	v_mov_b32_e32 v97, v0
	v_mov_b32_e32 v98, v0
	v_mov_b32_e32 v99, v0
	v_mov_b32_e32 v100, v0
	v_mov_b32_e32 v101, v0
	v_mov_b32_e32 v102, v0
	v_mov_b32_e32 v103, v0
	v_mov_b32_e32 v112, v0
	v_mov_b32_e32 v113, v0
	v_mov_b32_e32 v114, v0
	v_mov_b32_e32 v115, v0
	v_mov_b32_e32 v116, v0
	v_mov_b32_e32 v117, v0
	v_mov_b32_e32 v118, v0
	v_mov_b32_e32 v119, v0
	v_mov_b32_e32 v72, v0
	v_mov_b32_e32 v73, v0
	v_mov_b32_e32 v74, v0
	v_mov_b32_e32 v75, v0
	v_mov_b32_e32 v76, v0
	v_mov_b32_e32 v77, v0
	v_mov_b32_e32 v78, v0
	v_mov_b32_e32 v79, v0
	v_mov_b32_e32 v88, v0
	v_mov_b32_e32 v89, v0
	v_mov_b32_e32 v90, v0
	v_mov_b32_e32 v91, v0
	v_mov_b32_e32 v92, v0
	v_mov_b32_e32 v93, v0
	v_mov_b32_e32 v94, v0
	v_mov_b32_e32 v95, v0
	v_mov_b32_e32 v104, v0
	v_mov_b32_e32 v105, v0
	v_mov_b32_e32 v106, v0
	v_mov_b32_e32 v107, v0
	v_mov_b32_e32 v108, v0
	v_mov_b32_e32 v109, v0
	v_mov_b32_e32 v110, v0
	v_mov_b32_e32 v111, v0
	v_mov_b32_e32 v120, v0
	v_mov_b32_e32 v121, v0
	v_mov_b32_e32 v122, v0
	v_mov_b32_e32 v123, v0
	v_mov_b32_e32 v124, v0
	v_mov_b32_e32 v125, v0
	v_mov_b32_e32 v126, v0
	v_mov_b32_e32 v127, v0
	v_xor_b32_e32 v216, 64, v145
	v_xor_b32_e32 v217, 64, v146
	v_xor_b32_e32 v234, 64, v147
	v_add_u32_e32 v235, 0x18000, v144
	v_xor_b32_e32 v244, 64, v235
	s_cmpk_lt_u32 s3, 0x100
	s_cbranch_scc1 .Lst_in_s7
	s_barrier
.Lst_in_s7:
.LBB0_760:
	ds_read_b128 v[140:143], v145
	ds_read_b128 v[150:153], v216
	ds_read_b128 v[154:157], v145 offset:2048
	ds_read_b128 v[158:161], v216 offset:2048
	s_add_u32 s22, s20, 0xfff00080
	s_addc_u32 s23, s21, -1
	s_cmp_eq_u32 s45, 28
	s_cselect_b32 s25, s1, s23
	s_cselect_b32 s24, s9, s22
	s_cselect_b32 s23, s13, s44
	s_cselect_b32 s22, s15, s43
	s_add_i32 m0, s29, 0xc000
	ds_read_b128 v[176:179], v146
	ds_read_b128 v[180:183], v217
	ds_read_b128 v[184:187], v146 offset:2048
	ds_read_b128 v[188:191], v217 offset:2048
	ds_read_b128 v[192:195], v146 offset:4096
	ds_read_b128 v[196:199], v217 offset:4096
	ds_read_b128 v[200:203], v146 offset:6144
	ds_read_b128 v[204:207], v217 offset:6144
	global_load_lds_dwordx4 v132, s[20:21]
	s_add_i32 m0, s29, 0xe000
	s_nop 0
	global_load_lds_dwordx4 v134, s[20:21]
	s_waitcnt lgkmcnt(8)
	s_barrier
	s_waitcnt lgkmcnt(0)
	s_waitcnt lgkmcnt(0)
	v_mfma_f32_16x16x32_bf16 v[124:127], v[140:143], v[176:179], v[124:127]
	v_mfma_f32_16x16x32_bf16 v[124:127], v[150:153], v[180:183], v[124:127]
	v_mfma_f32_16x16x32_bf16 v[120:123], v[158:161], v[180:183], v[120:123]
	v_mfma_f32_16x16x32_bf16 v[120:123], v[154:157], v[176:179], v[120:123]
	v_mfma_f32_16x16x32_bf16 v[104:107], v[154:157], v[184:187], v[104:107]
	v_mfma_f32_16x16x32_bf16 v[104:107], v[158:161], v[188:191], v[104:107]
	v_mfma_f32_16x16x32_bf16 v[108:111], v[150:153], v[188:191], v[108:111]
	v_mfma_f32_16x16x32_bf16 v[108:111], v[140:143], v[184:187], v[108:111]
	v_mfma_f32_16x16x32_bf16 v[92:95], v[140:143], v[192:195], v[92:95]
	v_mfma_f32_16x16x32_bf16 v[92:95], v[150:153], v[196:199], v[92:95]
	v_mfma_f32_16x16x32_bf16 v[88:91], v[158:161], v[196:199], v[88:91]
	v_mfma_f32_16x16x32_bf16 v[88:91], v[154:157], v[192:195], v[88:91]
	v_mfma_f32_16x16x32_bf16 v[72:75], v[154:157], v[200:203], v[72:75]
	v_mfma_f32_16x16x32_bf16 v[72:75], v[158:161], v[204:207], v[72:75]
	v_mfma_f32_16x16x32_bf16 v[76:79], v[150:153], v[204:207], v[76:79]
	v_mfma_f32_16x16x32_bf16 v[76:79], v[140:143], v[200:203], v[76:79]
	s_barrier
	s_add_i32 s46, s41, s28
	s_add_u32 s98, s22, s10
	s_addc_u32 s99, s23, s11
	s_mov_b32 m0, s46
	ds_read_b128 v[208:211], v147
	ds_read_b128 v[212:215], v234
	ds_read_b128 v[236:239], v147 offset:2048
	ds_read_b128 v[240:243], v234 offset:2048
	global_load_lds_dwordx4 v164, s[22:23]
	s_add_i32 m0, s46, 0x2000
	s_nop 0
	global_load_lds_dwordx4 v166, s[22:23]
	s_barrier
	s_waitcnt lgkmcnt(0)
	s_waitcnt lgkmcnt(0)
	v_mfma_f32_16x16x32_bf16 v[116:119], v[208:211], v[176:179], v[116:119]
	v_mfma_f32_16x16x32_bf16 v[116:119], v[212:215], v[180:183], v[116:119]
	v_mfma_f32_16x16x32_bf16 v[112:115], v[240:243], v[180:183], v[112:115]
	v_mfma_f32_16x16x32_bf16 v[112:115], v[236:239], v[176:179], v[112:115]
	v_mfma_f32_16x16x32_bf16 v[96:99], v[236:239], v[184:187], v[96:99]
	v_mfma_f32_16x16x32_bf16 v[96:99], v[240:243], v[188:191], v[96:99]
	v_mfma_f32_16x16x32_bf16 v[100:103], v[212:215], v[188:191], v[100:103]
	v_mfma_f32_16x16x32_bf16 v[100:103], v[208:211], v[184:187], v[100:103]
	v_mfma_f32_16x16x32_bf16 v[84:87], v[208:211], v[192:195], v[84:87]
	v_mfma_f32_16x16x32_bf16 v[84:87], v[212:215], v[196:199], v[84:87]
	v_mfma_f32_16x16x32_bf16 v[80:83], v[240:243], v[196:199], v[80:83]
	v_mfma_f32_16x16x32_bf16 v[80:83], v[236:239], v[192:195], v[80:83]
	v_mfma_f32_16x16x32_bf16 v[64:67], v[236:239], v[200:203], v[64:67]
	v_mfma_f32_16x16x32_bf16 v[64:67], v[240:243], v[204:207], v[64:67]
	v_mfma_f32_16x16x32_bf16 v[68:71], v[212:215], v[204:207], v[68:71]
	v_mfma_f32_16x16x32_bf16 v[68:71], v[208:211], v[200:203], v[68:71]
	s_mov_b32 m0, s29
	s_add_u32 s100, s24, s10
	s_addc_u32 s101, s25, s11
	s_barrier
	ds_read_b128 v[176:179], v146 offset:16384
	ds_read_b128 v[180:183], v217 offset:16384
	ds_read_b128 v[184:187], v146 offset:18432
	ds_read_b128 v[188:191], v217 offset:18432
	ds_read_b128 v[192:195], v146 offset:20480
	ds_read_b128 v[196:199], v217 offset:20480
	ds_read_b128 v[200:203], v146 offset:22528
	ds_read_b128 v[204:207], v217 offset:22528
	global_load_lds_dwordx4 v128, s[24:25]
	s_mov_b32 m0, s30
	s_nop 0
	global_load_lds_dwordx4 v130, s[24:25]
	s_barrier
	s_waitcnt lgkmcnt(0)
	s_waitcnt lgkmcnt(0)
	v_mfma_f32_16x16x32_bf16 v[60:63], v[140:143], v[176:179], v[60:63]
	v_mfma_f32_16x16x32_bf16 v[60:63], v[150:153], v[180:183], v[60:63]
	v_mfma_f32_16x16x32_bf16 v[56:59], v[158:161], v[180:183], v[56:59]
	v_mfma_f32_16x16x32_bf16 v[56:59], v[154:157], v[176:179], v[56:59]
	v_mfma_f32_16x16x32_bf16 v[40:43], v[154:157], v[184:187], v[40:43]
	v_mfma_f32_16x16x32_bf16 v[40:43], v[158:161], v[188:191], v[40:43]
	v_mfma_f32_16x16x32_bf16 v[44:47], v[150:153], v[188:191], v[44:47]
	v_mfma_f32_16x16x32_bf16 v[44:47], v[140:143], v[184:187], v[44:47]
	v_mfma_f32_16x16x32_bf16 v[28:31], v[140:143], v[192:195], v[28:31]
	v_mfma_f32_16x16x32_bf16 v[28:31], v[150:153], v[196:199], v[28:31]
	v_mfma_f32_16x16x32_bf16 v[24:27], v[158:161], v[196:199], v[24:27]
	v_mfma_f32_16x16x32_bf16 v[24:27], v[154:157], v[192:195], v[24:27]
	v_mfma_f32_16x16x32_bf16 v[8:11], v[154:157], v[200:203], v[8:11]
	v_mfma_f32_16x16x32_bf16 v[8:11], v[158:161], v[204:207], v[8:11]
	v_mfma_f32_16x16x32_bf16 v[12:15], v[150:153], v[204:207], v[12:15]
	v_mfma_f32_16x16x32_bf16 v[12:15], v[140:143], v[200:203], v[12:15]
	s_barrier
	s_add_u32 s46, s22, 0x80000
	s_addc_u32 s47, s23, 0
	s_add_i32 s48, s42, s28
	s_mov_b32 m0, s48
	s_nop 0
	global_load_lds_dwordx4 v164, s[46:47]
	s_add_i32 m0, s48, 0x2000
	s_nop 0
	global_load_lds_dwordx4 v166, s[46:47]
	s_waitcnt vmcnt(6)
	s_barrier
	v_mfma_f32_16x16x32_bf16 v[52:55], v[208:211], v[176:179], v[52:55]
	v_mfma_f32_16x16x32_bf16 v[52:55], v[212:215], v[180:183], v[52:55]
	v_mfma_f32_16x16x32_bf16 v[48:51], v[240:243], v[180:183], v[48:51]
	v_mfma_f32_16x16x32_bf16 v[48:51], v[236:239], v[176:179], v[48:51]
	v_mfma_f32_16x16x32_bf16 v[32:35], v[236:239], v[184:187], v[32:35]
	v_mfma_f32_16x16x32_bf16 v[32:35], v[240:243], v[188:191], v[32:35]
	v_mfma_f32_16x16x32_bf16 v[36:39], v[212:215], v[188:191], v[36:39]
	v_mfma_f32_16x16x32_bf16 v[36:39], v[208:211], v[184:187], v[36:39]
	v_mfma_f32_16x16x32_bf16 v[20:23], v[208:211], v[192:195], v[20:23]
	v_mfma_f32_16x16x32_bf16 v[20:23], v[212:215], v[196:199], v[20:23]
	v_mfma_f32_16x16x32_bf16 v[16:19], v[240:243], v[196:199], v[16:19]
	v_mfma_f32_16x16x32_bf16 v[16:19], v[236:239], v[192:195], v[16:19]
	v_mfma_f32_16x16x32_bf16 v[0:3], v[236:239], v[200:203], v[0:3]
	v_mfma_f32_16x16x32_bf16 v[0:3], v[240:243], v[204:207], v[0:3]
	v_mfma_f32_16x16x32_bf16 v[4:7], v[212:215], v[204:207], v[4:7]
	v_mfma_f32_16x16x32_bf16 v[4:7], v[208:211], v[200:203], v[4:7]
	s_add_i32 s46, 0, 0x18000
	s_barrier
	ds_read_b128 v[140:143], v235
	ds_read_b128 v[150:153], v244
	ds_read_b128 v[154:157], v235 offset:2048
	ds_read_b128 v[158:161], v244 offset:2048
	s_add_u32 s24, s24, 0x100000
	s_addc_u32 s25, s25, 0
	s_mov_b32 m0, s31
	ds_read_b128 v[176:179], v146 offset:32768
	ds_read_b128 v[180:183], v217 offset:32768
	ds_read_b128 v[184:187], v146 offset:34816
	ds_read_b128 v[188:191], v217 offset:34816
	ds_read_b128 v[192:195], v146 offset:36864
	ds_read_b128 v[196:199], v217 offset:36864
	ds_read_b128 v[200:203], v146 offset:38912
	ds_read_b128 v[204:207], v217 offset:38912
	global_load_lds_dwordx4 v128, s[24:25]
	s_mov_b32 m0, s33
	s_nop 0
	global_load_lds_dwordx4 v130, s[24:25]
	s_waitcnt lgkmcnt(8)
	s_barrier
	s_waitcnt lgkmcnt(0)
	s_waitcnt lgkmcnt(0)
	v_mfma_f32_16x16x32_bf16 v[124:127], v[140:143], v[176:179], v[124:127]
	v_mfma_f32_16x16x32_bf16 v[124:127], v[150:153], v[180:183], v[124:127]
	v_mfma_f32_16x16x32_bf16 v[120:123], v[158:161], v[180:183], v[120:123]
	v_mfma_f32_16x16x32_bf16 v[120:123], v[154:157], v[176:179], v[120:123]
	v_mfma_f32_16x16x32_bf16 v[104:107], v[154:157], v[184:187], v[104:107]
	v_mfma_f32_16x16x32_bf16 v[104:107], v[158:161], v[188:191], v[104:107]
	v_mfma_f32_16x16x32_bf16 v[108:111], v[150:153], v[188:191], v[108:111]
	v_mfma_f32_16x16x32_bf16 v[108:111], v[140:143], v[184:187], v[108:111]
	v_mfma_f32_16x16x32_bf16 v[92:95], v[140:143], v[192:195], v[92:95]
	v_mfma_f32_16x16x32_bf16 v[92:95], v[150:153], v[196:199], v[92:95]
	v_mfma_f32_16x16x32_bf16 v[88:91], v[158:161], v[196:199], v[88:91]
	v_mfma_f32_16x16x32_bf16 v[88:91], v[154:157], v[192:195], v[88:91]
	v_mfma_f32_16x16x32_bf16 v[72:75], v[154:157], v[200:203], v[72:75]
	v_mfma_f32_16x16x32_bf16 v[72:75], v[158:161], v[204:207], v[72:75]
	v_mfma_f32_16x16x32_bf16 v[76:79], v[150:153], v[204:207], v[76:79]
	v_mfma_f32_16x16x32_bf16 v[76:79], v[140:143], v[200:203], v[76:79]
	s_barrier
	s_add_i32 s24, 0, 0x1c000
	s_add_i32 s25, s46, s28
	v_add_u32_e32 v149, s24, v144
	s_mov_b32 m0, s25
	ds_read_b128 v[208:211], v149
	v_xor_b32_e32 v243, 64, v149
	ds_read_b128 v[212:215], v243
	ds_read_b128 v[236:239], v149 offset:2048
	ds_read_b128 v[240:243], v243 offset:2048
	global_load_lds_dwordx4 v164, s[98:99]
	s_add_i32 m0, s25, 0x2000
	s_nop 0
	global_load_lds_dwordx4 v166, s[98:99]
	s_barrier
	s_waitcnt lgkmcnt(0)
	s_waitcnt lgkmcnt(0)
	v_mfma_f32_16x16x32_bf16 v[116:119], v[208:211], v[176:179], v[116:119]
	v_mfma_f32_16x16x32_bf16 v[116:119], v[212:215], v[180:183], v[116:119]
	v_mfma_f32_16x16x32_bf16 v[112:115], v[240:243], v[180:183], v[112:115]
	v_mfma_f32_16x16x32_bf16 v[112:115], v[236:239], v[176:179], v[112:115]
	v_mfma_f32_16x16x32_bf16 v[96:99], v[236:239], v[184:187], v[96:99]
	v_mfma_f32_16x16x32_bf16 v[96:99], v[240:243], v[188:191], v[96:99]
	v_mfma_f32_16x16x32_bf16 v[100:103], v[212:215], v[188:191], v[100:103]
	v_mfma_f32_16x16x32_bf16 v[100:103], v[208:211], v[184:187], v[100:103]
	v_mfma_f32_16x16x32_bf16 v[84:87], v[208:211], v[192:195], v[84:87]
	v_mfma_f32_16x16x32_bf16 v[84:87], v[212:215], v[196:199], v[84:87]
	v_mfma_f32_16x16x32_bf16 v[80:83], v[240:243], v[196:199], v[80:83]
	v_mfma_f32_16x16x32_bf16 v[80:83], v[236:239], v[192:195], v[80:83]
	v_mfma_f32_16x16x32_bf16 v[64:67], v[236:239], v[200:203], v[64:67]
	v_mfma_f32_16x16x32_bf16 v[64:67], v[240:243], v[204:207], v[64:67]
	v_mfma_f32_16x16x32_bf16 v[68:71], v[212:215], v[204:207], v[68:71]
	v_mfma_f32_16x16x32_bf16 v[68:71], v[208:211], v[200:203], v[68:71]
	s_mov_b32 m0, s37
	s_barrier
	ds_read_b128 v[176:179], v146 offset:49152
	ds_read_b128 v[180:183], v217 offset:49152
	ds_read_b128 v[184:187], v146 offset:51200
	ds_read_b128 v[188:191], v217 offset:51200
	ds_read_b128 v[192:195], v146 offset:53248
	ds_read_b128 v[196:199], v217 offset:53248
	ds_read_b128 v[200:203], v146 offset:55296
	ds_read_b128 v[204:207], v217 offset:55296
	global_load_lds_dwordx4 v128, s[100:101]
	s_mov_b32 m0, s38
	s_nop 0
	global_load_lds_dwordx4 v130, s[100:101]
	s_barrier
	s_waitcnt lgkmcnt(0)
	s_waitcnt lgkmcnt(0)
	v_mfma_f32_16x16x32_bf16 v[60:63], v[140:143], v[176:179], v[60:63]
	v_mfma_f32_16x16x32_bf16 v[60:63], v[150:153], v[180:183], v[60:63]
	v_mfma_f32_16x16x32_bf16 v[56:59], v[158:161], v[180:183], v[56:59]
	v_mfma_f32_16x16x32_bf16 v[56:59], v[154:157], v[176:179], v[56:59]
	v_mfma_f32_16x16x32_bf16 v[40:43], v[154:157], v[184:187], v[40:43]
	v_mfma_f32_16x16x32_bf16 v[40:43], v[158:161], v[188:191], v[40:43]
	v_mfma_f32_16x16x32_bf16 v[44:47], v[150:153], v[188:191], v[44:47]
	v_mfma_f32_16x16x32_bf16 v[44:47], v[140:143], v[184:187], v[44:47]
	v_mfma_f32_16x16x32_bf16 v[28:31], v[140:143], v[192:195], v[28:31]
	v_mfma_f32_16x16x32_bf16 v[28:31], v[150:153], v[196:199], v[28:31]
	v_mfma_f32_16x16x32_bf16 v[24:27], v[158:161], v[196:199], v[24:27]
	v_mfma_f32_16x16x32_bf16 v[24:27], v[154:157], v[192:195], v[24:27]
	v_mfma_f32_16x16x32_bf16 v[8:11], v[154:157], v[200:203], v[8:11]
	v_mfma_f32_16x16x32_bf16 v[8:11], v[158:161], v[204:207], v[8:11]
	v_mfma_f32_16x16x32_bf16 v[12:15], v[150:153], v[204:207], v[12:15]
	v_mfma_f32_16x16x32_bf16 v[12:15], v[140:143], v[200:203], v[12:15]
	s_barrier
	s_add_u32 s22, s22, 0x80080
	s_addc_u32 s23, s23, 0
	s_add_i32 s24, s24, s28
	s_mov_b32 m0, s24
	s_nop 0
	global_load_lds_dwordx4 v164, s[22:23]
	s_add_i32 m0, s24, 0x2000
	s_nop 0
	global_load_lds_dwordx4 v166, s[22:23]
	s_waitcnt vmcnt(6)
	s_barrier
	v_mfma_f32_16x16x32_bf16 v[52:55], v[208:211], v[176:179], v[52:55]
	v_mfma_f32_16x16x32_bf16 v[52:55], v[212:215], v[180:183], v[52:55]
	v_mfma_f32_16x16x32_bf16 v[48:51], v[240:243], v[180:183], v[48:51]
	v_mfma_f32_16x16x32_bf16 v[48:51], v[236:239], v[176:179], v[48:51]
	v_mfma_f32_16x16x32_bf16 v[32:35], v[236:239], v[184:187], v[32:35]
	v_mfma_f32_16x16x32_bf16 v[32:35], v[240:243], v[188:191], v[32:35]
	v_mfma_f32_16x16x32_bf16 v[36:39], v[212:215], v[188:191], v[36:39]
	v_mfma_f32_16x16x32_bf16 v[36:39], v[208:211], v[184:187], v[36:39]
	v_mfma_f32_16x16x32_bf16 v[20:23], v[208:211], v[192:195], v[20:23]
	v_mfma_f32_16x16x32_bf16 v[20:23], v[212:215], v[196:199], v[20:23]
	v_mfma_f32_16x16x32_bf16 v[16:19], v[240:243], v[196:199], v[16:19]
	v_mfma_f32_16x16x32_bf16 v[16:19], v[236:239], v[192:195], v[16:19]
	v_mfma_f32_16x16x32_bf16 v[0:3], v[236:239], v[200:203], v[0:3]
	v_mfma_f32_16x16x32_bf16 v[0:3], v[240:243], v[204:207], v[0:3]
	v_mfma_f32_16x16x32_bf16 v[4:7], v[212:215], v[204:207], v[4:7]
	v_mfma_f32_16x16x32_bf16 v[4:7], v[208:211], v[200:203], v[4:7]
	s_add_i32 s45, s45, 2
	s_add_u32 s20, s20, 0x100
	s_addc_u32 s21, s21, 0
	s_add_u32 s43, s43, 0x100
	s_addc_u32 s44, s44, 0
	s_cmp_gt_u32 s45, 29
	s_barrier
	s_cbranch_scc0 .LBB0_760
	s_cmpk_gt_u32 s3, 0xff
	s_cbranch_scc1 .Lst_out_s7
	s_barrier
.Lst_out_s7:
	v_lshl_add_u32 v217, s8, 8, v163
	v_add_u32_e32 v217, s35, v217
	v_lshlrev_b32_e32 v208, 2, v217
	v_lshl_add_u32 v214, v225, 3, s36
	v_lshl_add_u32 v214, s0, 8, v214
	v_lshl_add_u32 v209, v217, 11, v214
	v_lshlrev_b32_e32 v209, 1, v209
	v_lshlrev_b32_e32 v210, 1, v209
	v_lshl_add_u32 v217, v225, 4, v163
	v_xor_b32_e32 v215, 16, v217
	v_lshlrev_b32_e32 v215, 2, v215
	v_xor_b32_e32 v216, 32, v217
	v_lshlrev_b32_e32 v216, 2, v216
	v_add_u32_e32 v211, 0x0, v209
	global_load_dwordx4 v[176:179], v211, s[80:81]
	global_load_dwordx4 v[180:183], v211, s[80:81] offset:256
	v_add_u32_e32 v211, 0x10000, v209
	global_load_dwordx4 v[192:195], v211, s[80:81]
	global_load_dwordx4 v[196:199], v211, s[80:81] offset:256
	s_waitcnt vmcnt(2)
	v_lshlrev_b32_e32 v184, 16, v176
	v_and_b32_e32 v185, 0xffff0000, v176
	v_lshlrev_b32_e32 v186, 16, v177
	v_and_b32_e32 v187, 0xffff0000, v177
	v_lshlrev_b32_e32 v188, 16, v178
	v_and_b32_e32 v189, 0xffff0000, v178
	v_lshlrev_b32_e32 v190, 16, v179
	v_and_b32_e32 v191, 0xffff0000, v179
	v_pk_add_f32 v[124:125], v[124:125], v[184:185]
	v_pk_add_f32 v[126:127], v[126:127], v[186:187]
	v_pk_add_f32 v[120:121], v[120:121], v[188:189]
	v_pk_add_f32 v[122:123], v[122:123], v[190:191]
	v_mul_f32_e32 v213, v124, v124
	v_fmac_f32_e32 v213, v125, v125
	v_fmac_f32_e32 v213, v126, v126
	v_fmac_f32_e32 v213, v127, v127
	v_fmac_f32_e32 v213, v120, v120
	v_fmac_f32_e32 v213, v121, v121
	v_fmac_f32_e32 v213, v122, v122
	v_fmac_f32_e32 v213, v123, v123
	v_cvt_pk_bf16_f32 v176, v124, v125
	v_cvt_pk_bf16_f32 v177, v126, v127
	v_cvt_pk_bf16_f32 v178, v120, v121
	v_cvt_pk_bf16_f32 v179, v122, v123
	v_add_u32_e32 v217, 0x0, v209
	global_store_dwordx4 v217, v[176:179], s[80:81]
	v_lshlrev_b32_e32 v184, 16, v180
	v_and_b32_e32 v185, 0xffff0000, v180
	v_lshlrev_b32_e32 v186, 16, v181
	v_and_b32_e32 v187, 0xffff0000, v181
	v_lshlrev_b32_e32 v188, 16, v182
	v_and_b32_e32 v189, 0xffff0000, v182
	v_lshlrev_b32_e32 v190, 16, v183
	v_and_b32_e32 v191, 0xffff0000, v183
	v_pk_add_f32 v[116:117], v[116:117], v[184:185]
	v_pk_add_f32 v[118:119], v[118:119], v[186:187]
	v_pk_add_f32 v[112:113], v[112:113], v[188:189]
	v_pk_add_f32 v[114:115], v[114:115], v[190:191]
	v_fmac_f32_e32 v213, v116, v116
	v_fmac_f32_e32 v213, v117, v117
	v_fmac_f32_e32 v213, v118, v118
	v_fmac_f32_e32 v213, v119, v119
	v_fmac_f32_e32 v213, v112, v112
	v_fmac_f32_e32 v213, v113, v113
	v_fmac_f32_e32 v213, v114, v114
	v_fmac_f32_e32 v213, v115, v115
	v_cvt_pk_bf16_f32 v180, v116, v117
	v_cvt_pk_bf16_f32 v181, v118, v119
	v_cvt_pk_bf16_f32 v182, v112, v113
	v_cvt_pk_bf16_f32 v183, v114, v115
	global_store_dwordx4 v217, v[180:183], s[80:81] offset:256
	ds_bpermute_b32 v214, v215, v213
	s_waitcnt lgkmcnt(0)
	v_add_f32_e32 v213, v213, v214
	ds_bpermute_b32 v214, v216, v213
	s_waitcnt lgkmcnt(0)
	v_add_f32_e32 v213, v213, v214
	s_mov_b64 exec, 0xffff
	global_atomic_add_f32 v208, v213, s[4:5]
	s_mov_b64 exec, -1
	v_add_u32_e32 v211, 0x20000, v209
	global_load_dwordx4 v[176:179], v211, s[80:81]
	global_load_dwordx4 v[180:183], v211, s[80:81] offset:256
	s_waitcnt vmcnt(5)
	v_lshlrev_b32_e32 v200, 16, v192
	v_and_b32_e32 v201, 0xffff0000, v192
	v_lshlrev_b32_e32 v202, 16, v193
	v_and_b32_e32 v203, 0xffff0000, v193
	v_lshlrev_b32_e32 v204, 16, v194
	v_and_b32_e32 v205, 0xffff0000, v194
	v_lshlrev_b32_e32 v206, 16, v195
	v_and_b32_e32 v207, 0xffff0000, v195
	v_pk_add_f32 v[108:109], v[108:109], v[200:201]
	v_pk_add_f32 v[110:111], v[110:111], v[202:203]
	v_pk_add_f32 v[104:105], v[104:105], v[204:205]
	v_pk_add_f32 v[106:107], v[106:107], v[206:207]
	v_mul_f32_e32 v213, v108, v108
	v_fmac_f32_e32 v213, v109, v109
	v_fmac_f32_e32 v213, v110, v110
	v_fmac_f32_e32 v213, v111, v111
	v_fmac_f32_e32 v213, v104, v104
	v_fmac_f32_e32 v213, v105, v105
	v_fmac_f32_e32 v213, v106, v106
	v_fmac_f32_e32 v213, v107, v107
	v_cvt_pk_bf16_f32 v192, v108, v109
	v_cvt_pk_bf16_f32 v193, v110, v111
	v_cvt_pk_bf16_f32 v194, v104, v105
	v_cvt_pk_bf16_f32 v195, v106, v107
	v_add_u32_e32 v217, 0x10000, v209
	global_store_dwordx4 v217, v[192:195], s[80:81]
	v_lshlrev_b32_e32 v200, 16, v196
	v_and_b32_e32 v201, 0xffff0000, v196
	v_lshlrev_b32_e32 v202, 16, v197
	v_and_b32_e32 v203, 0xffff0000, v197
	v_lshlrev_b32_e32 v204, 16, v198
	v_and_b32_e32 v205, 0xffff0000, v198
	v_lshlrev_b32_e32 v206, 16, v199
	v_and_b32_e32 v207, 0xffff0000, v199
	v_pk_add_f32 v[100:101], v[100:101], v[200:201]
	v_pk_add_f32 v[102:103], v[102:103], v[202:203]
	v_pk_add_f32 v[96:97], v[96:97], v[204:205]
	v_pk_add_f32 v[98:99], v[98:99], v[206:207]
	v_fmac_f32_e32 v213, v100, v100
	v_fmac_f32_e32 v213, v101, v101
	v_fmac_f32_e32 v213, v102, v102
	v_fmac_f32_e32 v213, v103, v103
	v_fmac_f32_e32 v213, v96, v96
	v_fmac_f32_e32 v213, v97, v97
	v_fmac_f32_e32 v213, v98, v98
	v_fmac_f32_e32 v213, v99, v99
	v_cvt_pk_bf16_f32 v196, v100, v101
	v_cvt_pk_bf16_f32 v197, v102, v103
	v_cvt_pk_bf16_f32 v198, v96, v97
	v_cvt_pk_bf16_f32 v199, v98, v99
	global_store_dwordx4 v217, v[196:199], s[80:81] offset:256
	ds_bpermute_b32 v214, v215, v213
	s_waitcnt lgkmcnt(0)
	v_add_f32_e32 v213, v213, v214
	ds_bpermute_b32 v214, v216, v213
	s_waitcnt lgkmcnt(0)
	v_add_f32_e32 v213, v213, v214
	s_mov_b64 exec, 0xffff
	global_atomic_add_f32 v208, v213, s[4:5] offset:64
	s_mov_b64 exec, -1
	v_add_u32_e32 v211, 0x30000, v209
	global_load_dwordx4 v[192:195], v211, s[80:81]
	global_load_dwordx4 v[196:199], v211, s[80:81] offset:256
	s_waitcnt vmcnt(5)
	v_lshlrev_b32_e32 v184, 16, v176
	v_and_b32_e32 v185, 0xffff0000, v176
	v_lshlrev_b32_e32 v186, 16, v177
	v_and_b32_e32 v187, 0xffff0000, v177
	v_lshlrev_b32_e32 v188, 16, v178
	v_and_b32_e32 v189, 0xffff0000, v178
	v_lshlrev_b32_e32 v190, 16, v179
	v_and_b32_e32 v191, 0xffff0000, v179
	v_pk_add_f32 v[92:93], v[92:93], v[184:185]
	v_pk_add_f32 v[94:95], v[94:95], v[186:187]
	v_pk_add_f32 v[88:89], v[88:89], v[188:189]
	v_pk_add_f32 v[90:91], v[90:91], v[190:191]
	v_mul_f32_e32 v213, v92, v92
	v_fmac_f32_e32 v213, v93, v93
	v_fmac_f32_e32 v213, v94, v94
	v_fmac_f32_e32 v213, v95, v95
	v_fmac_f32_e32 v213, v88, v88
	v_fmac_f32_e32 v213, v89, v89
	v_fmac_f32_e32 v213, v90, v90
	v_fmac_f32_e32 v213, v91, v91
	v_cvt_pk_bf16_f32 v176, v92, v93
	v_cvt_pk_bf16_f32 v177, v94, v95
	v_cvt_pk_bf16_f32 v178, v88, v89
	v_cvt_pk_bf16_f32 v179, v90, v91
	v_add_u32_e32 v217, 0x20000, v209
	global_store_dwordx4 v217, v[176:179], s[80:81]
	v_lshlrev_b32_e32 v184, 16, v180
	v_and_b32_e32 v185, 0xffff0000, v180
	v_lshlrev_b32_e32 v186, 16, v181
	v_and_b32_e32 v187, 0xffff0000, v181
	v_lshlrev_b32_e32 v188, 16, v182
	v_and_b32_e32 v189, 0xffff0000, v182
	v_lshlrev_b32_e32 v190, 16, v183
	v_and_b32_e32 v191, 0xffff0000, v183
	v_pk_add_f32 v[84:85], v[84:85], v[184:185]
	v_pk_add_f32 v[86:87], v[86:87], v[186:187]
	v_pk_add_f32 v[80:81], v[80:81], v[188:189]
	v_pk_add_f32 v[82:83], v[82:83], v[190:191]
	v_fmac_f32_e32 v213, v84, v84
	v_fmac_f32_e32 v213, v85, v85
	v_fmac_f32_e32 v213, v86, v86
	v_fmac_f32_e32 v213, v87, v87
	v_fmac_f32_e32 v213, v80, v80
	v_fmac_f32_e32 v213, v81, v81
	v_fmac_f32_e32 v213, v82, v82
	v_fmac_f32_e32 v213, v83, v83
	v_cvt_pk_bf16_f32 v180, v84, v85
	v_cvt_pk_bf16_f32 v181, v86, v87
	v_cvt_pk_bf16_f32 v182, v80, v81
	v_cvt_pk_bf16_f32 v183, v82, v83
	global_store_dwordx4 v217, v[180:183], s[80:81] offset:256
	ds_bpermute_b32 v214, v215, v213
	s_waitcnt lgkmcnt(0)
	v_add_f32_e32 v213, v213, v214
	ds_bpermute_b32 v214, v216, v213
	s_waitcnt lgkmcnt(0)
	v_add_f32_e32 v213, v213, v214
	s_mov_b64 exec, 0xffff
	global_atomic_add_f32 v208, v213, s[4:5] offset:128
	s_mov_b64 exec, -1
	v_add_u32_e32 v211, 0x80000, v209
	global_load_dwordx4 v[176:179], v211, s[80:81]
	global_load_dwordx4 v[180:183], v211, s[80:81] offset:256
	s_waitcnt vmcnt(5)
	v_lshlrev_b32_e32 v200, 16, v192
	v_and_b32_e32 v201, 0xffff0000, v192
	v_lshlrev_b32_e32 v202, 16, v193
	v_and_b32_e32 v203, 0xffff0000, v193
	v_lshlrev_b32_e32 v204, 16, v194
	v_and_b32_e32 v205, 0xffff0000, v194
	v_lshlrev_b32_e32 v206, 16, v195
	v_and_b32_e32 v207, 0xffff0000, v195
	v_pk_add_f32 v[76:77], v[76:77], v[200:201]
	v_pk_add_f32 v[78:79], v[78:79], v[202:203]
	v_pk_add_f32 v[72:73], v[72:73], v[204:205]
	v_pk_add_f32 v[74:75], v[74:75], v[206:207]
	v_mul_f32_e32 v213, v76, v76
	v_fmac_f32_e32 v213, v77, v77
	v_fmac_f32_e32 v213, v78, v78
	v_fmac_f32_e32 v213, v79, v79
	v_fmac_f32_e32 v213, v72, v72
	v_fmac_f32_e32 v213, v73, v73
	v_fmac_f32_e32 v213, v74, v74
	v_fmac_f32_e32 v213, v75, v75
	v_cvt_pk_bf16_f32 v192, v76, v77
	v_cvt_pk_bf16_f32 v193, v78, v79
	v_cvt_pk_bf16_f32 v194, v72, v73
	v_cvt_pk_bf16_f32 v195, v74, v75
	v_add_u32_e32 v217, 0x30000, v209
	global_store_dwordx4 v217, v[192:195], s[80:81]
	v_lshlrev_b32_e32 v200, 16, v196
	v_and_b32_e32 v201, 0xffff0000, v196
	v_lshlrev_b32_e32 v202, 16, v197
	v_and_b32_e32 v203, 0xffff0000, v197
	v_lshlrev_b32_e32 v204, 16, v198
	v_and_b32_e32 v205, 0xffff0000, v198
	v_lshlrev_b32_e32 v206, 16, v199
	v_and_b32_e32 v207, 0xffff0000, v199
	v_pk_add_f32 v[68:69], v[68:69], v[200:201]
	v_pk_add_f32 v[70:71], v[70:71], v[202:203]
	v_pk_add_f32 v[64:65], v[64:65], v[204:205]
	v_pk_add_f32 v[66:67], v[66:67], v[206:207]
	v_fmac_f32_e32 v213, v68, v68
	v_fmac_f32_e32 v213, v69, v69
	v_fmac_f32_e32 v213, v70, v70
	v_fmac_f32_e32 v213, v71, v71
	v_fmac_f32_e32 v213, v64, v64
	v_fmac_f32_e32 v213, v65, v65
	v_fmac_f32_e32 v213, v66, v66
	v_fmac_f32_e32 v213, v67, v67
	v_cvt_pk_bf16_f32 v196, v68, v69
	v_cvt_pk_bf16_f32 v197, v70, v71
	v_cvt_pk_bf16_f32 v198, v64, v65
	v_cvt_pk_bf16_f32 v199, v66, v67
	global_store_dwordx4 v217, v[196:199], s[80:81] offset:256
	ds_bpermute_b32 v214, v215, v213
	s_waitcnt lgkmcnt(0)
	v_add_f32_e32 v213, v213, v214
	ds_bpermute_b32 v214, v216, v213
	s_waitcnt lgkmcnt(0)
	v_add_f32_e32 v213, v213, v214
	s_mov_b64 exec, 0xffff
	global_atomic_add_f32 v208, v213, s[4:5] offset:192
	s_mov_b64 exec, -1
	v_add_u32_e32 v211, 0x90000, v209
	global_load_dwordx4 v[192:195], v211, s[80:81]
	global_load_dwordx4 v[196:199], v211, s[80:81] offset:256
	s_waitcnt vmcnt(5)
	v_lshlrev_b32_e32 v184, 16, v176
	v_and_b32_e32 v185, 0xffff0000, v176
	v_lshlrev_b32_e32 v186, 16, v177
	v_and_b32_e32 v187, 0xffff0000, v177
	v_lshlrev_b32_e32 v188, 16, v178
	v_and_b32_e32 v189, 0xffff0000, v178
	v_lshlrev_b32_e32 v190, 16, v179
	v_and_b32_e32 v191, 0xffff0000, v179
	v_pk_add_f32 v[60:61], v[60:61], v[184:185]
	v_pk_add_f32 v[62:63], v[62:63], v[186:187]
	v_pk_add_f32 v[56:57], v[56:57], v[188:189]
	v_pk_add_f32 v[58:59], v[58:59], v[190:191]
	v_mul_f32_e32 v213, v60, v60
	v_fmac_f32_e32 v213, v61, v61
	v_fmac_f32_e32 v213, v62, v62
	v_fmac_f32_e32 v213, v63, v63
	v_fmac_f32_e32 v213, v56, v56
	v_fmac_f32_e32 v213, v57, v57
	v_fmac_f32_e32 v213, v58, v58
	v_fmac_f32_e32 v213, v59, v59
	v_cvt_pk_bf16_f32 v176, v60, v61
	v_cvt_pk_bf16_f32 v177, v62, v63
	v_cvt_pk_bf16_f32 v178, v56, v57
	v_cvt_pk_bf16_f32 v179, v58, v59
	v_add_u32_e32 v217, 0x80000, v209
	global_store_dwordx4 v217, v[176:179], s[80:81]
	v_lshlrev_b32_e32 v184, 16, v180
	v_and_b32_e32 v185, 0xffff0000, v180
	v_lshlrev_b32_e32 v186, 16, v181
	v_and_b32_e32 v187, 0xffff0000, v181
	v_lshlrev_b32_e32 v188, 16, v182
	v_and_b32_e32 v189, 0xffff0000, v182
	v_lshlrev_b32_e32 v190, 16, v183
	v_and_b32_e32 v191, 0xffff0000, v183
	v_pk_add_f32 v[52:53], v[52:53], v[184:185]
	v_pk_add_f32 v[54:55], v[54:55], v[186:187]
	v_pk_add_f32 v[48:49], v[48:49], v[188:189]
	v_pk_add_f32 v[50:51], v[50:51], v[190:191]
	v_fmac_f32_e32 v213, v52, v52
	v_fmac_f32_e32 v213, v53, v53
	v_fmac_f32_e32 v213, v54, v54
	v_fmac_f32_e32 v213, v55, v55
	v_fmac_f32_e32 v213, v48, v48
	v_fmac_f32_e32 v213, v49, v49
	v_fmac_f32_e32 v213, v50, v50
	v_fmac_f32_e32 v213, v51, v51
	v_cvt_pk_bf16_f32 v180, v52, v53
	v_cvt_pk_bf16_f32 v181, v54, v55
	v_cvt_pk_bf16_f32 v182, v48, v49
	v_cvt_pk_bf16_f32 v183, v50, v51
	global_store_dwordx4 v217, v[180:183], s[80:81] offset:256
	ds_bpermute_b32 v214, v215, v213
	s_waitcnt lgkmcnt(0)
	v_add_f32_e32 v213, v213, v214
	ds_bpermute_b32 v214, v216, v213
	s_waitcnt lgkmcnt(0)
	v_add_f32_e32 v213, v213, v214
	s_mov_b64 exec, 0xffff
	global_atomic_add_f32 v208, v213, s[4:5] offset:512
	s_mov_b64 exec, -1
	v_add_u32_e32 v211, 0xa0000, v209
	global_load_dwordx4 v[176:179], v211, s[80:81]
	global_load_dwordx4 v[180:183], v211, s[80:81] offset:256
	s_waitcnt vmcnt(5)
	v_lshlrev_b32_e32 v200, 16, v192
	v_and_b32_e32 v201, 0xffff0000, v192
	v_lshlrev_b32_e32 v202, 16, v193
	v_and_b32_e32 v203, 0xffff0000, v193
	v_lshlrev_b32_e32 v204, 16, v194
	v_and_b32_e32 v205, 0xffff0000, v194
	v_lshlrev_b32_e32 v206, 16, v195
	v_and_b32_e32 v207, 0xffff0000, v195
	v_pk_add_f32 v[44:45], v[44:45], v[200:201]
	v_pk_add_f32 v[46:47], v[46:47], v[202:203]
	v_pk_add_f32 v[40:41], v[40:41], v[204:205]
	v_pk_add_f32 v[42:43], v[42:43], v[206:207]
	v_mul_f32_e32 v213, v44, v44
	v_fmac_f32_e32 v213, v45, v45
	v_fmac_f32_e32 v213, v46, v46
	v_fmac_f32_e32 v213, v47, v47
	v_fmac_f32_e32 v213, v40, v40
	v_fmac_f32_e32 v213, v41, v41
	v_fmac_f32_e32 v213, v42, v42
	v_fmac_f32_e32 v213, v43, v43
	v_cvt_pk_bf16_f32 v192, v44, v45
	v_cvt_pk_bf16_f32 v193, v46, v47
	v_cvt_pk_bf16_f32 v194, v40, v41
	v_cvt_pk_bf16_f32 v195, v42, v43
	v_add_u32_e32 v217, 0x90000, v209
	global_store_dwordx4 v217, v[192:195], s[80:81]
	v_lshlrev_b32_e32 v200, 16, v196
	v_and_b32_e32 v201, 0xffff0000, v196
	v_lshlrev_b32_e32 v202, 16, v197
	v_and_b32_e32 v203, 0xffff0000, v197
	v_lshlrev_b32_e32 v204, 16, v198
	v_and_b32_e32 v205, 0xffff0000, v198
	v_lshlrev_b32_e32 v206, 16, v199
	v_and_b32_e32 v207, 0xffff0000, v199
	v_pk_add_f32 v[36:37], v[36:37], v[200:201]
	v_pk_add_f32 v[38:39], v[38:39], v[202:203]
	v_pk_add_f32 v[32:33], v[32:33], v[204:205]
	v_pk_add_f32 v[34:35], v[34:35], v[206:207]
	v_fmac_f32_e32 v213, v36, v36
	v_fmac_f32_e32 v213, v37, v37
	v_fmac_f32_e32 v213, v38, v38
	v_fmac_f32_e32 v213, v39, v39
	v_fmac_f32_e32 v213, v32, v32
	v_fmac_f32_e32 v213, v33, v33
	v_fmac_f32_e32 v213, v34, v34
	v_fmac_f32_e32 v213, v35, v35
	v_cvt_pk_bf16_f32 v196, v36, v37
	v_cvt_pk_bf16_f32 v197, v38, v39
	v_cvt_pk_bf16_f32 v198, v32, v33
	v_cvt_pk_bf16_f32 v199, v34, v35
	global_store_dwordx4 v217, v[196:199], s[80:81] offset:256
	ds_bpermute_b32 v214, v215, v213
	s_waitcnt lgkmcnt(0)
	v_add_f32_e32 v213, v213, v214
	ds_bpermute_b32 v214, v216, v213
	s_waitcnt lgkmcnt(0)
	v_add_f32_e32 v213, v213, v214
	s_mov_b64 exec, 0xffff
	global_atomic_add_f32 v208, v213, s[4:5] offset:576
	s_mov_b64 exec, -1
	v_add_u32_e32 v211, 0xb0000, v209
	global_load_dwordx4 v[192:195], v211, s[80:81]
	global_load_dwordx4 v[196:199], v211, s[80:81] offset:256
	s_waitcnt vmcnt(5)
	v_lshlrev_b32_e32 v184, 16, v176
	v_and_b32_e32 v185, 0xffff0000, v176
	v_lshlrev_b32_e32 v186, 16, v177
	v_and_b32_e32 v187, 0xffff0000, v177
	v_lshlrev_b32_e32 v188, 16, v178
	v_and_b32_e32 v189, 0xffff0000, v178
	v_lshlrev_b32_e32 v190, 16, v179
	v_and_b32_e32 v191, 0xffff0000, v179
	v_pk_add_f32 v[28:29], v[28:29], v[184:185]
	v_pk_add_f32 v[30:31], v[30:31], v[186:187]
	v_pk_add_f32 v[24:25], v[24:25], v[188:189]
	v_pk_add_f32 v[26:27], v[26:27], v[190:191]
	v_mul_f32_e32 v213, v28, v28
	v_fmac_f32_e32 v213, v29, v29
	v_fmac_f32_e32 v213, v30, v30
	v_fmac_f32_e32 v213, v31, v31
	v_fmac_f32_e32 v213, v24, v24
	v_fmac_f32_e32 v213, v25, v25
	v_fmac_f32_e32 v213, v26, v26
	v_fmac_f32_e32 v213, v27, v27
	v_cvt_pk_bf16_f32 v176, v28, v29
	v_cvt_pk_bf16_f32 v177, v30, v31
	v_cvt_pk_bf16_f32 v178, v24, v25
	v_cvt_pk_bf16_f32 v179, v26, v27
	v_add_u32_e32 v217, 0xa0000, v209
	global_store_dwordx4 v217, v[176:179], s[80:81]
	v_lshlrev_b32_e32 v184, 16, v180
	v_and_b32_e32 v185, 0xffff0000, v180
	v_lshlrev_b32_e32 v186, 16, v181
	v_and_b32_e32 v187, 0xffff0000, v181
	v_lshlrev_b32_e32 v188, 16, v182
	v_and_b32_e32 v189, 0xffff0000, v182
	v_lshlrev_b32_e32 v190, 16, v183
	v_and_b32_e32 v191, 0xffff0000, v183
	v_pk_add_f32 v[20:21], v[20:21], v[184:185]
	v_pk_add_f32 v[22:23], v[22:23], v[186:187]
	v_pk_add_f32 v[16:17], v[16:17], v[188:189]
	v_pk_add_f32 v[18:19], v[18:19], v[190:191]
	v_fmac_f32_e32 v213, v20, v20
	v_fmac_f32_e32 v213, v21, v21
	v_fmac_f32_e32 v213, v22, v22
	v_fmac_f32_e32 v213, v23, v23
	v_fmac_f32_e32 v213, v16, v16
	v_fmac_f32_e32 v213, v17, v17
	v_fmac_f32_e32 v213, v18, v18
	v_fmac_f32_e32 v213, v19, v19
	v_cvt_pk_bf16_f32 v180, v20, v21
	v_cvt_pk_bf16_f32 v181, v22, v23
	v_cvt_pk_bf16_f32 v182, v16, v17
	v_cvt_pk_bf16_f32 v183, v18, v19
	global_store_dwordx4 v217, v[180:183], s[80:81] offset:256
	ds_bpermute_b32 v214, v215, v213
	s_waitcnt lgkmcnt(0)
	v_add_f32_e32 v213, v213, v214
	ds_bpermute_b32 v214, v216, v213
	s_waitcnt lgkmcnt(0)
	v_add_f32_e32 v213, v213, v214
	s_mov_b64 exec, 0xffff
	global_atomic_add_f32 v208, v213, s[4:5] offset:640
	s_mov_b64 exec, -1
	s_waitcnt vmcnt(3)
	v_lshlrev_b32_e32 v200, 16, v192
	v_and_b32_e32 v201, 0xffff0000, v192
	v_lshlrev_b32_e32 v202, 16, v193
	v_and_b32_e32 v203, 0xffff0000, v193
	v_lshlrev_b32_e32 v204, 16, v194
	v_and_b32_e32 v205, 0xffff0000, v194
	v_lshlrev_b32_e32 v206, 16, v195
	v_and_b32_e32 v207, 0xffff0000, v195
	v_pk_add_f32 v[12:13], v[12:13], v[200:201]
	v_pk_add_f32 v[14:15], v[14:15], v[202:203]
	v_pk_add_f32 v[8:9], v[8:9], v[204:205]
	v_pk_add_f32 v[10:11], v[10:11], v[206:207]
	v_mul_f32_e32 v213, v12, v12
	v_fmac_f32_e32 v213, v13, v13
	v_fmac_f32_e32 v213, v14, v14
	v_fmac_f32_e32 v213, v15, v15
	v_fmac_f32_e32 v213, v8, v8
	v_fmac_f32_e32 v213, v9, v9
	v_fmac_f32_e32 v213, v10, v10
	v_fmac_f32_e32 v213, v11, v11
	v_cvt_pk_bf16_f32 v192, v12, v13
	v_cvt_pk_bf16_f32 v193, v14, v15
	v_cvt_pk_bf16_f32 v194, v8, v9
	v_cvt_pk_bf16_f32 v195, v10, v11
	v_add_u32_e32 v217, 0xb0000, v209
	global_store_dwordx4 v217, v[192:195], s[80:81]
	v_lshlrev_b32_e32 v200, 16, v196
	v_and_b32_e32 v201, 0xffff0000, v196
	v_lshlrev_b32_e32 v202, 16, v197
	v_and_b32_e32 v203, 0xffff0000, v197
	v_lshlrev_b32_e32 v204, 16, v198
	v_and_b32_e32 v205, 0xffff0000, v198
	v_lshlrev_b32_e32 v206, 16, v199
	v_and_b32_e32 v207, 0xffff0000, v199
	v_pk_add_f32 v[4:5], v[4:5], v[200:201]
	v_pk_add_f32 v[6:7], v[6:7], v[202:203]
	v_pk_add_f32 v[0:1], v[0:1], v[204:205]
	v_pk_add_f32 v[2:3], v[2:3], v[206:207]
	v_fmac_f32_e32 v213, v4, v4
	v_fmac_f32_e32 v213, v5, v5
	v_fmac_f32_e32 v213, v6, v6
	v_fmac_f32_e32 v213, v7, v7
	v_fmac_f32_e32 v213, v0, v0
	v_fmac_f32_e32 v213, v1, v1
	v_fmac_f32_e32 v213, v2, v2
	v_fmac_f32_e32 v213, v3, v3
	v_cvt_pk_bf16_f32 v196, v4, v5
	v_cvt_pk_bf16_f32 v197, v6, v7
	v_cvt_pk_bf16_f32 v198, v0, v1
	v_cvt_pk_bf16_f32 v199, v2, v3
	global_store_dwordx4 v217, v[196:199], s[80:81] offset:256
	ds_bpermute_b32 v214, v215, v213
	s_waitcnt lgkmcnt(0)
	v_add_f32_e32 v213, v213, v214
	ds_bpermute_b32 v214, v216, v213
	s_waitcnt lgkmcnt(0)
	v_add_f32_e32 v213, v213, v214
	s_mov_b64 exec, 0xffff
	global_atomic_add_f32 v208, v213, s[4:5] offset:704
	s_mov_b64 exec, -1
	s_branch .LBB0_752
.LBB0_777:
	s_waitcnt vmcnt(0)
	s_cmpk_gt_u32 s3, 0xff
	s_cbranch_scc1 .LBB0_779
.LBB0_779:
	s_barrier

.LBB0_832:
	s_or_b64 exec, exec, s[0:1]
	s_add_u32 s14, s82, 0x21000
	s_addc_u32 s15, s83, 0
	v_readlane_b32 s0, v255, 10
	s_add_u32 s16, s84, 0xb000
	v_readlane_b32 s1, v255, 11
	s_addc_u32 s17, s85, 0
	s_andn2_b64 vcc, exec, s[0:1]
	v_readfirstlane_b32 s3, v222
	s_waitcnt lgkmcnt(0)
	s_barrier
	s_cbranch_vccnz .LBB0_854
	s_add_u32 s44, s92, 0x7b00000
	s_addc_u32 s45, s93, 0
	s_lshr_b32 s0, s77, 29
	s_add_i32 s0, s2, s0
	s_lshr_b32 s12, s3, 6
	s_ashr_i32 s1, s0, 3
	s_and_b32 s0, s0, -8
	s_lshr_b32 s7, s3, 8
	s_lshl_b32 s46, s12, 10
	s_sub_i32 s0, s2, s0
	s_cmp_lt_i32 s0, 0
	s_movk_i32 s47, 0x161
	s_cselect_b32 s6, s47, 0x160
	s_mul_i32 s0, s6, s0
	s_add_i32 s0, s0, s1
	s_mul_hi_i32 s1, s0, 0x2e8ba2e9
	s_lshr_b32 s6, s1, 31
	s_ashr_i32 s1, s1, 5
	s_add_i32 s1, s1, s6
	s_lshl_b32 s8, s1, 2
	s_mulk_i32 s1, 0xb0
	s_sub_i32 s0, s0, s1
	s_sext_i32_i16 s1, s0
	s_bfe_u32 s1, s1, 0x2001d
	s_add_i32 s1, s0, s1
	s_sext_i32_i16 s6, s1
	s_and_b32 s1, s1, 0xfffc
	s_sub_i32 s0, s0, s1
	s_sext_i32_i16 s0, s0
	s_lshr_b32 s6, s6, 2
	s_add_i32 s0, s8, s0
	s_ashr_i32 s1, s0, 31
	s_bfe_i64 s[10:11], s[6:7], 0x100000
	s_lshl_b64 s[8:9], s[0:1], 20
	s_lshl_b64 s[10:11], s[10:11], 19
	s_add_u32 s10, s44, s10
	s_addc_u32 s11, s45, s11
	s_add_i32 s48, s46, 0
	v_and_b32_e32 v8, 0x180, v223
	s_add_i32 m0, s48, 0x10000
	v_or3_b32 v0, v220, v8, v218
	v_and_b32_e32 v9, 0x80, v254
	v_and_b32_e32 v191, 63, v222
	v_lshrrev_b32_e32 v192, 3, v191
	v_lshrrev_b32_e32 v193, 6, v222
	v_lshl_add_u32 v194, v193, 3, v192
	v_and_b32_e32 v195, 7, v191
	v_and_b32_e32 v196, 6, v192
	v_xor_b32_e32 v195, v195, v196
	v_lshlrev_b32_e32 v195, 4, v195
	v_mul_u32_u24_e32 v196, 0x1000, v194
	v_add_u32_e32 v196, v196, v195
	v_add_u32_e32 v176, 0x80000, v196
	v_mov_b32_e32 v178, v196
	v_add_u32_e32 v180, 0x40080, v196
	v_add_u32_e32 v182, 0xc0080, v196
	v_add_u32_e32 v176, 0x80000, v196
	v_add_u32_e32 v182, 0xc0080, v196
	v_and_b32_e32 v196, 31, v194
	v_and_b32_e32 v197, 12, v196
	v_lshlrev_b32_e32 v197, 1, v197
	v_lshrrev_b32_e32 v198, 4, v196
	v_lshlrev_b32_e32 v198, 2, v198
	v_and_b32_e32 v196, 3, v196
	v_or3_b32 v196, v197, v198, v196
	v_and_b32_e32 v197, 0x60, v194
	v_add_u32_e32 v196, v196, v197
	v_mul_u32_u24_e32 v196, 0x1000, v196
	v_add_u32_e32 v196, v196, v195
	v_mov_b32_e32 v164, v196
	v_add_u32_e32 v166, 0x40000, v196
	v_add_u32_e32 v166, 0x40000, v196
	v_and_b32_e32 v196, 15, v191
	v_lshrrev_b32_e32 v197, 4, v191
	v_and_b32_e32 v198, 6, v196
	v_xor_b32_e32 v197, v197, v198
	v_lshlrev_b32_e32 v197, 4, v197
	v_lshl_or_b32 v197, v196, 7, v197
	v_lshrrev_b32_e32 v198, 2, v193
	v_lshl_add_u32 v198, v198, 13, v197
	v_add_u32_e32 v173, 0x0, v198
	v_and_b32_e32 v196, 3, v193
	v_lshl_add_u32 v196, v196, 12, v197
	v_add_u32_e32 v171, 0x10000, v196
	v_add_u32_e32 v169, 0x0, v196
	v_add_u32_e32 v175, 0x14000, v196
	v_add_u32_e32 v242, 0x14000, v196
	v_mov_b32_e32 v181, 0x0
	v_mov_b32_e32 v183, 0x0
	global_load_lds_dwordx4 v164, s[10:11]
	s_add_i32 m0, s48, 0x12000
	v_or3_b32 v0, v221, v9, v218
	s_add_u32 s8, s80, s8
	global_load_lds_dwordx4 v166, s[10:11]
	s_addc_u32 s9, s81, s9
	s_mov_b32 m0, s48
	s_add_i32 s49, s48, 0x2000
	global_load_lds_dwordx4 v178, s[8:9]
	s_mov_b32 m0, s49
	s_add_u32 s18, s10, 0x1600000
	global_load_lds_dwordx4 v176, s[8:9]
	s_addc_u32 s19, s11, 0
	s_add_i32 m0, s48, 0x14000
	v_mov_b32_e32 v165, 0
	global_load_lds_dwordx4 v164, s[18:19]
	s_add_i32 m0, s48, 0x16000
	v_mov_b32_e32 v167, v165
	global_load_lds_dwordx4 v166, s[18:19]
	s_add_u32 s18, s8, 0x40000
	s_addc_u32 s19, s9, 0
	s_add_i32 s50, s48, 0x4000
	s_mov_b32 m0, s50
	s_add_i32 s51, s48, 0x6000
	global_load_lds_dwordx4 v178, s[18:19]
	s_mov_b32 m0, s51
	v_mov_b32_e32 v179, v165
	global_load_lds_dwordx4 v176, s[18:19]
	v_mov_b32_e32 v177, v165
	s_mov_b32 s52, 0
	v_lshl_add_u64 v[6:7], s[10:11], 0, v[164:165]
	v_lshl_add_u64 v[4:5], s[10:11], 0, v[166:167]
	v_lshl_add_u64 v[2:3], s[8:9], 0, v[178:179]
	s_cmp_lg_u32 s7, 1
	v_lshl_add_u64 v[0:1], s[8:9], 0, v[176:177]
	s_cbranch_scc1 .LBB0_835
.LBB0_835:
	s_mov_b64 s[18:19], 0x80
	s_lshl_b32 s1, s12, 5
	s_add_i32 m0, s48, 0x18000
	v_lshl_add_u64 v[6:7], v[6:7], 0, s[18:19]
	s_and_b32 s53, s1, 0x60
	s_waitcnt vmcnt(4)
	s_barrier
	global_load_lds_dwordx4 v[6:7], off
	v_lshl_add_u64 v[4:5], v[4:5], 0, s[18:19]
	s_add_i32 m0, s48, 0x1a000
	s_add_i32 s54, s48, 0x8000
	s_add_i32 s55, s48, 0xa000
	global_load_lds_dwordx4 v[4:5], off
	v_lshl_add_u64 v[2:3], v[2:3], 0, s[18:19]
	s_mov_b32 m0, s54
	s_add_u32 s12, s10, 0x1600080
	global_load_lds_dwordx4 v[2:3], off
	v_lshl_add_u64 v[0:1], v[0:1], 0, s[18:19]
	s_mov_b32 m0, s55
	s_addc_u32 s13, s11, 0
	global_load_lds_dwordx4 v[0:1], off
	s_add_i32 m0, s48, 0x1c000
	v_lshl_add_u64 v[0:1], s[12:13], 0, v[164:165]
	global_load_lds_dwordx4 v[0:1], off
	v_lshl_add_u64 v[0:1], s[12:13], 0, v[166:167]
	s_add_i32 m0, s48, 0x1e000
	s_ashr_i32 s56, s94, 31
	global_load_lds_dwordx4 v[0:1], off
	s_lshl_b32 s58, s7, 7
	s_lshl_b32 s59, s7, 2
	s_add_u32 s20, s82, 0x2c000
	s_addc_u32 s21, s83, 0
	s_add_u32 s22, s82, 0x37000
	s_addc_u32 s23, s83, 0
	s_add_u32 s24, s82, 0x26800
	s_addc_u32 s25, s83, 0
	s_add_u32 s26, s82, 0x31800
	v_add3_u32 v0, v9, v221, v218
	s_addc_u32 s27, s83, 0
	v_lshl_or_b32 v0, v0, 12, v226
	s_sext_i32_i16 s1, s6
	v_lshl_or_b32 v2, s7, 13, v230
	s_add_u32 s28, s82, 0x3c800
	v_add_u32_e32 v0, v0, v224
	v_mov_b32_e32 v1, v165
	s_mov_b64 s[6:7], 0x40080
	s_addc_u32 s29, s83, 0
	v_add3_u32 v0, v8, v220, v218
	s_waitcnt vmcnt(6)
	s_add_u32 s30, s84, 0x10800
	v_lshl_or_b32 v0, v0, 12, v226
	s_addc_u32 s31, s85, 0
	v_add_u32_e32 v0, v0, v224
	s_add_i32 s60, 0, 0x10000
	s_add_i32 s61, 0, 0x14000
	s_mov_b32 s57, s94
	v_mov_b64_e32 v[184:185], 0xb00
	v_mov_b64_e32 v[186:187], 0xaff
	v_mov_b32_e32 v230, 0x3727c5ac
	s_mov_b32 s62, 0xb000
	s_movk_i32 s63, 0x2c00
	s_barrier
	s_branch .LBB0_837

.LBB0_839:
	s_ashr_i32 s37, s36, 31
	v_cmp_lt_i64_e32 vcc, s[12:13], v[184:185]
	s_lshl_b64 s[12:13], s[36:37], 20
	s_add_u32 s38, s80, s12
	s_addc_u32 s39, s81, s13
	s_and_b64 s[12:13], vcc, exec
	s_cselect_b32 s33, s39, s9
	s_cselect_b32 s37, s38, s8
	s_ashr_i32 s35, s34, 31
	s_lshl_b64 s[12:13], s[34:35], 19
	s_add_u32 s40, s44, s12
	s_addc_u32 s41, s45, s13
	s_and_b64 s[12:13], vcc, exec
	s_cselect_b32 s35, s41, s11
	s_cselect_b32 s64, s40, s10
	s_add_u32 s65, s10, 0x100
	v_mov_b32_e32 v0, 0
	s_addc_u32 s66, s11, 0
	s_mov_b32 s67, -2
	v_mov_b32_e32 v1, v0
	v_mov_b32_e32 v2, v0
	v_mov_b32_e32 v3, v0
	v_mov_b32_e32 v64, v0
	v_mov_b32_e32 v65, v0
	v_mov_b32_e32 v66, v0
	v_mov_b32_e32 v67, v0
	v_mov_b32_e32 v8, v0
	v_mov_b32_e32 v9, v0
	s_waitcnt vmcnt(0)
	v_mov_b32_e32 v10, v0
	v_mov_b32_e32 v11, v0
	v_mov_b32_e32 v68, v0
	v_mov_b32_e32 v69, v0
	v_mov_b32_e32 v70, v0
	v_mov_b32_e32 v71, v0
	v_mov_b32_e32 v12, v0
	v_mov_b32_e32 v13, v0
	v_mov_b32_e32 v14, v0
	v_mov_b32_e32 v15, v0
	v_mov_b32_e32 v110, v0
	v_mov_b32_e32 v111, v0
	v_mov_b32_e32 v112, v0
	v_mov_b32_e32 v113, v0
	v_mov_b32_e32 v16, v0
	v_mov_b32_e32 v17, v0
	v_mov_b32_e32 v18, v0
	v_mov_b32_e32 v19, v0
	v_mov_b32_e32 v118, v0
	v_mov_b32_e32 v119, v0
	v_mov_b32_e32 v120, v0
	v_mov_b32_e32 v121, v0
	v_mov_b32_e32 v4, v0
	v_mov_b32_e32 v5, v0
	v_mov_b32_e32 v6, v0
	v_mov_b32_e32 v7, v0
	v_mov_b32_e32 v72, v0
	v_mov_b32_e32 v73, v0
	v_mov_b32_e32 v74, v0
	v_mov_b32_e32 v75, v0
	v_mov_b32_e32 v20, v0
	v_mov_b32_e32 v21, v0
	v_mov_b32_e32 v22, v0
	v_mov_b32_e32 v23, v0
	v_mov_b32_e32 v114, v0
	v_mov_b32_e32 v115, v0
	v_mov_b32_e32 v116, v0
	v_mov_b32_e32 v117, v0
	v_mov_b32_e32 v24, v0
	v_mov_b32_e32 v25, v0
	v_mov_b32_e32 v26, v0
	v_mov_b32_e32 v27, v0
	v_mov_b32_e32 v122, v0
	v_mov_b32_e32 v123, v0
	v_mov_b32_e32 v124, v0
	v_mov_b32_e32 v125, v0
	v_mov_b32_e32 v28, v0
	v_mov_b32_e32 v29, v0
	v_mov_b32_e32 v30, v0
	v_mov_b32_e32 v31, v0
	v_mov_b32_e32 v126, v0
	v_mov_b32_e32 v127, v0
	v_mov_b32_e32 v128, v0
	v_mov_b32_e32 v129, v0
	v_mov_b32_e32 v32, v0
	v_mov_b32_e32 v33, v0
	v_mov_b32_e32 v34, v0
	v_mov_b32_e32 v35, v0
	v_mov_b32_e32 v130, v0
	v_mov_b32_e32 v131, v0
	v_mov_b32_e32 v132, v0
	v_mov_b32_e32 v133, v0
	v_mov_b32_e32 v36, v0
	v_mov_b32_e32 v37, v0
	v_mov_b32_e32 v38, v0
	v_mov_b32_e32 v39, v0
	v_mov_b32_e32 v134, v0
	v_mov_b32_e32 v135, v0
	v_mov_b32_e32 v136, v0
	v_mov_b32_e32 v137, v0
	v_mov_b32_e32 v44, v0
	v_mov_b32_e32 v45, v0
	v_mov_b32_e32 v46, v0
	v_mov_b32_e32 v47, v0
	v_mov_b32_e32 v142, v0
	v_mov_b32_e32 v143, v0
	v_mov_b32_e32 v144, v0
	v_mov_b32_e32 v145, v0
	v_mov_b32_e32 v56, v0
	v_mov_b32_e32 v57, v0
	v_mov_b32_e32 v58, v0
	v_mov_b32_e32 v59, v0
	v_mov_b32_e32 v154, v0
	v_mov_b32_e32 v155, v0
	v_mov_b32_e32 v156, v0
	v_mov_b32_e32 v157, v0
	v_mov_b32_e32 v40, v0
	v_mov_b32_e32 v41, v0
	v_mov_b32_e32 v42, v0
	v_mov_b32_e32 v43, v0
	v_mov_b32_e32 v138, v0
	v_mov_b32_e32 v139, v0
	v_mov_b32_e32 v140, v0
	v_mov_b32_e32 v141, v0
	v_mov_b32_e32 v48, v0
	v_mov_b32_e32 v49, v0
	v_mov_b32_e32 v50, v0
	v_mov_b32_e32 v51, v0
	v_mov_b32_e32 v146, v0
	v_mov_b32_e32 v147, v0
	v_mov_b32_e32 v148, v0
	v_mov_b32_e32 v149, v0
	v_mov_b32_e32 v52, v0
	v_mov_b32_e32 v53, v0
	v_mov_b32_e32 v54, v0
	v_mov_b32_e32 v55, v0
	v_mov_b32_e32 v150, v0
	v_mov_b32_e32 v151, v0
	v_mov_b32_e32 v152, v0
	v_mov_b32_e32 v153, v0
	v_mov_b32_e32 v60, v0
	v_mov_b32_e32 v61, v0
	v_mov_b32_e32 v62, v0
	v_mov_b32_e32 v63, v0
	v_mov_b32_e32 v158, v0
	v_mov_b32_e32 v159, v0
	v_mov_b32_e32 v160, v0
	v_mov_b32_e32 v161, v0
	v_xor_b32_e32 v220, 64, v171
	v_xor_b32_e32 v221, 64, v173
	v_xor_b32_e32 v238, 64, v175
	v_add_u32_e32 v239, 0x18000, v169
	v_xor_b32_e32 v240, 64, v239
	v_add_u32_e32 v241, 0x1c000, v169
	v_xor_b32_e32 v242, 64, v241
	s_cmpk_lt_u32 s3, 0x100
	s_cbranch_scc1 .Lst_in_s8
	s_barrier
.Lst_in_s8:
.LBB0_840:
	ds_read_b128 v[76:79], v171
	ds_read_b128 v[80:83], v220
	ds_read_b128 v[84:87], v171 offset:2048
	ds_read_b128 v[88:91], v220 offset:2048
	s_add_u32 s10, s8, 0x100
	s_addc_u32 s11, s9, 0
	s_cmp_eq_u32 s67, 28
	s_cselect_b32 s43, s33, s11
	s_cselect_b32 s42, s37, s10
	s_cselect_b32 s13, s35, s66
	s_cselect_b32 s12, s64, s65
	s_add_i32 m0, s48, 0xc000
	ds_read_b128 v[92:95], v173
	ds_read_b128 v[96:99], v221
	ds_read_b128 v[100:103], v173 offset:2048
	ds_read_b128 v[104:107], v221 offset:2048
	ds_read_b128 v[188:191], v173 offset:4096
	ds_read_b128 v[192:195], v221 offset:4096
	ds_read_b128 v[196:199], v173 offset:6144
	ds_read_b128 v[200:203], v221 offset:6144
	global_load_lds_dwordx4 v180, s[8:9]
	s_add_i32 m0, s48, 0xe000
	s_nop 0
	global_load_lds_dwordx4 v182, s[8:9]
	s_waitcnt lgkmcnt(8)
	s_barrier
	s_waitcnt lgkmcnt(0)
	s_waitcnt lgkmcnt(0)
	v_mfma_f32_16x16x32_bf16 v[158:161], v[76:79], v[92:95], v[158:161]
	v_mfma_f32_16x16x32_bf16 v[158:161], v[80:83], v[96:99], v[158:161]
	v_mfma_f32_16x16x32_bf16 v[60:63], v[88:91], v[96:99], v[60:63]
	v_mfma_f32_16x16x32_bf16 v[60:63], v[84:87], v[92:95], v[60:63]
	v_mfma_f32_16x16x32_bf16 v[52:55], v[84:87], v[100:103], v[52:55]
	v_mfma_f32_16x16x32_bf16 v[52:55], v[88:91], v[104:107], v[52:55]
	v_mfma_f32_16x16x32_bf16 v[150:153], v[80:83], v[104:107], v[150:153]
	v_mfma_f32_16x16x32_bf16 v[150:153], v[76:79], v[100:103], v[150:153]
	v_mfma_f32_16x16x32_bf16 v[146:149], v[76:79], v[188:191], v[146:149]
	v_mfma_f32_16x16x32_bf16 v[146:149], v[80:83], v[192:195], v[146:149]
	v_mfma_f32_16x16x32_bf16 v[48:51], v[88:91], v[192:195], v[48:51]
	v_mfma_f32_16x16x32_bf16 v[48:51], v[84:87], v[188:191], v[48:51]
	v_mfma_f32_16x16x32_bf16 v[40:43], v[84:87], v[196:199], v[40:43]
	v_mfma_f32_16x16x32_bf16 v[40:43], v[88:91], v[200:203], v[40:43]
	v_mfma_f32_16x16x32_bf16 v[138:141], v[80:83], v[200:203], v[138:141]
	v_mfma_f32_16x16x32_bf16 v[138:141], v[76:79], v[196:199], v[138:141]
	s_barrier
	s_add_i32 s8, s60, s46
	s_add_u32 s98, s12, s18
	s_addc_u32 s99, s13, s19
	s_mov_b32 m0, s8
	ds_read_b128 v[204:207], v175
	ds_read_b128 v[208:211], v238
	ds_read_b128 v[212:215], v175 offset:2048
	ds_read_b128 v[216:219], v238 offset:2048
	global_load_lds_dwordx4 v164, s[12:13]
	s_add_i32 m0, s8, 0x2000
	s_nop 0
	global_load_lds_dwordx4 v166, s[12:13]
	s_barrier
	s_waitcnt lgkmcnt(0)
	s_waitcnt lgkmcnt(0)
	v_mfma_f32_16x16x32_bf16 v[154:157], v[204:207], v[92:95], v[154:157]
	v_mfma_f32_16x16x32_bf16 v[154:157], v[208:211], v[96:99], v[154:157]
	v_mfma_f32_16x16x32_bf16 v[56:59], v[216:219], v[96:99], v[56:59]
	v_mfma_f32_16x16x32_bf16 v[56:59], v[212:215], v[92:95], v[56:59]
	v_mfma_f32_16x16x32_bf16 v[44:47], v[212:215], v[100:103], v[44:47]
	v_mfma_f32_16x16x32_bf16 v[44:47], v[216:219], v[104:107], v[44:47]
	v_mfma_f32_16x16x32_bf16 v[36:39], v[216:219], v[192:195], v[36:39]
	v_mfma_f32_16x16x32_bf16 v[36:39], v[212:215], v[188:191], v[36:39]
	v_mfma_f32_16x16x32_bf16 v[32:35], v[212:215], v[196:199], v[32:35]
	v_mfma_f32_16x16x32_bf16 v[32:35], v[216:219], v[200:203], v[32:35]
	v_mfma_f32_16x16x32_bf16 v[92:95], v[204:207], v[100:103], v[142:145]
	v_mfma_f32_16x16x32_bf16 v[92:95], v[208:211], v[104:107], v[92:95]
	v_mfma_f32_16x16x32_bf16 v[96:99], v[208:211], v[192:195], v[134:137]
	v_mfma_f32_16x16x32_bf16 v[96:99], v[204:207], v[188:191], v[96:99]
	v_mfma_f32_16x16x32_bf16 v[100:103], v[204:207], v[196:199], v[130:133]
	v_mfma_f32_16x16x32_bf16 v[100:103], v[208:211], v[200:203], v[100:103]
	s_mov_b32 m0, s48
	s_add_u32 s100, s42, s18
	s_addc_u32 s101, s43, s19
	s_barrier
	ds_read_b128 v[104:107], v173 offset:16384
	ds_read_b128 v[130:133], v221 offset:16384
	ds_read_b128 v[134:137], v173 offset:18432
	ds_read_b128 v[142:145], v221 offset:18432
	ds_read_b128 v[188:191], v173 offset:20480
	ds_read_b128 v[192:195], v221 offset:20480
	ds_read_b128 v[196:199], v173 offset:22528
	ds_read_b128 v[200:203], v221 offset:22528
	global_load_lds_dwordx4 v178, s[42:43]
	s_mov_b32 m0, s49
	s_nop 0
	global_load_lds_dwordx4 v176, s[42:43]
	s_barrier
	s_waitcnt lgkmcnt(0)
	s_waitcnt lgkmcnt(0)
	v_mfma_f32_16x16x32_bf16 v[126:129], v[76:79], v[104:107], v[126:129]
	v_mfma_f32_16x16x32_bf16 v[126:129], v[80:83], v[130:133], v[126:129]
	v_mfma_f32_16x16x32_bf16 v[28:31], v[88:91], v[130:133], v[28:31]
	v_mfma_f32_16x16x32_bf16 v[28:31], v[84:87], v[104:107], v[28:31]
	v_mfma_f32_16x16x32_bf16 v[24:27], v[84:87], v[134:137], v[24:27]
	v_mfma_f32_16x16x32_bf16 v[24:27], v[88:91], v[142:145], v[24:27]
	v_mfma_f32_16x16x32_bf16 v[122:125], v[80:83], v[142:145], v[122:125]
	v_mfma_f32_16x16x32_bf16 v[122:125], v[76:79], v[134:137], v[122:125]
	v_mfma_f32_16x16x32_bf16 v[114:117], v[76:79], v[188:191], v[114:117]
	v_mfma_f32_16x16x32_bf16 v[114:117], v[80:83], v[192:195], v[114:117]
	v_mfma_f32_16x16x32_bf16 v[20:23], v[88:91], v[192:195], v[20:23]
	v_mfma_f32_16x16x32_bf16 v[20:23], v[84:87], v[188:191], v[20:23]
	v_mfma_f32_16x16x32_bf16 v[4:7], v[84:87], v[196:199], v[4:7]
	v_mfma_f32_16x16x32_bf16 v[4:7], v[88:91], v[200:203], v[4:7]
	v_mfma_f32_16x16x32_bf16 v[72:75], v[80:83], v[200:203], v[72:75]
	v_mfma_f32_16x16x32_bf16 v[72:75], v[76:79], v[196:199], v[72:75]
	s_barrier
	s_add_u32 s8, s12, 0x1600000
	s_addc_u32 s9, s13, 0
	s_add_i32 s68, s61, s46
	s_mov_b32 m0, s68
	s_nop 0
	global_load_lds_dwordx4 v164, s[8:9]
	s_add_i32 m0, s68, 0x2000
	s_nop 0
	global_load_lds_dwordx4 v166, s[8:9]
	s_waitcnt vmcnt(6)
	s_barrier
	v_mfma_f32_16x16x32_bf16 v[16:19], v[212:215], v[104:107], v[16:19]
	v_mfma_f32_16x16x32_bf16 v[16:19], v[216:219], v[130:133], v[16:19]
	v_mfma_f32_16x16x32_bf16 v[12:15], v[216:219], v[142:145], v[12:15]
	v_mfma_f32_16x16x32_bf16 v[12:15], v[212:215], v[134:137], v[12:15]
	v_mfma_f32_16x16x32_bf16 v[8:11], v[212:215], v[188:191], v[8:11]
	v_mfma_f32_16x16x32_bf16 v[8:11], v[216:219], v[192:195], v[8:11]
	v_mfma_f32_16x16x32_bf16 v[68:71], v[208:211], v[192:195], v[68:71]
	v_mfma_f32_16x16x32_bf16 v[68:71], v[204:207], v[188:191], v[68:71]
	v_mfma_f32_16x16x32_bf16 v[64:67], v[204:207], v[196:199], v[64:67]
	v_mfma_f32_16x16x32_bf16 v[64:67], v[208:211], v[200:203], v[64:67]
	v_mfma_f32_16x16x32_bf16 v[0:3], v[216:219], v[200:203], v[0:3]
	v_mfma_f32_16x16x32_bf16 v[0:3], v[212:215], v[196:199], v[0:3]
	v_mfma_f32_16x16x32_bf16 v[76:79], v[204:207], v[104:107], v[118:121]
	v_mfma_f32_16x16x32_bf16 v[76:79], v[208:211], v[130:133], v[76:79]
	v_mfma_f32_16x16x32_bf16 v[80:83], v[208:211], v[142:145], v[110:113]
	v_mfma_f32_16x16x32_bf16 v[80:83], v[204:207], v[134:137], v[80:83]
	s_add_i32 s68, 0, 0x18000
	s_barrier
	ds_read_b128 v[84:87], v239
	ds_read_b128 v[88:91], v240
	ds_read_b128 v[104:107], v239 offset:2048
	ds_read_b128 v[108:111], v240 offset:2048
	s_add_u32 s8, s42, 0x40000
	s_addc_u32 s9, s43, 0
	s_mov_b32 m0, s50
	ds_read_b128 v[118:121], v173 offset:32768
	ds_read_b128 v[130:133], v221 offset:32768
	ds_read_b128 v[134:137], v173 offset:34816
	ds_read_b128 v[188:191], v221 offset:34816
	ds_read_b128 v[192:195], v173 offset:36864
	ds_read_b128 v[196:199], v221 offset:36864
	ds_read_b128 v[200:203], v173 offset:38912
	ds_read_b128 v[204:207], v221 offset:38912
	global_load_lds_dwordx4 v178, s[8:9]
	s_mov_b32 m0, s51
	s_nop 0
	global_load_lds_dwordx4 v176, s[8:9]
	s_waitcnt lgkmcnt(8)
	s_barrier
	s_waitcnt lgkmcnt(0)
	s_waitcnt lgkmcnt(0)
	v_mfma_f32_16x16x32_bf16 v[142:145], v[84:87], v[118:121], v[158:161]
	v_mfma_f32_16x16x32_bf16 v[158:161], v[88:91], v[130:133], v[142:145]
	v_mfma_f32_16x16x32_bf16 v[60:63], v[108:111], v[130:133], v[60:63]
	v_mfma_f32_16x16x32_bf16 v[60:63], v[104:107], v[118:121], v[60:63]
	v_mfma_f32_16x16x32_bf16 v[52:55], v[104:107], v[134:137], v[52:55]
	v_mfma_f32_16x16x32_bf16 v[52:55], v[108:111], v[188:191], v[52:55]
	v_mfma_f32_16x16x32_bf16 v[48:51], v[108:111], v[196:199], v[48:51]
	v_mfma_f32_16x16x32_bf16 v[48:51], v[104:107], v[192:195], v[48:51]
	v_mfma_f32_16x16x32_bf16 v[40:43], v[104:107], v[200:203], v[40:43]
	v_mfma_f32_16x16x32_bf16 v[40:43], v[108:111], v[204:207], v[40:43]
	v_mfma_f32_16x16x32_bf16 v[138:141], v[88:91], v[204:207], v[138:141]
	v_mfma_f32_16x16x32_bf16 v[138:141], v[84:87], v[200:203], v[138:141]
	v_mfma_f32_16x16x32_bf16 v[142:145], v[84:87], v[134:137], v[150:153]
	v_mfma_f32_16x16x32_bf16 v[150:153], v[88:91], v[188:191], v[142:145]
	v_mfma_f32_16x16x32_bf16 v[142:145], v[84:87], v[192:195], v[146:149]
	v_mfma_f32_16x16x32_bf16 v[146:149], v[88:91], v[196:199], v[142:145]
	s_barrier
	s_add_i32 s42, 0, 0x1c000
	s_add_i32 s8, s68, s46
	ds_read_b128 v[208:211], v241
	ds_read_b128 v[212:215], v242
	ds_read_b128 v[216:219], v241 offset:2048
	ds_read_b128 v[234:237], v242 offset:2048
	s_mov_b32 m0, s8
	s_nop 0
	global_load_lds_dwordx4 v164, s[98:99]
	s_add_i32 m0, s8, 0x2000
	s_nop 0
	global_load_lds_dwordx4 v166, s[98:99]
	s_barrier
	s_waitcnt lgkmcnt(0)
	s_waitcnt lgkmcnt(0)
	v_mfma_f32_16x16x32_bf16 v[142:145], v[208:211], v[118:121], v[154:157]
	v_mfma_f32_16x16x32_bf16 v[154:157], v[212:215], v[130:133], v[142:145]
	v_mfma_f32_16x16x32_bf16 v[56:59], v[234:237], v[130:133], v[56:59]
	v_mfma_f32_16x16x32_bf16 v[56:59], v[216:219], v[118:121], v[56:59]
	v_mfma_f32_16x16x32_bf16 v[44:47], v[216:219], v[134:137], v[44:47]
	v_mfma_f32_16x16x32_bf16 v[44:47], v[234:237], v[188:191], v[44:47]
	v_mfma_f32_16x16x32_bf16 v[36:39], v[234:237], v[196:199], v[36:39]
	v_mfma_f32_16x16x32_bf16 v[36:39], v[216:219], v[192:195], v[36:39]
	v_mfma_f32_16x16x32_bf16 v[32:35], v[216:219], v[200:203], v[32:35]
	v_mfma_f32_16x16x32_bf16 v[32:35], v[234:237], v[204:207], v[32:35]
	v_mfma_f32_16x16x32_bf16 v[92:95], v[208:211], v[134:137], v[92:95]
	v_mfma_f32_16x16x32_bf16 v[142:145], v[212:215], v[188:191], v[92:95]
	v_mfma_f32_16x16x32_bf16 v[92:95], v[208:211], v[192:195], v[96:99]
	v_mfma_f32_16x16x32_bf16 v[134:137], v[212:215], v[196:199], v[92:95]
	v_mfma_f32_16x16x32_bf16 v[92:95], v[208:211], v[200:203], v[100:103]
	v_mfma_f32_16x16x32_bf16 v[130:133], v[212:215], v[204:207], v[92:95]
	s_mov_b32 m0, s54
	s_barrier
	ds_read_b128 v[92:95], v173 offset:49152
	ds_read_b128 v[96:99], v221 offset:49152
	ds_read_b128 v[100:103], v173 offset:51200
	ds_read_b128 v[188:191], v221 offset:51200
	ds_read_b128 v[192:195], v173 offset:53248
	ds_read_b128 v[196:199], v221 offset:53248
	ds_read_b128 v[200:203], v173 offset:55296
	ds_read_b128 v[204:207], v221 offset:55296
	global_load_lds_dwordx4 v178, s[100:101]
	s_mov_b32 m0, s55
	s_nop 0
	global_load_lds_dwordx4 v176, s[100:101]
	s_barrier
	s_waitcnt lgkmcnt(0)
	s_waitcnt lgkmcnt(0)
	v_mfma_f32_16x16x32_bf16 v[118:121], v[84:87], v[92:95], v[126:129]
	v_mfma_f32_16x16x32_bf16 v[126:129], v[88:91], v[96:99], v[118:121]
	v_mfma_f32_16x16x32_bf16 v[28:31], v[108:111], v[96:99], v[28:31]
	v_mfma_f32_16x16x32_bf16 v[28:31], v[104:107], v[92:95], v[28:31]
	v_mfma_f32_16x16x32_bf16 v[24:27], v[104:107], v[100:103], v[24:27]
	v_mfma_f32_16x16x32_bf16 v[24:27], v[108:111], v[188:191], v[24:27]
	v_mfma_f32_16x16x32_bf16 v[20:23], v[108:111], v[196:199], v[20:23]
	v_mfma_f32_16x16x32_bf16 v[20:23], v[104:107], v[192:195], v[20:23]
	v_mfma_f32_16x16x32_bf16 v[112:115], v[84:87], v[192:195], v[114:117]
	v_mfma_f32_16x16x32_bf16 v[114:117], v[88:91], v[196:199], v[112:115]
	v_mfma_f32_16x16x32_bf16 v[72:75], v[88:91], v[204:207], v[72:75]
	v_mfma_f32_16x16x32_bf16 v[72:75], v[84:87], v[200:203], v[72:75]
	v_mfma_f32_16x16x32_bf16 v[118:121], v[84:87], v[100:103], v[122:125]
	v_mfma_f32_16x16x32_bf16 v[122:125], v[88:91], v[188:191], v[118:121]
	v_mfma_f32_16x16x32_bf16 v[4:7], v[104:107], v[200:203], v[4:7]
	v_mfma_f32_16x16x32_bf16 v[4:7], v[108:111], v[204:207], v[4:7]
	s_barrier
	s_add_u32 s8, s12, 0x1600080
	s_addc_u32 s9, s13, 0
	s_add_i32 s12, s42, s46
	s_mov_b32 m0, s12
	s_nop 0
	global_load_lds_dwordx4 v164, s[8:9]
	s_add_i32 m0, s12, 0x2000
	s_nop 0
	global_load_lds_dwordx4 v166, s[8:9]
	s_waitcnt vmcnt(6)
	s_barrier
	v_mfma_f32_16x16x32_bf16 v[76:79], v[208:211], v[92:95], v[76:79]
	v_mfma_f32_16x16x32_bf16 v[118:121], v[212:215], v[96:99], v[76:79]
	v_mfma_f32_16x16x32_bf16 v[16:19], v[234:237], v[96:99], v[16:19]
	v_mfma_f32_16x16x32_bf16 v[16:19], v[216:219], v[92:95], v[16:19]
	v_mfma_f32_16x16x32_bf16 v[12:15], v[216:219], v[100:103], v[12:15]
	v_mfma_f32_16x16x32_bf16 v[12:15], v[234:237], v[188:191], v[12:15]
	v_mfma_f32_16x16x32_bf16 v[8:11], v[234:237], v[196:199], v[8:11]
	v_mfma_f32_16x16x32_bf16 v[8:11], v[216:219], v[192:195], v[8:11]
	v_mfma_f32_16x16x32_bf16 v[68:71], v[208:211], v[192:195], v[68:71]
	v_mfma_f32_16x16x32_bf16 v[68:71], v[212:215], v[196:199], v[68:71]
	v_mfma_f32_16x16x32_bf16 v[64:67], v[212:215], v[204:207], v[64:67]
	v_mfma_f32_16x16x32_bf16 v[64:67], v[208:211], v[200:203], v[64:67]
	v_mfma_f32_16x16x32_bf16 v[76:79], v[208:211], v[100:103], v[80:83]
	v_mfma_f32_16x16x32_bf16 v[110:113], v[212:215], v[188:191], v[76:79]
	v_mfma_f32_16x16x32_bf16 v[0:3], v[216:219], v[200:203], v[0:3]
	v_mfma_f32_16x16x32_bf16 v[0:3], v[234:237], v[204:207], v[0:3]
	s_add_i32 s67, s67, 2
	s_add_u32 s65, s65, 0x100
	s_addc_u32 s66, s66, 0
	s_cmp_gt_u32 s67, 29
	s_mov_b64 s[8:9], s[10:11]
	s_barrier
	s_cbranch_scc0 .LBB0_840
	s_cmpk_gt_u32 s3, 0xff
	s_cbranch_scc1 .Lst_out_s8
	s_barrier
.Lst_out_s8:
	s_lshl_b32 s8, s0, 8
	s_add_i32 s8, s8, s58
	s_lshl_b32 s9, s1, 7
	s_add_i32 s9, s9, s53
	s_lshl_b32 s10, s0, 3
	s_lshr_b32 s11, s58, 5
	s_add_i32 s10, s10, s11
	v_add_u32_e32 v200, s8, v163
	v_lshlrev_b32_e32 v213, 2, v200
	global_load_dword v188, v213, s[4:5]
	global_load_dword v189, v213, s[4:5] offset:64
	global_load_dword v190, v213, s[4:5] offset:128
	global_load_dword v191, v213, s[4:5] offset:192
	global_load_dword v192, v213, s[4:5] offset:256
	global_load_dword v193, v213, s[4:5] offset:320
	global_load_dword v194, v213, s[4:5] offset:384
	global_load_dword v195, v213, s[4:5] offset:448
	v_lshl_add_u32 v201, v225, 3, s9
	v_lshlrev_b32_e32 v212, 2, v201
	v_add_u32_e32 v213, 0x21000, v212
	global_load_dwordx4 v[76:79], v213, s[82:83]
	v_add_u32_e32 v213, 0x2c000, v212
	global_load_dwordx4 v[80:83], v213, s[82:83]
	v_add_u32_e32 v213, 0x37000, v212
	global_load_dwordx4 v[84:87], v213, s[82:83]
	v_add_u32_e32 v213, 0xb000, v212
	global_load_dwordx4 v[88:91], v213, s[84:85]
	v_add_u32_e32 v213, 0x26800, v212
	global_load_dwordx4 v[92:95], v213, s[82:83]
	v_add_u32_e32 v213, 0x31800, v212
	global_load_dwordx4 v[96:99], v213, s[82:83]
	v_add_u32_e32 v213, 0x3c800, v212
	global_load_dwordx4 v[100:103], v213, s[82:83]
	v_add_u32_e32 v213, 0x10800, v212
	global_load_dwordx4 v[104:107], v213, s[84:85]
	v_mul_u32_u24_e32 v215, 0x2c00, v200
	v_lshl_add_u32 v215, v201, 1, v215
	v_add_u32_e32 v213, s10, v163
	v_mul_u32_u24_e32 v217, 0xb000, v213
	v_add_u32_e32 v217, v217, v212
	v_cmp_gt_u32_e64 s[8:9], 2, v163
	v_cmp_lt_u32_e64 s[10:11], 13, v163
	v_cmp_lt_u32_e32 vcc, 1, v163
	v_mov_b32_e32 v214, 1.0
	v_mov_b32_e32 v216, 0xbfb8aa3b
	v_mov_b32_e32 v108, 0x3727c5ac
	s_waitcnt vmcnt(8)
	v_fmamk_f32 v188, v188, 0x3a000000, v108
	v_fmamk_f32 v189, v189, 0x3a000000, v108
	v_fmamk_f32 v190, v190, 0x3a000000, v108
	v_fmamk_f32 v191, v191, 0x3a000000, v108
	v_fmamk_f32 v192, v192, 0x3a000000, v108
	v_fmamk_f32 v193, v193, 0x3a000000, v108
	v_fmamk_f32 v194, v194, 0x3a000000, v108
	v_fmamk_f32 v195, v195, 0x3a000000, v108
	v_rsq_f32_e32 v188, v188
	v_rsq_f32_e32 v189, v189
	v_rsq_f32_e32 v190, v190
	v_rsq_f32_e32 v191, v191
	v_rsq_f32_e32 v192, v192
	v_rsq_f32_e32 v193, v193
	v_rsq_f32_e32 v194, v194
	v_rsq_f32_e32 v195, v195
	v_pk_mul_f32 v[158:159], v[158:159], v[188:189] op_sel_hi:[1,0]
	v_pk_mul_f32 v[160:161], v[160:161], v[188:189] op_sel_hi:[1,0]
	v_pk_mul_f32 v[60:61], v[60:61], v[188:189] op_sel_hi:[1,0]
	v_pk_mul_f32 v[62:63], v[62:63], v[188:189] op_sel_hi:[1,0]
	v_pk_mul_f32 v[154:155], v[154:155], v[188:189] op_sel_hi:[1,0]
	v_pk_mul_f32 v[156:157], v[156:157], v[188:189] op_sel_hi:[1,0]
	v_pk_mul_f32 v[56:57], v[56:57], v[188:189] op_sel_hi:[1,0]
	v_pk_mul_f32 v[58:59], v[58:59], v[188:189] op_sel_hi:[1,0]
	v_pk_mul_f32 v[150:151], v[150:151], v[188:189] op_sel:[0,1] op_sel_hi:[1,1]
	v_pk_mul_f32 v[152:153], v[152:153], v[188:189] op_sel:[0,1] op_sel_hi:[1,1]
	v_pk_mul_f32 v[52:53], v[52:53], v[188:189] op_sel:[0,1] op_sel_hi:[1,1]
	v_pk_mul_f32 v[54:55], v[54:55], v[188:189] op_sel:[0,1] op_sel_hi:[1,1]
	v_pk_mul_f32 v[142:143], v[142:143], v[188:189] op_sel:[0,1] op_sel_hi:[1,1]
	v_pk_mul_f32 v[144:145], v[144:145], v[188:189] op_sel:[0,1] op_sel_hi:[1,1]
	v_pk_mul_f32 v[44:45], v[44:45], v[188:189] op_sel:[0,1] op_sel_hi:[1,1]
	v_pk_mul_f32 v[46:47], v[46:47], v[188:189] op_sel:[0,1] op_sel_hi:[1,1]
	v_pk_mul_f32 v[146:147], v[146:147], v[190:191] op_sel_hi:[1,0]
	v_pk_mul_f32 v[148:149], v[148:149], v[190:191] op_sel_hi:[1,0]
	v_pk_mul_f32 v[48:49], v[48:49], v[190:191] op_sel_hi:[1,0]
	v_pk_mul_f32 v[50:51], v[50:51], v[190:191] op_sel_hi:[1,0]
	v_pk_mul_f32 v[134:135], v[134:135], v[190:191] op_sel_hi:[1,0]
	v_pk_mul_f32 v[136:137], v[136:137], v[190:191] op_sel_hi:[1,0]
	v_pk_mul_f32 v[36:37], v[36:37], v[190:191] op_sel_hi:[1,0]
	v_pk_mul_f32 v[38:39], v[38:39], v[190:191] op_sel_hi:[1,0]
	v_pk_mul_f32 v[138:139], v[138:139], v[190:191] op_sel:[0,1] op_sel_hi:[1,1]
	v_pk_mul_f32 v[140:141], v[140:141], v[190:191] op_sel:[0,1] op_sel_hi:[1,1]
	v_pk_mul_f32 v[40:41], v[40:41], v[190:191] op_sel:[0,1] op_sel_hi:[1,1]
	v_pk_mul_f32 v[42:43], v[42:43], v[190:191] op_sel:[0,1] op_sel_hi:[1,1]
	v_pk_mul_f32 v[130:131], v[130:131], v[190:191] op_sel:[0,1] op_sel_hi:[1,1]
	v_pk_mul_f32 v[132:133], v[132:133], v[190:191] op_sel:[0,1] op_sel_hi:[1,1]
	v_pk_mul_f32 v[32:33], v[32:33], v[190:191] op_sel:[0,1] op_sel_hi:[1,1]
	v_pk_mul_f32 v[34:35], v[34:35], v[190:191] op_sel:[0,1] op_sel_hi:[1,1]
	v_pk_mul_f32 v[126:127], v[126:127], v[192:193] op_sel_hi:[1,0]
	v_pk_mul_f32 v[128:129], v[128:129], v[192:193] op_sel_hi:[1,0]
	v_pk_mul_f32 v[28:29], v[28:29], v[192:193] op_sel_hi:[1,0]
	v_pk_mul_f32 v[30:31], v[30:31], v[192:193] op_sel_hi:[1,0]
	v_pk_mul_f32 v[118:119], v[118:119], v[192:193] op_sel_hi:[1,0]
	v_pk_mul_f32 v[120:121], v[120:121], v[192:193] op_sel_hi:[1,0]
	v_pk_mul_f32 v[16:17], v[16:17], v[192:193] op_sel_hi:[1,0]
	v_pk_mul_f32 v[18:19], v[18:19], v[192:193] op_sel_hi:[1,0]
	v_pk_mul_f32 v[122:123], v[122:123], v[192:193] op_sel:[0,1] op_sel_hi:[1,1]
	v_pk_mul_f32 v[124:125], v[124:125], v[192:193] op_sel:[0,1] op_sel_hi:[1,1]
	v_pk_mul_f32 v[24:25], v[24:25], v[192:193] op_sel:[0,1] op_sel_hi:[1,1]
	v_pk_mul_f32 v[26:27], v[26:27], v[192:193] op_sel:[0,1] op_sel_hi:[1,1]
	v_pk_mul_f32 v[110:111], v[110:111], v[192:193] op_sel:[0,1] op_sel_hi:[1,1]
	v_pk_mul_f32 v[112:113], v[112:113], v[192:193] op_sel:[0,1] op_sel_hi:[1,1]
	v_pk_mul_f32 v[12:13], v[12:13], v[192:193] op_sel:[0,1] op_sel_hi:[1,1]
	v_pk_mul_f32 v[14:15], v[14:15], v[192:193] op_sel:[0,1] op_sel_hi:[1,1]
	v_pk_mul_f32 v[114:115], v[114:115], v[194:195] op_sel_hi:[1,0]
	v_pk_mul_f32 v[116:117], v[116:117], v[194:195] op_sel_hi:[1,0]
	v_pk_mul_f32 v[20:21], v[20:21], v[194:195] op_sel_hi:[1,0]
	v_pk_mul_f32 v[22:23], v[22:23], v[194:195] op_sel_hi:[1,0]
	v_pk_mul_f32 v[68:69], v[68:69], v[194:195] op_sel_hi:[1,0]
	v_pk_mul_f32 v[70:71], v[70:71], v[194:195] op_sel_hi:[1,0]
	v_pk_mul_f32 v[8:9], v[8:9], v[194:195] op_sel_hi:[1,0]
	v_pk_mul_f32 v[10:11], v[10:11], v[194:195] op_sel_hi:[1,0]
	v_pk_mul_f32 v[72:73], v[72:73], v[194:195] op_sel:[0,1] op_sel_hi:[1,1]
	v_pk_mul_f32 v[74:75], v[74:75], v[194:195] op_sel:[0,1] op_sel_hi:[1,1]
	v_pk_mul_f32 v[4:5], v[4:5], v[194:195] op_sel:[0,1] op_sel_hi:[1,1]
	v_pk_mul_f32 v[6:7], v[6:7], v[194:195] op_sel:[0,1] op_sel_hi:[1,1]
	v_pk_mul_f32 v[64:65], v[64:65], v[194:195] op_sel:[0,1] op_sel_hi:[1,1]
	v_pk_mul_f32 v[66:67], v[66:67], v[194:195] op_sel:[0,1] op_sel_hi:[1,1]
	v_pk_mul_f32 v[0:1], v[0:1], v[194:195] op_sel:[0,1] op_sel_hi:[1,1]
	v_pk_mul_f32 v[2:3], v[2:3], v[194:195] op_sel:[0,1] op_sel_hi:[1,1]
	s_nop 1
	s_mov_b64 exec, s[8:9]
	v_add_u32_e32 v213, 0x5800, v217
	global_store_dwordx4 v217, v[158:161], s[70:71]
	global_store_dwordx4 v213, v[154:157], s[70:71]
	global_store_dwordx4 v217, v[60:63], s[70:71] offset:16
	global_store_dwordx4 v213, v[56:59], s[70:71] offset:16
	s_mov_b64 exec, s[10:11]
	v_add_u32_e32 v213, 0xfff7c000, v217
	global_store_dwordx4 v213, v[72:75], s[70:71]
	global_store_dwordx4 v213, v[4:7], s[70:71] offset:16
	v_add_u32_e32 v213, 0xfff81800, v217
	global_store_dwordx4 v213, v[64:67], s[70:71]
	global_store_dwordx4 v213, v[0:3], s[70:71] offset:16
	s_mov_b64 exec, -1
	v_add_u32_e32 v213, 0x3c800, v212
	global_load_dwordx4 v[204:207], v213, s[82:83] offset:16
	v_add_u32_e32 v213, 0x10800, v212
	global_load_dwordx4 v[208:211], v213, s[84:85] offset:16
	s_waitcnt vmcnt(10)
	v_pk_fma_f32 v[188:189], v[158:159], v[84:85], v[88:89]
	v_pk_fma_f32 v[190:191], v[160:161], v[86:87], v[90:91]
	v_pk_fma_f32 v[192:193], v[154:155], v[100:101], v[104:105]
	v_pk_fma_f32 v[194:195], v[156:157], v[102:103], v[106:107]
	v_fmac_f32_dpp v188, v158, v80 row_shr:1 row_mask:0xf bank_mask:0xf
	v_fmac_f32_dpp v189, v159, v81 row_shr:1 row_mask:0xf bank_mask:0xf
	v_fmac_f32_dpp v190, v160, v82 row_shr:1 row_mask:0xf bank_mask:0xf
	v_fmac_f32_dpp v191, v161, v83 row_shr:1 row_mask:0xf bank_mask:0xf
	v_fmac_f32_dpp v192, v154, v96 row_shr:1 row_mask:0xf bank_mask:0xf
	v_fmac_f32_dpp v193, v155, v97 row_shr:1 row_mask:0xf bank_mask:0xf
	v_fmac_f32_dpp v194, v156, v98 row_shr:1 row_mask:0xf bank_mask:0xf
	v_fmac_f32_dpp v195, v157, v99 row_shr:1 row_mask:0xf bank_mask:0xf
	v_fmac_f32_dpp v188, v158, v76 row_shr:2 row_mask:0xf bank_mask:0xf
	v_fmac_f32_dpp v189, v159, v77 row_shr:2 row_mask:0xf bank_mask:0xf
	v_fmac_f32_dpp v190, v160, v78 row_shr:2 row_mask:0xf bank_mask:0xf
	v_fmac_f32_dpp v191, v161, v79 row_shr:2 row_mask:0xf bank_mask:0xf
	v_fmac_f32_dpp v192, v154, v92 row_shr:2 row_mask:0xf bank_mask:0xf
	v_fmac_f32_dpp v193, v155, v93 row_shr:2 row_mask:0xf bank_mask:0xf
	v_fmac_f32_dpp v194, v156, v94 row_shr:2 row_mask:0xf bank_mask:0xf
	v_fmac_f32_dpp v195, v157, v95 row_shr:2 row_mask:0xf bank_mask:0xf
	v_pk_mul_f32 v[196:197], v[188:189], v[216:217] op_sel_hi:[1,0]
	v_pk_mul_f32 v[198:199], v[190:191], v[216:217] op_sel_hi:[1,0]
	v_exp_f32_e32 v196, v196
	v_exp_f32_e32 v197, v197
	v_exp_f32_e32 v198, v198
	v_exp_f32_e32 v199, v199
	v_pk_add_f32 v[196:197], v[196:197], v[214:215] op_sel_hi:[1,0]
	v_pk_add_f32 v[198:199], v[198:199], v[214:215] op_sel_hi:[1,0]
	v_rcp_f32_e32 v196, v196
	v_rcp_f32_e32 v197, v197
	v_rcp_f32_e32 v198, v198
	v_rcp_f32_e32 v199, v199
	v_pk_mul_f32 v[188:189], v[188:189], v[196:197]
	v_pk_mul_f32 v[190:191], v[190:191], v[198:199]
	v_pk_mul_f32 v[188:189], v[188:189], v[192:193]
	v_pk_mul_f32 v[190:191], v[190:191], v[194:195]
	v_cvt_pk_bf16_f32 v200, v188, v189
	v_cvt_pk_bf16_f32 v201, v190, v191
	v_pk_fma_f32 v[188:189], v[150:151], v[84:85], v[88:89]
	v_pk_fma_f32 v[190:191], v[152:153], v[86:87], v[90:91]
	v_pk_fma_f32 v[192:193], v[142:143], v[100:101], v[104:105]
	v_pk_fma_f32 v[194:195], v[144:145], v[102:103], v[106:107]
	v_fmac_f32_dpp v188, v150, v80 row_shr:1 row_mask:0xf bank_mask:0xf
	v_fmac_f32_dpp v189, v151, v81 row_shr:1 row_mask:0xf bank_mask:0xf
	v_fmac_f32_dpp v190, v152, v82 row_shr:1 row_mask:0xf bank_mask:0xf
	v_fmac_f32_dpp v191, v153, v83 row_shr:1 row_mask:0xf bank_mask:0xf
	v_fmac_f32_dpp v192, v142, v96 row_shr:1 row_mask:0xf bank_mask:0xf
	v_fmac_f32_dpp v193, v143, v97 row_shr:1 row_mask:0xf bank_mask:0xf
	v_fmac_f32_dpp v194, v144, v98 row_shr:1 row_mask:0xf bank_mask:0xf
	v_fmac_f32_dpp v195, v145, v99 row_shr:1 row_mask:0xf bank_mask:0xf
	v_fmac_f32_dpp v188, v150, v76 row_shr:2 row_mask:0xf bank_mask:0xf
	v_fmac_f32_dpp v189, v151, v77 row_shr:2 row_mask:0xf bank_mask:0xf
	v_fmac_f32_dpp v190, v152, v78 row_shr:2 row_mask:0xf bank_mask:0xf
	v_fmac_f32_dpp v191, v153, v79 row_shr:2 row_mask:0xf bank_mask:0xf
	v_fmac_f32_dpp v192, v142, v92 row_shr:2 row_mask:0xf bank_mask:0xf
	v_fmac_f32_dpp v193, v143, v93 row_shr:2 row_mask:0xf bank_mask:0xf
	v_fmac_f32_dpp v194, v144, v94 row_shr:2 row_mask:0xf bank_mask:0xf
	v_fmac_f32_dpp v195, v145, v95 row_shr:2 row_mask:0xf bank_mask:0xf
	v_fmac_f32_dpp v188, v158, v80 row_shl:15 row_mask:0xf bank_mask:0xf
	v_fmac_f32_dpp v189, v159, v81 row_shl:15 row_mask:0xf bank_mask:0xf
	v_fmac_f32_dpp v190, v160, v82 row_shl:15 row_mask:0xf bank_mask:0xf
	v_fmac_f32_dpp v191, v161, v83 row_shl:15 row_mask:0xf bank_mask:0xf
	v_fmac_f32_dpp v192, v154, v96 row_shl:15 row_mask:0xf bank_mask:0xf
	v_fmac_f32_dpp v193, v155, v97 row_shl:15 row_mask:0xf bank_mask:0xf
	v_fmac_f32_dpp v194, v156, v98 row_shl:15 row_mask:0xf bank_mask:0xf
	v_fmac_f32_dpp v195, v157, v99 row_shl:15 row_mask:0xf bank_mask:0xf
	v_fmac_f32_dpp v188, v158, v76 row_shl:14 row_mask:0xf bank_mask:0xf
	v_fmac_f32_dpp v189, v159, v77 row_shl:14 row_mask:0xf bank_mask:0xf
	v_fmac_f32_dpp v190, v160, v78 row_shl:14 row_mask:0xf bank_mask:0xf
	v_fmac_f32_dpp v191, v161, v79 row_shl:14 row_mask:0xf bank_mask:0xf
	v_fmac_f32_dpp v192, v154, v92 row_shl:14 row_mask:0xf bank_mask:0xf
	v_fmac_f32_dpp v193, v155, v93 row_shl:14 row_mask:0xf bank_mask:0xf
	v_fmac_f32_dpp v194, v156, v94 row_shl:14 row_mask:0xf bank_mask:0xf
	v_fmac_f32_dpp v195, v157, v95 row_shl:14 row_mask:0xf bank_mask:0xf
	v_pk_mul_f32 v[196:197], v[188:189], v[216:217] op_sel_hi:[1,0]
	v_pk_mul_f32 v[198:199], v[190:191], v[216:217] op_sel_hi:[1,0]
	v_exp_f32_e32 v196, v196
	v_exp_f32_e32 v197, v197
	v_exp_f32_e32 v198, v198
	v_exp_f32_e32 v199, v199
	v_pk_add_f32 v[196:197], v[196:197], v[214:215] op_sel_hi:[1,0]
	v_pk_add_f32 v[198:199], v[198:199], v[214:215] op_sel_hi:[1,0]
	v_rcp_f32_e32 v196, v196
	v_rcp_f32_e32 v197, v197
	v_rcp_f32_e32 v198, v198
	v_rcp_f32_e32 v199, v199
	v_pk_mul_f32 v[188:189], v[188:189], v[196:197]
	v_pk_mul_f32 v[190:191], v[190:191], v[198:199]
	v_pk_mul_f32 v[188:189], v[188:189], v[192:193]
	v_pk_mul_f32 v[190:191], v[190:191], v[194:195]
	v_cvt_pk_bf16_f32 v158, v188, v189
	v_cvt_pk_bf16_f32 v159, v190, v191
	v_add_u32_e32 v213, 0x21000, v212
	global_load_dwordx4 v[154:157], v213, s[82:83] offset:16
	v_pk_fma_f32 v[188:189], v[146:147], v[84:85], v[88:89]
	v_pk_fma_f32 v[190:191], v[148:149], v[86:87], v[90:91]
	v_pk_fma_f32 v[192:193], v[134:135], v[100:101], v[104:105]
	v_pk_fma_f32 v[194:195], v[136:137], v[102:103], v[106:107]
	v_fmac_f32_dpp v188, v146, v80 row_shr:1 row_mask:0xf bank_mask:0xf
	v_fmac_f32_dpp v189, v147, v81 row_shr:1 row_mask:0xf bank_mask:0xf
	v_fmac_f32_dpp v190, v148, v82 row_shr:1 row_mask:0xf bank_mask:0xf
	v_fmac_f32_dpp v191, v149, v83 row_shr:1 row_mask:0xf bank_mask:0xf
	v_fmac_f32_dpp v192, v134, v96 row_shr:1 row_mask:0xf bank_mask:0xf
	v_fmac_f32_dpp v193, v135, v97 row_shr:1 row_mask:0xf bank_mask:0xf
	v_fmac_f32_dpp v194, v136, v98 row_shr:1 row_mask:0xf bank_mask:0xf
	v_fmac_f32_dpp v195, v137, v99 row_shr:1 row_mask:0xf bank_mask:0xf
	v_fmac_f32_dpp v188, v146, v76 row_shr:2 row_mask:0xf bank_mask:0xf
	v_fmac_f32_dpp v189, v147, v77 row_shr:2 row_mask:0xf bank_mask:0xf
	v_fmac_f32_dpp v190, v148, v78 row_shr:2 row_mask:0xf bank_mask:0xf
	v_fmac_f32_dpp v191, v149, v79 row_shr:2 row_mask:0xf bank_mask:0xf
	v_fmac_f32_dpp v192, v134, v92 row_shr:2 row_mask:0xf bank_mask:0xf
	v_fmac_f32_dpp v193, v135, v93 row_shr:2 row_mask:0xf bank_mask:0xf
	v_fmac_f32_dpp v194, v136, v94 row_shr:2 row_mask:0xf bank_mask:0xf
	v_fmac_f32_dpp v195, v137, v95 row_shr:2 row_mask:0xf bank_mask:0xf
	v_fmac_f32_dpp v188, v150, v80 row_shl:15 row_mask:0xf bank_mask:0xf
	v_fmac_f32_dpp v189, v151, v81 row_shl:15 row_mask:0xf bank_mask:0xf
	v_fmac_f32_dpp v190, v152, v82 row_shl:15 row_mask:0xf bank_mask:0xf
	v_fmac_f32_dpp v191, v153, v83 row_shl:15 row_mask:0xf bank_mask:0xf
	v_fmac_f32_dpp v192, v142, v96 row_shl:15 row_mask:0xf bank_mask:0xf
	v_fmac_f32_dpp v193, v143, v97 row_shl:15 row_mask:0xf bank_mask:0xf
	v_fmac_f32_dpp v194, v144, v98 row_shl:15 row_mask:0xf bank_mask:0xf
	v_fmac_f32_dpp v195, v145, v99 row_shl:15 row_mask:0xf bank_mask:0xf
	v_fmac_f32_dpp v188, v150, v76 row_shl:14 row_mask:0xf bank_mask:0xf
	v_fmac_f32_dpp v189, v151, v77 row_shl:14 row_mask:0xf bank_mask:0xf
	v_fmac_f32_dpp v190, v152, v78 row_shl:14 row_mask:0xf bank_mask:0xf
	v_fmac_f32_dpp v191, v153, v79 row_shl:14 row_mask:0xf bank_mask:0xf
	v_fmac_f32_dpp v192, v142, v92 row_shl:14 row_mask:0xf bank_mask:0xf
	v_fmac_f32_dpp v193, v143, v93 row_shl:14 row_mask:0xf bank_mask:0xf
	v_fmac_f32_dpp v194, v144, v94 row_shl:14 row_mask:0xf bank_mask:0xf
	v_fmac_f32_dpp v195, v145, v95 row_shl:14 row_mask:0xf bank_mask:0xf
	v_pk_mul_f32 v[196:197], v[188:189], v[216:217] op_sel_hi:[1,0]
	v_pk_mul_f32 v[198:199], v[190:191], v[216:217] op_sel_hi:[1,0]
	v_exp_f32_e32 v196, v196
	v_exp_f32_e32 v197, v197
	v_exp_f32_e32 v198, v198
	v_exp_f32_e32 v199, v199
	v_pk_add_f32 v[196:197], v[196:197], v[214:215] op_sel_hi:[1,0]
	v_pk_add_f32 v[198:199], v[198:199], v[214:215] op_sel_hi:[1,0]
	v_rcp_f32_e32 v196, v196
	v_rcp_f32_e32 v197, v197
	v_rcp_f32_e32 v198, v198
	v_rcp_f32_e32 v199, v199
	v_pk_mul_f32 v[188:189], v[188:189], v[196:197]
	v_pk_mul_f32 v[190:191], v[190:191], v[198:199]
	v_pk_mul_f32 v[188:189], v[188:189], v[192:193]
	v_pk_mul_f32 v[190:191], v[190:191], v[194:195]
	v_cvt_pk_bf16_f32 v150, v188, v189
	v_cvt_pk_bf16_f32 v151, v190, v191
	v_add_u32_e32 v213, 0x2c000, v212
	global_load_dwordx4 v[142:145], v213, s[82:83] offset:16
	v_pk_fma_f32 v[188:189], v[138:139], v[84:85], v[88:89]
	v_pk_fma_f32 v[190:191], v[140:141], v[86:87], v[90:91]
	v_pk_fma_f32 v[192:193], v[130:131], v[100:101], v[104:105]
	v_pk_fma_f32 v[194:195], v[132:133], v[102:103], v[106:107]
	v_fmac_f32_dpp v188, v138, v80 row_shr:1 row_mask:0xf bank_mask:0xf
	v_fmac_f32_dpp v189, v139, v81 row_shr:1 row_mask:0xf bank_mask:0xf
	v_fmac_f32_dpp v190, v140, v82 row_shr:1 row_mask:0xf bank_mask:0xf
	v_fmac_f32_dpp v191, v141, v83 row_shr:1 row_mask:0xf bank_mask:0xf
	v_fmac_f32_dpp v192, v130, v96 row_shr:1 row_mask:0xf bank_mask:0xf
	v_fmac_f32_dpp v193, v131, v97 row_shr:1 row_mask:0xf bank_mask:0xf
	v_fmac_f32_dpp v194, v132, v98 row_shr:1 row_mask:0xf bank_mask:0xf
	v_fmac_f32_dpp v195, v133, v99 row_shr:1 row_mask:0xf bank_mask:0xf
	v_fmac_f32_dpp v188, v138, v76 row_shr:2 row_mask:0xf bank_mask:0xf
	v_fmac_f32_dpp v189, v139, v77 row_shr:2 row_mask:0xf bank_mask:0xf
	v_fmac_f32_dpp v190, v140, v78 row_shr:2 row_mask:0xf bank_mask:0xf
	v_fmac_f32_dpp v191, v141, v79 row_shr:2 row_mask:0xf bank_mask:0xf
	v_fmac_f32_dpp v192, v130, v92 row_shr:2 row_mask:0xf bank_mask:0xf
	v_fmac_f32_dpp v193, v131, v93 row_shr:2 row_mask:0xf bank_mask:0xf
	v_fmac_f32_dpp v194, v132, v94 row_shr:2 row_mask:0xf bank_mask:0xf
	v_fmac_f32_dpp v195, v133, v95 row_shr:2 row_mask:0xf bank_mask:0xf
	v_fmac_f32_dpp v188, v146, v80 row_shl:15 row_mask:0xf bank_mask:0xf
	v_fmac_f32_dpp v189, v147, v81 row_shl:15 row_mask:0xf bank_mask:0xf
	v_fmac_f32_dpp v190, v148, v82 row_shl:15 row_mask:0xf bank_mask:0xf
	v_fmac_f32_dpp v191, v149, v83 row_shl:15 row_mask:0xf bank_mask:0xf
	v_fmac_f32_dpp v192, v134, v96 row_shl:15 row_mask:0xf bank_mask:0xf
	v_fmac_f32_dpp v193, v135, v97 row_shl:15 row_mask:0xf bank_mask:0xf
	v_fmac_f32_dpp v194, v136, v98 row_shl:15 row_mask:0xf bank_mask:0xf
	v_fmac_f32_dpp v195, v137, v99 row_shl:15 row_mask:0xf bank_mask:0xf
	v_fmac_f32_dpp v188, v146, v76 row_shl:14 row_mask:0xf bank_mask:0xf
	v_fmac_f32_dpp v189, v147, v77 row_shl:14 row_mask:0xf bank_mask:0xf
	v_fmac_f32_dpp v190, v148, v78 row_shl:14 row_mask:0xf bank_mask:0xf
	v_fmac_f32_dpp v191, v149, v79 row_shl:14 row_mask:0xf bank_mask:0xf
	v_fmac_f32_dpp v192, v134, v92 row_shl:14 row_mask:0xf bank_mask:0xf
	v_fmac_f32_dpp v193, v135, v93 row_shl:14 row_mask:0xf bank_mask:0xf
	v_fmac_f32_dpp v194, v136, v94 row_shl:14 row_mask:0xf bank_mask:0xf
	v_fmac_f32_dpp v195, v137, v95 row_shl:14 row_mask:0xf bank_mask:0xf
	v_pk_mul_f32 v[196:197], v[188:189], v[216:217] op_sel_hi:[1,0]
	v_pk_mul_f32 v[198:199], v[190:191], v[216:217] op_sel_hi:[1,0]
	v_exp_f32_e32 v196, v196
	v_exp_f32_e32 v197, v197
	v_exp_f32_e32 v198, v198
	v_exp_f32_e32 v199, v199
	v_pk_add_f32 v[196:197], v[196:197], v[214:215] op_sel_hi:[1,0]
	v_pk_add_f32 v[198:199], v[198:199], v[214:215] op_sel_hi:[1,0]
	v_rcp_f32_e32 v196, v196
	v_rcp_f32_e32 v197, v197
	v_rcp_f32_e32 v198, v198
	v_rcp_f32_e32 v199, v199
	v_pk_mul_f32 v[188:189], v[188:189], v[196:197]
	v_pk_mul_f32 v[190:191], v[190:191], v[198:199]
	v_pk_mul_f32 v[188:189], v[188:189], v[192:193]
	v_pk_mul_f32 v[190:191], v[190:191], v[194:195]
	v_cvt_pk_bf16_f32 v146, v188, v189
	v_cvt_pk_bf16_f32 v147, v190, v191
	v_add_u32_e32 v213, 0x37000, v212
	global_load_dwordx4 v[134:137], v213, s[82:83] offset:16
	v_pk_fma_f32 v[188:189], v[126:127], v[84:85], v[88:89]
	v_pk_fma_f32 v[190:191], v[128:129], v[86:87], v[90:91]
	v_pk_fma_f32 v[192:193], v[118:119], v[100:101], v[104:105]
	v_pk_fma_f32 v[194:195], v[120:121], v[102:103], v[106:107]
	v_fmac_f32_dpp v188, v126, v80 row_shr:1 row_mask:0xf bank_mask:0xf
	v_fmac_f32_dpp v189, v127, v81 row_shr:1 row_mask:0xf bank_mask:0xf
	v_fmac_f32_dpp v190, v128, v82 row_shr:1 row_mask:0xf bank_mask:0xf
	v_fmac_f32_dpp v191, v129, v83 row_shr:1 row_mask:0xf bank_mask:0xf
	v_fmac_f32_dpp v192, v118, v96 row_shr:1 row_mask:0xf bank_mask:0xf
	v_fmac_f32_dpp v193, v119, v97 row_shr:1 row_mask:0xf bank_mask:0xf
	v_fmac_f32_dpp v194, v120, v98 row_shr:1 row_mask:0xf bank_mask:0xf
	v_fmac_f32_dpp v195, v121, v99 row_shr:1 row_mask:0xf bank_mask:0xf
	v_fmac_f32_dpp v188, v126, v76 row_shr:2 row_mask:0xf bank_mask:0xf
	v_fmac_f32_dpp v189, v127, v77 row_shr:2 row_mask:0xf bank_mask:0xf
	v_fmac_f32_dpp v190, v128, v78 row_shr:2 row_mask:0xf bank_mask:0xf
	v_fmac_f32_dpp v191, v129, v79 row_shr:2 row_mask:0xf bank_mask:0xf
	v_fmac_f32_dpp v192, v118, v92 row_shr:2 row_mask:0xf bank_mask:0xf
	v_fmac_f32_dpp v193, v119, v93 row_shr:2 row_mask:0xf bank_mask:0xf
	v_fmac_f32_dpp v194, v120, v94 row_shr:2 row_mask:0xf bank_mask:0xf
	v_fmac_f32_dpp v195, v121, v95 row_shr:2 row_mask:0xf bank_mask:0xf
	v_fmac_f32_dpp v188, v138, v80 row_shl:15 row_mask:0xf bank_mask:0xf
	v_fmac_f32_dpp v189, v139, v81 row_shl:15 row_mask:0xf bank_mask:0xf
	v_fmac_f32_dpp v190, v140, v82 row_shl:15 row_mask:0xf bank_mask:0xf
	v_fmac_f32_dpp v191, v141, v83 row_shl:15 row_mask:0xf bank_mask:0xf
	v_fmac_f32_dpp v192, v130, v96 row_shl:15 row_mask:0xf bank_mask:0xf
	v_fmac_f32_dpp v193, v131, v97 row_shl:15 row_mask:0xf bank_mask:0xf
	v_fmac_f32_dpp v194, v132, v98 row_shl:15 row_mask:0xf bank_mask:0xf
	v_fmac_f32_dpp v195, v133, v99 row_shl:15 row_mask:0xf bank_mask:0xf
	v_fmac_f32_dpp v188, v138, v76 row_shl:14 row_mask:0xf bank_mask:0xf
	v_fmac_f32_dpp v189, v139, v77 row_shl:14 row_mask:0xf bank_mask:0xf
	v_fmac_f32_dpp v190, v140, v78 row_shl:14 row_mask:0xf bank_mask:0xf
	v_fmac_f32_dpp v191, v141, v79 row_shl:14 row_mask:0xf bank_mask:0xf
	v_fmac_f32_dpp v192, v130, v92 row_shl:14 row_mask:0xf bank_mask:0xf
	v_fmac_f32_dpp v193, v131, v93 row_shl:14 row_mask:0xf bank_mask:0xf
	v_fmac_f32_dpp v194, v132, v94 row_shl:14 row_mask:0xf bank_mask:0xf
	v_fmac_f32_dpp v195, v133, v95 row_shl:14 row_mask:0xf bank_mask:0xf
	v_pk_mul_f32 v[196:197], v[188:189], v[216:217] op_sel_hi:[1,0]
	v_pk_mul_f32 v[198:199], v[190:191], v[216:217] op_sel_hi:[1,0]
	v_exp_f32_e32 v196, v196
	v_exp_f32_e32 v197, v197
	v_exp_f32_e32 v198, v198
	v_exp_f32_e32 v199, v199
	v_pk_add_f32 v[196:197], v[196:197], v[214:215] op_sel_hi:[1,0]
	v_pk_add_f32 v[198:199], v[198:199], v[214:215] op_sel_hi:[1,0]
	v_rcp_f32_e32 v196, v196
	v_rcp_f32_e32 v197, v197
	v_rcp_f32_e32 v198, v198
	v_rcp_f32_e32 v199, v199
	v_pk_mul_f32 v[188:189], v[188:189], v[196:197]
	v_pk_mul_f32 v[190:191], v[190:191], v[198:199]
	v_pk_mul_f32 v[188:189], v[188:189], v[192:193]
	v_pk_mul_f32 v[190:191], v[190:191], v[194:195]
	v_cvt_pk_bf16_f32 v138, v188, v189
	v_cvt_pk_bf16_f32 v139, v190, v191
	v_add_u32_e32 v213, 0xb000, v212
	global_load_dwordx4 v[130:133], v213, s[84:85] offset:16
	v_pk_fma_f32 v[188:189], v[122:123], v[84:85], v[88:89]
	v_pk_fma_f32 v[190:191], v[124:125], v[86:87], v[90:91]
	v_pk_fma_f32 v[192:193], v[110:111], v[100:101], v[104:105]
	v_pk_fma_f32 v[194:195], v[112:113], v[102:103], v[106:107]
	v_fmac_f32_dpp v188, v122, v80 row_shr:1 row_mask:0xf bank_mask:0xf
	v_fmac_f32_dpp v189, v123, v81 row_shr:1 row_mask:0xf bank_mask:0xf
	v_fmac_f32_dpp v190, v124, v82 row_shr:1 row_mask:0xf bank_mask:0xf
	v_fmac_f32_dpp v191, v125, v83 row_shr:1 row_mask:0xf bank_mask:0xf
	v_fmac_f32_dpp v192, v110, v96 row_shr:1 row_mask:0xf bank_mask:0xf
	v_fmac_f32_dpp v193, v111, v97 row_shr:1 row_mask:0xf bank_mask:0xf
	v_fmac_f32_dpp v194, v112, v98 row_shr:1 row_mask:0xf bank_mask:0xf
	v_fmac_f32_dpp v195, v113, v99 row_shr:1 row_mask:0xf bank_mask:0xf
	v_fmac_f32_dpp v188, v122, v76 row_shr:2 row_mask:0xf bank_mask:0xf
	v_fmac_f32_dpp v189, v123, v77 row_shr:2 row_mask:0xf bank_mask:0xf
	v_fmac_f32_dpp v190, v124, v78 row_shr:2 row_mask:0xf bank_mask:0xf
	v_fmac_f32_dpp v191, v125, v79 row_shr:2 row_mask:0xf bank_mask:0xf
	v_fmac_f32_dpp v192, v110, v92 row_shr:2 row_mask:0xf bank_mask:0xf
	v_fmac_f32_dpp v193, v111, v93 row_shr:2 row_mask:0xf bank_mask:0xf
	v_fmac_f32_dpp v194, v112, v94 row_shr:2 row_mask:0xf bank_mask:0xf
	v_fmac_f32_dpp v195, v113, v95 row_shr:2 row_mask:0xf bank_mask:0xf
	v_fmac_f32_dpp v188, v126, v80 row_shl:15 row_mask:0xf bank_mask:0xf
	v_fmac_f32_dpp v189, v127, v81 row_shl:15 row_mask:0xf bank_mask:0xf
	v_fmac_f32_dpp v190, v128, v82 row_shl:15 row_mask:0xf bank_mask:0xf
	v_fmac_f32_dpp v191, v129, v83 row_shl:15 row_mask:0xf bank_mask:0xf
	v_fmac_f32_dpp v192, v118, v96 row_shl:15 row_mask:0xf bank_mask:0xf
	v_fmac_f32_dpp v193, v119, v97 row_shl:15 row_mask:0xf bank_mask:0xf
	v_fmac_f32_dpp v194, v120, v98 row_shl:15 row_mask:0xf bank_mask:0xf
	v_fmac_f32_dpp v195, v121, v99 row_shl:15 row_mask:0xf bank_mask:0xf
	v_fmac_f32_dpp v188, v126, v76 row_shl:14 row_mask:0xf bank_mask:0xf
	v_fmac_f32_dpp v189, v127, v77 row_shl:14 row_mask:0xf bank_mask:0xf
	v_fmac_f32_dpp v190, v128, v78 row_shl:14 row_mask:0xf bank_mask:0xf
	v_fmac_f32_dpp v191, v129, v79 row_shl:14 row_mask:0xf bank_mask:0xf
	v_fmac_f32_dpp v192, v118, v92 row_shl:14 row_mask:0xf bank_mask:0xf
	v_fmac_f32_dpp v193, v119, v93 row_shl:14 row_mask:0xf bank_mask:0xf
	v_fmac_f32_dpp v194, v120, v94 row_shl:14 row_mask:0xf bank_mask:0xf
	v_fmac_f32_dpp v195, v121, v95 row_shl:14 row_mask:0xf bank_mask:0xf
	v_pk_mul_f32 v[196:197], v[188:189], v[216:217] op_sel_hi:[1,0]
	v_pk_mul_f32 v[198:199], v[190:191], v[216:217] op_sel_hi:[1,0]
	v_exp_f32_e32 v196, v196
	v_exp_f32_e32 v197, v197
	v_exp_f32_e32 v198, v198
	v_exp_f32_e32 v199, v199
	v_pk_add_f32 v[196:197], v[196:197], v[214:215] op_sel_hi:[1,0]
	v_pk_add_f32 v[198:199], v[198:199], v[214:215] op_sel_hi:[1,0]
	v_rcp_f32_e32 v196, v196
	v_rcp_f32_e32 v197, v197
	v_rcp_f32_e32 v198, v198
	v_rcp_f32_e32 v199, v199
	v_pk_mul_f32 v[188:189], v[188:189], v[196:197]
	v_pk_mul_f32 v[190:191], v[190:191], v[198:199]
	v_pk_mul_f32 v[188:189], v[188:189], v[192:193]
	v_pk_mul_f32 v[190:191], v[190:191], v[194:195]
	v_cvt_pk_bf16_f32 v126, v188, v189
	v_cvt_pk_bf16_f32 v127, v190, v191
	v_add_u32_e32 v213, 0x26800, v212
	global_load_dwordx4 v[118:121], v213, s[82:83] offset:16
	v_pk_fma_f32 v[188:189], v[114:115], v[84:85], v[88:89]
	v_pk_fma_f32 v[190:191], v[116:117], v[86:87], v[90:91]
	v_pk_fma_f32 v[192:193], v[68:69], v[100:101], v[104:105]
	v_pk_fma_f32 v[194:195], v[70:71], v[102:103], v[106:107]
	v_fmac_f32_dpp v188, v114, v80 row_shr:1 row_mask:0xf bank_mask:0xf
	v_fmac_f32_dpp v189, v115, v81 row_shr:1 row_mask:0xf bank_mask:0xf
	v_fmac_f32_dpp v190, v116, v82 row_shr:1 row_mask:0xf bank_mask:0xf
	v_fmac_f32_dpp v191, v117, v83 row_shr:1 row_mask:0xf bank_mask:0xf
	v_fmac_f32_dpp v192, v68, v96 row_shr:1 row_mask:0xf bank_mask:0xf
	v_fmac_f32_dpp v193, v69, v97 row_shr:1 row_mask:0xf bank_mask:0xf
	v_fmac_f32_dpp v194, v70, v98 row_shr:1 row_mask:0xf bank_mask:0xf
	v_fmac_f32_dpp v195, v71, v99 row_shr:1 row_mask:0xf bank_mask:0xf
	v_fmac_f32_dpp v188, v114, v76 row_shr:2 row_mask:0xf bank_mask:0xf
	v_fmac_f32_dpp v189, v115, v77 row_shr:2 row_mask:0xf bank_mask:0xf
	v_fmac_f32_dpp v190, v116, v78 row_shr:2 row_mask:0xf bank_mask:0xf
	v_fmac_f32_dpp v191, v117, v79 row_shr:2 row_mask:0xf bank_mask:0xf
	v_fmac_f32_dpp v192, v68, v92 row_shr:2 row_mask:0xf bank_mask:0xf
	v_fmac_f32_dpp v193, v69, v93 row_shr:2 row_mask:0xf bank_mask:0xf
	v_fmac_f32_dpp v194, v70, v94 row_shr:2 row_mask:0xf bank_mask:0xf
	v_fmac_f32_dpp v195, v71, v95 row_shr:2 row_mask:0xf bank_mask:0xf
	v_fmac_f32_dpp v188, v122, v80 row_shl:15 row_mask:0xf bank_mask:0xf
	v_fmac_f32_dpp v189, v123, v81 row_shl:15 row_mask:0xf bank_mask:0xf
	v_fmac_f32_dpp v190, v124, v82 row_shl:15 row_mask:0xf bank_mask:0xf
	v_fmac_f32_dpp v191, v125, v83 row_shl:15 row_mask:0xf bank_mask:0xf
	v_fmac_f32_dpp v192, v110, v96 row_shl:15 row_mask:0xf bank_mask:0xf
	v_fmac_f32_dpp v193, v111, v97 row_shl:15 row_mask:0xf bank_mask:0xf
	v_fmac_f32_dpp v194, v112, v98 row_shl:15 row_mask:0xf bank_mask:0xf
	v_fmac_f32_dpp v195, v113, v99 row_shl:15 row_mask:0xf bank_mask:0xf
	v_fmac_f32_dpp v188, v122, v76 row_shl:14 row_mask:0xf bank_mask:0xf
	v_fmac_f32_dpp v189, v123, v77 row_shl:14 row_mask:0xf bank_mask:0xf
	v_fmac_f32_dpp v190, v124, v78 row_shl:14 row_mask:0xf bank_mask:0xf
	v_fmac_f32_dpp v191, v125, v79 row_shl:14 row_mask:0xf bank_mask:0xf
	v_fmac_f32_dpp v192, v110, v92 row_shl:14 row_mask:0xf bank_mask:0xf
	v_fmac_f32_dpp v193, v111, v93 row_shl:14 row_mask:0xf bank_mask:0xf
	v_fmac_f32_dpp v194, v112, v94 row_shl:14 row_mask:0xf bank_mask:0xf
	v_fmac_f32_dpp v195, v113, v95 row_shl:14 row_mask:0xf bank_mask:0xf
	v_pk_mul_f32 v[196:197], v[188:189], v[216:217] op_sel_hi:[1,0]
	v_pk_mul_f32 v[198:199], v[190:191], v[216:217] op_sel_hi:[1,0]
	v_exp_f32_e32 v196, v196
	v_exp_f32_e32 v197, v197
	v_exp_f32_e32 v198, v198
	v_exp_f32_e32 v199, v199
	v_pk_add_f32 v[196:197], v[196:197], v[214:215] op_sel_hi:[1,0]
	v_pk_add_f32 v[198:199], v[198:199], v[214:215] op_sel_hi:[1,0]
	v_rcp_f32_e32 v196, v196
	v_rcp_f32_e32 v197, v197
	v_rcp_f32_e32 v198, v198
	v_rcp_f32_e32 v199, v199
	v_pk_mul_f32 v[188:189], v[188:189], v[196:197]
	v_pk_mul_f32 v[190:191], v[190:191], v[198:199]
	v_pk_mul_f32 v[188:189], v[188:189], v[192:193]
	v_pk_mul_f32 v[190:191], v[190:191], v[194:195]
	v_cvt_pk_bf16_f32 v122, v188, v189
	v_cvt_pk_bf16_f32 v123, v190, v191
	v_add_u32_e32 v213, 0x31800, v212
	global_load_dwordx4 v[110:113], v213, s[82:83] offset:16
	v_pk_fma_f32 v[188:189], v[72:73], v[84:85], v[88:89]
	v_pk_fma_f32 v[190:191], v[74:75], v[86:87], v[90:91]
	v_pk_fma_f32 v[192:193], v[64:65], v[100:101], v[104:105]
	v_pk_fma_f32 v[194:195], v[66:67], v[102:103], v[106:107]
	v_fmac_f32_dpp v188, v72, v80 row_shr:1 row_mask:0xf bank_mask:0xf
	v_fmac_f32_dpp v189, v73, v81 row_shr:1 row_mask:0xf bank_mask:0xf
	v_fmac_f32_dpp v190, v74, v82 row_shr:1 row_mask:0xf bank_mask:0xf
	v_fmac_f32_dpp v191, v75, v83 row_shr:1 row_mask:0xf bank_mask:0xf
	v_fmac_f32_dpp v192, v64, v96 row_shr:1 row_mask:0xf bank_mask:0xf
	v_fmac_f32_dpp v193, v65, v97 row_shr:1 row_mask:0xf bank_mask:0xf
	v_fmac_f32_dpp v194, v66, v98 row_shr:1 row_mask:0xf bank_mask:0xf
	v_fmac_f32_dpp v195, v67, v99 row_shr:1 row_mask:0xf bank_mask:0xf
	v_fmac_f32_dpp v188, v72, v76 row_shr:2 row_mask:0xf bank_mask:0xf
	v_fmac_f32_dpp v189, v73, v77 row_shr:2 row_mask:0xf bank_mask:0xf
	v_fmac_f32_dpp v190, v74, v78 row_shr:2 row_mask:0xf bank_mask:0xf
	v_fmac_f32_dpp v191, v75, v79 row_shr:2 row_mask:0xf bank_mask:0xf
	v_fmac_f32_dpp v192, v64, v92 row_shr:2 row_mask:0xf bank_mask:0xf
	v_fmac_f32_dpp v193, v65, v93 row_shr:2 row_mask:0xf bank_mask:0xf
	v_fmac_f32_dpp v194, v66, v94 row_shr:2 row_mask:0xf bank_mask:0xf
	v_fmac_f32_dpp v195, v67, v95 row_shr:2 row_mask:0xf bank_mask:0xf
	v_fmac_f32_dpp v188, v114, v80 row_shl:15 row_mask:0xf bank_mask:0xf
	v_fmac_f32_dpp v189, v115, v81 row_shl:15 row_mask:0xf bank_mask:0xf
	v_fmac_f32_dpp v190, v116, v82 row_shl:15 row_mask:0xf bank_mask:0xf
	v_fmac_f32_dpp v191, v117, v83 row_shl:15 row_mask:0xf bank_mask:0xf
	v_fmac_f32_dpp v192, v68, v96 row_shl:15 row_mask:0xf bank_mask:0xf
	v_fmac_f32_dpp v193, v69, v97 row_shl:15 row_mask:0xf bank_mask:0xf
	v_fmac_f32_dpp v194, v70, v98 row_shl:15 row_mask:0xf bank_mask:0xf
	v_fmac_f32_dpp v195, v71, v99 row_shl:15 row_mask:0xf bank_mask:0xf
	v_fmac_f32_dpp v188, v114, v76 row_shl:14 row_mask:0xf bank_mask:0xf
	v_fmac_f32_dpp v189, v115, v77 row_shl:14 row_mask:0xf bank_mask:0xf
	v_fmac_f32_dpp v190, v116, v78 row_shl:14 row_mask:0xf bank_mask:0xf
	v_fmac_f32_dpp v191, v117, v79 row_shl:14 row_mask:0xf bank_mask:0xf
	v_fmac_f32_dpp v192, v68, v92 row_shl:14 row_mask:0xf bank_mask:0xf
	v_fmac_f32_dpp v193, v69, v93 row_shl:14 row_mask:0xf bank_mask:0xf
	v_fmac_f32_dpp v194, v70, v94 row_shl:14 row_mask:0xf bank_mask:0xf
	v_fmac_f32_dpp v195, v71, v95 row_shl:14 row_mask:0xf bank_mask:0xf
	v_pk_mul_f32 v[196:197], v[188:189], v[216:217] op_sel_hi:[1,0]
	v_pk_mul_f32 v[198:199], v[190:191], v[216:217] op_sel_hi:[1,0]
	v_exp_f32_e32 v196, v196
	v_exp_f32_e32 v197, v197
	v_exp_f32_e32 v198, v198
	v_exp_f32_e32 v199, v199
	v_pk_add_f32 v[196:197], v[196:197], v[214:215] op_sel_hi:[1,0]
	v_pk_add_f32 v[198:199], v[198:199], v[214:215] op_sel_hi:[1,0]
	v_rcp_f32_e32 v196, v196
	v_rcp_f32_e32 v197, v197
	v_rcp_f32_e32 v198, v198
	v_rcp_f32_e32 v199, v199
	v_pk_mul_f32 v[188:189], v[188:189], v[196:197]
	v_pk_mul_f32 v[190:191], v[190:191], v[198:199]
	v_pk_mul_f32 v[188:189], v[188:189], v[192:193]
	v_pk_mul_f32 v[190:191], v[190:191], v[194:195]
	v_cvt_pk_bf16_f32 v114, v188, v189
	v_cvt_pk_bf16_f32 v115, v190, v191
	s_waitcnt vmcnt(0)
	v_pk_fma_f32 v[188:189], v[60:61], v[134:135], v[130:131]
	v_pk_fma_f32 v[190:191], v[62:63], v[136:137], v[132:133]
	v_pk_fma_f32 v[192:193], v[56:57], v[204:205], v[208:209]
	v_pk_fma_f32 v[194:195], v[58:59], v[206:207], v[210:211]
	v_fmac_f32_dpp v188, v60, v142 row_shr:1 row_mask:0xf bank_mask:0xf
	v_fmac_f32_dpp v189, v61, v143 row_shr:1 row_mask:0xf bank_mask:0xf
	v_fmac_f32_dpp v190, v62, v144 row_shr:1 row_mask:0xf bank_mask:0xf
	v_fmac_f32_dpp v191, v63, v145 row_shr:1 row_mask:0xf bank_mask:0xf
	v_fmac_f32_dpp v192, v56, v110 row_shr:1 row_mask:0xf bank_mask:0xf
	v_fmac_f32_dpp v193, v57, v111 row_shr:1 row_mask:0xf bank_mask:0xf
	v_fmac_f32_dpp v194, v58, v112 row_shr:1 row_mask:0xf bank_mask:0xf
	v_fmac_f32_dpp v195, v59, v113 row_shr:1 row_mask:0xf bank_mask:0xf
	v_fmac_f32_dpp v188, v60, v154 row_shr:2 row_mask:0xf bank_mask:0xf
	v_fmac_f32_dpp v189, v61, v155 row_shr:2 row_mask:0xf bank_mask:0xf
	v_fmac_f32_dpp v190, v62, v156 row_shr:2 row_mask:0xf bank_mask:0xf
	v_fmac_f32_dpp v191, v63, v157 row_shr:2 row_mask:0xf bank_mask:0xf
	v_fmac_f32_dpp v192, v56, v118 row_shr:2 row_mask:0xf bank_mask:0xf
	v_fmac_f32_dpp v193, v57, v119 row_shr:2 row_mask:0xf bank_mask:0xf
	v_fmac_f32_dpp v194, v58, v120 row_shr:2 row_mask:0xf bank_mask:0xf
	v_fmac_f32_dpp v195, v59, v121 row_shr:2 row_mask:0xf bank_mask:0xf
	v_pk_mul_f32 v[196:197], v[188:189], v[216:217] op_sel_hi:[1,0]
	v_pk_mul_f32 v[198:199], v[190:191], v[216:217] op_sel_hi:[1,0]
	v_exp_f32_e32 v196, v196
	v_exp_f32_e32 v197, v197
	v_exp_f32_e32 v198, v198
	v_exp_f32_e32 v199, v199
	v_pk_add_f32 v[196:197], v[196:197], v[214:215] op_sel_hi:[1,0]
	v_pk_add_f32 v[198:199], v[198:199], v[214:215] op_sel_hi:[1,0]
	v_rcp_f32_e32 v196, v196
	v_rcp_f32_e32 v197, v197
	v_rcp_f32_e32 v198, v198
	v_rcp_f32_e32 v199, v199
	v_pk_mul_f32 v[188:189], v[188:189], v[196:197]
	v_pk_mul_f32 v[190:191], v[190:191], v[198:199]
	v_pk_mul_f32 v[188:189], v[188:189], v[192:193]
	v_pk_mul_f32 v[190:191], v[190:191], v[194:195]
	v_cvt_pk_bf16_f32 v202, v188, v189
	v_cvt_pk_bf16_f32 v203, v190, v191
	s_mov_b64 exec, vcc
	global_store_dwordx4 v215, v[200:203], s[96:97]
	s_mov_b64 exec, -1
	v_pk_fma_f32 v[188:189], v[52:53], v[134:135], v[130:131]
	v_pk_fma_f32 v[190:191], v[54:55], v[136:137], v[132:133]
	v_pk_fma_f32 v[192:193], v[44:45], v[204:205], v[208:209]
	v_pk_fma_f32 v[194:195], v[46:47], v[206:207], v[210:211]
	v_fmac_f32_dpp v188, v52, v142 row_shr:1 row_mask:0xf bank_mask:0xf
	v_fmac_f32_dpp v189, v53, v143 row_shr:1 row_mask:0xf bank_mask:0xf
	v_fmac_f32_dpp v190, v54, v144 row_shr:1 row_mask:0xf bank_mask:0xf
	v_fmac_f32_dpp v191, v55, v145 row_shr:1 row_mask:0xf bank_mask:0xf
	v_fmac_f32_dpp v192, v44, v110 row_shr:1 row_mask:0xf bank_mask:0xf
	v_fmac_f32_dpp v193, v45, v111 row_shr:1 row_mask:0xf bank_mask:0xf
	v_fmac_f32_dpp v194, v46, v112 row_shr:1 row_mask:0xf bank_mask:0xf
	v_fmac_f32_dpp v195, v47, v113 row_shr:1 row_mask:0xf bank_mask:0xf
	v_fmac_f32_dpp v188, v52, v154 row_shr:2 row_mask:0xf bank_mask:0xf
	v_fmac_f32_dpp v189, v53, v155 row_shr:2 row_mask:0xf bank_mask:0xf
	v_fmac_f32_dpp v190, v54, v156 row_shr:2 row_mask:0xf bank_mask:0xf
	v_fmac_f32_dpp v191, v55, v157 row_shr:2 row_mask:0xf bank_mask:0xf
	v_fmac_f32_dpp v192, v44, v118 row_shr:2 row_mask:0xf bank_mask:0xf
	v_fmac_f32_dpp v193, v45, v119 row_shr:2 row_mask:0xf bank_mask:0xf
	v_fmac_f32_dpp v194, v46, v120 row_shr:2 row_mask:0xf bank_mask:0xf
	v_fmac_f32_dpp v195, v47, v121 row_shr:2 row_mask:0xf bank_mask:0xf
	v_fmac_f32_dpp v188, v60, v142 row_shl:15 row_mask:0xf bank_mask:0xf
	v_fmac_f32_dpp v189, v61, v143 row_shl:15 row_mask:0xf bank_mask:0xf
	v_fmac_f32_dpp v190, v62, v144 row_shl:15 row_mask:0xf bank_mask:0xf
	v_fmac_f32_dpp v191, v63, v145 row_shl:15 row_mask:0xf bank_mask:0xf
	v_fmac_f32_dpp v192, v56, v110 row_shl:15 row_mask:0xf bank_mask:0xf
	v_fmac_f32_dpp v193, v57, v111 row_shl:15 row_mask:0xf bank_mask:0xf
	v_fmac_f32_dpp v194, v58, v112 row_shl:15 row_mask:0xf bank_mask:0xf
	v_fmac_f32_dpp v195, v59, v113 row_shl:15 row_mask:0xf bank_mask:0xf
	v_fmac_f32_dpp v188, v60, v154 row_shl:14 row_mask:0xf bank_mask:0xf
	v_fmac_f32_dpp v189, v61, v155 row_shl:14 row_mask:0xf bank_mask:0xf
	v_fmac_f32_dpp v190, v62, v156 row_shl:14 row_mask:0xf bank_mask:0xf
	v_fmac_f32_dpp v191, v63, v157 row_shl:14 row_mask:0xf bank_mask:0xf
	v_fmac_f32_dpp v192, v56, v118 row_shl:14 row_mask:0xf bank_mask:0xf
	v_fmac_f32_dpp v193, v57, v119 row_shl:14 row_mask:0xf bank_mask:0xf
	v_fmac_f32_dpp v194, v58, v120 row_shl:14 row_mask:0xf bank_mask:0xf
	v_fmac_f32_dpp v195, v59, v121 row_shl:14 row_mask:0xf bank_mask:0xf
	v_pk_mul_f32 v[196:197], v[188:189], v[216:217] op_sel_hi:[1,0]
	v_pk_mul_f32 v[198:199], v[190:191], v[216:217] op_sel_hi:[1,0]
	v_exp_f32_e32 v196, v196
	v_exp_f32_e32 v197, v197
	v_exp_f32_e32 v198, v198
	v_exp_f32_e32 v199, v199
	v_pk_add_f32 v[196:197], v[196:197], v[214:215] op_sel_hi:[1,0]
	v_pk_add_f32 v[198:199], v[198:199], v[214:215] op_sel_hi:[1,0]
	v_rcp_f32_e32 v196, v196
	v_rcp_f32_e32 v197, v197
	v_rcp_f32_e32 v198, v198
	v_rcp_f32_e32 v199, v199
	v_pk_mul_f32 v[188:189], v[188:189], v[196:197]
	v_pk_mul_f32 v[190:191], v[190:191], v[198:199]
	v_pk_mul_f32 v[188:189], v[188:189], v[192:193]
	v_pk_mul_f32 v[190:191], v[190:191], v[194:195]
	v_cvt_pk_bf16_f32 v160, v188, v189
	v_cvt_pk_bf16_f32 v161, v190, v191
	v_add_u32_e32 v213, 0x2c000, v215
	global_store_dwordx4 v213, v[158:161], s[96:97]
	v_pk_fma_f32 v[188:189], v[48:49], v[134:135], v[130:131]
	v_pk_fma_f32 v[190:191], v[50:51], v[136:137], v[132:133]
	v_pk_fma_f32 v[192:193], v[36:37], v[204:205], v[208:209]
	v_pk_fma_f32 v[194:195], v[38:39], v[206:207], v[210:211]
	v_fmac_f32_dpp v188, v48, v142 row_shr:1 row_mask:0xf bank_mask:0xf
	v_fmac_f32_dpp v189, v49, v143 row_shr:1 row_mask:0xf bank_mask:0xf
	v_fmac_f32_dpp v190, v50, v144 row_shr:1 row_mask:0xf bank_mask:0xf
	v_fmac_f32_dpp v191, v51, v145 row_shr:1 row_mask:0xf bank_mask:0xf
	v_fmac_f32_dpp v192, v36, v110 row_shr:1 row_mask:0xf bank_mask:0xf
	v_fmac_f32_dpp v193, v37, v111 row_shr:1 row_mask:0xf bank_mask:0xf
	v_fmac_f32_dpp v194, v38, v112 row_shr:1 row_mask:0xf bank_mask:0xf
	v_fmac_f32_dpp v195, v39, v113 row_shr:1 row_mask:0xf bank_mask:0xf
	v_fmac_f32_dpp v188, v48, v154 row_shr:2 row_mask:0xf bank_mask:0xf
	v_fmac_f32_dpp v189, v49, v155 row_shr:2 row_mask:0xf bank_mask:0xf
	v_fmac_f32_dpp v190, v50, v156 row_shr:2 row_mask:0xf bank_mask:0xf
	v_fmac_f32_dpp v191, v51, v157 row_shr:2 row_mask:0xf bank_mask:0xf
	v_fmac_f32_dpp v192, v36, v118 row_shr:2 row_mask:0xf bank_mask:0xf
	v_fmac_f32_dpp v193, v37, v119 row_shr:2 row_mask:0xf bank_mask:0xf
	v_fmac_f32_dpp v194, v38, v120 row_shr:2 row_mask:0xf bank_mask:0xf
	v_fmac_f32_dpp v195, v39, v121 row_shr:2 row_mask:0xf bank_mask:0xf
	v_fmac_f32_dpp v188, v52, v142 row_shl:15 row_mask:0xf bank_mask:0xf
	v_fmac_f32_dpp v189, v53, v143 row_shl:15 row_mask:0xf bank_mask:0xf
	v_fmac_f32_dpp v190, v54, v144 row_shl:15 row_mask:0xf bank_mask:0xf
	v_fmac_f32_dpp v191, v55, v145 row_shl:15 row_mask:0xf bank_mask:0xf
	v_fmac_f32_dpp v192, v44, v110 row_shl:15 row_mask:0xf bank_mask:0xf
	v_fmac_f32_dpp v193, v45, v111 row_shl:15 row_mask:0xf bank_mask:0xf
	v_fmac_f32_dpp v194, v46, v112 row_shl:15 row_mask:0xf bank_mask:0xf
	v_fmac_f32_dpp v195, v47, v113 row_shl:15 row_mask:0xf bank_mask:0xf
	v_fmac_f32_dpp v188, v52, v154 row_shl:14 row_mask:0xf bank_mask:0xf
	v_fmac_f32_dpp v189, v53, v155 row_shl:14 row_mask:0xf bank_mask:0xf
	v_fmac_f32_dpp v190, v54, v156 row_shl:14 row_mask:0xf bank_mask:0xf
	v_fmac_f32_dpp v191, v55, v157 row_shl:14 row_mask:0xf bank_mask:0xf
	v_fmac_f32_dpp v192, v44, v118 row_shl:14 row_mask:0xf bank_mask:0xf
	v_fmac_f32_dpp v193, v45, v119 row_shl:14 row_mask:0xf bank_mask:0xf
	v_fmac_f32_dpp v194, v46, v120 row_shl:14 row_mask:0xf bank_mask:0xf
	v_fmac_f32_dpp v195, v47, v121 row_shl:14 row_mask:0xf bank_mask:0xf
	v_pk_mul_f32 v[196:197], v[188:189], v[216:217] op_sel_hi:[1,0]
	v_pk_mul_f32 v[198:199], v[190:191], v[216:217] op_sel_hi:[1,0]
	v_exp_f32_e32 v196, v196
	v_exp_f32_e32 v197, v197
	v_exp_f32_e32 v198, v198
	v_exp_f32_e32 v199, v199
	v_pk_add_f32 v[196:197], v[196:197], v[214:215] op_sel_hi:[1,0]
	v_pk_add_f32 v[198:199], v[198:199], v[214:215] op_sel_hi:[1,0]
	v_rcp_f32_e32 v196, v196
	v_rcp_f32_e32 v197, v197
	v_rcp_f32_e32 v198, v198
	v_rcp_f32_e32 v199, v199
	v_pk_mul_f32 v[188:189], v[188:189], v[196:197]
	v_pk_mul_f32 v[190:191], v[190:191], v[198:199]
	v_pk_mul_f32 v[188:189], v[188:189], v[192:193]
	v_pk_mul_f32 v[190:191], v[190:191], v[194:195]
	v_cvt_pk_bf16_f32 v152, v188, v189
	v_cvt_pk_bf16_f32 v153, v190, v191
	v_add_u32_e32 v213, 0x58000, v215
	global_store_dwordx4 v213, v[150:153], s[96:97]
	v_pk_fma_f32 v[188:189], v[40:41], v[134:135], v[130:131]
	v_pk_fma_f32 v[190:191], v[42:43], v[136:137], v[132:133]
	v_pk_fma_f32 v[192:193], v[32:33], v[204:205], v[208:209]
	v_pk_fma_f32 v[194:195], v[34:35], v[206:207], v[210:211]
	v_fmac_f32_dpp v188, v40, v142 row_shr:1 row_mask:0xf bank_mask:0xf
	v_fmac_f32_dpp v189, v41, v143 row_shr:1 row_mask:0xf bank_mask:0xf
	v_fmac_f32_dpp v190, v42, v144 row_shr:1 row_mask:0xf bank_mask:0xf
	v_fmac_f32_dpp v191, v43, v145 row_shr:1 row_mask:0xf bank_mask:0xf
	v_fmac_f32_dpp v192, v32, v110 row_shr:1 row_mask:0xf bank_mask:0xf
	v_fmac_f32_dpp v193, v33, v111 row_shr:1 row_mask:0xf bank_mask:0xf
	v_fmac_f32_dpp v194, v34, v112 row_shr:1 row_mask:0xf bank_mask:0xf
	v_fmac_f32_dpp v195, v35, v113 row_shr:1 row_mask:0xf bank_mask:0xf
	v_fmac_f32_dpp v188, v40, v154 row_shr:2 row_mask:0xf bank_mask:0xf
	v_fmac_f32_dpp v189, v41, v155 row_shr:2 row_mask:0xf bank_mask:0xf
	v_fmac_f32_dpp v190, v42, v156 row_shr:2 row_mask:0xf bank_mask:0xf
	v_fmac_f32_dpp v191, v43, v157 row_shr:2 row_mask:0xf bank_mask:0xf
	v_fmac_f32_dpp v192, v32, v118 row_shr:2 row_mask:0xf bank_mask:0xf
	v_fmac_f32_dpp v193, v33, v119 row_shr:2 row_mask:0xf bank_mask:0xf
	v_fmac_f32_dpp v194, v34, v120 row_shr:2 row_mask:0xf bank_mask:0xf
	v_fmac_f32_dpp v195, v35, v121 row_shr:2 row_mask:0xf bank_mask:0xf
	v_fmac_f32_dpp v188, v48, v142 row_shl:15 row_mask:0xf bank_mask:0xf
	v_fmac_f32_dpp v189, v49, v143 row_shl:15 row_mask:0xf bank_mask:0xf
	v_fmac_f32_dpp v190, v50, v144 row_shl:15 row_mask:0xf bank_mask:0xf
	v_fmac_f32_dpp v191, v51, v145 row_shl:15 row_mask:0xf bank_mask:0xf
	v_fmac_f32_dpp v192, v36, v110 row_shl:15 row_mask:0xf bank_mask:0xf
	v_fmac_f32_dpp v193, v37, v111 row_shl:15 row_mask:0xf bank_mask:0xf
	v_fmac_f32_dpp v194, v38, v112 row_shl:15 row_mask:0xf bank_mask:0xf
	v_fmac_f32_dpp v195, v39, v113 row_shl:15 row_mask:0xf bank_mask:0xf
	v_fmac_f32_dpp v188, v48, v154 row_shl:14 row_mask:0xf bank_mask:0xf
	v_fmac_f32_dpp v189, v49, v155 row_shl:14 row_mask:0xf bank_mask:0xf
	v_fmac_f32_dpp v190, v50, v156 row_shl:14 row_mask:0xf bank_mask:0xf
	v_fmac_f32_dpp v191, v51, v157 row_shl:14 row_mask:0xf bank_mask:0xf
	v_fmac_f32_dpp v192, v36, v118 row_shl:14 row_mask:0xf bank_mask:0xf
	v_fmac_f32_dpp v193, v37, v119 row_shl:14 row_mask:0xf bank_mask:0xf
	v_fmac_f32_dpp v194, v38, v120 row_shl:14 row_mask:0xf bank_mask:0xf
	v_fmac_f32_dpp v195, v39, v121 row_shl:14 row_mask:0xf bank_mask:0xf
	v_pk_mul_f32 v[196:197], v[188:189], v[216:217] op_sel_hi:[1,0]
	v_pk_mul_f32 v[198:199], v[190:191], v[216:217] op_sel_hi:[1,0]
	v_exp_f32_e32 v196, v196
	v_exp_f32_e32 v197, v197
	v_exp_f32_e32 v198, v198
	v_exp_f32_e32 v199, v199
	v_pk_add_f32 v[196:197], v[196:197], v[214:215] op_sel_hi:[1,0]
	v_pk_add_f32 v[198:199], v[198:199], v[214:215] op_sel_hi:[1,0]
	v_rcp_f32_e32 v196, v196
	v_rcp_f32_e32 v197, v197
	v_rcp_f32_e32 v198, v198
	v_rcp_f32_e32 v199, v199
	v_pk_mul_f32 v[188:189], v[188:189], v[196:197]
	v_pk_mul_f32 v[190:191], v[190:191], v[198:199]
	v_pk_mul_f32 v[188:189], v[188:189], v[192:193]
	v_pk_mul_f32 v[190:191], v[190:191], v[194:195]
	v_cvt_pk_bf16_f32 v148, v188, v189
	v_cvt_pk_bf16_f32 v149, v190, v191
	v_add_u32_e32 v213, 0x84000, v215
	global_store_dwordx4 v213, v[146:149], s[96:97]
	v_pk_fma_f32 v[188:189], v[28:29], v[134:135], v[130:131]
	v_pk_fma_f32 v[190:191], v[30:31], v[136:137], v[132:133]
	v_pk_fma_f32 v[192:193], v[16:17], v[204:205], v[208:209]
	v_pk_fma_f32 v[194:195], v[18:19], v[206:207], v[210:211]
	v_fmac_f32_dpp v188, v28, v142 row_shr:1 row_mask:0xf bank_mask:0xf
	v_fmac_f32_dpp v189, v29, v143 row_shr:1 row_mask:0xf bank_mask:0xf
	v_fmac_f32_dpp v190, v30, v144 row_shr:1 row_mask:0xf bank_mask:0xf
	v_fmac_f32_dpp v191, v31, v145 row_shr:1 row_mask:0xf bank_mask:0xf
	v_fmac_f32_dpp v192, v16, v110 row_shr:1 row_mask:0xf bank_mask:0xf
	v_fmac_f32_dpp v193, v17, v111 row_shr:1 row_mask:0xf bank_mask:0xf
	v_fmac_f32_dpp v194, v18, v112 row_shr:1 row_mask:0xf bank_mask:0xf
	v_fmac_f32_dpp v195, v19, v113 row_shr:1 row_mask:0xf bank_mask:0xf
	v_fmac_f32_dpp v188, v28, v154 row_shr:2 row_mask:0xf bank_mask:0xf
	v_fmac_f32_dpp v189, v29, v155 row_shr:2 row_mask:0xf bank_mask:0xf
	v_fmac_f32_dpp v190, v30, v156 row_shr:2 row_mask:0xf bank_mask:0xf
	v_fmac_f32_dpp v191, v31, v157 row_shr:2 row_mask:0xf bank_mask:0xf
	v_fmac_f32_dpp v192, v16, v118 row_shr:2 row_mask:0xf bank_mask:0xf
	v_fmac_f32_dpp v193, v17, v119 row_shr:2 row_mask:0xf bank_mask:0xf
	v_fmac_f32_dpp v194, v18, v120 row_shr:2 row_mask:0xf bank_mask:0xf
	v_fmac_f32_dpp v195, v19, v121 row_shr:2 row_mask:0xf bank_mask:0xf
	v_fmac_f32_dpp v188, v40, v142 row_shl:15 row_mask:0xf bank_mask:0xf
	v_fmac_f32_dpp v189, v41, v143 row_shl:15 row_mask:0xf bank_mask:0xf
	v_fmac_f32_dpp v190, v42, v144 row_shl:15 row_mask:0xf bank_mask:0xf
	v_fmac_f32_dpp v191, v43, v145 row_shl:15 row_mask:0xf bank_mask:0xf
	v_fmac_f32_dpp v192, v32, v110 row_shl:15 row_mask:0xf bank_mask:0xf
	v_fmac_f32_dpp v193, v33, v111 row_shl:15 row_mask:0xf bank_mask:0xf
	v_fmac_f32_dpp v194, v34, v112 row_shl:15 row_mask:0xf bank_mask:0xf
	v_fmac_f32_dpp v195, v35, v113 row_shl:15 row_mask:0xf bank_mask:0xf
	v_fmac_f32_dpp v188, v40, v154 row_shl:14 row_mask:0xf bank_mask:0xf
	v_fmac_f32_dpp v189, v41, v155 row_shl:14 row_mask:0xf bank_mask:0xf
	v_fmac_f32_dpp v190, v42, v156 row_shl:14 row_mask:0xf bank_mask:0xf
	v_fmac_f32_dpp v191, v43, v157 row_shl:14 row_mask:0xf bank_mask:0xf
	v_fmac_f32_dpp v192, v32, v118 row_shl:14 row_mask:0xf bank_mask:0xf
	v_fmac_f32_dpp v193, v33, v119 row_shl:14 row_mask:0xf bank_mask:0xf
	v_fmac_f32_dpp v194, v34, v120 row_shl:14 row_mask:0xf bank_mask:0xf
	v_fmac_f32_dpp v195, v35, v121 row_shl:14 row_mask:0xf bank_mask:0xf
	v_pk_mul_f32 v[196:197], v[188:189], v[216:217] op_sel_hi:[1,0]
	v_pk_mul_f32 v[198:199], v[190:191], v[216:217] op_sel_hi:[1,0]
	v_exp_f32_e32 v196, v196
	v_exp_f32_e32 v197, v197
	v_exp_f32_e32 v198, v198
	v_exp_f32_e32 v199, v199
	v_pk_add_f32 v[196:197], v[196:197], v[214:215] op_sel_hi:[1,0]
	v_pk_add_f32 v[198:199], v[198:199], v[214:215] op_sel_hi:[1,0]
	v_rcp_f32_e32 v196, v196
	v_rcp_f32_e32 v197, v197
	v_rcp_f32_e32 v198, v198
	v_rcp_f32_e32 v199, v199
	v_pk_mul_f32 v[188:189], v[188:189], v[196:197]
	v_pk_mul_f32 v[190:191], v[190:191], v[198:199]
	v_pk_mul_f32 v[188:189], v[188:189], v[192:193]
	v_pk_mul_f32 v[190:191], v[190:191], v[194:195]
	v_cvt_pk_bf16_f32 v140, v188, v189
	v_cvt_pk_bf16_f32 v141, v190, v191
	v_add_u32_e32 v213, 0xb0000, v215
	global_store_dwordx4 v213, v[138:141], s[96:97]
	v_pk_fma_f32 v[188:189], v[24:25], v[134:135], v[130:131]
	v_pk_fma_f32 v[190:191], v[26:27], v[136:137], v[132:133]
	v_pk_fma_f32 v[192:193], v[12:13], v[204:205], v[208:209]
	v_pk_fma_f32 v[194:195], v[14:15], v[206:207], v[210:211]
	v_fmac_f32_dpp v188, v24, v142 row_shr:1 row_mask:0xf bank_mask:0xf
	v_fmac_f32_dpp v189, v25, v143 row_shr:1 row_mask:0xf bank_mask:0xf
	v_fmac_f32_dpp v190, v26, v144 row_shr:1 row_mask:0xf bank_mask:0xf
	v_fmac_f32_dpp v191, v27, v145 row_shr:1 row_mask:0xf bank_mask:0xf
	v_fmac_f32_dpp v192, v12, v110 row_shr:1 row_mask:0xf bank_mask:0xf
	v_fmac_f32_dpp v193, v13, v111 row_shr:1 row_mask:0xf bank_mask:0xf
	v_fmac_f32_dpp v194, v14, v112 row_shr:1 row_mask:0xf bank_mask:0xf
	v_fmac_f32_dpp v195, v15, v113 row_shr:1 row_mask:0xf bank_mask:0xf
	v_fmac_f32_dpp v188, v24, v154 row_shr:2 row_mask:0xf bank_mask:0xf
	v_fmac_f32_dpp v189, v25, v155 row_shr:2 row_mask:0xf bank_mask:0xf
	v_fmac_f32_dpp v190, v26, v156 row_shr:2 row_mask:0xf bank_mask:0xf
	v_fmac_f32_dpp v191, v27, v157 row_shr:2 row_mask:0xf bank_mask:0xf
	v_fmac_f32_dpp v192, v12, v118 row_shr:2 row_mask:0xf bank_mask:0xf
	v_fmac_f32_dpp v193, v13, v119 row_shr:2 row_mask:0xf bank_mask:0xf
	v_fmac_f32_dpp v194, v14, v120 row_shr:2 row_mask:0xf bank_mask:0xf
	v_fmac_f32_dpp v195, v15, v121 row_shr:2 row_mask:0xf bank_mask:0xf
	v_fmac_f32_dpp v188, v28, v142 row_shl:15 row_mask:0xf bank_mask:0xf
	v_fmac_f32_dpp v189, v29, v143 row_shl:15 row_mask:0xf bank_mask:0xf
	v_fmac_f32_dpp v190, v30, v144 row_shl:15 row_mask:0xf bank_mask:0xf
	v_fmac_f32_dpp v191, v31, v145 row_shl:15 row_mask:0xf bank_mask:0xf
	v_fmac_f32_dpp v192, v16, v110 row_shl:15 row_mask:0xf bank_mask:0xf
	v_fmac_f32_dpp v193, v17, v111 row_shl:15 row_mask:0xf bank_mask:0xf
	v_fmac_f32_dpp v194, v18, v112 row_shl:15 row_mask:0xf bank_mask:0xf
	v_fmac_f32_dpp v195, v19, v113 row_shl:15 row_mask:0xf bank_mask:0xf
	v_fmac_f32_dpp v188, v28, v154 row_shl:14 row_mask:0xf bank_mask:0xf
	v_fmac_f32_dpp v189, v29, v155 row_shl:14 row_mask:0xf bank_mask:0xf
	v_fmac_f32_dpp v190, v30, v156 row_shl:14 row_mask:0xf bank_mask:0xf
	v_fmac_f32_dpp v191, v31, v157 row_shl:14 row_mask:0xf bank_mask:0xf
	v_fmac_f32_dpp v192, v16, v118 row_shl:14 row_mask:0xf bank_mask:0xf
	v_fmac_f32_dpp v193, v17, v119 row_shl:14 row_mask:0xf bank_mask:0xf
	v_fmac_f32_dpp v194, v18, v120 row_shl:14 row_mask:0xf bank_mask:0xf
	v_fmac_f32_dpp v195, v19, v121 row_shl:14 row_mask:0xf bank_mask:0xf
	v_pk_mul_f32 v[196:197], v[188:189], v[216:217] op_sel_hi:[1,0]
	v_pk_mul_f32 v[198:199], v[190:191], v[216:217] op_sel_hi:[1,0]
	v_exp_f32_e32 v196, v196
	v_exp_f32_e32 v197, v197
	v_exp_f32_e32 v198, v198
	v_exp_f32_e32 v199, v199
	v_pk_add_f32 v[196:197], v[196:197], v[214:215] op_sel_hi:[1,0]
	v_pk_add_f32 v[198:199], v[198:199], v[214:215] op_sel_hi:[1,0]
	v_rcp_f32_e32 v196, v196
	v_rcp_f32_e32 v197, v197
	v_rcp_f32_e32 v198, v198
	v_rcp_f32_e32 v199, v199
	v_pk_mul_f32 v[188:189], v[188:189], v[196:197]
	v_pk_mul_f32 v[190:191], v[190:191], v[198:199]
	v_pk_mul_f32 v[188:189], v[188:189], v[192:193]
	v_pk_mul_f32 v[190:191], v[190:191], v[194:195]
	v_cvt_pk_bf16_f32 v128, v188, v189
	v_cvt_pk_bf16_f32 v129, v190, v191
	v_add_u32_e32 v213, 0xdc000, v215
	global_store_dwordx4 v213, v[126:129], s[96:97]
	v_pk_fma_f32 v[188:189], v[20:21], v[134:135], v[130:131]
	v_pk_fma_f32 v[190:191], v[22:23], v[136:137], v[132:133]
	v_pk_fma_f32 v[192:193], v[8:9], v[204:205], v[208:209]
	v_pk_fma_f32 v[194:195], v[10:11], v[206:207], v[210:211]
	v_fmac_f32_dpp v188, v20, v142 row_shr:1 row_mask:0xf bank_mask:0xf
	v_fmac_f32_dpp v189, v21, v143 row_shr:1 row_mask:0xf bank_mask:0xf
	v_fmac_f32_dpp v190, v22, v144 row_shr:1 row_mask:0xf bank_mask:0xf
	v_fmac_f32_dpp v191, v23, v145 row_shr:1 row_mask:0xf bank_mask:0xf
	v_fmac_f32_dpp v192, v8, v110 row_shr:1 row_mask:0xf bank_mask:0xf
	v_fmac_f32_dpp v193, v9, v111 row_shr:1 row_mask:0xf bank_mask:0xf
	v_fmac_f32_dpp v194, v10, v112 row_shr:1 row_mask:0xf bank_mask:0xf
	v_fmac_f32_dpp v195, v11, v113 row_shr:1 row_mask:0xf bank_mask:0xf
	v_fmac_f32_dpp v188, v20, v154 row_shr:2 row_mask:0xf bank_mask:0xf
	v_fmac_f32_dpp v189, v21, v155 row_shr:2 row_mask:0xf bank_mask:0xf
	v_fmac_f32_dpp v190, v22, v156 row_shr:2 row_mask:0xf bank_mask:0xf
	v_fmac_f32_dpp v191, v23, v157 row_shr:2 row_mask:0xf bank_mask:0xf
	v_fmac_f32_dpp v192, v8, v118 row_shr:2 row_mask:0xf bank_mask:0xf
	v_fmac_f32_dpp v193, v9, v119 row_shr:2 row_mask:0xf bank_mask:0xf
	v_fmac_f32_dpp v194, v10, v120 row_shr:2 row_mask:0xf bank_mask:0xf
	v_fmac_f32_dpp v195, v11, v121 row_shr:2 row_mask:0xf bank_mask:0xf
	v_fmac_f32_dpp v188, v24, v142 row_shl:15 row_mask:0xf bank_mask:0xf
	v_fmac_f32_dpp v189, v25, v143 row_shl:15 row_mask:0xf bank_mask:0xf
	v_fmac_f32_dpp v190, v26, v144 row_shl:15 row_mask:0xf bank_mask:0xf
	v_fmac_f32_dpp v191, v27, v145 row_shl:15 row_mask:0xf bank_mask:0xf
	v_fmac_f32_dpp v192, v12, v110 row_shl:15 row_mask:0xf bank_mask:0xf
	v_fmac_f32_dpp v193, v13, v111 row_shl:15 row_mask:0xf bank_mask:0xf
	v_fmac_f32_dpp v194, v14, v112 row_shl:15 row_mask:0xf bank_mask:0xf
	v_fmac_f32_dpp v195, v15, v113 row_shl:15 row_mask:0xf bank_mask:0xf
	v_fmac_f32_dpp v188, v24, v154 row_shl:14 row_mask:0xf bank_mask:0xf
	v_fmac_f32_dpp v189, v25, v155 row_shl:14 row_mask:0xf bank_mask:0xf
	v_fmac_f32_dpp v190, v26, v156 row_shl:14 row_mask:0xf bank_mask:0xf
	v_fmac_f32_dpp v191, v27, v157 row_shl:14 row_mask:0xf bank_mask:0xf
	v_fmac_f32_dpp v192, v12, v118 row_shl:14 row_mask:0xf bank_mask:0xf
	v_fmac_f32_dpp v193, v13, v119 row_shl:14 row_mask:0xf bank_mask:0xf
	v_fmac_f32_dpp v194, v14, v120 row_shl:14 row_mask:0xf bank_mask:0xf
	v_fmac_f32_dpp v195, v15, v121 row_shl:14 row_mask:0xf bank_mask:0xf
	v_pk_mul_f32 v[196:197], v[188:189], v[216:217] op_sel_hi:[1,0]
	v_pk_mul_f32 v[198:199], v[190:191], v[216:217] op_sel_hi:[1,0]
	v_exp_f32_e32 v196, v196
	v_exp_f32_e32 v197, v197
	v_exp_f32_e32 v198, v198
	v_exp_f32_e32 v199, v199
	v_pk_add_f32 v[196:197], v[196:197], v[214:215] op_sel_hi:[1,0]
	v_pk_add_f32 v[198:199], v[198:199], v[214:215] op_sel_hi:[1,0]
	v_rcp_f32_e32 v196, v196
	v_rcp_f32_e32 v197, v197
	v_rcp_f32_e32 v198, v198
	v_rcp_f32_e32 v199, v199
	v_pk_mul_f32 v[188:189], v[188:189], v[196:197]
	v_pk_mul_f32 v[190:191], v[190:191], v[198:199]
	v_pk_mul_f32 v[188:189], v[188:189], v[192:193]
	v_pk_mul_f32 v[190:191], v[190:191], v[194:195]
	v_cvt_pk_bf16_f32 v124, v188, v189
	v_cvt_pk_bf16_f32 v125, v190, v191
	v_add_u32_e32 v213, 0x108000, v215
	global_store_dwordx4 v213, v[122:125], s[96:97]
	v_pk_fma_f32 v[188:189], v[4:5], v[134:135], v[130:131]
	v_pk_fma_f32 v[190:191], v[6:7], v[136:137], v[132:133]
	v_pk_fma_f32 v[192:193], v[0:1], v[204:205], v[208:209]
	v_pk_fma_f32 v[194:195], v[2:3], v[206:207], v[210:211]
	v_fmac_f32_dpp v188, v4, v142 row_shr:1 row_mask:0xf bank_mask:0xf
	v_fmac_f32_dpp v189, v5, v143 row_shr:1 row_mask:0xf bank_mask:0xf
	v_fmac_f32_dpp v190, v6, v144 row_shr:1 row_mask:0xf bank_mask:0xf
	v_fmac_f32_dpp v191, v7, v145 row_shr:1 row_mask:0xf bank_mask:0xf
	v_fmac_f32_dpp v192, v0, v110 row_shr:1 row_mask:0xf bank_mask:0xf
	v_fmac_f32_dpp v193, v1, v111 row_shr:1 row_mask:0xf bank_mask:0xf
	v_fmac_f32_dpp v194, v2, v112 row_shr:1 row_mask:0xf bank_mask:0xf
	v_fmac_f32_dpp v195, v3, v113 row_shr:1 row_mask:0xf bank_mask:0xf
	v_fmac_f32_dpp v188, v4, v154 row_shr:2 row_mask:0xf bank_mask:0xf
	v_fmac_f32_dpp v189, v5, v155 row_shr:2 row_mask:0xf bank_mask:0xf
	v_fmac_f32_dpp v190, v6, v156 row_shr:2 row_mask:0xf bank_mask:0xf
	v_fmac_f32_dpp v191, v7, v157 row_shr:2 row_mask:0xf bank_mask:0xf
	v_fmac_f32_dpp v192, v0, v118 row_shr:2 row_mask:0xf bank_mask:0xf
	v_fmac_f32_dpp v193, v1, v119 row_shr:2 row_mask:0xf bank_mask:0xf
	v_fmac_f32_dpp v194, v2, v120 row_shr:2 row_mask:0xf bank_mask:0xf
	v_fmac_f32_dpp v195, v3, v121 row_shr:2 row_mask:0xf bank_mask:0xf
	v_fmac_f32_dpp v188, v20, v142 row_shl:15 row_mask:0xf bank_mask:0xf
	v_fmac_f32_dpp v189, v21, v143 row_shl:15 row_mask:0xf bank_mask:0xf
	v_fmac_f32_dpp v190, v22, v144 row_shl:15 row_mask:0xf bank_mask:0xf
	v_fmac_f32_dpp v191, v23, v145 row_shl:15 row_mask:0xf bank_mask:0xf
	v_fmac_f32_dpp v192, v8, v110 row_shl:15 row_mask:0xf bank_mask:0xf
	v_fmac_f32_dpp v193, v9, v111 row_shl:15 row_mask:0xf bank_mask:0xf
	v_fmac_f32_dpp v194, v10, v112 row_shl:15 row_mask:0xf bank_mask:0xf
	v_fmac_f32_dpp v195, v11, v113 row_shl:15 row_mask:0xf bank_mask:0xf
	v_fmac_f32_dpp v188, v20, v154 row_shl:14 row_mask:0xf bank_mask:0xf
	v_fmac_f32_dpp v189, v21, v155 row_shl:14 row_mask:0xf bank_mask:0xf
	v_fmac_f32_dpp v190, v22, v156 row_shl:14 row_mask:0xf bank_mask:0xf
	v_fmac_f32_dpp v191, v23, v157 row_shl:14 row_mask:0xf bank_mask:0xf
	v_fmac_f32_dpp v192, v8, v118 row_shl:14 row_mask:0xf bank_mask:0xf
	v_fmac_f32_dpp v193, v9, v119 row_shl:14 row_mask:0xf bank_mask:0xf
	v_fmac_f32_dpp v194, v10, v120 row_shl:14 row_mask:0xf bank_mask:0xf
	v_fmac_f32_dpp v195, v11, v121 row_shl:14 row_mask:0xf bank_mask:0xf
	v_pk_mul_f32 v[196:197], v[188:189], v[216:217] op_sel_hi:[1,0]
	v_pk_mul_f32 v[198:199], v[190:191], v[216:217] op_sel_hi:[1,0]
	v_exp_f32_e32 v196, v196
	v_exp_f32_e32 v197, v197
	v_exp_f32_e32 v198, v198
	v_exp_f32_e32 v199, v199
	v_pk_add_f32 v[196:197], v[196:197], v[214:215] op_sel_hi:[1,0]
	v_pk_add_f32 v[198:199], v[198:199], v[214:215] op_sel_hi:[1,0]
	v_rcp_f32_e32 v196, v196
	v_rcp_f32_e32 v197, v197
	v_rcp_f32_e32 v198, v198
	v_rcp_f32_e32 v199, v199
	v_pk_mul_f32 v[188:189], v[188:189], v[196:197]
	v_pk_mul_f32 v[190:191], v[190:191], v[198:199]
	v_pk_mul_f32 v[188:189], v[188:189], v[192:193]
	v_pk_mul_f32 v[190:191], v[190:191], v[194:195]
	v_cvt_pk_bf16_f32 v116, v188, v189
	v_cvt_pk_bf16_f32 v117, v190, v191
	v_add_u32_e32 v213, 0x134000, v215
	global_store_dwordx4 v213, v[114:117], s[96:97]
	s_branch .LBB0_836
.LBB0_851:
	s_waitcnt vmcnt(0)
	s_cmpk_gt_u32 s3, 0xff
	s_cbranch_scc1 .LBB0_853
.LBB0_853:
	s_barrier

.LBB0_969:
	v_readlane_b32 s0, v255, 8
	v_readlane_b32 s1, v255, 9
	s_and_b64 vcc, exec, s[0:1]
	s_cbranch_vccnz .LBB0_1005
	s_add_u32 s18, s92, 0xa700000
	s_addc_u32 s19, s93, 0
	s_lshr_b32 s4, s3, 6
	s_lshr_b32 s5, s3, 8
	s_lshl_b32 s20, s4, 10
	s_mul_i32 s7, s37, 0x2c0000
	s_mul_hi_i32 s6, s37, 0x2c0000
	s_add_u32 s14, s18, s7
	s_addc_u32 s15, s19, s6
	s_add_i32 s21, s20, 0
	s_add_i32 m0, s21, 0x10000
	s_mul_i32 s0, s38, 0x2c0000
	v_and_b32_e32 v136, 63, v222
	v_lshrrev_b32_e32 v137, 3, v136
	v_lshrrev_b32_e32 v138, 6, v222
	v_lshl_add_u32 v139, v138, 3, v137
	v_and_b32_e32 v146, 7, v136
	v_and_b32_e32 v147, 6, v137
	v_xor_b32_e32 v146, v146, v147
	v_lshlrev_b32_e32 v146, 4, v146
	v_mul_u32_u24_e32 v147, 0x2c00, v139
	v_add_u32_e32 v147, v147, v146
	v_mov_b32_e32 v128, v147
	v_add_u32_e32 v130, 0xb0000, v147
	v_mov_b32_e32 v168, v147
	v_add_u32_e32 v172, 0xb0000, v147
	v_add_u32_e32 v130, 0xb0000, v147
	v_add_u32_e32 v172, 0xb0000, v147
	v_and_b32_e32 v147, 31, v139
	v_and_b32_e32 v148, 12, v147
	v_lshlrev_b32_e32 v148, 1, v148
	v_lshrrev_b32_e32 v149, 4, v147
	v_lshlrev_b32_e32 v149, 2, v149
	v_and_b32_e32 v147, 3, v147
	v_or3_b32 v147, v148, v149, v147
	v_and_b32_e32 v148, 0x60, v139
	v_add_u32_e32 v147, v147, v148
	v_mul_u32_u24_e32 v147, 0x2c00, v147
	v_add_u32_e32 v147, v147, v146
	v_mov_b32_e32 v170, v147
	v_add_u32_e32 v174, 0xb0000, v147
	v_add_u32_e32 v174, 0xb0000, v147
	v_and_b32_e32 v147, 15, v136
	v_lshrrev_b32_e32 v148, 4, v136
	v_and_b32_e32 v149, 6, v147
	v_xor_b32_e32 v148, v148, v149
	v_lshlrev_b32_e32 v148, 4, v148
	v_lshl_or_b32 v148, v147, 7, v148
	v_lshrrev_b32_e32 v149, 2, v138
	v_lshl_add_u32 v149, v149, 13, v148
	v_add_u32_e32 v142, 0x0, v149
	v_and_b32_e32 v147, 3, v138
	v_lshl_add_u32 v147, v147, 12, v148
	v_add_u32_e32 v140, 0x0, v147
	v_add_u32_e32 v141, 0x10000, v147
	v_add_u32_e32 v143, 0x14000, v147
	v_add_u32_e32 v145, 0x10000, v147
	global_load_lds_dwordx4 v170, s[14:15]
	s_add_i32 m0, s21, 0x12000
	s_mul_hi_i32 s1, s38, 0x2c0000
	s_add_u32 s0, s96, s0
	global_load_lds_dwordx4 v174, s[14:15]
	s_addc_u32 s1, s97, s1
	s_mov_b32 m0, s21
	s_add_i32 s22, s21, 0x2000
	global_load_lds_dwordx4 v168, s[0:1]
	s_mov_b32 m0, s22
	s_add_u32 s6, s14, 0x160000
	global_load_lds_dwordx4 v172, s[0:1]
	s_addc_u32 s7, s15, 0
	s_add_i32 m0, s21, 0x14000
	v_mov_b32_e32 v171, 0
	global_load_lds_dwordx4 v170, s[6:7]
	s_add_i32 m0, s21, 0x16000
	v_mov_b32_e32 v175, v171
	global_load_lds_dwordx4 v174, s[6:7]
	s_add_u32 s6, s0, 0x160000
	s_addc_u32 s7, s1, 0
	s_add_i32 s23, s21, 0x4000
	s_mov_b32 m0, s23
	s_add_i32 s24, s21, 0x6000
	global_load_lds_dwordx4 v168, s[6:7]
	s_mov_b32 m0, s24
	v_mov_b32_e32 v169, v171
	global_load_lds_dwordx4 v172, s[6:7]
	v_mov_b32_e32 v173, v171
	s_mov_b32 s25, 0
	v_lshl_add_u64 v[6:7], s[14:15], 0, v[170:171]
	v_lshl_add_u64 v[4:5], s[14:15], 0, v[174:175]
	v_lshl_add_u64 v[2:3], s[0:1], 0, v[168:169]
	s_cmp_lg_u32 s5, 1
	v_lshl_add_u64 v[0:1], s[0:1], 0, v[172:173]
	s_cbranch_scc1 .LBB0_972
.LBB0_972:
	s_lshl_b32 s4, s4, 5
	s_lshl_b32 s26, s5, 6
	s_lshl_b32 s6, s5, 13
	s_and_b32 s27, s4, 0x60
	s_add_u32 s10, s92, 0x50000
	s_mov_b64 s[12:13], 0x80
	s_addc_u32 s11, s93, 0
	s_add_i32 m0, s21, 0x18000
	v_lshl_add_u64 v[6:7], v[6:7], 0, s[12:13]
	s_waitcnt vmcnt(4)
	s_barrier
	global_load_lds_dwordx4 v[6:7], off
	v_lshl_add_u64 v[4:5], v[4:5], 0, s[12:13]
	s_add_i32 m0, s21, 0x1a000
	s_add_i32 s28, s21, 0x8000
	s_add_i32 s29, s21, 0xa000
	global_load_lds_dwordx4 v[4:5], off
	v_lshl_add_u64 v[2:3], v[2:3], 0, s[12:13]
	s_mov_b32 m0, s28
	s_add_u32 s4, s14, 0x160080
	global_load_lds_dwordx4 v[2:3], off
	v_lshl_add_u64 v[0:1], v[0:1], 0, s[12:13]
	s_mov_b32 m0, s29
	s_addc_u32 s5, s15, 0
	global_load_lds_dwordx4 v[0:1], off
	s_add_i32 m0, s21, 0x1c000
	v_lshl_add_u64 v[0:1], s[4:5], 0, v[170:171]
	global_load_lds_dwordx4 v[0:1], off
	v_lshl_add_u64 v[0:1], s[4:5], 0, v[174:175]
	s_add_i32 m0, s21, 0x1e000
	global_load_lds_dwordx4 v[0:1], off
	v_lshlrev_b32_e32 v1, 2, v163
	v_lshl_or_b32 v0, v163, 6, v227
	v_and_b32_e32 v1, 32, v1
	v_bitop3_b32 v0, v0, s6, v1 bitop3:0xde
	s_waitcnt vmcnt(6)
	v_add_u16_e32 v1, v226, v224
	v_lshrrev_b16_e32 v1, 1, v1
	s_add_i32 s33, 0, 0x10000
	s_add_i32 s34, 0, 0x14000
	v_mbcnt_lo_u32_b32 v0, -1, 0
	s_ashr_i32 s30, s94, 31
	s_mov_b32 s31, s94
	v_mov_b32_e32 v129, v171
	v_mov_b32_e32 v131, v171
	v_mov_b64_e32 v[132:133], 0x200
	v_mov_b64_e32 v[134:135], 0x1ff
	v_mbcnt_hi_u32_b32 v144, -1, v0
	s_barrier
	s_branch .LBB0_974

.LBB0_984:
	s_add_u32 s0, s0, 0x160080
	s_addc_u32 s1, s1, 0
	s_add_u32 s39, s14, 0x100
	v_mov_b32_e32 v0, 0
	s_addc_u32 s40, s15, 0
	s_mov_b32 s41, -2
	s_waitcnt lgkmcnt(0)
	v_mov_b32_e32 v1, v0
	v_mov_b32_e32 v2, v0
	v_mov_b32_e32 v3, v0
	v_mov_b32_e32 v4, v0
	v_mov_b32_e32 v5, v0
	v_mov_b32_e32 v6, v0
	v_mov_b32_e32 v7, v0
	s_waitcnt vmcnt(0)
	v_mov_b32_e32 v16, v0
	v_mov_b32_e32 v17, v0
	v_mov_b32_e32 v18, v0
	v_mov_b32_e32 v19, v0
	v_mov_b32_e32 v20, v0
	v_mov_b32_e32 v21, v0
	v_mov_b32_e32 v22, v0
	v_mov_b32_e32 v23, v0
	v_mov_b32_e32 v32, v0
	v_mov_b32_e32 v33, v0
	v_mov_b32_e32 v34, v0
	v_mov_b32_e32 v35, v0
	v_mov_b32_e32 v36, v0
	v_mov_b32_e32 v37, v0
	v_mov_b32_e32 v38, v0
	v_mov_b32_e32 v39, v0
	v_mov_b32_e32 v48, v0
	v_mov_b32_e32 v49, v0
	v_mov_b32_e32 v50, v0
	v_mov_b32_e32 v51, v0
	v_mov_b32_e32 v52, v0
	v_mov_b32_e32 v53, v0
	v_mov_b32_e32 v54, v0
	v_mov_b32_e32 v55, v0
	v_mov_b32_e32 v8, v0
	v_mov_b32_e32 v9, v0
	v_mov_b32_e32 v10, v0
	v_mov_b32_e32 v11, v0
	v_mov_b32_e32 v12, v0
	v_mov_b32_e32 v13, v0
	v_mov_b32_e32 v14, v0
	v_mov_b32_e32 v15, v0
	v_mov_b32_e32 v24, v0
	v_mov_b32_e32 v25, v0
	v_mov_b32_e32 v26, v0
	v_mov_b32_e32 v27, v0
	v_mov_b32_e32 v28, v0
	v_mov_b32_e32 v29, v0
	v_mov_b32_e32 v30, v0
	v_mov_b32_e32 v31, v0
	v_mov_b32_e32 v40, v0
	v_mov_b32_e32 v41, v0
	v_mov_b32_e32 v42, v0
	v_mov_b32_e32 v43, v0
	v_mov_b32_e32 v44, v0
	v_mov_b32_e32 v45, v0
	v_mov_b32_e32 v46, v0
	v_mov_b32_e32 v47, v0
	v_mov_b32_e32 v56, v0
	v_mov_b32_e32 v57, v0
	v_mov_b32_e32 v58, v0
	v_mov_b32_e32 v59, v0
	v_mov_b32_e32 v60, v0
	v_mov_b32_e32 v61, v0
	v_mov_b32_e32 v62, v0
	v_mov_b32_e32 v63, v0
	v_mov_b32_e32 v64, v0
	v_mov_b32_e32 v65, v0
	v_mov_b32_e32 v66, v0
	v_mov_b32_e32 v67, v0
	v_mov_b32_e32 v68, v0
	v_mov_b32_e32 v69, v0
	v_mov_b32_e32 v70, v0
	v_mov_b32_e32 v71, v0
	v_mov_b32_e32 v80, v0
	v_mov_b32_e32 v81, v0
	v_mov_b32_e32 v82, v0
	v_mov_b32_e32 v83, v0
	v_mov_b32_e32 v84, v0
	v_mov_b32_e32 v85, v0
	v_mov_b32_e32 v86, v0
	v_mov_b32_e32 v87, v0
	v_mov_b32_e32 v96, v0
	v_mov_b32_e32 v97, v0
	v_mov_b32_e32 v98, v0
	v_mov_b32_e32 v99, v0
	v_mov_b32_e32 v100, v0
	v_mov_b32_e32 v101, v0
	v_mov_b32_e32 v102, v0
	v_mov_b32_e32 v103, v0
	v_mov_b32_e32 v112, v0
	v_mov_b32_e32 v113, v0
	v_mov_b32_e32 v114, v0
	v_mov_b32_e32 v115, v0
	v_mov_b32_e32 v116, v0
	v_mov_b32_e32 v117, v0
	v_mov_b32_e32 v118, v0
	v_mov_b32_e32 v119, v0
	v_mov_b32_e32 v72, v0
	v_mov_b32_e32 v73, v0
	v_mov_b32_e32 v74, v0
	v_mov_b32_e32 v75, v0
	v_mov_b32_e32 v76, v0
	v_mov_b32_e32 v77, v0
	v_mov_b32_e32 v78, v0
	v_mov_b32_e32 v79, v0
	v_mov_b32_e32 v88, v0
	v_mov_b32_e32 v89, v0
	v_mov_b32_e32 v90, v0
	v_mov_b32_e32 v91, v0
	v_mov_b32_e32 v92, v0
	v_mov_b32_e32 v93, v0
	v_mov_b32_e32 v94, v0
	v_mov_b32_e32 v95, v0
	v_mov_b32_e32 v104, v0
	v_mov_b32_e32 v105, v0
	v_mov_b32_e32 v106, v0
	v_mov_b32_e32 v107, v0
	v_mov_b32_e32 v108, v0
	v_mov_b32_e32 v109, v0
	v_mov_b32_e32 v110, v0
	v_mov_b32_e32 v111, v0
	v_mov_b32_e32 v120, v0
	v_mov_b32_e32 v121, v0
	v_mov_b32_e32 v122, v0
	v_mov_b32_e32 v123, v0
	v_mov_b32_e32 v124, v0
	v_mov_b32_e32 v125, v0
	v_mov_b32_e32 v126, v0
	v_mov_b32_e32 v127, v0
	v_xor_b32_e32 v216, 64, v141
	v_xor_b32_e32 v217, 64, v142
	v_xor_b32_e32 v218, 64, v143
	v_add_u32_e32 v219, 0x18000, v140
	v_xor_b32_e32 v220, 64, v219
	s_cmpk_lt_u32 s3, 0x100
	s_cbranch_scc1 .Lst_in_s9
	s_barrier
.Lst_in_s9:
.LBB0_985:
	ds_read_b128 v[136:139], v141
	ds_read_b128 v[146:149], v216
	ds_read_b128 v[150:153], v141 offset:2048
	ds_read_b128 v[154:157], v216 offset:2048
	s_add_u32 s14, s0, 0xffea0080
	s_addc_u32 s15, s1, -1
	s_cmpk_eq_i32 s41, 0x54
	s_cselect_b32 s17, s5, s15
	s_cselect_b32 s16, s4, s14
	s_cselect_b32 s15, s7, s40
	s_cselect_b32 s14, s6, s39
	s_add_i32 m0, s21, 0xc000
	ds_read_b128 v[158:161], v142
	ds_read_b128 v[164:167], v217
	ds_read_b128 v[176:179], v142 offset:2048
	ds_read_b128 v[180:183], v217 offset:2048
	ds_read_b128 v[184:187], v142 offset:4096
	ds_read_b128 v[188:191], v217 offset:4096
	ds_read_b128 v[192:195], v142 offset:6144
	ds_read_b128 v[196:199], v217 offset:6144
	global_load_lds_dwordx4 v128, s[0:1]
	s_add_i32 m0, s21, 0xe000
	s_nop 0
	global_load_lds_dwordx4 v130, s[0:1]
	s_waitcnt lgkmcnt(8)
	s_barrier
	s_waitcnt lgkmcnt(0)
	s_waitcnt lgkmcnt(0)
	v_mfma_f32_16x16x32_bf16 v[124:127], v[136:139], v[158:161], v[124:127]
	v_mfma_f32_16x16x32_bf16 v[124:127], v[146:149], v[164:167], v[124:127]
	v_mfma_f32_16x16x32_bf16 v[120:123], v[154:157], v[164:167], v[120:123]
	v_mfma_f32_16x16x32_bf16 v[120:123], v[150:153], v[158:161], v[120:123]
	v_mfma_f32_16x16x32_bf16 v[104:107], v[150:153], v[176:179], v[104:107]
	v_mfma_f32_16x16x32_bf16 v[104:107], v[154:157], v[180:183], v[104:107]
	v_mfma_f32_16x16x32_bf16 v[108:111], v[146:149], v[180:183], v[108:111]
	v_mfma_f32_16x16x32_bf16 v[108:111], v[136:139], v[176:179], v[108:111]
	v_mfma_f32_16x16x32_bf16 v[92:95], v[136:139], v[184:187], v[92:95]
	v_mfma_f32_16x16x32_bf16 v[92:95], v[146:149], v[188:191], v[92:95]
	v_mfma_f32_16x16x32_bf16 v[88:91], v[154:157], v[188:191], v[88:91]
	v_mfma_f32_16x16x32_bf16 v[88:91], v[150:153], v[184:187], v[88:91]
	v_mfma_f32_16x16x32_bf16 v[72:75], v[150:153], v[192:195], v[72:75]
	v_mfma_f32_16x16x32_bf16 v[72:75], v[154:157], v[196:199], v[72:75]
	v_mfma_f32_16x16x32_bf16 v[76:79], v[146:149], v[196:199], v[76:79]
	v_mfma_f32_16x16x32_bf16 v[76:79], v[136:139], v[192:195], v[76:79]
	s_barrier
	s_add_i32 s42, s33, s20
	s_add_u32 s98, s14, s12
	s_addc_u32 s99, s15, s13
	s_mov_b32 m0, s42
	ds_read_b128 v[200:203], v143
	ds_read_b128 v[204:207], v218
	ds_read_b128 v[208:211], v143 offset:2048
	ds_read_b128 v[212:215], v218 offset:2048
	global_load_lds_dwordx4 v170, s[14:15]
	s_add_i32 m0, s42, 0x2000
	s_nop 0
	global_load_lds_dwordx4 v174, s[14:15]
	s_barrier
	s_waitcnt lgkmcnt(0)
	s_waitcnt lgkmcnt(0)
	v_mfma_f32_16x16x32_bf16 v[116:119], v[200:203], v[158:161], v[116:119]
	v_mfma_f32_16x16x32_bf16 v[116:119], v[204:207], v[164:167], v[116:119]
	v_mfma_f32_16x16x32_bf16 v[112:115], v[212:215], v[164:167], v[112:115]
	v_mfma_f32_16x16x32_bf16 v[112:115], v[208:211], v[158:161], v[112:115]
	v_mfma_f32_16x16x32_bf16 v[96:99], v[208:211], v[176:179], v[96:99]
	v_mfma_f32_16x16x32_bf16 v[96:99], v[212:215], v[180:183], v[96:99]
	v_mfma_f32_16x16x32_bf16 v[100:103], v[204:207], v[180:183], v[100:103]
	v_mfma_f32_16x16x32_bf16 v[100:103], v[200:203], v[176:179], v[100:103]
	v_mfma_f32_16x16x32_bf16 v[84:87], v[200:203], v[184:187], v[84:87]
	v_mfma_f32_16x16x32_bf16 v[84:87], v[204:207], v[188:191], v[84:87]
	v_mfma_f32_16x16x32_bf16 v[80:83], v[212:215], v[188:191], v[80:83]
	v_mfma_f32_16x16x32_bf16 v[80:83], v[208:211], v[184:187], v[80:83]
	v_mfma_f32_16x16x32_bf16 v[64:67], v[208:211], v[192:195], v[64:67]
	v_mfma_f32_16x16x32_bf16 v[64:67], v[212:215], v[196:199], v[64:67]
	v_mfma_f32_16x16x32_bf16 v[68:71], v[204:207], v[196:199], v[68:71]
	v_mfma_f32_16x16x32_bf16 v[68:71], v[200:203], v[192:195], v[68:71]
	s_mov_b32 m0, s21
	s_add_u32 s100, s16, s12
	s_addc_u32 s101, s17, s13
	s_barrier
	ds_read_b128 v[158:161], v142 offset:16384
	ds_read_b128 v[164:167], v217 offset:16384
	ds_read_b128 v[176:179], v142 offset:18432
	ds_read_b128 v[180:183], v217 offset:18432
	ds_read_b128 v[184:187], v142 offset:20480
	ds_read_b128 v[188:191], v217 offset:20480
	ds_read_b128 v[192:195], v142 offset:22528
	ds_read_b128 v[196:199], v217 offset:22528
	global_load_lds_dwordx4 v168, s[16:17]
	s_mov_b32 m0, s22
	s_nop 0
	global_load_lds_dwordx4 v172, s[16:17]
	s_barrier
	s_waitcnt lgkmcnt(0)
	s_waitcnt lgkmcnt(0)
	v_mfma_f32_16x16x32_bf16 v[60:63], v[136:139], v[158:161], v[60:63]
	v_mfma_f32_16x16x32_bf16 v[60:63], v[146:149], v[164:167], v[60:63]
	v_mfma_f32_16x16x32_bf16 v[56:59], v[154:157], v[164:167], v[56:59]
	v_mfma_f32_16x16x32_bf16 v[56:59], v[150:153], v[158:161], v[56:59]
	v_mfma_f32_16x16x32_bf16 v[40:43], v[150:153], v[176:179], v[40:43]
	v_mfma_f32_16x16x32_bf16 v[40:43], v[154:157], v[180:183], v[40:43]
	v_mfma_f32_16x16x32_bf16 v[44:47], v[146:149], v[180:183], v[44:47]
	v_mfma_f32_16x16x32_bf16 v[44:47], v[136:139], v[176:179], v[44:47]
	v_mfma_f32_16x16x32_bf16 v[28:31], v[136:139], v[184:187], v[28:31]
	v_mfma_f32_16x16x32_bf16 v[28:31], v[146:149], v[188:191], v[28:31]
	v_mfma_f32_16x16x32_bf16 v[24:27], v[154:157], v[188:191], v[24:27]
	v_mfma_f32_16x16x32_bf16 v[24:27], v[150:153], v[184:187], v[24:27]
	v_mfma_f32_16x16x32_bf16 v[8:11], v[150:153], v[192:195], v[8:11]
	v_mfma_f32_16x16x32_bf16 v[8:11], v[154:157], v[196:199], v[8:11]
	v_mfma_f32_16x16x32_bf16 v[12:15], v[146:149], v[196:199], v[12:15]
	v_mfma_f32_16x16x32_bf16 v[12:15], v[136:139], v[192:195], v[12:15]
	s_barrier
	s_add_u32 s42, s14, 0x160000
	s_addc_u32 s43, s15, 0
	s_add_i32 s44, s34, s20
	s_mov_b32 m0, s44
	s_nop 0
	global_load_lds_dwordx4 v170, s[42:43]
	s_add_i32 m0, s44, 0x2000
	s_nop 0
	global_load_lds_dwordx4 v174, s[42:43]
	s_waitcnt vmcnt(6)
	s_barrier
	v_mfma_f32_16x16x32_bf16 v[52:55], v[200:203], v[158:161], v[52:55]
	v_mfma_f32_16x16x32_bf16 v[52:55], v[204:207], v[164:167], v[52:55]
	v_mfma_f32_16x16x32_bf16 v[48:51], v[212:215], v[164:167], v[48:51]
	v_mfma_f32_16x16x32_bf16 v[48:51], v[208:211], v[158:161], v[48:51]
	v_mfma_f32_16x16x32_bf16 v[32:35], v[208:211], v[176:179], v[32:35]
	v_mfma_f32_16x16x32_bf16 v[32:35], v[212:215], v[180:183], v[32:35]
	v_mfma_f32_16x16x32_bf16 v[36:39], v[204:207], v[180:183], v[36:39]
	v_mfma_f32_16x16x32_bf16 v[36:39], v[200:203], v[176:179], v[36:39]
	v_mfma_f32_16x16x32_bf16 v[20:23], v[200:203], v[184:187], v[20:23]
	v_mfma_f32_16x16x32_bf16 v[20:23], v[204:207], v[188:191], v[20:23]
	v_mfma_f32_16x16x32_bf16 v[16:19], v[212:215], v[188:191], v[16:19]
	v_mfma_f32_16x16x32_bf16 v[16:19], v[208:211], v[184:187], v[16:19]
	v_mfma_f32_16x16x32_bf16 v[0:3], v[208:211], v[192:195], v[0:3]
	v_mfma_f32_16x16x32_bf16 v[0:3], v[212:215], v[196:199], v[0:3]
	v_mfma_f32_16x16x32_bf16 v[4:7], v[204:207], v[196:199], v[4:7]
	v_mfma_f32_16x16x32_bf16 v[4:7], v[200:203], v[192:195], v[4:7]
	s_add_i32 s42, 0, 0x18000
	s_barrier
	ds_read_b128 v[136:139], v219
	ds_read_b128 v[146:149], v220
	ds_read_b128 v[150:153], v219 offset:2048
	ds_read_b128 v[154:157], v220 offset:2048
	s_add_u32 s16, s16, 0x160000
	s_addc_u32 s17, s17, 0
	s_mov_b32 m0, s23
	ds_read_b128 v[158:161], v142 offset:32768
	ds_read_b128 v[164:167], v217 offset:32768
	ds_read_b128 v[176:179], v142 offset:34816
	ds_read_b128 v[180:183], v217 offset:34816
	ds_read_b128 v[184:187], v142 offset:36864
	ds_read_b128 v[188:191], v217 offset:36864
	ds_read_b128 v[192:195], v142 offset:38912
	ds_read_b128 v[196:199], v217 offset:38912
	global_load_lds_dwordx4 v168, s[16:17]
	s_mov_b32 m0, s24
	s_nop 0
	global_load_lds_dwordx4 v172, s[16:17]
	s_waitcnt lgkmcnt(8)
	s_barrier
	s_waitcnt lgkmcnt(0)
	s_waitcnt lgkmcnt(0)
	v_mfma_f32_16x16x32_bf16 v[124:127], v[136:139], v[158:161], v[124:127]
	v_mfma_f32_16x16x32_bf16 v[124:127], v[146:149], v[164:167], v[124:127]
	v_mfma_f32_16x16x32_bf16 v[120:123], v[154:157], v[164:167], v[120:123]
	v_mfma_f32_16x16x32_bf16 v[120:123], v[150:153], v[158:161], v[120:123]
	v_mfma_f32_16x16x32_bf16 v[104:107], v[150:153], v[176:179], v[104:107]
	v_mfma_f32_16x16x32_bf16 v[104:107], v[154:157], v[180:183], v[104:107]
	v_mfma_f32_16x16x32_bf16 v[108:111], v[146:149], v[180:183], v[108:111]
	v_mfma_f32_16x16x32_bf16 v[108:111], v[136:139], v[176:179], v[108:111]
	v_mfma_f32_16x16x32_bf16 v[92:95], v[136:139], v[184:187], v[92:95]
	v_mfma_f32_16x16x32_bf16 v[92:95], v[146:149], v[188:191], v[92:95]
	v_mfma_f32_16x16x32_bf16 v[88:91], v[154:157], v[188:191], v[88:91]
	v_mfma_f32_16x16x32_bf16 v[88:91], v[150:153], v[184:187], v[88:91]
	v_mfma_f32_16x16x32_bf16 v[72:75], v[150:153], v[192:195], v[72:75]
	v_mfma_f32_16x16x32_bf16 v[72:75], v[154:157], v[196:199], v[72:75]
	v_mfma_f32_16x16x32_bf16 v[76:79], v[146:149], v[196:199], v[76:79]
	v_mfma_f32_16x16x32_bf16 v[76:79], v[136:139], v[192:195], v[76:79]
	s_barrier
	s_add_i32 s16, 0, 0x1c000
	s_add_i32 s17, s42, s20
	v_add_u32_e32 v145, s16, v140
	s_mov_b32 m0, s17
	ds_read_b128 v[200:203], v145
	v_xor_b32_e32 v215, 64, v145
	ds_read_b128 v[204:207], v215
	ds_read_b128 v[208:211], v145 offset:2048
	ds_read_b128 v[212:215], v215 offset:2048
	global_load_lds_dwordx4 v170, s[98:99]
	s_add_i32 m0, s17, 0x2000
	s_nop 0
	global_load_lds_dwordx4 v174, s[98:99]
	s_barrier
	s_waitcnt lgkmcnt(0)
	s_waitcnt lgkmcnt(0)
	v_mfma_f32_16x16x32_bf16 v[116:119], v[200:203], v[158:161], v[116:119]
	v_mfma_f32_16x16x32_bf16 v[116:119], v[204:207], v[164:167], v[116:119]
	v_mfma_f32_16x16x32_bf16 v[112:115], v[212:215], v[164:167], v[112:115]
	v_mfma_f32_16x16x32_bf16 v[112:115], v[208:211], v[158:161], v[112:115]
	v_mfma_f32_16x16x32_bf16 v[96:99], v[208:211], v[176:179], v[96:99]
	v_mfma_f32_16x16x32_bf16 v[96:99], v[212:215], v[180:183], v[96:99]
	v_mfma_f32_16x16x32_bf16 v[100:103], v[204:207], v[180:183], v[100:103]
	v_mfma_f32_16x16x32_bf16 v[100:103], v[200:203], v[176:179], v[100:103]
	v_mfma_f32_16x16x32_bf16 v[84:87], v[200:203], v[184:187], v[84:87]
	v_mfma_f32_16x16x32_bf16 v[84:87], v[204:207], v[188:191], v[84:87]
	v_mfma_f32_16x16x32_bf16 v[80:83], v[212:215], v[188:191], v[80:83]
	v_mfma_f32_16x16x32_bf16 v[80:83], v[208:211], v[184:187], v[80:83]
	v_mfma_f32_16x16x32_bf16 v[64:67], v[208:211], v[192:195], v[64:67]
	v_mfma_f32_16x16x32_bf16 v[64:67], v[212:215], v[196:199], v[64:67]
	v_mfma_f32_16x16x32_bf16 v[68:71], v[204:207], v[196:199], v[68:71]
	v_mfma_f32_16x16x32_bf16 v[68:71], v[200:203], v[192:195], v[68:71]
	s_mov_b32 m0, s28
	s_barrier
	ds_read_b128 v[158:161], v142 offset:49152
	ds_read_b128 v[164:167], v217 offset:49152
	ds_read_b128 v[176:179], v142 offset:51200
	ds_read_b128 v[180:183], v217 offset:51200
	ds_read_b128 v[184:187], v142 offset:53248
	ds_read_b128 v[188:191], v217 offset:53248
	ds_read_b128 v[192:195], v142 offset:55296
	ds_read_b128 v[196:199], v217 offset:55296
	global_load_lds_dwordx4 v168, s[100:101]
	s_mov_b32 m0, s29
	s_nop 0
	global_load_lds_dwordx4 v172, s[100:101]
	s_barrier
	s_waitcnt lgkmcnt(0)
	s_waitcnt lgkmcnt(0)
	v_mfma_f32_16x16x32_bf16 v[60:63], v[136:139], v[158:161], v[60:63]
	v_mfma_f32_16x16x32_bf16 v[60:63], v[146:149], v[164:167], v[60:63]
	v_mfma_f32_16x16x32_bf16 v[56:59], v[154:157], v[164:167], v[56:59]
	v_mfma_f32_16x16x32_bf16 v[56:59], v[150:153], v[158:161], v[56:59]
	v_mfma_f32_16x16x32_bf16 v[40:43], v[150:153], v[176:179], v[40:43]
	v_mfma_f32_16x16x32_bf16 v[40:43], v[154:157], v[180:183], v[40:43]
	v_mfma_f32_16x16x32_bf16 v[44:47], v[146:149], v[180:183], v[44:47]
	v_mfma_f32_16x16x32_bf16 v[44:47], v[136:139], v[176:179], v[44:47]
	v_mfma_f32_16x16x32_bf16 v[28:31], v[136:139], v[184:187], v[28:31]
	v_mfma_f32_16x16x32_bf16 v[28:31], v[146:149], v[188:191], v[28:31]
	v_mfma_f32_16x16x32_bf16 v[24:27], v[154:157], v[188:191], v[24:27]
	v_mfma_f32_16x16x32_bf16 v[24:27], v[150:153], v[184:187], v[24:27]
	v_mfma_f32_16x16x32_bf16 v[8:11], v[150:153], v[192:195], v[8:11]
	v_mfma_f32_16x16x32_bf16 v[8:11], v[154:157], v[196:199], v[8:11]
	v_mfma_f32_16x16x32_bf16 v[12:15], v[146:149], v[196:199], v[12:15]
	v_mfma_f32_16x16x32_bf16 v[12:15], v[136:139], v[192:195], v[12:15]
	s_barrier
	s_add_u32 s14, s14, 0x160080
	s_addc_u32 s15, s15, 0
	s_add_i32 s16, s16, s20
	s_mov_b32 m0, s16
	s_nop 0
	global_load_lds_dwordx4 v170, s[14:15]
	s_add_i32 m0, s16, 0x2000
	s_nop 0
	global_load_lds_dwordx4 v174, s[14:15]
	s_waitcnt vmcnt(6)
	s_barrier
	v_mfma_f32_16x16x32_bf16 v[52:55], v[200:203], v[158:161], v[52:55]
	v_mfma_f32_16x16x32_bf16 v[52:55], v[204:207], v[164:167], v[52:55]
	v_mfma_f32_16x16x32_bf16 v[48:51], v[212:215], v[164:167], v[48:51]
	v_mfma_f32_16x16x32_bf16 v[48:51], v[208:211], v[158:161], v[48:51]
	v_mfma_f32_16x16x32_bf16 v[32:35], v[208:211], v[176:179], v[32:35]
	v_mfma_f32_16x16x32_bf16 v[32:35], v[212:215], v[180:183], v[32:35]
	v_mfma_f32_16x16x32_bf16 v[36:39], v[204:207], v[180:183], v[36:39]
	v_mfma_f32_16x16x32_bf16 v[36:39], v[200:203], v[176:179], v[36:39]
	v_mfma_f32_16x16x32_bf16 v[20:23], v[200:203], v[184:187], v[20:23]
	v_mfma_f32_16x16x32_bf16 v[20:23], v[204:207], v[188:191], v[20:23]
	v_mfma_f32_16x16x32_bf16 v[16:19], v[212:215], v[188:191], v[16:19]
	v_mfma_f32_16x16x32_bf16 v[16:19], v[208:211], v[184:187], v[16:19]
	v_mfma_f32_16x16x32_bf16 v[0:3], v[208:211], v[192:195], v[0:3]
	v_mfma_f32_16x16x32_bf16 v[0:3], v[212:215], v[196:199], v[0:3]
	v_mfma_f32_16x16x32_bf16 v[4:7], v[204:207], v[196:199], v[4:7]
	v_mfma_f32_16x16x32_bf16 v[4:7], v[200:203], v[192:195], v[4:7]
	s_add_i32 s41, s41, 2
	s_add_u32 s0, s0, 0x100
	s_addc_u32 s1, s1, 0
	s_add_u32 s39, s39, 0x100
	s_addc_u32 s40, s40, 0
	s_cmpk_gt_u32 s41, 0x55
	s_barrier
	s_cbranch_scc0 .LBB0_985
	s_cmpk_gt_u32 s3, 0xff
	s_cbranch_scc1 .Lst_out_s9
	s_barrier
.Lst_out_s9:
	v_lshl_add_u32 v217, s38, 8, v163
	v_add_u32_e32 v217, s26, v217
	v_lshlrev_b32_e32 v208, 2, v217
	v_lshl_add_u32 v214, v225, 3, s27
	v_lshl_add_u32 v214, s37, 8, v214
	v_lshl_add_u32 v209, v217, 11, v214
	v_lshlrev_b32_e32 v209, 1, v209
	v_lshlrev_b32_e32 v210, 1, v209
	v_lshl_add_u32 v217, v225, 4, v163
	v_xor_b32_e32 v215, 16, v217
	v_lshlrev_b32_e32 v215, 2, v215
	v_xor_b32_e32 v216, 32, v217
	v_lshlrev_b32_e32 v216, 2, v216
	v_add_u32_e32 v211, 0x0, v209
	global_load_dwordx4 v[176:179], v211, s[80:81]
	global_load_dwordx4 v[180:183], v211, s[80:81] offset:256
	v_add_u32_e32 v211, 0x10000, v209
	global_load_dwordx4 v[192:195], v211, s[80:81]
	global_load_dwordx4 v[196:199], v211, s[80:81] offset:256
	s_waitcnt vmcnt(2)
	v_lshlrev_b32_e32 v184, 16, v176
	v_and_b32_e32 v185, 0xffff0000, v176
	v_lshlrev_b32_e32 v186, 16, v177
	v_and_b32_e32 v187, 0xffff0000, v177
	v_lshlrev_b32_e32 v188, 16, v178
	v_and_b32_e32 v189, 0xffff0000, v178
	v_lshlrev_b32_e32 v190, 16, v179
	v_and_b32_e32 v191, 0xffff0000, v179
	v_pk_add_f32 v[124:125], v[124:125], v[184:185]
	v_pk_add_f32 v[126:127], v[126:127], v[186:187]
	v_pk_add_f32 v[120:121], v[120:121], v[188:189]
	v_pk_add_f32 v[122:123], v[122:123], v[190:191]
	v_mul_f32_e32 v213, v124, v124
	v_fmac_f32_e32 v213, v125, v125
	v_fmac_f32_e32 v213, v126, v126
	v_fmac_f32_e32 v213, v127, v127
	v_fmac_f32_e32 v213, v120, v120
	v_fmac_f32_e32 v213, v121, v121
	v_fmac_f32_e32 v213, v122, v122
	v_fmac_f32_e32 v213, v123, v123
	v_add_u32_e32 v212, 0x0, v210
	global_store_dwordx4 v212, v[124:127], s[90:91]
	global_store_dwordx4 v212, v[120:123], s[90:91] offset:16
	v_lshlrev_b32_e32 v184, 16, v180
	v_and_b32_e32 v185, 0xffff0000, v180
	v_lshlrev_b32_e32 v186, 16, v181
	v_and_b32_e32 v187, 0xffff0000, v181
	v_lshlrev_b32_e32 v188, 16, v182
	v_and_b32_e32 v189, 0xffff0000, v182
	v_lshlrev_b32_e32 v190, 16, v183
	v_and_b32_e32 v191, 0xffff0000, v183
	v_pk_add_f32 v[116:117], v[116:117], v[184:185]
	v_pk_add_f32 v[118:119], v[118:119], v[186:187]
	v_pk_add_f32 v[112:113], v[112:113], v[188:189]
	v_pk_add_f32 v[114:115], v[114:115], v[190:191]
	v_fmac_f32_e32 v213, v116, v116
	v_fmac_f32_e32 v213, v117, v117
	v_fmac_f32_e32 v213, v118, v118
	v_fmac_f32_e32 v213, v119, v119
	v_fmac_f32_e32 v213, v112, v112
	v_fmac_f32_e32 v213, v113, v113
	v_fmac_f32_e32 v213, v114, v114
	v_fmac_f32_e32 v213, v115, v115
	global_store_dwordx4 v212, v[116:119], s[90:91] offset:512
	global_store_dwordx4 v212, v[112:115], s[90:91] offset:528
	ds_bpermute_b32 v214, v215, v213
	s_waitcnt lgkmcnt(0)
	v_add_f32_e32 v213, v213, v214
	ds_bpermute_b32 v214, v216, v213
	s_waitcnt lgkmcnt(0)
	v_add_f32_e32 v213, v213, v214
	s_mov_b64 exec, 0xffff
	global_atomic_add_f32 v208, v213, s[10:11]
	s_mov_b64 exec, -1
	v_add_u32_e32 v211, 0x20000, v209
	global_load_dwordx4 v[176:179], v211, s[80:81]
	global_load_dwordx4 v[180:183], v211, s[80:81] offset:256
	s_waitcnt vmcnt(7)
	v_lshlrev_b32_e32 v200, 16, v192
	v_and_b32_e32 v201, 0xffff0000, v192
	v_lshlrev_b32_e32 v202, 16, v193
	v_and_b32_e32 v203, 0xffff0000, v193
	v_lshlrev_b32_e32 v204, 16, v194
	v_and_b32_e32 v205, 0xffff0000, v194
	v_lshlrev_b32_e32 v206, 16, v195
	v_and_b32_e32 v207, 0xffff0000, v195
	v_pk_add_f32 v[108:109], v[108:109], v[200:201]
	v_pk_add_f32 v[110:111], v[110:111], v[202:203]
	v_pk_add_f32 v[104:105], v[104:105], v[204:205]
	v_pk_add_f32 v[106:107], v[106:107], v[206:207]
	v_mul_f32_e32 v213, v108, v108
	v_fmac_f32_e32 v213, v109, v109
	v_fmac_f32_e32 v213, v110, v110
	v_fmac_f32_e32 v213, v111, v111
	v_fmac_f32_e32 v213, v104, v104
	v_fmac_f32_e32 v213, v105, v105
	v_fmac_f32_e32 v213, v106, v106
	v_fmac_f32_e32 v213, v107, v107
	v_add_u32_e32 v212, 0x20000, v210
	global_store_dwordx4 v212, v[108:111], s[90:91]
	global_store_dwordx4 v212, v[104:107], s[90:91] offset:16
	v_lshlrev_b32_e32 v200, 16, v196
	v_and_b32_e32 v201, 0xffff0000, v196
	v_lshlrev_b32_e32 v202, 16, v197
	v_and_b32_e32 v203, 0xffff0000, v197
	v_lshlrev_b32_e32 v204, 16, v198
	v_and_b32_e32 v205, 0xffff0000, v198
	v_lshlrev_b32_e32 v206, 16, v199
	v_and_b32_e32 v207, 0xffff0000, v199
	v_pk_add_f32 v[100:101], v[100:101], v[200:201]
	v_pk_add_f32 v[102:103], v[102:103], v[202:203]
	v_pk_add_f32 v[96:97], v[96:97], v[204:205]
	v_pk_add_f32 v[98:99], v[98:99], v[206:207]
	v_fmac_f32_e32 v213, v100, v100
	v_fmac_f32_e32 v213, v101, v101
	v_fmac_f32_e32 v213, v102, v102
	v_fmac_f32_e32 v213, v103, v103
	v_fmac_f32_e32 v213, v96, v96
	v_fmac_f32_e32 v213, v97, v97
	v_fmac_f32_e32 v213, v98, v98
	v_fmac_f32_e32 v213, v99, v99
	global_store_dwordx4 v212, v[100:103], s[90:91] offset:512
	global_store_dwordx4 v212, v[96:99], s[90:91] offset:528
	ds_bpermute_b32 v214, v215, v213
	s_waitcnt lgkmcnt(0)
	v_add_f32_e32 v213, v213, v214
	ds_bpermute_b32 v214, v216, v213
	s_waitcnt lgkmcnt(0)
	v_add_f32_e32 v213, v213, v214
	s_mov_b64 exec, 0xffff
	global_atomic_add_f32 v208, v213, s[10:11] offset:64
	s_mov_b64 exec, -1
	v_add_u32_e32 v211, 0x30000, v209
	global_load_dwordx4 v[192:195], v211, s[80:81]
	global_load_dwordx4 v[196:199], v211, s[80:81] offset:256
	s_waitcnt vmcnt(7)
	v_lshlrev_b32_e32 v184, 16, v176
	v_and_b32_e32 v185, 0xffff0000, v176
	v_lshlrev_b32_e32 v186, 16, v177
	v_and_b32_e32 v187, 0xffff0000, v177
	v_lshlrev_b32_e32 v188, 16, v178
	v_and_b32_e32 v189, 0xffff0000, v178
	v_lshlrev_b32_e32 v190, 16, v179
	v_and_b32_e32 v191, 0xffff0000, v179
	v_pk_add_f32 v[92:93], v[92:93], v[184:185]
	v_pk_add_f32 v[94:95], v[94:95], v[186:187]
	v_pk_add_f32 v[88:89], v[88:89], v[188:189]
	v_pk_add_f32 v[90:91], v[90:91], v[190:191]
	v_mul_f32_e32 v213, v92, v92
	v_fmac_f32_e32 v213, v93, v93
	v_fmac_f32_e32 v213, v94, v94
	v_fmac_f32_e32 v213, v95, v95
	v_fmac_f32_e32 v213, v88, v88
	v_fmac_f32_e32 v213, v89, v89
	v_fmac_f32_e32 v213, v90, v90
	v_fmac_f32_e32 v213, v91, v91
	v_add_u32_e32 v212, 0x40000, v210
	global_store_dwordx4 v212, v[92:95], s[90:91]
	global_store_dwordx4 v212, v[88:91], s[90:91] offset:16
	v_lshlrev_b32_e32 v184, 16, v180
	v_and_b32_e32 v185, 0xffff0000, v180
	v_lshlrev_b32_e32 v186, 16, v181
	v_and_b32_e32 v187, 0xffff0000, v181
	v_lshlrev_b32_e32 v188, 16, v182
	v_and_b32_e32 v189, 0xffff0000, v182
	v_lshlrev_b32_e32 v190, 16, v183
	v_and_b32_e32 v191, 0xffff0000, v183
	v_pk_add_f32 v[84:85], v[84:85], v[184:185]
	v_pk_add_f32 v[86:87], v[86:87], v[186:187]
	v_pk_add_f32 v[80:81], v[80:81], v[188:189]
	v_pk_add_f32 v[82:83], v[82:83], v[190:191]
	v_fmac_f32_e32 v213, v84, v84
	v_fmac_f32_e32 v213, v85, v85
	v_fmac_f32_e32 v213, v86, v86
	v_fmac_f32_e32 v213, v87, v87
	v_fmac_f32_e32 v213, v80, v80
	v_fmac_f32_e32 v213, v81, v81
	v_fmac_f32_e32 v213, v82, v82
	v_fmac_f32_e32 v213, v83, v83
	global_store_dwordx4 v212, v[84:87], s[90:91] offset:512
	global_store_dwordx4 v212, v[80:83], s[90:91] offset:528
	ds_bpermute_b32 v214, v215, v213
	s_waitcnt lgkmcnt(0)
	v_add_f32_e32 v213, v213, v214
	ds_bpermute_b32 v214, v216, v213
	s_waitcnt lgkmcnt(0)
	v_add_f32_e32 v213, v213, v214
	s_mov_b64 exec, 0xffff
	global_atomic_add_f32 v208, v213, s[10:11] offset:128
	s_mov_b64 exec, -1
	v_add_u32_e32 v211, 0x80000, v209
	global_load_dwordx4 v[176:179], v211, s[80:81]
	global_load_dwordx4 v[180:183], v211, s[80:81] offset:256
	s_waitcnt vmcnt(7)
	v_lshlrev_b32_e32 v200, 16, v192
	v_and_b32_e32 v201, 0xffff0000, v192
	v_lshlrev_b32_e32 v202, 16, v193
	v_and_b32_e32 v203, 0xffff0000, v193
	v_lshlrev_b32_e32 v204, 16, v194
	v_and_b32_e32 v205, 0xffff0000, v194
	v_lshlrev_b32_e32 v206, 16, v195
	v_and_b32_e32 v207, 0xffff0000, v195
	v_pk_add_f32 v[76:77], v[76:77], v[200:201]
	v_pk_add_f32 v[78:79], v[78:79], v[202:203]
	v_pk_add_f32 v[72:73], v[72:73], v[204:205]
	v_pk_add_f32 v[74:75], v[74:75], v[206:207]
	v_mul_f32_e32 v213, v76, v76
	v_fmac_f32_e32 v213, v77, v77
	v_fmac_f32_e32 v213, v78, v78
	v_fmac_f32_e32 v213, v79, v79
	v_fmac_f32_e32 v213, v72, v72
	v_fmac_f32_e32 v213, v73, v73
	v_fmac_f32_e32 v213, v74, v74
	v_fmac_f32_e32 v213, v75, v75
	v_add_u32_e32 v212, 0x60000, v210
	global_store_dwordx4 v212, v[76:79], s[90:91]
	global_store_dwordx4 v212, v[72:75], s[90:91] offset:16
	v_lshlrev_b32_e32 v200, 16, v196
	v_and_b32_e32 v201, 0xffff0000, v196
	v_lshlrev_b32_e32 v202, 16, v197
	v_and_b32_e32 v203, 0xffff0000, v197
	v_lshlrev_b32_e32 v204, 16, v198
	v_and_b32_e32 v205, 0xffff0000, v198
	v_lshlrev_b32_e32 v206, 16, v199
	v_and_b32_e32 v207, 0xffff0000, v199
	v_pk_add_f32 v[68:69], v[68:69], v[200:201]
	v_pk_add_f32 v[70:71], v[70:71], v[202:203]
	v_pk_add_f32 v[64:65], v[64:65], v[204:205]
	v_pk_add_f32 v[66:67], v[66:67], v[206:207]
	v_fmac_f32_e32 v213, v68, v68
	v_fmac_f32_e32 v213, v69, v69
	v_fmac_f32_e32 v213, v70, v70
	v_fmac_f32_e32 v213, v71, v71
	v_fmac_f32_e32 v213, v64, v64
	v_fmac_f32_e32 v213, v65, v65
	v_fmac_f32_e32 v213, v66, v66
	v_fmac_f32_e32 v213, v67, v67
	global_store_dwordx4 v212, v[68:71], s[90:91] offset:512
	global_store_dwordx4 v212, v[64:67], s[90:91] offset:528
	ds_bpermute_b32 v214, v215, v213
	s_waitcnt lgkmcnt(0)
	v_add_f32_e32 v213, v213, v214
	ds_bpermute_b32 v214, v216, v213
	s_waitcnt lgkmcnt(0)
	v_add_f32_e32 v213, v213, v214
	s_mov_b64 exec, 0xffff
	global_atomic_add_f32 v208, v213, s[10:11] offset:192
	s_mov_b64 exec, -1
	v_add_u32_e32 v211, 0x90000, v209
	global_load_dwordx4 v[192:195], v211, s[80:81]
	global_load_dwordx4 v[196:199], v211, s[80:81] offset:256
	s_waitcnt vmcnt(7)
	v_lshlrev_b32_e32 v184, 16, v176
	v_and_b32_e32 v185, 0xffff0000, v176
	v_lshlrev_b32_e32 v186, 16, v177
	v_and_b32_e32 v187, 0xffff0000, v177
	v_lshlrev_b32_e32 v188, 16, v178
	v_and_b32_e32 v189, 0xffff0000, v178
	v_lshlrev_b32_e32 v190, 16, v179
	v_and_b32_e32 v191, 0xffff0000, v179
	v_pk_add_f32 v[60:61], v[60:61], v[184:185]
	v_pk_add_f32 v[62:63], v[62:63], v[186:187]
	v_pk_add_f32 v[56:57], v[56:57], v[188:189]
	v_pk_add_f32 v[58:59], v[58:59], v[190:191]
	v_mul_f32_e32 v213, v60, v60
	v_fmac_f32_e32 v213, v61, v61
	v_fmac_f32_e32 v213, v62, v62
	v_fmac_f32_e32 v213, v63, v63
	v_fmac_f32_e32 v213, v56, v56
	v_fmac_f32_e32 v213, v57, v57
	v_fmac_f32_e32 v213, v58, v58
	v_fmac_f32_e32 v213, v59, v59
	v_add_u32_e32 v212, 0x100000, v210
	global_store_dwordx4 v212, v[60:63], s[90:91]
	global_store_dwordx4 v212, v[56:59], s[90:91] offset:16
	v_lshlrev_b32_e32 v184, 16, v180
	v_and_b32_e32 v185, 0xffff0000, v180
	v_lshlrev_b32_e32 v186, 16, v181
	v_and_b32_e32 v187, 0xffff0000, v181
	v_lshlrev_b32_e32 v188, 16, v182
	v_and_b32_e32 v189, 0xffff0000, v182
	v_lshlrev_b32_e32 v190, 16, v183
	v_and_b32_e32 v191, 0xffff0000, v183
	v_pk_add_f32 v[52:53], v[52:53], v[184:185]
	v_pk_add_f32 v[54:55], v[54:55], v[186:187]
	v_pk_add_f32 v[48:49], v[48:49], v[188:189]
	v_pk_add_f32 v[50:51], v[50:51], v[190:191]
	v_fmac_f32_e32 v213, v52, v52
	v_fmac_f32_e32 v213, v53, v53
	v_fmac_f32_e32 v213, v54, v54
	v_fmac_f32_e32 v213, v55, v55
	v_fmac_f32_e32 v213, v48, v48
	v_fmac_f32_e32 v213, v49, v49
	v_fmac_f32_e32 v213, v50, v50
	v_fmac_f32_e32 v213, v51, v51
	global_store_dwordx4 v212, v[52:55], s[90:91] offset:512
	global_store_dwordx4 v212, v[48:51], s[90:91] offset:528
	ds_bpermute_b32 v214, v215, v213
	s_waitcnt lgkmcnt(0)
	v_add_f32_e32 v213, v213, v214
	ds_bpermute_b32 v214, v216, v213
	s_waitcnt lgkmcnt(0)
	v_add_f32_e32 v213, v213, v214
	s_mov_b64 exec, 0xffff
	global_atomic_add_f32 v208, v213, s[10:11] offset:512
	s_mov_b64 exec, -1
	v_add_u32_e32 v211, 0xa0000, v209
	global_load_dwordx4 v[176:179], v211, s[80:81]
	global_load_dwordx4 v[180:183], v211, s[80:81] offset:256
	s_waitcnt vmcnt(7)
	v_lshlrev_b32_e32 v200, 16, v192
	v_and_b32_e32 v201, 0xffff0000, v192
	v_lshlrev_b32_e32 v202, 16, v193
	v_and_b32_e32 v203, 0xffff0000, v193
	v_lshlrev_b32_e32 v204, 16, v194
	v_and_b32_e32 v205, 0xffff0000, v194
	v_lshlrev_b32_e32 v206, 16, v195
	v_and_b32_e32 v207, 0xffff0000, v195
	v_pk_add_f32 v[44:45], v[44:45], v[200:201]
	v_pk_add_f32 v[46:47], v[46:47], v[202:203]
	v_pk_add_f32 v[40:41], v[40:41], v[204:205]
	v_pk_add_f32 v[42:43], v[42:43], v[206:207]
	v_mul_f32_e32 v213, v44, v44
	v_fmac_f32_e32 v213, v45, v45
	v_fmac_f32_e32 v213, v46, v46
	v_fmac_f32_e32 v213, v47, v47
	v_fmac_f32_e32 v213, v40, v40
	v_fmac_f32_e32 v213, v41, v41
	v_fmac_f32_e32 v213, v42, v42
	v_fmac_f32_e32 v213, v43, v43
	v_add_u32_e32 v212, 0x120000, v210
	global_store_dwordx4 v212, v[44:47], s[90:91]
	global_store_dwordx4 v212, v[40:43], s[90:91] offset:16
	v_lshlrev_b32_e32 v200, 16, v196
	v_and_b32_e32 v201, 0xffff0000, v196
	v_lshlrev_b32_e32 v202, 16, v197
	v_and_b32_e32 v203, 0xffff0000, v197
	v_lshlrev_b32_e32 v204, 16, v198
	v_and_b32_e32 v205, 0xffff0000, v198
	v_lshlrev_b32_e32 v206, 16, v199
	v_and_b32_e32 v207, 0xffff0000, v199
	v_pk_add_f32 v[36:37], v[36:37], v[200:201]
	v_pk_add_f32 v[38:39], v[38:39], v[202:203]
	v_pk_add_f32 v[32:33], v[32:33], v[204:205]
	v_pk_add_f32 v[34:35], v[34:35], v[206:207]
	v_fmac_f32_e32 v213, v36, v36
	v_fmac_f32_e32 v213, v37, v37
	v_fmac_f32_e32 v213, v38, v38
	v_fmac_f32_e32 v213, v39, v39
	v_fmac_f32_e32 v213, v32, v32
	v_fmac_f32_e32 v213, v33, v33
	v_fmac_f32_e32 v213, v34, v34
	v_fmac_f32_e32 v213, v35, v35
	global_store_dwordx4 v212, v[36:39], s[90:91] offset:512
	global_store_dwordx4 v212, v[32:35], s[90:91] offset:528
	ds_bpermute_b32 v214, v215, v213
	s_waitcnt lgkmcnt(0)
	v_add_f32_e32 v213, v213, v214
	ds_bpermute_b32 v214, v216, v213
	s_waitcnt lgkmcnt(0)
	v_add_f32_e32 v213, v213, v214
	s_mov_b64 exec, 0xffff
	global_atomic_add_f32 v208, v213, s[10:11] offset:576
	s_mov_b64 exec, -1
	v_add_u32_e32 v211, 0xb0000, v209
	global_load_dwordx4 v[192:195], v211, s[80:81]
	global_load_dwordx4 v[196:199], v211, s[80:81] offset:256
	s_waitcnt vmcnt(7)
	v_lshlrev_b32_e32 v184, 16, v176
	v_and_b32_e32 v185, 0xffff0000, v176
	v_lshlrev_b32_e32 v186, 16, v177
	v_and_b32_e32 v187, 0xffff0000, v177
	v_lshlrev_b32_e32 v188, 16, v178
	v_and_b32_e32 v189, 0xffff0000, v178
	v_lshlrev_b32_e32 v190, 16, v179
	v_and_b32_e32 v191, 0xffff0000, v179
	v_pk_add_f32 v[28:29], v[28:29], v[184:185]
	v_pk_add_f32 v[30:31], v[30:31], v[186:187]
	v_pk_add_f32 v[24:25], v[24:25], v[188:189]
	v_pk_add_f32 v[26:27], v[26:27], v[190:191]
	v_mul_f32_e32 v213, v28, v28
	v_fmac_f32_e32 v213, v29, v29
	v_fmac_f32_e32 v213, v30, v30
	v_fmac_f32_e32 v213, v31, v31
	v_fmac_f32_e32 v213, v24, v24
	v_fmac_f32_e32 v213, v25, v25
	v_fmac_f32_e32 v213, v26, v26
	v_fmac_f32_e32 v213, v27, v27
	v_add_u32_e32 v212, 0x140000, v210
	global_store_dwordx4 v212, v[28:31], s[90:91]
	global_store_dwordx4 v212, v[24:27], s[90:91] offset:16
	v_lshlrev_b32_e32 v184, 16, v180
	v_and_b32_e32 v185, 0xffff0000, v180
	v_lshlrev_b32_e32 v186, 16, v181
	v_and_b32_e32 v187, 0xffff0000, v181
	v_lshlrev_b32_e32 v188, 16, v182
	v_and_b32_e32 v189, 0xffff0000, v182
	v_lshlrev_b32_e32 v190, 16, v183
	v_and_b32_e32 v191, 0xffff0000, v183
	v_pk_add_f32 v[20:21], v[20:21], v[184:185]
	v_pk_add_f32 v[22:23], v[22:23], v[186:187]
	v_pk_add_f32 v[16:17], v[16:17], v[188:189]
	v_pk_add_f32 v[18:19], v[18:19], v[190:191]
	v_fmac_f32_e32 v213, v20, v20
	v_fmac_f32_e32 v213, v21, v21
	v_fmac_f32_e32 v213, v22, v22
	v_fmac_f32_e32 v213, v23, v23
	v_fmac_f32_e32 v213, v16, v16
	v_fmac_f32_e32 v213, v17, v17
	v_fmac_f32_e32 v213, v18, v18
	v_fmac_f32_e32 v213, v19, v19
	global_store_dwordx4 v212, v[20:23], s[90:91] offset:512
	global_store_dwordx4 v212, v[16:19], s[90:91] offset:528
	ds_bpermute_b32 v214, v215, v213
	s_waitcnt lgkmcnt(0)
	v_add_f32_e32 v213, v213, v214
	ds_bpermute_b32 v214, v216, v213
	s_waitcnt lgkmcnt(0)
	v_add_f32_e32 v213, v213, v214
	s_mov_b64 exec, 0xffff
	global_atomic_add_f32 v208, v213, s[10:11] offset:640
	s_mov_b64 exec, -1
	s_waitcnt vmcnt(5)
	v_lshlrev_b32_e32 v200, 16, v192
	v_and_b32_e32 v201, 0xffff0000, v192
	v_lshlrev_b32_e32 v202, 16, v193
	v_and_b32_e32 v203, 0xffff0000, v193
	v_lshlrev_b32_e32 v204, 16, v194
	v_and_b32_e32 v205, 0xffff0000, v194
	v_lshlrev_b32_e32 v206, 16, v195
	v_and_b32_e32 v207, 0xffff0000, v195
	v_pk_add_f32 v[12:13], v[12:13], v[200:201]
	v_pk_add_f32 v[14:15], v[14:15], v[202:203]
	v_pk_add_f32 v[8:9], v[8:9], v[204:205]
	v_pk_add_f32 v[10:11], v[10:11], v[206:207]
	v_mul_f32_e32 v213, v12, v12
	v_fmac_f32_e32 v213, v13, v13
	v_fmac_f32_e32 v213, v14, v14
	v_fmac_f32_e32 v213, v15, v15
	v_fmac_f32_e32 v213, v8, v8
	v_fmac_f32_e32 v213, v9, v9
	v_fmac_f32_e32 v213, v10, v10
	v_fmac_f32_e32 v213, v11, v11
	v_add_u32_e32 v212, 0x160000, v210
	global_store_dwordx4 v212, v[12:15], s[90:91]
	global_store_dwordx4 v212, v[8:11], s[90:91] offset:16
	v_lshlrev_b32_e32 v200, 16, v196
	v_and_b32_e32 v201, 0xffff0000, v196
	v_lshlrev_b32_e32 v202, 16, v197
	v_and_b32_e32 v203, 0xffff0000, v197
	v_lshlrev_b32_e32 v204, 16, v198
	v_and_b32_e32 v205, 0xffff0000, v198
	v_lshlrev_b32_e32 v206, 16, v199
	v_and_b32_e32 v207, 0xffff0000, v199
	v_pk_add_f32 v[4:5], v[4:5], v[200:201]
	v_pk_add_f32 v[6:7], v[6:7], v[202:203]
	v_pk_add_f32 v[0:1], v[0:1], v[204:205]
	v_pk_add_f32 v[2:3], v[2:3], v[206:207]
	v_fmac_f32_e32 v213, v4, v4
	v_fmac_f32_e32 v213, v5, v5
	v_fmac_f32_e32 v213, v6, v6
	v_fmac_f32_e32 v213, v7, v7
	v_fmac_f32_e32 v213, v0, v0
	v_fmac_f32_e32 v213, v1, v1
	v_fmac_f32_e32 v213, v2, v2
	v_fmac_f32_e32 v213, v3, v3
	global_store_dwordx4 v212, v[4:7], s[90:91] offset:512
	global_store_dwordx4 v212, v[0:3], s[90:91] offset:528
	ds_bpermute_b32 v214, v215, v213
	s_waitcnt lgkmcnt(0)
	v_add_f32_e32 v213, v213, v214
	ds_bpermute_b32 v214, v216, v213
	s_waitcnt lgkmcnt(0)
	v_add_f32_e32 v213, v213, v214
	s_mov_b64 exec, 0xffff
	global_atomic_add_f32 v208, v213, s[10:11] offset:704
	s_mov_b64 exec, -1
	s_branch .LBB0_973
.LBB0_1002:
	s_waitcnt vmcnt(0)
	s_cmpk_gt_u32 s3, 0xff
	s_cbranch_scc1 .LBB0_1004
.LBB0_1004:
	s_barrier
